# K=1024 GEMM k-loops (in-proj, SwiGLU, out-proj) restaged through direct global-to-LDS loads with an XOR-swizzled unpadded LDS image and pipelined fragment reads; DIFF attention K-fragment reads hoiste
# speedup vs baseline: 1.0436x; 1.0348x over previous
;     ...
;     const u16* Ag = A + (size_t)(m0 + lrow) * K + lkc * 8;
;     const u16* Bg = Bt + (size_t)(n0 + lrow) * K + lkc * 8;
;     const size_t K32 = (size_t)32 * K;
;     uint4 xa0, xa1, xa2, xa3, xb0, xb1, xb2, xb3;
;     uint4 ya0, ya1, ya2, ya3, yb0, yb1, yb2, yb3;
;     ...
;     G_LOAD(x, 0);
;     G_STORE(x, 0);
;     __syncthreads();
;     if (KT > 1) G_LOAD(x, 1);
;     for (int kt = 0; kt < KT; kt += 2) {
;       if (kt + 2 < KT && dummy != 2) G_LOAD(y, kt + 2);
;       G_COMPUTE(0);
;       if (kt + 1 < KT && dummy != 2) G_STORE(x, 1);
;       __syncthreads();
;       if (kt + 1 >= KT) break;
;       if (kt + 3 < KT && dummy != 2) G_LOAD(x, kt + 3);
;       G_COMPUTE(1);
;       if (kt + 2 < KT && dummy != 2) G_STORE(y, 0);
;       __syncthreads();
;     }
.LBB0_188:
	s_lshl_b32 s0, s4, 3
	v_readlane_b32 s1, v252, 34
	s_or_b32 s5, s0, s1
	v_readlane_b32 s0, v252, 28
	v_readlane_b32 s1, v252, 29
	s_and_b64 s[0:1], s[0:1], exec
	s_cselect_b32 s0, s5, s4
	s_lshl_b32 s0, s0, 7
	s_lshl_b32 s1, s3, 7
	v_add_u32_e32 v0, s0, v154
	v_ashrrev_i32_e32 v1, 31, v0
	v_lshlrev_b64 v[0:1], 11, v[0:1]
	v_lshl_add_u64 v[138:139], v[130:131], 0, v[0:1]
	v_add_u32_e32 v0, s1, v154
	v_ashrrev_i32_e32 v1, 31, v0
	v_lshlrev_b64 v[0:1], 11, v[0:1]
	v_lshl_add_u64 v[140:141], v[132:133], 0, v[0:1]
	v_and_b32_e32 v194, 7, v206
	v_bfe_u32 v195, v206, 4, 3
	v_xor_b32_e32 v195, v195, v194
	v_sub_u32_e32 v195, v195, v194
	v_lshlrev_b32_e32 v192, 4, v195
	v_ashrrev_i32_e32 v193, 31, v192
	v_lshl_add_u64 v[138:139], v[138:139], 0, v[192:193]
	v_lshl_add_u64 v[140:141], v[140:141], 0, v[192:193]
	s_mov_b64 s[78:79], 0x10000
	v_lshl_add_u64 v[142:143], v[138:139], 0, s[78:79]
	v_lshl_add_u64 v[146:147], v[140:141], 0, s[78:79]
	s_mov_b64 s[78:79], 0x20000
	v_lshl_add_u64 v[144:145], v[138:139], 0, s[78:79]
	v_lshl_add_u64 v[148:149], v[140:141], 0, s[78:79]
	s_mov_b64 s[78:79], 0x30000
	v_lshl_add_u64 v[152:153], v[138:139], 0, s[78:79]
	v_lshl_add_u64 v[150:151], v[140:141], 0, s[78:79]
	v_lshrrev_b32_e32 v194, 6, v206
	v_lshlrev_b32_e32 v194, 10, v194
	s_nop 0
	v_readfirstlane_b32 s76, v194
	v_bfe_u32 v195, v206, 1, 3
	v_bfe_u32 v194, v206, 5, 1
	v_and_b32_e32 v192, 1, v195
	v_xor_b32_e32 v194, v194, v192
	v_lshrrev_b32_e32 v195, 1, v195
	v_and_b32_e32 v192, 31, v206
	v_lshrrev_b32_e32 v193, 7, v206
	v_lshl_add_u32 v193, v193, 6, v192
	v_lshlrev_b32_e32 v193, 7, v193
	v_lshl_add_u32 v193, v194, 4, v193
	v_add_u32_e32 v193, 2048, v193
	v_bfe_u32 v172, v206, 6, 1
	v_lshl_add_u32 v172, v172, 6, v192
	v_lshlrev_b32_e32 v172, 7, v172
	v_lshl_add_u32 v172, v194, 4, v172
	v_add_u32_e32 v172, 18432, v172
	v_xor_b32_e32 v192, 0, v195
	v_lshl_add_u32 v196, v192, 5, v193
	v_lshl_add_u32 v200, v192, 5, v172
	v_xor_b32_e32 v192, 1, v195
	v_lshl_add_u32 v197, v192, 5, v193
	v_lshl_add_u32 v201, v192, 5, v172
	v_xor_b32_e32 v192, 2, v195
	v_lshl_add_u32 v198, v192, 5, v193
	v_lshl_add_u32 v202, v192, 5, v172
	v_xor_b32_e32 v192, 3, v195
	v_lshl_add_u32 v199, v192, 5, v193
	v_lshl_add_u32 v203, v192, 5, v172
	s_add_u32 m0, s76, 0x800
	s_nop 0
	global_load_lds_dwordx4 v[138:139], off
	s_add_u32 m0, s76, 0x1800
	s_nop 0
	global_load_lds_dwordx4 v[142:143], off
	s_add_u32 m0, s76, 0x2800
	s_nop 0
	global_load_lds_dwordx4 v[144:145], off
	s_add_u32 m0, s76, 0x3800
	s_nop 0
	global_load_lds_dwordx4 v[152:153], off
	s_add_u32 m0, s76, 0x4800
	s_nop 0
	global_load_lds_dwordx4 v[140:141], off
	s_add_u32 m0, s76, 0x5800
	s_nop 0
	global_load_lds_dwordx4 v[146:147], off
	s_add_u32 m0, s76, 0x6800
	s_nop 0
	global_load_lds_dwordx4 v[148:149], off
	s_add_u32 m0, s76, 0x7800
	s_nop 0
	global_load_lds_dwordx4 v[150:151], off
	s_waitcnt vmcnt(0)
	s_barrier
	s_setprio 1
	ds_read_b128 v[156:159], v196
	ds_read_b128 v[164:167], v200
	ds_read_b128 v[168:171], v200 offset:4096
	ds_read_b128 v[172:175], v196 offset:4096
	ds_read_b128 v[176:179], v197
	ds_read_b128 v[180:183], v201
	ds_read_b128 v[184:187], v201 offset:4096
	ds_read_b128 v[188:191], v197 offset:4096
	s_add_u32 m0, s76, 0x8780
	s_nop 0
	global_load_lds_dwordx4 v[138:139], off offset:128
	s_add_u32 m0, s76, 0x9780
	s_nop 0
	global_load_lds_dwordx4 v[142:143], off offset:128
	s_add_u32 m0, s76, 0xa780
	s_nop 0
	global_load_lds_dwordx4 v[144:145], off offset:128
	s_add_u32 m0, s76, 0xb780
	s_nop 0
	global_load_lds_dwordx4 v[152:153], off offset:128
	s_add_u32 m0, s76, 0xc780
	s_nop 0
	global_load_lds_dwordx4 v[140:141], off offset:128
	s_add_u32 m0, s76, 0xd780
	s_nop 0
	global_load_lds_dwordx4 v[146:147], off offset:128
	s_add_u32 m0, s76, 0xe780
	s_nop 0
	global_load_lds_dwordx4 v[148:149], off offset:128
	s_add_u32 m0, s76, 0xf780
	s_nop 0
	global_load_lds_dwordx4 v[150:151], off offset:128
	s_waitcnt lgkmcnt(6)
	v_mfma_f32_32x32x16_bf16 v[32:47], v[156:159], v[164:167], 0
	s_waitcnt lgkmcnt(5)
	v_mfma_f32_32x32x16_bf16 v[48:63], v[156:159], v[168:171], 0
	s_waitcnt lgkmcnt(4)
	v_mfma_f32_32x32x16_bf16 v[0:15], v[172:175], v[164:167], 0
	v_mfma_f32_32x32x16_bf16 v[16:31], v[172:175], v[168:171], 0
	ds_read_b128 v[156:159], v198
	ds_read_b128 v[164:167], v202
	ds_read_b128 v[168:171], v202 offset:4096
	ds_read_b128 v[172:175], v198 offset:4096
	s_waitcnt lgkmcnt(6)
	v_mfma_f32_32x32x16_bf16 v[32:47], v[176:179], v[180:183], v[32:47]
	s_waitcnt lgkmcnt(5)
	v_mfma_f32_32x32x16_bf16 v[48:63], v[176:179], v[184:187], v[48:63]
	s_waitcnt lgkmcnt(4)
	v_mfma_f32_32x32x16_bf16 v[0:15], v[188:191], v[180:183], v[0:15]
	v_mfma_f32_32x32x16_bf16 v[16:31], v[188:191], v[184:187], v[16:31]
	ds_read_b128 v[176:179], v199
	ds_read_b128 v[180:183], v203
	ds_read_b128 v[184:187], v203 offset:4096
	ds_read_b128 v[188:191], v199 offset:4096
	s_waitcnt lgkmcnt(6)
	v_mfma_f32_32x32x16_bf16 v[32:47], v[156:159], v[164:167], v[32:47]
	s_waitcnt lgkmcnt(5)
	v_mfma_f32_32x32x16_bf16 v[48:63], v[156:159], v[168:171], v[48:63]
	s_waitcnt lgkmcnt(4)
	v_mfma_f32_32x32x16_bf16 v[0:15], v[172:175], v[164:167], v[0:15]
	v_mfma_f32_32x32x16_bf16 v[16:31], v[172:175], v[168:171], v[16:31]
	s_waitcnt lgkmcnt(2)
	v_mfma_f32_32x32x16_bf16 v[32:47], v[176:179], v[180:183], v[32:47]
	s_waitcnt lgkmcnt(1)
	v_mfma_f32_32x32x16_bf16 v[48:63], v[176:179], v[184:187], v[48:63]
	s_waitcnt lgkmcnt(0)
	v_mfma_f32_32x32x16_bf16 v[0:15], v[188:191], v[180:183], v[0:15]
	v_mfma_f32_32x32x16_bf16 v[16:31], v[188:191], v[184:187], v[16:31]
	s_setprio 0
	s_waitcnt vmcnt(0)
	s_barrier
;     ...
;     G_LOAD(x, 0);
;     G_STORE(x, 0);
;     __syncthreads();
;     if (KT > 1) G_LOAD(x, 1);
;     for (int kt = 0; kt < KT; kt += 2) {
;       if (kt + 2 < KT && dummy != 2) G_LOAD(y, kt + 2);
;       G_COMPUTE(0);
;       if (kt + 1 < KT && dummy != 2) G_STORE(x, 1);
;       __syncthreads();
;       if (kt + 1 >= KT) break;
;       if (kt + 3 < KT && dummy != 2) G_LOAD(x, kt + 3);
;       G_COMPUTE(1);
;       if (kt + 2 < KT && dummy != 2) G_STORE(y, 0);
;       __syncthreads();
	s_setprio 1
	ds_read_b128 v[156:159], v196 offset:32768
	ds_read_b128 v[164:167], v200 offset:32768
	ds_read_b128 v[168:171], v200 offset:36864
	ds_read_b128 v[172:175], v196 offset:36864
	ds_read_b128 v[176:179], v197 offset:32768
	ds_read_b128 v[180:183], v201 offset:32768
	ds_read_b128 v[184:187], v201 offset:36864
	ds_read_b128 v[188:191], v197 offset:36864
	s_add_u32 m0, s76, 0x700
	s_nop 0
	global_load_lds_dwordx4 v[138:139], off offset:256
	s_add_u32 m0, s76, 0x1700
	s_nop 0
	global_load_lds_dwordx4 v[142:143], off offset:256
	s_add_u32 m0, s76, 0x2700
	s_nop 0
	global_load_lds_dwordx4 v[144:145], off offset:256
	s_add_u32 m0, s76, 0x3700
	s_nop 0
	global_load_lds_dwordx4 v[152:153], off offset:256
	s_add_u32 m0, s76, 0x4700
	s_nop 0
	global_load_lds_dwordx4 v[140:141], off offset:256
	s_add_u32 m0, s76, 0x5700
	s_nop 0
	global_load_lds_dwordx4 v[146:147], off offset:256
	s_add_u32 m0, s76, 0x6700
	s_nop 0
	global_load_lds_dwordx4 v[148:149], off offset:256
	s_add_u32 m0, s76, 0x7700
	s_nop 0
	global_load_lds_dwordx4 v[150:151], off offset:256
	s_waitcnt lgkmcnt(6)
	v_mfma_f32_32x32x16_bf16 v[32:47], v[156:159], v[164:167], v[32:47]
	s_waitcnt lgkmcnt(5)
	v_mfma_f32_32x32x16_bf16 v[48:63], v[156:159], v[168:171], v[48:63]
	s_waitcnt lgkmcnt(4)
	v_mfma_f32_32x32x16_bf16 v[0:15], v[172:175], v[164:167], v[0:15]
	v_mfma_f32_32x32x16_bf16 v[16:31], v[172:175], v[168:171], v[16:31]
	ds_read_b128 v[156:159], v198 offset:32768
	ds_read_b128 v[164:167], v202 offset:32768
	ds_read_b128 v[168:171], v202 offset:36864
	ds_read_b128 v[172:175], v198 offset:36864
	s_waitcnt lgkmcnt(6)
	v_mfma_f32_32x32x16_bf16 v[32:47], v[176:179], v[180:183], v[32:47]
	s_waitcnt lgkmcnt(5)
	v_mfma_f32_32x32x16_bf16 v[48:63], v[176:179], v[184:187], v[48:63]
	s_waitcnt lgkmcnt(4)
	v_mfma_f32_32x32x16_bf16 v[0:15], v[188:191], v[180:183], v[0:15]
	v_mfma_f32_32x32x16_bf16 v[16:31], v[188:191], v[184:187], v[16:31]
	ds_read_b128 v[176:179], v199 offset:32768
	ds_read_b128 v[180:183], v203 offset:32768
	ds_read_b128 v[184:187], v203 offset:36864
	ds_read_b128 v[188:191], v199 offset:36864
	s_waitcnt lgkmcnt(6)
	v_mfma_f32_32x32x16_bf16 v[32:47], v[156:159], v[164:167], v[32:47]
	s_waitcnt lgkmcnt(5)
	v_mfma_f32_32x32x16_bf16 v[48:63], v[156:159], v[168:171], v[48:63]
	s_waitcnt lgkmcnt(4)
	v_mfma_f32_32x32x16_bf16 v[0:15], v[172:175], v[164:167], v[0:15]
	v_mfma_f32_32x32x16_bf16 v[16:31], v[172:175], v[168:171], v[16:31]
	s_waitcnt lgkmcnt(2)
	v_mfma_f32_32x32x16_bf16 v[32:47], v[176:179], v[180:183], v[32:47]
	s_waitcnt lgkmcnt(1)
	v_mfma_f32_32x32x16_bf16 v[48:63], v[176:179], v[184:187], v[48:63]
	s_waitcnt lgkmcnt(0)
	v_mfma_f32_32x32x16_bf16 v[0:15], v[188:191], v[180:183], v[0:15]
	v_mfma_f32_32x32x16_bf16 v[16:31], v[188:191], v[184:187], v[16:31]
	s_setprio 0
	s_waitcnt vmcnt(0)
	s_barrier
	s_setprio 1
	ds_read_b128 v[156:159], v196
	ds_read_b128 v[164:167], v200
	ds_read_b128 v[168:171], v200 offset:4096
	ds_read_b128 v[172:175], v196 offset:4096
	ds_read_b128 v[176:179], v197
	ds_read_b128 v[180:183], v201
	ds_read_b128 v[184:187], v201 offset:4096
	ds_read_b128 v[188:191], v197 offset:4096
	s_add_u32 m0, s76, 0x8680
	s_nop 0
	global_load_lds_dwordx4 v[138:139], off offset:384
	s_add_u32 m0, s76, 0x9680
	s_nop 0
	global_load_lds_dwordx4 v[142:143], off offset:384
	s_add_u32 m0, s76, 0xa680
	s_nop 0
	global_load_lds_dwordx4 v[144:145], off offset:384
	s_add_u32 m0, s76, 0xb680
	s_nop 0
	global_load_lds_dwordx4 v[152:153], off offset:384
	s_add_u32 m0, s76, 0xc680
	s_nop 0
	global_load_lds_dwordx4 v[140:141], off offset:384
	s_add_u32 m0, s76, 0xd680
	s_nop 0
	global_load_lds_dwordx4 v[146:147], off offset:384
	s_add_u32 m0, s76, 0xe680
	s_nop 0
	global_load_lds_dwordx4 v[148:149], off offset:384
	s_add_u32 m0, s76, 0xf680
	s_nop 0
	global_load_lds_dwordx4 v[150:151], off offset:384
	s_waitcnt lgkmcnt(6)
	v_mfma_f32_32x32x16_bf16 v[32:47], v[156:159], v[164:167], v[32:47]
	s_waitcnt lgkmcnt(5)
	v_mfma_f32_32x32x16_bf16 v[48:63], v[156:159], v[168:171], v[48:63]
	s_waitcnt lgkmcnt(4)
	v_mfma_f32_32x32x16_bf16 v[0:15], v[172:175], v[164:167], v[0:15]
	v_mfma_f32_32x32x16_bf16 v[16:31], v[172:175], v[168:171], v[16:31]
	ds_read_b128 v[156:159], v198
	ds_read_b128 v[164:167], v202
	ds_read_b128 v[168:171], v202 offset:4096
	ds_read_b128 v[172:175], v198 offset:4096
	s_waitcnt lgkmcnt(6)
	v_mfma_f32_32x32x16_bf16 v[32:47], v[176:179], v[180:183], v[32:47]
	s_waitcnt lgkmcnt(5)
	v_mfma_f32_32x32x16_bf16 v[48:63], v[176:179], v[184:187], v[48:63]
	s_waitcnt lgkmcnt(4)
	v_mfma_f32_32x32x16_bf16 v[0:15], v[188:191], v[180:183], v[0:15]
	v_mfma_f32_32x32x16_bf16 v[16:31], v[188:191], v[184:187], v[16:31]
	ds_read_b128 v[176:179], v199
	ds_read_b128 v[180:183], v203
	ds_read_b128 v[184:187], v203 offset:4096
	ds_read_b128 v[188:191], v199 offset:4096
	s_waitcnt lgkmcnt(6)
	v_mfma_f32_32x32x16_bf16 v[32:47], v[156:159], v[164:167], v[32:47]
	s_waitcnt lgkmcnt(5)
	v_mfma_f32_32x32x16_bf16 v[48:63], v[156:159], v[168:171], v[48:63]
	s_waitcnt lgkmcnt(4)
	v_mfma_f32_32x32x16_bf16 v[0:15], v[172:175], v[164:167], v[0:15]
	v_mfma_f32_32x32x16_bf16 v[16:31], v[172:175], v[168:171], v[16:31]
	s_waitcnt lgkmcnt(2)
	v_mfma_f32_32x32x16_bf16 v[32:47], v[176:179], v[180:183], v[32:47]
	s_waitcnt lgkmcnt(1)
	v_mfma_f32_32x32x16_bf16 v[48:63], v[176:179], v[184:187], v[48:63]
	s_waitcnt lgkmcnt(0)
	v_mfma_f32_32x32x16_bf16 v[0:15], v[188:191], v[180:183], v[0:15]
	v_mfma_f32_32x32x16_bf16 v[16:31], v[188:191], v[184:187], v[16:31]
	s_setprio 0
	s_waitcnt vmcnt(0)
	s_barrier
;     ...
;     G_LOAD(x, 0);
;     G_STORE(x, 0);
;     __syncthreads();
;     if (KT > 1) G_LOAD(x, 1);
;     for (int kt = 0; kt < KT; kt += 2) {
;       if (kt + 2 < KT && dummy != 2) G_LOAD(y, kt + 2);
;       G_COMPUTE(0);
;       if (kt + 1 < KT && dummy != 2) G_STORE(x, 1);
;       __syncthreads();
;       if (kt + 1 >= KT) break;
;       if (kt + 3 < KT && dummy != 2) G_LOAD(x, kt + 3);
;       G_COMPUTE(1);
;       if (kt + 2 < KT && dummy != 2) G_STORE(y, 0);
;       __syncthreads();
	s_setprio 1
	ds_read_b128 v[156:159], v196 offset:32768
	ds_read_b128 v[164:167], v200 offset:32768
	ds_read_b128 v[168:171], v200 offset:36864
	ds_read_b128 v[172:175], v196 offset:36864
	ds_read_b128 v[176:179], v197 offset:32768
	ds_read_b128 v[180:183], v201 offset:32768
	ds_read_b128 v[184:187], v201 offset:36864
	ds_read_b128 v[188:191], v197 offset:36864
	s_add_u32 m0, s76, 0x600
	s_nop 0
	global_load_lds_dwordx4 v[138:139], off offset:512
	s_add_u32 m0, s76, 0x1600
	s_nop 0
	global_load_lds_dwordx4 v[142:143], off offset:512
	s_add_u32 m0, s76, 0x2600
	s_nop 0
	global_load_lds_dwordx4 v[144:145], off offset:512
	s_add_u32 m0, s76, 0x3600
	s_nop 0
	global_load_lds_dwordx4 v[152:153], off offset:512
	s_add_u32 m0, s76, 0x4600
	s_nop 0
	global_load_lds_dwordx4 v[140:141], off offset:512
	s_add_u32 m0, s76, 0x5600
	s_nop 0
	global_load_lds_dwordx4 v[146:147], off offset:512
	s_add_u32 m0, s76, 0x6600
	s_nop 0
	global_load_lds_dwordx4 v[148:149], off offset:512
	s_add_u32 m0, s76, 0x7600
	s_nop 0
	global_load_lds_dwordx4 v[150:151], off offset:512
	s_waitcnt lgkmcnt(6)
	v_mfma_f32_32x32x16_bf16 v[32:47], v[156:159], v[164:167], v[32:47]
	s_waitcnt lgkmcnt(5)
	v_mfma_f32_32x32x16_bf16 v[48:63], v[156:159], v[168:171], v[48:63]
	s_waitcnt lgkmcnt(4)
	v_mfma_f32_32x32x16_bf16 v[0:15], v[172:175], v[164:167], v[0:15]
	v_mfma_f32_32x32x16_bf16 v[16:31], v[172:175], v[168:171], v[16:31]
	ds_read_b128 v[156:159], v198 offset:32768
	ds_read_b128 v[164:167], v202 offset:32768
	ds_read_b128 v[168:171], v202 offset:36864
	ds_read_b128 v[172:175], v198 offset:36864
	s_waitcnt lgkmcnt(6)
	v_mfma_f32_32x32x16_bf16 v[32:47], v[176:179], v[180:183], v[32:47]
	s_waitcnt lgkmcnt(5)
	v_mfma_f32_32x32x16_bf16 v[48:63], v[176:179], v[184:187], v[48:63]
	s_waitcnt lgkmcnt(4)
	v_mfma_f32_32x32x16_bf16 v[0:15], v[188:191], v[180:183], v[0:15]
	v_mfma_f32_32x32x16_bf16 v[16:31], v[188:191], v[184:187], v[16:31]
	ds_read_b128 v[176:179], v199 offset:32768
	ds_read_b128 v[180:183], v203 offset:32768
	ds_read_b128 v[184:187], v203 offset:36864
	ds_read_b128 v[188:191], v199 offset:36864
	s_waitcnt lgkmcnt(6)
	v_mfma_f32_32x32x16_bf16 v[32:47], v[156:159], v[164:167], v[32:47]
	s_waitcnt lgkmcnt(5)
	v_mfma_f32_32x32x16_bf16 v[48:63], v[156:159], v[168:171], v[48:63]
	s_waitcnt lgkmcnt(4)
	v_mfma_f32_32x32x16_bf16 v[0:15], v[172:175], v[164:167], v[0:15]
	v_mfma_f32_32x32x16_bf16 v[16:31], v[172:175], v[168:171], v[16:31]
	s_waitcnt lgkmcnt(2)
	v_mfma_f32_32x32x16_bf16 v[32:47], v[176:179], v[180:183], v[32:47]
	s_waitcnt lgkmcnt(1)
	v_mfma_f32_32x32x16_bf16 v[48:63], v[176:179], v[184:187], v[48:63]
	s_waitcnt lgkmcnt(0)
	v_mfma_f32_32x32x16_bf16 v[0:15], v[188:191], v[180:183], v[0:15]
	v_mfma_f32_32x32x16_bf16 v[16:31], v[188:191], v[184:187], v[16:31]
	s_setprio 0
	s_waitcnt vmcnt(0)
	s_barrier
	s_setprio 1
	ds_read_b128 v[156:159], v196
	ds_read_b128 v[164:167], v200
	ds_read_b128 v[168:171], v200 offset:4096
	ds_read_b128 v[172:175], v196 offset:4096
	ds_read_b128 v[176:179], v197
	ds_read_b128 v[180:183], v201
	ds_read_b128 v[184:187], v201 offset:4096
	ds_read_b128 v[188:191], v197 offset:4096
	s_add_u32 m0, s76, 0x8580
	s_nop 0
	global_load_lds_dwordx4 v[138:139], off offset:640
	s_add_u32 m0, s76, 0x9580
	s_nop 0
	global_load_lds_dwordx4 v[142:143], off offset:640
	s_add_u32 m0, s76, 0xa580
	s_nop 0
	global_load_lds_dwordx4 v[144:145], off offset:640
	s_add_u32 m0, s76, 0xb580
	s_nop 0
	global_load_lds_dwordx4 v[152:153], off offset:640
	s_add_u32 m0, s76, 0xc580
	s_nop 0
	global_load_lds_dwordx4 v[140:141], off offset:640
	s_add_u32 m0, s76, 0xd580
	s_nop 0
	global_load_lds_dwordx4 v[146:147], off offset:640
	s_add_u32 m0, s76, 0xe580
	s_nop 0
	global_load_lds_dwordx4 v[148:149], off offset:640
	s_add_u32 m0, s76, 0xf580
	s_nop 0
	global_load_lds_dwordx4 v[150:151], off offset:640
	s_waitcnt lgkmcnt(6)
	v_mfma_f32_32x32x16_bf16 v[32:47], v[156:159], v[164:167], v[32:47]
	s_waitcnt lgkmcnt(5)
	v_mfma_f32_32x32x16_bf16 v[48:63], v[156:159], v[168:171], v[48:63]
	s_waitcnt lgkmcnt(4)
	v_mfma_f32_32x32x16_bf16 v[0:15], v[172:175], v[164:167], v[0:15]
	v_mfma_f32_32x32x16_bf16 v[16:31], v[172:175], v[168:171], v[16:31]
	ds_read_b128 v[156:159], v198
	ds_read_b128 v[164:167], v202
	ds_read_b128 v[168:171], v202 offset:4096
	ds_read_b128 v[172:175], v198 offset:4096
	s_waitcnt lgkmcnt(6)
	v_mfma_f32_32x32x16_bf16 v[32:47], v[176:179], v[180:183], v[32:47]
	s_waitcnt lgkmcnt(5)
	v_mfma_f32_32x32x16_bf16 v[48:63], v[176:179], v[184:187], v[48:63]
	s_waitcnt lgkmcnt(4)
	v_mfma_f32_32x32x16_bf16 v[0:15], v[188:191], v[180:183], v[0:15]
	v_mfma_f32_32x32x16_bf16 v[16:31], v[188:191], v[184:187], v[16:31]
	ds_read_b128 v[176:179], v199
	ds_read_b128 v[180:183], v203
	ds_read_b128 v[184:187], v203 offset:4096
	ds_read_b128 v[188:191], v199 offset:4096
	s_waitcnt lgkmcnt(6)
	v_mfma_f32_32x32x16_bf16 v[32:47], v[156:159], v[164:167], v[32:47]
	s_waitcnt lgkmcnt(5)
	v_mfma_f32_32x32x16_bf16 v[48:63], v[156:159], v[168:171], v[48:63]
	s_waitcnt lgkmcnt(4)
	v_mfma_f32_32x32x16_bf16 v[0:15], v[172:175], v[164:167], v[0:15]
	v_mfma_f32_32x32x16_bf16 v[16:31], v[172:175], v[168:171], v[16:31]
	s_waitcnt lgkmcnt(2)
	v_mfma_f32_32x32x16_bf16 v[32:47], v[176:179], v[180:183], v[32:47]
	s_waitcnt lgkmcnt(1)
	v_mfma_f32_32x32x16_bf16 v[48:63], v[176:179], v[184:187], v[48:63]
	s_waitcnt lgkmcnt(0)
	v_mfma_f32_32x32x16_bf16 v[0:15], v[188:191], v[180:183], v[0:15]
	v_mfma_f32_32x32x16_bf16 v[16:31], v[188:191], v[184:187], v[16:31]
	s_setprio 0
	s_waitcnt vmcnt(0)
	s_barrier
;     ...
;     G_LOAD(x, 0);
;     G_STORE(x, 0);
;     __syncthreads();
;     if (KT > 1) G_LOAD(x, 1);
;     for (int kt = 0; kt < KT; kt += 2) {
;       if (kt + 2 < KT && dummy != 2) G_LOAD(y, kt + 2);
;       G_COMPUTE(0);
;       if (kt + 1 < KT && dummy != 2) G_STORE(x, 1);
;       __syncthreads();
;       if (kt + 1 >= KT) break;
;       if (kt + 3 < KT && dummy != 2) G_LOAD(x, kt + 3);
;       G_COMPUTE(1);
;       if (kt + 2 < KT && dummy != 2) G_STORE(y, 0);
;       __syncthreads();
	s_setprio 1
	ds_read_b128 v[156:159], v196 offset:32768
	ds_read_b128 v[164:167], v200 offset:32768
	ds_read_b128 v[168:171], v200 offset:36864
	ds_read_b128 v[172:175], v196 offset:36864
	ds_read_b128 v[176:179], v197 offset:32768
	ds_read_b128 v[180:183], v201 offset:32768
	ds_read_b128 v[184:187], v201 offset:36864
	ds_read_b128 v[188:191], v197 offset:36864
	s_add_u32 m0, s76, 0x500
	s_nop 0
	global_load_lds_dwordx4 v[138:139], off offset:768
	s_add_u32 m0, s76, 0x1500
	s_nop 0
	global_load_lds_dwordx4 v[142:143], off offset:768
	s_add_u32 m0, s76, 0x2500
	s_nop 0
	global_load_lds_dwordx4 v[144:145], off offset:768
	s_add_u32 m0, s76, 0x3500
	s_nop 0
	global_load_lds_dwordx4 v[152:153], off offset:768
	s_add_u32 m0, s76, 0x4500
	s_nop 0
	global_load_lds_dwordx4 v[140:141], off offset:768
	s_add_u32 m0, s76, 0x5500
	s_nop 0
	global_load_lds_dwordx4 v[146:147], off offset:768
	s_add_u32 m0, s76, 0x6500
	s_nop 0
	global_load_lds_dwordx4 v[148:149], off offset:768
	s_add_u32 m0, s76, 0x7500
	s_nop 0
	global_load_lds_dwordx4 v[150:151], off offset:768
	s_waitcnt lgkmcnt(6)
	v_mfma_f32_32x32x16_bf16 v[32:47], v[156:159], v[164:167], v[32:47]
	s_waitcnt lgkmcnt(5)
	v_mfma_f32_32x32x16_bf16 v[48:63], v[156:159], v[168:171], v[48:63]
	s_waitcnt lgkmcnt(4)
	v_mfma_f32_32x32x16_bf16 v[0:15], v[172:175], v[164:167], v[0:15]
	v_mfma_f32_32x32x16_bf16 v[16:31], v[172:175], v[168:171], v[16:31]
	ds_read_b128 v[156:159], v198 offset:32768
	ds_read_b128 v[164:167], v202 offset:32768
	ds_read_b128 v[168:171], v202 offset:36864
	ds_read_b128 v[172:175], v198 offset:36864
	s_waitcnt lgkmcnt(6)
	v_mfma_f32_32x32x16_bf16 v[32:47], v[176:179], v[180:183], v[32:47]
	s_waitcnt lgkmcnt(5)
	v_mfma_f32_32x32x16_bf16 v[48:63], v[176:179], v[184:187], v[48:63]
	s_waitcnt lgkmcnt(4)
	v_mfma_f32_32x32x16_bf16 v[0:15], v[188:191], v[180:183], v[0:15]
	v_mfma_f32_32x32x16_bf16 v[16:31], v[188:191], v[184:187], v[16:31]
	ds_read_b128 v[176:179], v199 offset:32768
	ds_read_b128 v[180:183], v203 offset:32768
	ds_read_b128 v[184:187], v203 offset:36864
	ds_read_b128 v[188:191], v199 offset:36864
	s_waitcnt lgkmcnt(6)
	v_mfma_f32_32x32x16_bf16 v[32:47], v[156:159], v[164:167], v[32:47]
	s_waitcnt lgkmcnt(5)
	v_mfma_f32_32x32x16_bf16 v[48:63], v[156:159], v[168:171], v[48:63]
	s_waitcnt lgkmcnt(4)
	v_mfma_f32_32x32x16_bf16 v[0:15], v[172:175], v[164:167], v[0:15]
	v_mfma_f32_32x32x16_bf16 v[16:31], v[172:175], v[168:171], v[16:31]
	s_waitcnt lgkmcnt(2)
	v_mfma_f32_32x32x16_bf16 v[32:47], v[176:179], v[180:183], v[32:47]
	s_waitcnt lgkmcnt(1)
	v_mfma_f32_32x32x16_bf16 v[48:63], v[176:179], v[184:187], v[48:63]
	s_waitcnt lgkmcnt(0)
	v_mfma_f32_32x32x16_bf16 v[0:15], v[188:191], v[180:183], v[0:15]
	v_mfma_f32_32x32x16_bf16 v[16:31], v[188:191], v[184:187], v[16:31]
	s_setprio 0
	s_waitcnt vmcnt(0)
	s_barrier
	s_setprio 1
	ds_read_b128 v[156:159], v196
	ds_read_b128 v[164:167], v200
	ds_read_b128 v[168:171], v200 offset:4096
	ds_read_b128 v[172:175], v196 offset:4096
	ds_read_b128 v[176:179], v197
	ds_read_b128 v[180:183], v201
	ds_read_b128 v[184:187], v201 offset:4096
	ds_read_b128 v[188:191], v197 offset:4096
	s_add_u32 m0, s76, 0x8480
	s_nop 0
	global_load_lds_dwordx4 v[138:139], off offset:896
	s_add_u32 m0, s76, 0x9480
	s_nop 0
	global_load_lds_dwordx4 v[142:143], off offset:896
	s_add_u32 m0, s76, 0xa480
	s_nop 0
	global_load_lds_dwordx4 v[144:145], off offset:896
	s_add_u32 m0, s76, 0xb480
	s_nop 0
	global_load_lds_dwordx4 v[152:153], off offset:896
	s_add_u32 m0, s76, 0xc480
	s_nop 0
	global_load_lds_dwordx4 v[140:141], off offset:896
	s_add_u32 m0, s76, 0xd480
	s_nop 0
	global_load_lds_dwordx4 v[146:147], off offset:896
	s_add_u32 m0, s76, 0xe480
	s_nop 0
	global_load_lds_dwordx4 v[148:149], off offset:896
	s_add_u32 m0, s76, 0xf480
	s_nop 0
	global_load_lds_dwordx4 v[150:151], off offset:896
	s_waitcnt lgkmcnt(6)
	v_mfma_f32_32x32x16_bf16 v[32:47], v[156:159], v[164:167], v[32:47]
	s_waitcnt lgkmcnt(5)
	v_mfma_f32_32x32x16_bf16 v[48:63], v[156:159], v[168:171], v[48:63]
	s_waitcnt lgkmcnt(4)
	v_mfma_f32_32x32x16_bf16 v[0:15], v[172:175], v[164:167], v[0:15]
	v_mfma_f32_32x32x16_bf16 v[16:31], v[172:175], v[168:171], v[16:31]
	ds_read_b128 v[156:159], v198
	ds_read_b128 v[164:167], v202
	ds_read_b128 v[168:171], v202 offset:4096
	ds_read_b128 v[172:175], v198 offset:4096
	s_waitcnt lgkmcnt(6)
	v_mfma_f32_32x32x16_bf16 v[32:47], v[176:179], v[180:183], v[32:47]
	s_waitcnt lgkmcnt(5)
	v_mfma_f32_32x32x16_bf16 v[48:63], v[176:179], v[184:187], v[48:63]
	s_waitcnt lgkmcnt(4)
	v_mfma_f32_32x32x16_bf16 v[0:15], v[188:191], v[180:183], v[0:15]
	v_mfma_f32_32x32x16_bf16 v[16:31], v[188:191], v[184:187], v[16:31]
	ds_read_b128 v[176:179], v199
	ds_read_b128 v[180:183], v203
	ds_read_b128 v[184:187], v203 offset:4096
	ds_read_b128 v[188:191], v199 offset:4096
	s_waitcnt lgkmcnt(6)
	v_mfma_f32_32x32x16_bf16 v[32:47], v[156:159], v[164:167], v[32:47]
	s_waitcnt lgkmcnt(5)
	v_mfma_f32_32x32x16_bf16 v[48:63], v[156:159], v[168:171], v[48:63]
	s_waitcnt lgkmcnt(4)
	v_mfma_f32_32x32x16_bf16 v[0:15], v[172:175], v[164:167], v[0:15]
	v_mfma_f32_32x32x16_bf16 v[16:31], v[172:175], v[168:171], v[16:31]
	s_waitcnt lgkmcnt(2)
	v_mfma_f32_32x32x16_bf16 v[32:47], v[176:179], v[180:183], v[32:47]
	s_waitcnt lgkmcnt(1)
	v_mfma_f32_32x32x16_bf16 v[48:63], v[176:179], v[184:187], v[48:63]
	s_waitcnt lgkmcnt(0)
	v_mfma_f32_32x32x16_bf16 v[0:15], v[188:191], v[180:183], v[0:15]
	v_mfma_f32_32x32x16_bf16 v[16:31], v[188:191], v[184:187], v[16:31]
	s_setprio 0
	s_waitcnt vmcnt(0)
	s_barrier
;     ...
;     G_LOAD(x, 0);
;     G_STORE(x, 0);
;     __syncthreads();
;     if (KT > 1) G_LOAD(x, 1);
;     for (int kt = 0; kt < KT; kt += 2) {
;       if (kt + 2 < KT && dummy != 2) G_LOAD(y, kt + 2);
;       G_COMPUTE(0);
;       if (kt + 1 < KT && dummy != 2) G_STORE(x, 1);
;       __syncthreads();
;       if (kt + 1 >= KT) break;
;       if (kt + 3 < KT && dummy != 2) G_LOAD(x, kt + 3);
;       G_COMPUTE(1);
;       if (kt + 2 < KT && dummy != 2) G_STORE(y, 0);
;       __syncthreads();
	s_setprio 1
	ds_read_b128 v[156:159], v196 offset:32768
	ds_read_b128 v[164:167], v200 offset:32768
	ds_read_b128 v[168:171], v200 offset:36864
	ds_read_b128 v[172:175], v196 offset:36864
	ds_read_b128 v[176:179], v197 offset:32768
	ds_read_b128 v[180:183], v201 offset:32768
	ds_read_b128 v[184:187], v201 offset:36864
	ds_read_b128 v[188:191], v197 offset:36864
	s_add_u32 m0, s76, 0x400
	s_nop 0
	global_load_lds_dwordx4 v[138:139], off offset:1024
	s_add_u32 m0, s76, 0x1400
	s_nop 0
	global_load_lds_dwordx4 v[142:143], off offset:1024
	s_add_u32 m0, s76, 0x2400
	s_nop 0
	global_load_lds_dwordx4 v[144:145], off offset:1024
	s_add_u32 m0, s76, 0x3400
	s_nop 0
	global_load_lds_dwordx4 v[152:153], off offset:1024
	s_add_u32 m0, s76, 0x4400
	s_nop 0
	global_load_lds_dwordx4 v[140:141], off offset:1024
	s_add_u32 m0, s76, 0x5400
	s_nop 0
	global_load_lds_dwordx4 v[146:147], off offset:1024
	s_add_u32 m0, s76, 0x6400
	s_nop 0
	global_load_lds_dwordx4 v[148:149], off offset:1024
	s_add_u32 m0, s76, 0x7400
	s_nop 0
	global_load_lds_dwordx4 v[150:151], off offset:1024
	s_waitcnt lgkmcnt(6)
	v_mfma_f32_32x32x16_bf16 v[32:47], v[156:159], v[164:167], v[32:47]
	s_waitcnt lgkmcnt(5)
	v_mfma_f32_32x32x16_bf16 v[48:63], v[156:159], v[168:171], v[48:63]
	s_waitcnt lgkmcnt(4)
	v_mfma_f32_32x32x16_bf16 v[0:15], v[172:175], v[164:167], v[0:15]
	v_mfma_f32_32x32x16_bf16 v[16:31], v[172:175], v[168:171], v[16:31]
	ds_read_b128 v[156:159], v198 offset:32768
	ds_read_b128 v[164:167], v202 offset:32768
	ds_read_b128 v[168:171], v202 offset:36864
	ds_read_b128 v[172:175], v198 offset:36864
	s_waitcnt lgkmcnt(6)
	v_mfma_f32_32x32x16_bf16 v[32:47], v[176:179], v[180:183], v[32:47]
	s_waitcnt lgkmcnt(5)
	v_mfma_f32_32x32x16_bf16 v[48:63], v[176:179], v[184:187], v[48:63]
	s_waitcnt lgkmcnt(4)
	v_mfma_f32_32x32x16_bf16 v[0:15], v[188:191], v[180:183], v[0:15]
	v_mfma_f32_32x32x16_bf16 v[16:31], v[188:191], v[184:187], v[16:31]
	ds_read_b128 v[176:179], v199 offset:32768
	ds_read_b128 v[180:183], v203 offset:32768
	ds_read_b128 v[184:187], v203 offset:36864
	ds_read_b128 v[188:191], v199 offset:36864
	s_waitcnt lgkmcnt(6)
	v_mfma_f32_32x32x16_bf16 v[32:47], v[156:159], v[164:167], v[32:47]
	s_waitcnt lgkmcnt(5)
	v_mfma_f32_32x32x16_bf16 v[48:63], v[156:159], v[168:171], v[48:63]
	s_waitcnt lgkmcnt(4)
	v_mfma_f32_32x32x16_bf16 v[0:15], v[172:175], v[164:167], v[0:15]
	v_mfma_f32_32x32x16_bf16 v[16:31], v[172:175], v[168:171], v[16:31]
	s_waitcnt lgkmcnt(2)
	v_mfma_f32_32x32x16_bf16 v[32:47], v[176:179], v[180:183], v[32:47]
	s_waitcnt lgkmcnt(1)
	v_mfma_f32_32x32x16_bf16 v[48:63], v[176:179], v[184:187], v[48:63]
	s_waitcnt lgkmcnt(0)
	v_mfma_f32_32x32x16_bf16 v[0:15], v[188:191], v[180:183], v[0:15]
	v_mfma_f32_32x32x16_bf16 v[16:31], v[188:191], v[184:187], v[16:31]
	s_setprio 0
	s_waitcnt vmcnt(0)
	s_barrier
	s_setprio 1
	ds_read_b128 v[156:159], v196
	ds_read_b128 v[164:167], v200
	ds_read_b128 v[168:171], v200 offset:4096
	ds_read_b128 v[172:175], v196 offset:4096
	ds_read_b128 v[176:179], v197
	ds_read_b128 v[180:183], v201
	ds_read_b128 v[184:187], v201 offset:4096
	ds_read_b128 v[188:191], v197 offset:4096
	s_add_u32 m0, s76, 0x8380
	s_nop 0
	global_load_lds_dwordx4 v[138:139], off offset:1152
	s_add_u32 m0, s76, 0x9380
	s_nop 0
	global_load_lds_dwordx4 v[142:143], off offset:1152
	s_add_u32 m0, s76, 0xa380
	s_nop 0
	global_load_lds_dwordx4 v[144:145], off offset:1152
	s_add_u32 m0, s76, 0xb380
	s_nop 0
	global_load_lds_dwordx4 v[152:153], off offset:1152
	s_add_u32 m0, s76, 0xc380
	s_nop 0
	global_load_lds_dwordx4 v[140:141], off offset:1152
	s_add_u32 m0, s76, 0xd380
	s_nop 0
	global_load_lds_dwordx4 v[146:147], off offset:1152
	s_add_u32 m0, s76, 0xe380
	s_nop 0
	global_load_lds_dwordx4 v[148:149], off offset:1152
	s_add_u32 m0, s76, 0xf380
	s_nop 0
	global_load_lds_dwordx4 v[150:151], off offset:1152
	s_waitcnt lgkmcnt(6)
	v_mfma_f32_32x32x16_bf16 v[32:47], v[156:159], v[164:167], v[32:47]
	s_waitcnt lgkmcnt(5)
	v_mfma_f32_32x32x16_bf16 v[48:63], v[156:159], v[168:171], v[48:63]
	s_waitcnt lgkmcnt(4)
	v_mfma_f32_32x32x16_bf16 v[0:15], v[172:175], v[164:167], v[0:15]
	v_mfma_f32_32x32x16_bf16 v[16:31], v[172:175], v[168:171], v[16:31]
	ds_read_b128 v[156:159], v198
	ds_read_b128 v[164:167], v202
	ds_read_b128 v[168:171], v202 offset:4096
	ds_read_b128 v[172:175], v198 offset:4096
	s_waitcnt lgkmcnt(6)
	v_mfma_f32_32x32x16_bf16 v[32:47], v[176:179], v[180:183], v[32:47]
	s_waitcnt lgkmcnt(5)
	v_mfma_f32_32x32x16_bf16 v[48:63], v[176:179], v[184:187], v[48:63]
	s_waitcnt lgkmcnt(4)
	v_mfma_f32_32x32x16_bf16 v[0:15], v[188:191], v[180:183], v[0:15]
	v_mfma_f32_32x32x16_bf16 v[16:31], v[188:191], v[184:187], v[16:31]
	ds_read_b128 v[176:179], v199
	ds_read_b128 v[180:183], v203
	ds_read_b128 v[184:187], v203 offset:4096
	ds_read_b128 v[188:191], v199 offset:4096
	s_waitcnt lgkmcnt(6)
	v_mfma_f32_32x32x16_bf16 v[32:47], v[156:159], v[164:167], v[32:47]
	s_waitcnt lgkmcnt(5)
	v_mfma_f32_32x32x16_bf16 v[48:63], v[156:159], v[168:171], v[48:63]
	s_waitcnt lgkmcnt(4)
	v_mfma_f32_32x32x16_bf16 v[0:15], v[172:175], v[164:167], v[0:15]
	v_mfma_f32_32x32x16_bf16 v[16:31], v[172:175], v[168:171], v[16:31]
	s_waitcnt lgkmcnt(2)
	v_mfma_f32_32x32x16_bf16 v[32:47], v[176:179], v[180:183], v[32:47]
	s_waitcnt lgkmcnt(1)
	v_mfma_f32_32x32x16_bf16 v[48:63], v[176:179], v[184:187], v[48:63]
	s_waitcnt lgkmcnt(0)
	v_mfma_f32_32x32x16_bf16 v[0:15], v[188:191], v[180:183], v[0:15]
	v_mfma_f32_32x32x16_bf16 v[16:31], v[188:191], v[184:187], v[16:31]
	s_setprio 0
	s_waitcnt vmcnt(0)
	s_barrier
;     ...
;     G_LOAD(x, 0);
;     G_STORE(x, 0);
;     __syncthreads();
;     if (KT > 1) G_LOAD(x, 1);
;     for (int kt = 0; kt < KT; kt += 2) {
;       if (kt + 2 < KT && dummy != 2) G_LOAD(y, kt + 2);
;       G_COMPUTE(0);
;       if (kt + 1 < KT && dummy != 2) G_STORE(x, 1);
;       __syncthreads();
;       if (kt + 1 >= KT) break;
;       if (kt + 3 < KT && dummy != 2) G_LOAD(x, kt + 3);
;       G_COMPUTE(1);
;       if (kt + 2 < KT && dummy != 2) G_STORE(y, 0);
;       __syncthreads();
	s_setprio 1
	ds_read_b128 v[156:159], v196 offset:32768
	ds_read_b128 v[164:167], v200 offset:32768
	ds_read_b128 v[168:171], v200 offset:36864
	ds_read_b128 v[172:175], v196 offset:36864
	ds_read_b128 v[176:179], v197 offset:32768
	ds_read_b128 v[180:183], v201 offset:32768
	ds_read_b128 v[184:187], v201 offset:36864
	ds_read_b128 v[188:191], v197 offset:36864
	s_add_u32 m0, s76, 0x300
	s_nop 0
	global_load_lds_dwordx4 v[138:139], off offset:1280
	s_add_u32 m0, s76, 0x1300
	s_nop 0
	global_load_lds_dwordx4 v[142:143], off offset:1280
	s_add_u32 m0, s76, 0x2300
	s_nop 0
	global_load_lds_dwordx4 v[144:145], off offset:1280
	s_add_u32 m0, s76, 0x3300
	s_nop 0
	global_load_lds_dwordx4 v[152:153], off offset:1280
	s_add_u32 m0, s76, 0x4300
	s_nop 0
	global_load_lds_dwordx4 v[140:141], off offset:1280
	s_add_u32 m0, s76, 0x5300
	s_nop 0
	global_load_lds_dwordx4 v[146:147], off offset:1280
	s_add_u32 m0, s76, 0x6300
	s_nop 0
	global_load_lds_dwordx4 v[148:149], off offset:1280
	s_add_u32 m0, s76, 0x7300
	s_nop 0
	global_load_lds_dwordx4 v[150:151], off offset:1280
	s_waitcnt lgkmcnt(6)
	v_mfma_f32_32x32x16_bf16 v[32:47], v[156:159], v[164:167], v[32:47]
	s_waitcnt lgkmcnt(5)
	v_mfma_f32_32x32x16_bf16 v[48:63], v[156:159], v[168:171], v[48:63]
	s_waitcnt lgkmcnt(4)
	v_mfma_f32_32x32x16_bf16 v[0:15], v[172:175], v[164:167], v[0:15]
	v_mfma_f32_32x32x16_bf16 v[16:31], v[172:175], v[168:171], v[16:31]
	ds_read_b128 v[156:159], v198 offset:32768
	ds_read_b128 v[164:167], v202 offset:32768
	ds_read_b128 v[168:171], v202 offset:36864
	ds_read_b128 v[172:175], v198 offset:36864
	s_waitcnt lgkmcnt(6)
	v_mfma_f32_32x32x16_bf16 v[32:47], v[176:179], v[180:183], v[32:47]
	s_waitcnt lgkmcnt(5)
	v_mfma_f32_32x32x16_bf16 v[48:63], v[176:179], v[184:187], v[48:63]
	s_waitcnt lgkmcnt(4)
	v_mfma_f32_32x32x16_bf16 v[0:15], v[188:191], v[180:183], v[0:15]
	v_mfma_f32_32x32x16_bf16 v[16:31], v[188:191], v[184:187], v[16:31]
	ds_read_b128 v[176:179], v199 offset:32768
	ds_read_b128 v[180:183], v203 offset:32768
	ds_read_b128 v[184:187], v203 offset:36864
	ds_read_b128 v[188:191], v199 offset:36864
	s_waitcnt lgkmcnt(6)
	v_mfma_f32_32x32x16_bf16 v[32:47], v[156:159], v[164:167], v[32:47]
	s_waitcnt lgkmcnt(5)
	v_mfma_f32_32x32x16_bf16 v[48:63], v[156:159], v[168:171], v[48:63]
	s_waitcnt lgkmcnt(4)
	v_mfma_f32_32x32x16_bf16 v[0:15], v[172:175], v[164:167], v[0:15]
	v_mfma_f32_32x32x16_bf16 v[16:31], v[172:175], v[168:171], v[16:31]
	s_waitcnt lgkmcnt(2)
	v_mfma_f32_32x32x16_bf16 v[32:47], v[176:179], v[180:183], v[32:47]
	s_waitcnt lgkmcnt(1)
	v_mfma_f32_32x32x16_bf16 v[48:63], v[176:179], v[184:187], v[48:63]
	s_waitcnt lgkmcnt(0)
	v_mfma_f32_32x32x16_bf16 v[0:15], v[188:191], v[180:183], v[0:15]
	v_mfma_f32_32x32x16_bf16 v[16:31], v[188:191], v[184:187], v[16:31]
	s_setprio 0
	s_waitcnt vmcnt(0)
	s_barrier
	s_setprio 1
	ds_read_b128 v[156:159], v196
	ds_read_b128 v[164:167], v200
	ds_read_b128 v[168:171], v200 offset:4096
	ds_read_b128 v[172:175], v196 offset:4096
	ds_read_b128 v[176:179], v197
	ds_read_b128 v[180:183], v201
	ds_read_b128 v[184:187], v201 offset:4096
	ds_read_b128 v[188:191], v197 offset:4096
	s_add_u32 m0, s76, 0x8280
	s_nop 0
	global_load_lds_dwordx4 v[138:139], off offset:1408
	s_add_u32 m0, s76, 0x9280
	s_nop 0
	global_load_lds_dwordx4 v[142:143], off offset:1408
	s_add_u32 m0, s76, 0xa280
	s_nop 0
	global_load_lds_dwordx4 v[144:145], off offset:1408
	s_add_u32 m0, s76, 0xb280
	s_nop 0
	global_load_lds_dwordx4 v[152:153], off offset:1408
	s_add_u32 m0, s76, 0xc280
	s_nop 0
	global_load_lds_dwordx4 v[140:141], off offset:1408
	s_add_u32 m0, s76, 0xd280
	s_nop 0
	global_load_lds_dwordx4 v[146:147], off offset:1408
	s_add_u32 m0, s76, 0xe280
	s_nop 0
	global_load_lds_dwordx4 v[148:149], off offset:1408
	s_add_u32 m0, s76, 0xf280
	s_nop 0
	global_load_lds_dwordx4 v[150:151], off offset:1408
	s_waitcnt lgkmcnt(6)
	v_mfma_f32_32x32x16_bf16 v[32:47], v[156:159], v[164:167], v[32:47]
	s_waitcnt lgkmcnt(5)
	v_mfma_f32_32x32x16_bf16 v[48:63], v[156:159], v[168:171], v[48:63]
	s_waitcnt lgkmcnt(4)
	v_mfma_f32_32x32x16_bf16 v[0:15], v[172:175], v[164:167], v[0:15]
	v_mfma_f32_32x32x16_bf16 v[16:31], v[172:175], v[168:171], v[16:31]
	ds_read_b128 v[156:159], v198
	ds_read_b128 v[164:167], v202
	ds_read_b128 v[168:171], v202 offset:4096
	ds_read_b128 v[172:175], v198 offset:4096
	s_waitcnt lgkmcnt(6)
	v_mfma_f32_32x32x16_bf16 v[32:47], v[176:179], v[180:183], v[32:47]
	s_waitcnt lgkmcnt(5)
	v_mfma_f32_32x32x16_bf16 v[48:63], v[176:179], v[184:187], v[48:63]
	s_waitcnt lgkmcnt(4)
	v_mfma_f32_32x32x16_bf16 v[0:15], v[188:191], v[180:183], v[0:15]
	v_mfma_f32_32x32x16_bf16 v[16:31], v[188:191], v[184:187], v[16:31]
	ds_read_b128 v[176:179], v199
	ds_read_b128 v[180:183], v203
	ds_read_b128 v[184:187], v203 offset:4096
	ds_read_b128 v[188:191], v199 offset:4096
	s_waitcnt lgkmcnt(6)
	v_mfma_f32_32x32x16_bf16 v[32:47], v[156:159], v[164:167], v[32:47]
	s_waitcnt lgkmcnt(5)
	v_mfma_f32_32x32x16_bf16 v[48:63], v[156:159], v[168:171], v[48:63]
	s_waitcnt lgkmcnt(4)
	v_mfma_f32_32x32x16_bf16 v[0:15], v[172:175], v[164:167], v[0:15]
	v_mfma_f32_32x32x16_bf16 v[16:31], v[172:175], v[168:171], v[16:31]
	s_waitcnt lgkmcnt(2)
	v_mfma_f32_32x32x16_bf16 v[32:47], v[176:179], v[180:183], v[32:47]
	s_waitcnt lgkmcnt(1)
	v_mfma_f32_32x32x16_bf16 v[48:63], v[176:179], v[184:187], v[48:63]
	s_waitcnt lgkmcnt(0)
	v_mfma_f32_32x32x16_bf16 v[0:15], v[188:191], v[180:183], v[0:15]
	v_mfma_f32_32x32x16_bf16 v[16:31], v[188:191], v[184:187], v[16:31]
	s_setprio 0
	s_waitcnt vmcnt(0)
	s_barrier
;     ...
;     G_LOAD(x, 0);
;     G_STORE(x, 0);
;     __syncthreads();
;     if (KT > 1) G_LOAD(x, 1);
;     for (int kt = 0; kt < KT; kt += 2) {
;       if (kt + 2 < KT && dummy != 2) G_LOAD(y, kt + 2);
;       G_COMPUTE(0);
;       if (kt + 1 < KT && dummy != 2) G_STORE(x, 1);
;       __syncthreads();
;       if (kt + 1 >= KT) break;
;       if (kt + 3 < KT && dummy != 2) G_LOAD(x, kt + 3);
;       G_COMPUTE(1);
;       if (kt + 2 < KT && dummy != 2) G_STORE(y, 0);
;       __syncthreads();
	s_setprio 1
	ds_read_b128 v[156:159], v196 offset:32768
	ds_read_b128 v[164:167], v200 offset:32768
	ds_read_b128 v[168:171], v200 offset:36864
	ds_read_b128 v[172:175], v196 offset:36864
	ds_read_b128 v[176:179], v197 offset:32768
	ds_read_b128 v[180:183], v201 offset:32768
	ds_read_b128 v[184:187], v201 offset:36864
	ds_read_b128 v[188:191], v197 offset:36864
	s_add_u32 m0, s76, 0x200
	s_nop 0
	global_load_lds_dwordx4 v[138:139], off offset:1536
	s_add_u32 m0, s76, 0x1200
	s_nop 0
	global_load_lds_dwordx4 v[142:143], off offset:1536
	s_add_u32 m0, s76, 0x2200
	s_nop 0
	global_load_lds_dwordx4 v[144:145], off offset:1536
	s_add_u32 m0, s76, 0x3200
	s_nop 0
	global_load_lds_dwordx4 v[152:153], off offset:1536
	s_add_u32 m0, s76, 0x4200
	s_nop 0
	global_load_lds_dwordx4 v[140:141], off offset:1536
	s_add_u32 m0, s76, 0x5200
	s_nop 0
	global_load_lds_dwordx4 v[146:147], off offset:1536
	s_add_u32 m0, s76, 0x6200
	s_nop 0
	global_load_lds_dwordx4 v[148:149], off offset:1536
	s_add_u32 m0, s76, 0x7200
	s_nop 0
	global_load_lds_dwordx4 v[150:151], off offset:1536
	s_waitcnt lgkmcnt(6)
	v_mfma_f32_32x32x16_bf16 v[32:47], v[156:159], v[164:167], v[32:47]
	s_waitcnt lgkmcnt(5)
	v_mfma_f32_32x32x16_bf16 v[48:63], v[156:159], v[168:171], v[48:63]
	s_waitcnt lgkmcnt(4)
	v_mfma_f32_32x32x16_bf16 v[0:15], v[172:175], v[164:167], v[0:15]
	v_mfma_f32_32x32x16_bf16 v[16:31], v[172:175], v[168:171], v[16:31]
	ds_read_b128 v[156:159], v198 offset:32768
	ds_read_b128 v[164:167], v202 offset:32768
	ds_read_b128 v[168:171], v202 offset:36864
	ds_read_b128 v[172:175], v198 offset:36864
	s_waitcnt lgkmcnt(6)
	v_mfma_f32_32x32x16_bf16 v[32:47], v[176:179], v[180:183], v[32:47]
	s_waitcnt lgkmcnt(5)
	v_mfma_f32_32x32x16_bf16 v[48:63], v[176:179], v[184:187], v[48:63]
	s_waitcnt lgkmcnt(4)
	v_mfma_f32_32x32x16_bf16 v[0:15], v[188:191], v[180:183], v[0:15]
	v_mfma_f32_32x32x16_bf16 v[16:31], v[188:191], v[184:187], v[16:31]
	ds_read_b128 v[176:179], v199 offset:32768
	ds_read_b128 v[180:183], v203 offset:32768
	ds_read_b128 v[184:187], v203 offset:36864
	ds_read_b128 v[188:191], v199 offset:36864
	s_waitcnt lgkmcnt(6)
	v_mfma_f32_32x32x16_bf16 v[32:47], v[156:159], v[164:167], v[32:47]
	s_waitcnt lgkmcnt(5)
	v_mfma_f32_32x32x16_bf16 v[48:63], v[156:159], v[168:171], v[48:63]
	s_waitcnt lgkmcnt(4)
	v_mfma_f32_32x32x16_bf16 v[0:15], v[172:175], v[164:167], v[0:15]
	v_mfma_f32_32x32x16_bf16 v[16:31], v[172:175], v[168:171], v[16:31]
	s_waitcnt lgkmcnt(2)
	v_mfma_f32_32x32x16_bf16 v[32:47], v[176:179], v[180:183], v[32:47]
	s_waitcnt lgkmcnt(1)
	v_mfma_f32_32x32x16_bf16 v[48:63], v[176:179], v[184:187], v[48:63]
	s_waitcnt lgkmcnt(0)
	v_mfma_f32_32x32x16_bf16 v[0:15], v[188:191], v[180:183], v[0:15]
	v_mfma_f32_32x32x16_bf16 v[16:31], v[188:191], v[184:187], v[16:31]
	s_setprio 0
	s_waitcnt vmcnt(0)
	s_barrier
	s_setprio 1
	ds_read_b128 v[156:159], v196
	ds_read_b128 v[164:167], v200
	ds_read_b128 v[168:171], v200 offset:4096
	ds_read_b128 v[172:175], v196 offset:4096
	ds_read_b128 v[176:179], v197
	ds_read_b128 v[180:183], v201
	ds_read_b128 v[184:187], v201 offset:4096
	ds_read_b128 v[188:191], v197 offset:4096
	s_add_u32 m0, s76, 0x8180
	s_nop 0
	global_load_lds_dwordx4 v[138:139], off offset:1664
	s_add_u32 m0, s76, 0x9180
	s_nop 0
	global_load_lds_dwordx4 v[142:143], off offset:1664
	s_add_u32 m0, s76, 0xa180
	s_nop 0
	global_load_lds_dwordx4 v[144:145], off offset:1664
	s_add_u32 m0, s76, 0xb180
	s_nop 0
	global_load_lds_dwordx4 v[152:153], off offset:1664
	s_add_u32 m0, s76, 0xc180
	s_nop 0
	global_load_lds_dwordx4 v[140:141], off offset:1664
	s_add_u32 m0, s76, 0xd180
	s_nop 0
	global_load_lds_dwordx4 v[146:147], off offset:1664
	s_add_u32 m0, s76, 0xe180
	s_nop 0
	global_load_lds_dwordx4 v[148:149], off offset:1664
	s_add_u32 m0, s76, 0xf180
	s_nop 0
	global_load_lds_dwordx4 v[150:151], off offset:1664
	s_waitcnt lgkmcnt(6)
	v_mfma_f32_32x32x16_bf16 v[32:47], v[156:159], v[164:167], v[32:47]
	s_waitcnt lgkmcnt(5)
	v_mfma_f32_32x32x16_bf16 v[48:63], v[156:159], v[168:171], v[48:63]
	s_waitcnt lgkmcnt(4)
	v_mfma_f32_32x32x16_bf16 v[0:15], v[172:175], v[164:167], v[0:15]
	v_mfma_f32_32x32x16_bf16 v[16:31], v[172:175], v[168:171], v[16:31]
	ds_read_b128 v[156:159], v198
	ds_read_b128 v[164:167], v202
	ds_read_b128 v[168:171], v202 offset:4096
	ds_read_b128 v[172:175], v198 offset:4096
	s_waitcnt lgkmcnt(6)
	v_mfma_f32_32x32x16_bf16 v[32:47], v[176:179], v[180:183], v[32:47]
	s_waitcnt lgkmcnt(5)
	v_mfma_f32_32x32x16_bf16 v[48:63], v[176:179], v[184:187], v[48:63]
	s_waitcnt lgkmcnt(4)
	v_mfma_f32_32x32x16_bf16 v[0:15], v[188:191], v[180:183], v[0:15]
	v_mfma_f32_32x32x16_bf16 v[16:31], v[188:191], v[184:187], v[16:31]
	ds_read_b128 v[176:179], v199
	ds_read_b128 v[180:183], v203
	ds_read_b128 v[184:187], v203 offset:4096
	ds_read_b128 v[188:191], v199 offset:4096
	s_waitcnt lgkmcnt(6)
	v_mfma_f32_32x32x16_bf16 v[32:47], v[156:159], v[164:167], v[32:47]
	s_waitcnt lgkmcnt(5)
	v_mfma_f32_32x32x16_bf16 v[48:63], v[156:159], v[168:171], v[48:63]
	s_waitcnt lgkmcnt(4)
	v_mfma_f32_32x32x16_bf16 v[0:15], v[172:175], v[164:167], v[0:15]
	v_mfma_f32_32x32x16_bf16 v[16:31], v[172:175], v[168:171], v[16:31]
	s_waitcnt lgkmcnt(2)
	v_mfma_f32_32x32x16_bf16 v[32:47], v[176:179], v[180:183], v[32:47]
	s_waitcnt lgkmcnt(1)
	v_mfma_f32_32x32x16_bf16 v[48:63], v[176:179], v[184:187], v[48:63]
	s_waitcnt lgkmcnt(0)
	v_mfma_f32_32x32x16_bf16 v[0:15], v[188:191], v[180:183], v[0:15]
	v_mfma_f32_32x32x16_bf16 v[16:31], v[188:191], v[184:187], v[16:31]
	s_setprio 0
	s_waitcnt vmcnt(0)
	s_barrier
;     ...
;     G_LOAD(x, 0);
;     G_STORE(x, 0);
;     __syncthreads();
;     if (KT > 1) G_LOAD(x, 1);
;     for (int kt = 0; kt < KT; kt += 2) {
;       if (kt + 2 < KT && dummy != 2) G_LOAD(y, kt + 2);
;       G_COMPUTE(0);
;       if (kt + 1 < KT && dummy != 2) G_STORE(x, 1);
;       __syncthreads();
;       if (kt + 1 >= KT) break;
;       if (kt + 3 < KT && dummy != 2) G_LOAD(x, kt + 3);
;       G_COMPUTE(1);
;       if (kt + 2 < KT && dummy != 2) G_STORE(y, 0);
;       __syncthreads();
	s_setprio 1
	ds_read_b128 v[156:159], v196 offset:32768
	ds_read_b128 v[164:167], v200 offset:32768
	ds_read_b128 v[168:171], v200 offset:36864
	ds_read_b128 v[172:175], v196 offset:36864
	ds_read_b128 v[176:179], v197 offset:32768
	ds_read_b128 v[180:183], v201 offset:32768
	ds_read_b128 v[184:187], v201 offset:36864
	ds_read_b128 v[188:191], v197 offset:36864
	s_add_u32 m0, s76, 0x100
	s_nop 0
	global_load_lds_dwordx4 v[138:139], off offset:1792
	s_add_u32 m0, s76, 0x1100
	s_nop 0
	global_load_lds_dwordx4 v[142:143], off offset:1792
	s_add_u32 m0, s76, 0x2100
	s_nop 0
	global_load_lds_dwordx4 v[144:145], off offset:1792
	s_add_u32 m0, s76, 0x3100
	s_nop 0
	global_load_lds_dwordx4 v[152:153], off offset:1792
	s_add_u32 m0, s76, 0x4100
	s_nop 0
	global_load_lds_dwordx4 v[140:141], off offset:1792
	s_add_u32 m0, s76, 0x5100
	s_nop 0
	global_load_lds_dwordx4 v[146:147], off offset:1792
	s_add_u32 m0, s76, 0x6100
	s_nop 0
	global_load_lds_dwordx4 v[148:149], off offset:1792
	s_add_u32 m0, s76, 0x7100
	s_nop 0
	global_load_lds_dwordx4 v[150:151], off offset:1792
	s_waitcnt lgkmcnt(6)
	v_mfma_f32_32x32x16_bf16 v[32:47], v[156:159], v[164:167], v[32:47]
	s_waitcnt lgkmcnt(5)
	v_mfma_f32_32x32x16_bf16 v[48:63], v[156:159], v[168:171], v[48:63]
	s_waitcnt lgkmcnt(4)
	v_mfma_f32_32x32x16_bf16 v[0:15], v[172:175], v[164:167], v[0:15]
	v_mfma_f32_32x32x16_bf16 v[16:31], v[172:175], v[168:171], v[16:31]
	ds_read_b128 v[156:159], v198 offset:32768
	ds_read_b128 v[164:167], v202 offset:32768
	ds_read_b128 v[168:171], v202 offset:36864
	ds_read_b128 v[172:175], v198 offset:36864
	s_waitcnt lgkmcnt(6)
	v_mfma_f32_32x32x16_bf16 v[32:47], v[176:179], v[180:183], v[32:47]
	s_waitcnt lgkmcnt(5)
	v_mfma_f32_32x32x16_bf16 v[48:63], v[176:179], v[184:187], v[48:63]
	s_waitcnt lgkmcnt(4)
	v_mfma_f32_32x32x16_bf16 v[0:15], v[188:191], v[180:183], v[0:15]
	v_mfma_f32_32x32x16_bf16 v[16:31], v[188:191], v[184:187], v[16:31]
	ds_read_b128 v[176:179], v199 offset:32768
	ds_read_b128 v[180:183], v203 offset:32768
	ds_read_b128 v[184:187], v203 offset:36864
	ds_read_b128 v[188:191], v199 offset:36864
	s_waitcnt lgkmcnt(6)
	v_mfma_f32_32x32x16_bf16 v[32:47], v[156:159], v[164:167], v[32:47]
	s_waitcnt lgkmcnt(5)
	v_mfma_f32_32x32x16_bf16 v[48:63], v[156:159], v[168:171], v[48:63]
	s_waitcnt lgkmcnt(4)
	v_mfma_f32_32x32x16_bf16 v[0:15], v[172:175], v[164:167], v[0:15]
	v_mfma_f32_32x32x16_bf16 v[16:31], v[172:175], v[168:171], v[16:31]
	s_waitcnt lgkmcnt(2)
	v_mfma_f32_32x32x16_bf16 v[32:47], v[176:179], v[180:183], v[32:47]
	s_waitcnt lgkmcnt(1)
	v_mfma_f32_32x32x16_bf16 v[48:63], v[176:179], v[184:187], v[48:63]
	s_waitcnt lgkmcnt(0)
	v_mfma_f32_32x32x16_bf16 v[0:15], v[188:191], v[180:183], v[0:15]
	v_mfma_f32_32x32x16_bf16 v[16:31], v[188:191], v[184:187], v[16:31]
	s_setprio 0
	s_waitcnt vmcnt(0)
	s_barrier
	s_setprio 1
	ds_read_b128 v[156:159], v196
	ds_read_b128 v[164:167], v200
	ds_read_b128 v[168:171], v200 offset:4096
	ds_read_b128 v[172:175], v196 offset:4096
	ds_read_b128 v[176:179], v197
	ds_read_b128 v[180:183], v201
	ds_read_b128 v[184:187], v201 offset:4096
	ds_read_b128 v[188:191], v197 offset:4096
	s_add_u32 m0, s76, 0x8080
	s_nop 0
	global_load_lds_dwordx4 v[138:139], off offset:1920
	s_add_u32 m0, s76, 0x9080
	s_nop 0
	global_load_lds_dwordx4 v[142:143], off offset:1920
	s_add_u32 m0, s76, 0xa080
	s_nop 0
	global_load_lds_dwordx4 v[144:145], off offset:1920
	s_add_u32 m0, s76, 0xb080
	s_nop 0
	global_load_lds_dwordx4 v[152:153], off offset:1920
	s_add_u32 m0, s76, 0xc080
	s_nop 0
	global_load_lds_dwordx4 v[140:141], off offset:1920
	s_add_u32 m0, s76, 0xd080
	s_nop 0
	global_load_lds_dwordx4 v[146:147], off offset:1920
	s_add_u32 m0, s76, 0xe080
	s_nop 0
	global_load_lds_dwordx4 v[148:149], off offset:1920
	s_add_u32 m0, s76, 0xf080
	s_nop 0
	global_load_lds_dwordx4 v[150:151], off offset:1920
	s_waitcnt lgkmcnt(6)
	v_mfma_f32_32x32x16_bf16 v[32:47], v[156:159], v[164:167], v[32:47]
	s_waitcnt lgkmcnt(5)
	v_mfma_f32_32x32x16_bf16 v[48:63], v[156:159], v[168:171], v[48:63]
	s_waitcnt lgkmcnt(4)
	v_mfma_f32_32x32x16_bf16 v[0:15], v[172:175], v[164:167], v[0:15]
	v_mfma_f32_32x32x16_bf16 v[16:31], v[172:175], v[168:171], v[16:31]
	ds_read_b128 v[156:159], v198
	ds_read_b128 v[164:167], v202
	ds_read_b128 v[168:171], v202 offset:4096
	ds_read_b128 v[172:175], v198 offset:4096
	s_waitcnt lgkmcnt(6)
	v_mfma_f32_32x32x16_bf16 v[32:47], v[176:179], v[180:183], v[32:47]
	s_waitcnt lgkmcnt(5)
	v_mfma_f32_32x32x16_bf16 v[48:63], v[176:179], v[184:187], v[48:63]
	s_waitcnt lgkmcnt(4)
	v_mfma_f32_32x32x16_bf16 v[0:15], v[188:191], v[180:183], v[0:15]
	v_mfma_f32_32x32x16_bf16 v[16:31], v[188:191], v[184:187], v[16:31]
	ds_read_b128 v[176:179], v199
	ds_read_b128 v[180:183], v203
	ds_read_b128 v[184:187], v203 offset:4096
	ds_read_b128 v[188:191], v199 offset:4096
	s_waitcnt lgkmcnt(6)
	v_mfma_f32_32x32x16_bf16 v[32:47], v[156:159], v[164:167], v[32:47]
	s_waitcnt lgkmcnt(5)
	v_mfma_f32_32x32x16_bf16 v[48:63], v[156:159], v[168:171], v[48:63]
	s_waitcnt lgkmcnt(4)
	v_mfma_f32_32x32x16_bf16 v[0:15], v[172:175], v[164:167], v[0:15]
	v_mfma_f32_32x32x16_bf16 v[16:31], v[172:175], v[168:171], v[16:31]
	s_waitcnt lgkmcnt(2)
	v_mfma_f32_32x32x16_bf16 v[32:47], v[176:179], v[180:183], v[32:47]
	s_waitcnt lgkmcnt(1)
	v_mfma_f32_32x32x16_bf16 v[48:63], v[176:179], v[184:187], v[48:63]
	s_waitcnt lgkmcnt(0)
	v_mfma_f32_32x32x16_bf16 v[0:15], v[188:191], v[180:183], v[0:15]
	v_mfma_f32_32x32x16_bf16 v[16:31], v[188:191], v[184:187], v[16:31]
	s_setprio 0
	s_waitcnt vmcnt(0)
	s_barrier
; DI unsigned pack2(float a, float b) { f32v2 v = {a, b}; bf16v2 r = __builtin_convertvector(v, bf16v2); return __builtin_bit_cast(unsigned, r); }
;     ...
;     for (int kt = 0; kt < KT; kt += 2) {
;       if (kt + 2 < KT && dummy != 2) G_LOAD(y, kt + 2);
;       G_COMPUTE(0);
;       if (kt + 1 < KT && dummy != 2) G_STORE(x, 1);
;       __syncthreads();
;       if (kt + 1 >= KT) break;
;       if (kt + 3 < KT && dummy != 2) G_LOAD(x, kt + 3);
;       G_COMPUTE(1);
;       if (kt + 2 < KT && dummy != 2) G_STORE(y, 0);
;       __syncthreads();
;     }
;     ...
;       const int hb = (n0e >> 7) * 64 + (cb >> 6) * 32 + (cb & 31);
;       const bool odd = (cb & 1) != 0;
; #pragma unroll
;       for (int mi = 0; mi < 2; ++mi)
; #pragma unroll
;         for (int i = 0; i < 16; i += 2) {
;           const float u0 = acc[mi][0][i], g0 = acc[mi][1][i], u1 = acc[mi][0][i + 1], g1 = acc[mi][1][i + 1];
;           const float a = u0 * __builtin_amdgcn_rcpf(1.f + __expf(-u0)) * g0, b2 = u1 * __builtin_amdgcn_rcpf(1.f + __expf(-u1)) * g1;
;           const float recv = dpp_f(odd ? a : b2, 0);
;           const int row = m0e + rb + mi * 32 + (i & 3) + 8 * (i >> 2) + (odd ? 1 : 0);
;           const unsigned w = odd ? pack2(recv, b2) : pack2(a, recv);
;           __builtin_nontemporal_store(w, (unsigned*)(P.pbuf + (size_t)row * DFF + (hb & ~1)));
;         }
	s_setprio 1
	ds_read_b128 v[156:159], v196 offset:32768
	ds_read_b128 v[164:167], v200 offset:32768
	ds_read_b128 v[168:171], v200 offset:36864
	ds_read_b128 v[172:175], v196 offset:36864
	ds_read_b128 v[176:179], v197 offset:32768
	ds_read_b128 v[180:183], v201 offset:32768
	ds_read_b128 v[184:187], v201 offset:36864
	ds_read_b128 v[188:191], v197 offset:36864
	s_waitcnt lgkmcnt(6)
	v_mfma_f32_32x32x16_bf16 v[32:47], v[156:159], v[164:167], v[32:47]
	s_waitcnt lgkmcnt(5)
	v_mfma_f32_32x32x16_bf16 v[48:63], v[156:159], v[168:171], v[48:63]
	s_waitcnt lgkmcnt(4)
	v_mfma_f32_32x32x16_bf16 v[0:15], v[172:175], v[164:167], v[0:15]
	v_mfma_f32_32x32x16_bf16 v[16:31], v[172:175], v[168:171], v[16:31]
	ds_read_b128 v[156:159], v198 offset:32768
	ds_read_b128 v[164:167], v202 offset:32768
	ds_read_b128 v[168:171], v202 offset:36864
	ds_read_b128 v[172:175], v198 offset:36864
	s_waitcnt lgkmcnt(6)
	v_mfma_f32_32x32x16_bf16 v[32:47], v[176:179], v[180:183], v[32:47]
	s_waitcnt lgkmcnt(5)
	v_mfma_f32_32x32x16_bf16 v[48:63], v[176:179], v[184:187], v[48:63]
	s_waitcnt lgkmcnt(4)
	v_mfma_f32_32x32x16_bf16 v[0:15], v[188:191], v[180:183], v[0:15]
	v_mfma_f32_32x32x16_bf16 v[16:31], v[188:191], v[184:187], v[16:31]
	ds_read_b128 v[176:179], v199 offset:32768
	ds_read_b128 v[180:183], v203 offset:32768
	ds_read_b128 v[184:187], v203 offset:36864
	ds_read_b128 v[188:191], v199 offset:36864
	s_waitcnt lgkmcnt(6)
	v_mfma_f32_32x32x16_bf16 v[32:47], v[156:159], v[164:167], v[32:47]
	s_waitcnt lgkmcnt(5)
	v_mfma_f32_32x32x16_bf16 v[48:63], v[156:159], v[168:171], v[48:63]
	s_waitcnt lgkmcnt(4)
	v_mfma_f32_32x32x16_bf16 v[0:15], v[172:175], v[164:167], v[0:15]
	v_mfma_f32_32x32x16_bf16 v[16:31], v[172:175], v[168:171], v[16:31]
	s_waitcnt lgkmcnt(2)
	v_mfma_f32_32x32x16_bf16 v[32:47], v[176:179], v[180:183], v[32:47]
	s_waitcnt lgkmcnt(1)
	v_mfma_f32_32x32x16_bf16 v[48:63], v[176:179], v[184:187], v[48:63]
	s_waitcnt lgkmcnt(0)
	v_mfma_f32_32x32x16_bf16 v[0:15], v[188:191], v[180:183], v[0:15]
	v_mfma_f32_32x32x16_bf16 v[16:31], v[188:191], v[184:187], v[16:31]
	s_setprio 0
	s_nop 4
	v_mul_f32_e32 v67, 0xbfb8aa3b, v32
	v_exp_f32_e32 v67, v67
	s_barrier
	v_add_f32_e32 v67, 1.0, v67
	v_rcp_f32_e32 v67, v67
	v_mov_b32_e32 v65, v155
	v_mov_b32_e32 v66, v96
	v_mul_f32_e32 v32, v32, v67
	v_mul_f32_e32 v32, v48, v32
	v_mul_f32_e32 v48, 0xbfb8aa3b, v33
	v_exp_f32_e32 v48, v48
	s_ashr_i32 s1, s1, 1
	v_ashrrev_i32_e32 v64, 1, v66
	v_add_f32_e32 v48, 1.0, v48
	v_rcp_f32_e32 v48, v48
	s_andn2_b32 s1, s1, 63
	v_and_b32_e32 v64, 0xffffffe0, v64
	v_add_u32_e32 v64, s1, v64
	v_and_or_b32 v64, v66, 30, v64
	v_and_b32_e32 v66, 1, v66
	v_mul_f32_e32 v33, v33, v48
	v_cmp_eq_u32_e32 vcc, 0, v66
	v_mul_f32_e32 v33, v49, v33
	v_add3_u32 v66, v65, s0, v66
	v_cndmask_b32_e32 v48, v32, v33, vcc
	v_ashrrev_i32_e32 v65, 31, v64
	v_lshl_add_u64 v[64:65], v[64:65], 1, s[64:65]
	v_mov_b32_dpp v48, v48 quad_perm:[1,0,3,2] row_mask:0xf bank_mask:0xf bound_ctrl:1
	v_cndmask_b32_e32 v33, v33, v48, vcc
	v_cndmask_b32_e32 v32, v48, v32, vcc
	s_movk_i32 s3, 0x1600
	v_cvt_pk_bf16_f32 v48, v32, v33
	v_mad_i64_i32 v[32:33], s[0:1], v66, s3, v[64:65]
	global_store_dword v[32:33], v48, off nt
	v_mul_f32_e32 v32, 0xbfb8aa3b, v34
	v_mul_f32_e32 v33, 0xbfb8aa3b, v35
	v_exp_f32_e32 v32, v32
	v_exp_f32_e32 v33, v33
	v_add_f32_e32 v32, 1.0, v32
	v_add_f32_e32 v33, 1.0, v33
	v_rcp_f32_e32 v32, v32
	v_rcp_f32_e32 v33, v33
	v_mul_f32_e32 v32, v34, v32
	v_mul_f32_e32 v33, v35, v33
	v_mul_f32_e32 v32, v50, v32
	v_mul_f32_e32 v33, v51, v33
	v_cndmask_b32_e32 v34, v32, v33, vcc
	v_add_u32_e32 v35, 2, v66
	s_nop 0
	v_mov_b32_dpp v34, v34 quad_perm:[1,0,3,2] row_mask:0xf bank_mask:0xf bound_ctrl:1
	v_cndmask_b32_e32 v33, v33, v34, vcc
	v_cndmask_b32_e32 v32, v34, v32, vcc
	v_cvt_pk_bf16_f32 v34, v32, v33
	v_mad_i64_i32 v[32:33], s[0:1], v35, s3, v[64:65]
	global_store_dword v[32:33], v34, off nt
	v_mul_f32_e32 v32, 0xbfb8aa3b, v36
	v_mul_f32_e32 v33, 0xbfb8aa3b, v37
	v_exp_f32_e32 v32, v32
	v_exp_f32_e32 v33, v33
	v_add_u32_e32 v35, 8, v66
	v_add_f32_e32 v32, 1.0, v32
	v_add_f32_e32 v33, 1.0, v33
	v_rcp_f32_e32 v32, v32
	v_rcp_f32_e32 v33, v33
	v_mul_f32_e32 v32, v36, v32
	v_mul_f32_e32 v33, v37, v33
	v_mul_f32_e32 v32, v52, v32
	v_mul_f32_e32 v33, v53, v33
	v_cndmask_b32_e32 v34, v32, v33, vcc
	s_nop 1
	v_mov_b32_dpp v34, v34 quad_perm:[1,0,3,2] row_mask:0xf bank_mask:0xf bound_ctrl:1
	v_cndmask_b32_e32 v33, v33, v34, vcc
	v_cndmask_b32_e32 v32, v34, v32, vcc
	v_cvt_pk_bf16_f32 v34, v32, v33
	v_mad_i64_i32 v[32:33], s[0:1], v35, s3, v[64:65]
	global_store_dword v[32:33], v34, off nt
	v_mul_f32_e32 v32, 0xbfb8aa3b, v38
	v_mul_f32_e32 v33, 0xbfb8aa3b, v39
	v_exp_f32_e32 v32, v32
	v_exp_f32_e32 v33, v33
	v_add_u32_e32 v35, 10, v66
	v_add_f32_e32 v32, 1.0, v32
	v_add_f32_e32 v33, 1.0, v33
	v_rcp_f32_e32 v32, v32
	v_rcp_f32_e32 v33, v33
	v_mul_f32_e32 v32, v38, v32
	v_mul_f32_e32 v33, v39, v33
	v_mul_f32_e32 v32, v54, v32
	v_mul_f32_e32 v33, v55, v33
	v_cndmask_b32_e32 v34, v32, v33, vcc
	s_nop 1
	v_mov_b32_dpp v34, v34 quad_perm:[1,0,3,2] row_mask:0xf bank_mask:0xf bound_ctrl:1
	v_cndmask_b32_e32 v33, v33, v34, vcc
	v_cndmask_b32_e32 v32, v34, v32, vcc
	v_cvt_pk_bf16_f32 v34, v32, v33
	v_mad_i64_i32 v[32:33], s[0:1], v35, s3, v[64:65]
	global_store_dword v[32:33], v34, off nt
	v_mul_f32_e32 v32, 0xbfb8aa3b, v40
	v_mul_f32_e32 v33, 0xbfb8aa3b, v41
	v_exp_f32_e32 v32, v32
	v_exp_f32_e32 v33, v33
	v_add_u32_e32 v35, 16, v66
	v_add_f32_e32 v32, 1.0, v32
	v_add_f32_e32 v33, 1.0, v33
	v_rcp_f32_e32 v32, v32
	v_rcp_f32_e32 v33, v33
	v_mul_f32_e32 v32, v40, v32
	v_mul_f32_e32 v33, v41, v33
	v_mul_f32_e32 v32, v56, v32
; DI unsigned pack2(float a, float b) { f32v2 v = {a, b}; bf16v2 r = __builtin_convertvector(v, bf16v2); return __builtin_bit_cast(unsigned, r); }
;     ...
; #pragma unroll
;       for (int mi = 0; mi < 2; ++mi)
; #pragma unroll
;         for (int i = 0; i < 16; i += 2) {
;           const float u0 = acc[mi][0][i], g0 = acc[mi][1][i], u1 = acc[mi][0][i + 1], g1 = acc[mi][1][i + 1];
;           const float a = u0 * __builtin_amdgcn_rcpf(1.f + __expf(-u0)) * g0, b2 = u1 * __builtin_amdgcn_rcpf(1.f + __expf(-u1)) * g1;
;           const float recv = dpp_f(odd ? a : b2, 0);
;           const int row = m0e + rb + mi * 32 + (i & 3) + 8 * (i >> 2) + (odd ? 1 : 0);
;           const unsigned w = odd ? pack2(recv, b2) : pack2(a, recv);
;           __builtin_nontemporal_store(w, (unsigned*)(P.pbuf + (size_t)row * DFF + (hb & ~1)));
;         }
	v_mul_f32_e32 v33, v57, v33
	v_cndmask_b32_e32 v34, v32, v33, vcc
	s_nop 1
	v_mov_b32_dpp v34, v34 quad_perm:[1,0,3,2] row_mask:0xf bank_mask:0xf bound_ctrl:1
	v_cndmask_b32_e32 v33, v33, v34, vcc
	v_cndmask_b32_e32 v32, v34, v32, vcc
	v_cvt_pk_bf16_f32 v34, v32, v33
	v_mad_i64_i32 v[32:33], s[0:1], v35, s3, v[64:65]
	global_store_dword v[32:33], v34, off nt
	v_mul_f32_e32 v32, 0xbfb8aa3b, v42
	v_mul_f32_e32 v33, 0xbfb8aa3b, v43
	v_exp_f32_e32 v32, v32
	v_exp_f32_e32 v33, v33
	v_add_u32_e32 v35, 18, v66
	v_add_f32_e32 v32, 1.0, v32
	v_add_f32_e32 v33, 1.0, v33
	v_rcp_f32_e32 v32, v32
	v_rcp_f32_e32 v33, v33
	v_mul_f32_e32 v32, v42, v32
	v_mul_f32_e32 v33, v43, v33
	v_mul_f32_e32 v32, v58, v32
	v_mul_f32_e32 v33, v59, v33
	v_cndmask_b32_e32 v34, v32, v33, vcc
	s_nop 1
	v_mov_b32_dpp v34, v34 quad_perm:[1,0,3,2] row_mask:0xf bank_mask:0xf bound_ctrl:1
	v_cndmask_b32_e32 v33, v33, v34, vcc
	v_cndmask_b32_e32 v32, v34, v32, vcc
	v_cvt_pk_bf16_f32 v34, v32, v33
	v_mad_i64_i32 v[32:33], s[0:1], v35, s3, v[64:65]
	global_store_dword v[32:33], v34, off nt
	v_mul_f32_e32 v32, 0xbfb8aa3b, v44
	v_mul_f32_e32 v33, 0xbfb8aa3b, v45
	v_exp_f32_e32 v32, v32
	v_exp_f32_e32 v33, v33
	v_add_u32_e32 v35, 24, v66
	v_add_f32_e32 v32, 1.0, v32
	v_add_f32_e32 v33, 1.0, v33
	v_rcp_f32_e32 v32, v32
	v_rcp_f32_e32 v33, v33
	v_mul_f32_e32 v32, v44, v32
	v_mul_f32_e32 v33, v45, v33
	v_mul_f32_e32 v32, v60, v32
	v_mul_f32_e32 v33, v61, v33
	v_cndmask_b32_e32 v34, v32, v33, vcc
	s_nop 1
	v_mov_b32_dpp v34, v34 quad_perm:[1,0,3,2] row_mask:0xf bank_mask:0xf bound_ctrl:1
	v_cndmask_b32_e32 v33, v33, v34, vcc
	v_cndmask_b32_e32 v32, v34, v32, vcc
	v_cvt_pk_bf16_f32 v34, v32, v33
	v_mad_i64_i32 v[32:33], s[0:1], v35, s3, v[64:65]
	global_store_dword v[32:33], v34, off nt
	v_mul_f32_e32 v32, 0xbfb8aa3b, v46
	v_mul_f32_e32 v33, 0xbfb8aa3b, v47
	v_exp_f32_e32 v32, v32
	v_exp_f32_e32 v33, v33
	v_add_u32_e32 v35, 26, v66
	v_add_f32_e32 v32, 1.0, v32
	v_add_f32_e32 v33, 1.0, v33
	v_rcp_f32_e32 v32, v32
	v_rcp_f32_e32 v33, v33
	v_mul_f32_e32 v32, v46, v32
	v_mul_f32_e32 v33, v47, v33
	v_mul_f32_e32 v32, v62, v32
	v_mul_f32_e32 v33, v63, v33
	v_cndmask_b32_e32 v34, v32, v33, vcc
	s_nop 1
	v_mov_b32_dpp v34, v34 quad_perm:[1,0,3,2] row_mask:0xf bank_mask:0xf bound_ctrl:1
	v_cndmask_b32_e32 v33, v33, v34, vcc
	v_cndmask_b32_e32 v32, v34, v32, vcc
	v_cvt_pk_bf16_f32 v34, v32, v33
	v_mad_i64_i32 v[32:33], s[0:1], v35, s3, v[64:65]
	global_store_dword v[32:33], v34, off nt
	v_mul_f32_e32 v33, 0xbfb8aa3b, v0
	v_exp_f32_e32 v33, v33
	v_add_u32_e32 v32, 32, v66
	v_add_f32_e32 v33, 1.0, v33
	v_rcp_f32_e32 v33, v33
	s_nop 0
	v_mul_f32_e32 v0, v0, v33
	v_mul_f32_e32 v0, v16, v0
	v_mul_f32_e32 v16, 0xbfb8aa3b, v1
	v_exp_f32_e32 v16, v16
	s_nop 0
	v_add_f32_e32 v16, 1.0, v16
	v_rcp_f32_e32 v16, v16
	s_nop 0
	v_mul_f32_e32 v1, v1, v16
	v_mul_f32_e32 v1, v17, v1
	v_cndmask_b32_e32 v16, v0, v1, vcc
	s_nop 1
	v_mov_b32_dpp v16, v16 quad_perm:[1,0,3,2] row_mask:0xf bank_mask:0xf bound_ctrl:1
	v_cndmask_b32_e32 v1, v1, v16, vcc
	v_cndmask_b32_e32 v0, v16, v0, vcc
	v_cvt_pk_bf16_f32 v16, v0, v1
	v_mad_i64_i32 v[0:1], s[0:1], v32, s3, v[64:65]
	global_store_dword v[0:1], v16, off nt
	v_mul_f32_e32 v0, 0xbfb8aa3b, v2
	v_mul_f32_e32 v1, 0xbfb8aa3b, v3
	v_exp_f32_e32 v0, v0
	v_exp_f32_e32 v1, v1
	v_add_f32_e32 v0, 1.0, v0
	v_add_f32_e32 v1, 1.0, v1
	v_rcp_f32_e32 v0, v0
	v_rcp_f32_e32 v1, v1
	v_mul_f32_e32 v0, v2, v0
	v_mul_f32_e32 v1, v3, v1
	v_mul_f32_e32 v0, v18, v0
	v_mul_f32_e32 v1, v19, v1
	v_cndmask_b32_e32 v2, v0, v1, vcc
	v_add_u32_e32 v3, 34, v66
	s_nop 0
	v_mov_b32_dpp v2, v2 quad_perm:[1,0,3,2] row_mask:0xf bank_mask:0xf bound_ctrl:1
	v_cndmask_b32_e32 v1, v1, v2, vcc
	v_cndmask_b32_e32 v0, v2, v0, vcc
	v_cvt_pk_bf16_f32 v2, v0, v1
	v_mad_i64_i32 v[0:1], s[0:1], v3, s3, v[64:65]
	global_store_dword v[0:1], v2, off nt
	v_mul_f32_e32 v0, 0xbfb8aa3b, v4
	v_mul_f32_e32 v1, 0xbfb8aa3b, v5
	v_exp_f32_e32 v0, v0
	v_exp_f32_e32 v1, v1
; DI unsigned pack2(float a, float b) { f32v2 v = {a, b}; bf16v2 r = __builtin_convertvector(v, bf16v2); return __builtin_bit_cast(unsigned, r); }
;     ...
; #pragma unroll
;       for (int mi = 0; mi < 2; ++mi)
; #pragma unroll
;         for (int i = 0; i < 16; i += 2) {
;           const float u0 = acc[mi][0][i], g0 = acc[mi][1][i], u1 = acc[mi][0][i + 1], g1 = acc[mi][1][i + 1];
;           const float a = u0 * __builtin_amdgcn_rcpf(1.f + __expf(-u0)) * g0, b2 = u1 * __builtin_amdgcn_rcpf(1.f + __expf(-u1)) * g1;
;           const float recv = dpp_f(odd ? a : b2, 0);
;           const int row = m0e + rb + mi * 32 + (i & 3) + 8 * (i >> 2) + (odd ? 1 : 0);
;           const unsigned w = odd ? pack2(recv, b2) : pack2(a, recv);
;           __builtin_nontemporal_store(w, (unsigned*)(P.pbuf + (size_t)row * DFF + (hb & ~1)));
;         }
;     }
;   }
	v_add_u32_e32 v3, 40, v66
	v_add_f32_e32 v0, 1.0, v0
	v_add_f32_e32 v1, 1.0, v1
	v_rcp_f32_e32 v0, v0
	v_rcp_f32_e32 v1, v1
	v_mul_f32_e32 v0, v4, v0
	v_mul_f32_e32 v1, v5, v1
	v_mul_f32_e32 v0, v20, v0
	v_mul_f32_e32 v1, v21, v1
	v_cndmask_b32_e32 v2, v0, v1, vcc
	s_nop 1
	v_mov_b32_dpp v2, v2 quad_perm:[1,0,3,2] row_mask:0xf bank_mask:0xf bound_ctrl:1
	v_cndmask_b32_e32 v1, v1, v2, vcc
	v_cndmask_b32_e32 v0, v2, v0, vcc
	v_cvt_pk_bf16_f32 v2, v0, v1
	v_mad_i64_i32 v[0:1], s[0:1], v3, s3, v[64:65]
	global_store_dword v[0:1], v2, off nt
	v_mul_f32_e32 v0, 0xbfb8aa3b, v6
	v_mul_f32_e32 v1, 0xbfb8aa3b, v7
	v_exp_f32_e32 v0, v0
	v_exp_f32_e32 v1, v1
	v_add_u32_e32 v3, 42, v66
	v_add_f32_e32 v0, 1.0, v0
	v_add_f32_e32 v1, 1.0, v1
	v_rcp_f32_e32 v0, v0
	v_rcp_f32_e32 v1, v1
	v_mul_f32_e32 v0, v6, v0
	v_mul_f32_e32 v1, v7, v1
	v_mul_f32_e32 v0, v22, v0
	v_mul_f32_e32 v1, v23, v1
	v_cndmask_b32_e32 v2, v0, v1, vcc
	s_nop 1
	v_mov_b32_dpp v2, v2 quad_perm:[1,0,3,2] row_mask:0xf bank_mask:0xf bound_ctrl:1
	v_cndmask_b32_e32 v1, v1, v2, vcc
	v_cndmask_b32_e32 v0, v2, v0, vcc
	v_cvt_pk_bf16_f32 v2, v0, v1
	v_mad_i64_i32 v[0:1], s[0:1], v3, s3, v[64:65]
	global_store_dword v[0:1], v2, off nt
	v_mul_f32_e32 v0, 0xbfb8aa3b, v8
	v_mul_f32_e32 v1, 0xbfb8aa3b, v9
	v_exp_f32_e32 v0, v0
	v_exp_f32_e32 v1, v1
	v_add_u32_e32 v3, 48, v66
	v_add_f32_e32 v0, 1.0, v0
	v_add_f32_e32 v1, 1.0, v1
	v_rcp_f32_e32 v0, v0
	v_rcp_f32_e32 v1, v1
	v_mul_f32_e32 v0, v8, v0
	v_mul_f32_e32 v1, v9, v1
	v_mul_f32_e32 v0, v24, v0
	v_mul_f32_e32 v1, v25, v1
	v_cndmask_b32_e32 v2, v0, v1, vcc
	s_nop 1
	v_mov_b32_dpp v2, v2 quad_perm:[1,0,3,2] row_mask:0xf bank_mask:0xf bound_ctrl:1
	v_cndmask_b32_e32 v1, v1, v2, vcc
	v_cndmask_b32_e32 v0, v2, v0, vcc
	v_cvt_pk_bf16_f32 v2, v0, v1
	v_mad_i64_i32 v[0:1], s[0:1], v3, s3, v[64:65]
	global_store_dword v[0:1], v2, off nt
	v_mul_f32_e32 v0, 0xbfb8aa3b, v10
	v_mul_f32_e32 v1, 0xbfb8aa3b, v11
	v_exp_f32_e32 v0, v0
	v_exp_f32_e32 v1, v1
	v_add_u32_e32 v3, 50, v66
	v_add_f32_e32 v0, 1.0, v0
	v_add_f32_e32 v1, 1.0, v1
	v_rcp_f32_e32 v0, v0
	v_rcp_f32_e32 v1, v1
	v_mul_f32_e32 v0, v10, v0
	v_mul_f32_e32 v1, v11, v1
	v_mul_f32_e32 v0, v26, v0
	v_mul_f32_e32 v1, v27, v1
	v_cndmask_b32_e32 v2, v0, v1, vcc
	s_nop 1
	v_mov_b32_dpp v2, v2 quad_perm:[1,0,3,2] row_mask:0xf bank_mask:0xf bound_ctrl:1
	v_cndmask_b32_e32 v1, v1, v2, vcc
	v_cndmask_b32_e32 v0, v2, v0, vcc
	v_cvt_pk_bf16_f32 v2, v0, v1
	v_mad_i64_i32 v[0:1], s[0:1], v3, s3, v[64:65]
	global_store_dword v[0:1], v2, off nt
	v_mul_f32_e32 v0, 0xbfb8aa3b, v12
	v_mul_f32_e32 v1, 0xbfb8aa3b, v13
	v_exp_f32_e32 v0, v0
	v_exp_f32_e32 v1, v1
	v_add_u32_e32 v3, 56, v66
	v_add_f32_e32 v0, 1.0, v0
	v_add_f32_e32 v1, 1.0, v1
	v_rcp_f32_e32 v0, v0
	v_rcp_f32_e32 v1, v1
	v_mul_f32_e32 v0, v12, v0
	v_mul_f32_e32 v1, v13, v1
	v_mul_f32_e32 v0, v28, v0
	v_mul_f32_e32 v1, v29, v1
	v_cndmask_b32_e32 v2, v0, v1, vcc
	s_nop 1
	v_mov_b32_dpp v2, v2 quad_perm:[1,0,3,2] row_mask:0xf bank_mask:0xf bound_ctrl:1
	v_cndmask_b32_e32 v1, v1, v2, vcc
	v_cndmask_b32_e32 v0, v2, v0, vcc
	v_cvt_pk_bf16_f32 v2, v0, v1
	v_mad_i64_i32 v[0:1], s[0:1], v3, s3, v[64:65]
	global_store_dword v[0:1], v2, off nt
	v_mul_f32_e32 v0, 0xbfb8aa3b, v14
	v_mul_f32_e32 v1, 0xbfb8aa3b, v15
	v_exp_f32_e32 v0, v0
	v_exp_f32_e32 v1, v1
	v_add_u32_e32 v3, 58, v66
	v_add_f32_e32 v0, 1.0, v0
	v_add_f32_e32 v1, 1.0, v1
	v_rcp_f32_e32 v0, v0
	v_rcp_f32_e32 v1, v1
	v_mul_f32_e32 v0, v14, v0
	v_mul_f32_e32 v1, v15, v1
	v_mul_f32_e32 v0, v30, v0
	v_mul_f32_e32 v1, v31, v1
	v_cndmask_b32_e32 v2, v0, v1, vcc
	s_nop 1
	v_mov_b32_dpp v2, v2 quad_perm:[1,0,3,2] row_mask:0xf bank_mask:0xf bound_ctrl:1
	v_cndmask_b32_e32 v1, v1, v2, vcc
	v_cndmask_b32_e32 v0, v2, v0, vcc
	v_cvt_pk_bf16_f32 v2, v0, v1
	v_mad_i64_i32 v[0:1], s[0:1], v3, s3, v[64:65]
	v_readlane_b32 s0, v252, 30
	s_add_i32 s2, s2, s0
	v_readlane_b32 s0, v252, 44
	s_cmp_ge_i32 s2, s0
	global_store_dword v[0:1], v2, off nt
	s_cbranch_scc1 .LBB0_193

;     ...
;     const int mi_ = swz ? (mq * 8 + (bid & 7)) : mq;
;     const int mt = latent_only ? ((mi_ >> 4) * 18 + 2 + (mi_ & 15)) : mi_;
;     const int m0 = mt * 128, n0 = nt * 128;
;     f32x16 acc[2][2];
; #pragma unroll
;     for (int a = 0; a < 2; ++a)
; #pragma unroll
;       for (int b = 0; b < 2; ++b)
; #pragma unroll
;         for (int i = 0; i < 16; ++i) acc[a][b][i] = 0.f;
;     const u16* Ag = A + (size_t)(m0 + lrow) * K + lkc * 8;
;     const u16* Bg = Bt + (size_t)(n0 + lrow) * K + lkc * 8;
;     const size_t K32 = (size_t)32 * K;
;     uint4 xa0, xa1, xa2, xa3, xb0, xb1, xb2, xb3;
;     uint4 ya0, ya1, ya2, ya3, yb0, yb1, yb2, yb3;
;     ...
;     G_LOAD(x, 0);
;     G_STORE(x, 0);
;     __syncthreads();
;     if (KT > 1) G_LOAD(x, 1);
;     for (int kt = 0; kt < KT; kt += 2) {
;       if (kt + 2 < KT && dummy != 2) G_LOAD(y, kt + 2);
;       G_COMPUTE(0);
;       if (kt + 1 < KT && dummy != 2) G_STORE(x, 1);
;       __syncthreads();
;       if (kt + 1 >= KT) break;
;       if (kt + 3 < KT && dummy != 2) G_LOAD(x, kt + 3);
;       G_COMPUTE(1);
;       if (kt + 2 < KT && dummy != 2) G_STORE(y, 0);
;       __syncthreads();
;     }
.LBB0_197:
	s_lshl_b32 s0, s4, 3
	v_readlane_b32 s1, v252, 34
	s_or_b32 s5, s0, s1
	v_readlane_b32 s0, v252, 28
	v_readlane_b32 s1, v252, 29
	s_and_b64 s[0:1], s[0:1], exec
	s_cselect_b32 s0, s5, s4
	s_lshr_b32 s1, s0, 4
	s_mul_i32 s1, s1, 18
	s_and_b32 s0, s0, 15
	s_add_i32 s0, s0, s1
	s_lshl_b32 s0, s0, 7
	s_addk_i32 s0, 0x100
	s_lshl_b32 s1, s3, 7
	v_add_u32_e32 v0, s0, v154
	v_ashrrev_i32_e32 v1, 31, v0
	v_lshlrev_b64 v[0:1], 11, v[0:1]
	v_lshl_add_u64 v[138:139], v[130:131], 0, v[0:1]
	v_add_u32_e32 v0, s1, v154
	v_ashrrev_i32_e32 v1, 31, v0
	v_lshlrev_b64 v[0:1], 11, v[0:1]
	v_lshl_add_u64 v[140:141], v[132:133], 0, v[0:1]
	v_and_b32_e32 v194, 7, v206
	v_bfe_u32 v195, v206, 4, 3
	v_xor_b32_e32 v195, v195, v194
	v_sub_u32_e32 v195, v195, v194
	v_lshlrev_b32_e32 v192, 4, v195
	v_ashrrev_i32_e32 v193, 31, v192
	v_lshl_add_u64 v[138:139], v[138:139], 0, v[192:193]
	v_lshl_add_u64 v[140:141], v[140:141], 0, v[192:193]
	s_mov_b64 s[78:79], 0x10000
	v_lshl_add_u64 v[142:143], v[138:139], 0, s[78:79]
	v_lshl_add_u64 v[146:147], v[140:141], 0, s[78:79]
	s_mov_b64 s[78:79], 0x20000
	v_lshl_add_u64 v[144:145], v[138:139], 0, s[78:79]
	v_lshl_add_u64 v[148:149], v[140:141], 0, s[78:79]
	s_mov_b64 s[78:79], 0x30000
	v_lshl_add_u64 v[152:153], v[138:139], 0, s[78:79]
	v_lshl_add_u64 v[150:151], v[140:141], 0, s[78:79]
	v_lshrrev_b32_e32 v194, 6, v206
	v_lshlrev_b32_e32 v194, 10, v194
	s_nop 0
	v_readfirstlane_b32 s76, v194
	v_bfe_u32 v195, v206, 1, 3
	v_bfe_u32 v194, v206, 5, 1
	v_and_b32_e32 v192, 1, v195
	v_xor_b32_e32 v194, v194, v192
	v_lshrrev_b32_e32 v195, 1, v195
	v_and_b32_e32 v192, 31, v206
	v_lshrrev_b32_e32 v193, 7, v206
	v_lshl_add_u32 v193, v193, 6, v192
	v_lshlrev_b32_e32 v193, 7, v193
	v_lshl_add_u32 v193, v194, 4, v193
	v_add_u32_e32 v193, 2048, v193
	v_bfe_u32 v172, v206, 6, 1
	v_lshl_add_u32 v172, v172, 6, v192
	v_lshlrev_b32_e32 v172, 7, v172
	v_lshl_add_u32 v172, v194, 4, v172
	v_add_u32_e32 v172, 18432, v172
	v_xor_b32_e32 v192, 0, v195
	v_lshl_add_u32 v196, v192, 5, v193
	v_lshl_add_u32 v200, v192, 5, v172
	v_xor_b32_e32 v192, 1, v195
	v_lshl_add_u32 v197, v192, 5, v193
	v_lshl_add_u32 v201, v192, 5, v172
	v_xor_b32_e32 v192, 2, v195
	v_lshl_add_u32 v198, v192, 5, v193
	v_lshl_add_u32 v202, v192, 5, v172
	v_xor_b32_e32 v192, 3, v195
	v_lshl_add_u32 v199, v192, 5, v193
	v_lshl_add_u32 v203, v192, 5, v172
	s_add_u32 m0, s76, 0x800
	s_nop 0
	global_load_lds_dwordx4 v[138:139], off
	s_add_u32 m0, s76, 0x1800
	s_nop 0
	global_load_lds_dwordx4 v[142:143], off
	s_add_u32 m0, s76, 0x2800
	s_nop 0
	global_load_lds_dwordx4 v[144:145], off
	s_add_u32 m0, s76, 0x3800
	s_nop 0
	global_load_lds_dwordx4 v[152:153], off
	s_add_u32 m0, s76, 0x4800
	s_nop 0
	global_load_lds_dwordx4 v[140:141], off
	s_add_u32 m0, s76, 0x5800
	s_nop 0
	global_load_lds_dwordx4 v[146:147], off
	s_add_u32 m0, s76, 0x6800
	s_nop 0
	global_load_lds_dwordx4 v[148:149], off
	s_add_u32 m0, s76, 0x7800
	s_nop 0
	global_load_lds_dwordx4 v[150:151], off
	s_waitcnt vmcnt(0)
	s_barrier
	s_setprio 1
	ds_read_b128 v[156:159], v196
	ds_read_b128 v[164:167], v200
	ds_read_b128 v[168:171], v200 offset:4096
	ds_read_b128 v[172:175], v196 offset:4096
	ds_read_b128 v[176:179], v197
	ds_read_b128 v[180:183], v201
	ds_read_b128 v[184:187], v201 offset:4096
	ds_read_b128 v[188:191], v197 offset:4096
	s_add_u32 m0, s76, 0x8780
	s_nop 0
	global_load_lds_dwordx4 v[138:139], off offset:128
	s_add_u32 m0, s76, 0x9780
	s_nop 0
	global_load_lds_dwordx4 v[142:143], off offset:128
	s_add_u32 m0, s76, 0xa780
	s_nop 0
	global_load_lds_dwordx4 v[144:145], off offset:128
	s_add_u32 m0, s76, 0xb780
	s_nop 0
	global_load_lds_dwordx4 v[152:153], off offset:128
	s_add_u32 m0, s76, 0xc780
	s_nop 0
	global_load_lds_dwordx4 v[140:141], off offset:128
	s_add_u32 m0, s76, 0xd780
	s_nop 0
	global_load_lds_dwordx4 v[146:147], off offset:128
	s_add_u32 m0, s76, 0xe780
	s_nop 0
	global_load_lds_dwordx4 v[148:149], off offset:128
	s_add_u32 m0, s76, 0xf780
	s_nop 0
	global_load_lds_dwordx4 v[150:151], off offset:128
	s_waitcnt lgkmcnt(6)
	v_mfma_f32_32x32x16_bf16 v[32:47], v[156:159], v[164:167], 0
	s_waitcnt lgkmcnt(5)
	v_mfma_f32_32x32x16_bf16 v[48:63], v[156:159], v[168:171], 0
	s_waitcnt lgkmcnt(4)
	v_mfma_f32_32x32x16_bf16 v[0:15], v[172:175], v[164:167], 0
	v_mfma_f32_32x32x16_bf16 v[16:31], v[172:175], v[168:171], 0
	ds_read_b128 v[156:159], v198
	ds_read_b128 v[164:167], v202
	ds_read_b128 v[168:171], v202 offset:4096
	ds_read_b128 v[172:175], v198 offset:4096
	s_waitcnt lgkmcnt(6)
	v_mfma_f32_32x32x16_bf16 v[32:47], v[176:179], v[180:183], v[32:47]
	s_waitcnt lgkmcnt(5)
	v_mfma_f32_32x32x16_bf16 v[48:63], v[176:179], v[184:187], v[48:63]
	s_waitcnt lgkmcnt(4)
	v_mfma_f32_32x32x16_bf16 v[0:15], v[188:191], v[180:183], v[0:15]
	v_mfma_f32_32x32x16_bf16 v[16:31], v[188:191], v[184:187], v[16:31]
	ds_read_b128 v[176:179], v199
	ds_read_b128 v[180:183], v203
	ds_read_b128 v[184:187], v203 offset:4096
	ds_read_b128 v[188:191], v199 offset:4096
	s_waitcnt lgkmcnt(6)
	v_mfma_f32_32x32x16_bf16 v[32:47], v[156:159], v[164:167], v[32:47]
	s_waitcnt lgkmcnt(5)
	v_mfma_f32_32x32x16_bf16 v[48:63], v[156:159], v[168:171], v[48:63]
	s_waitcnt lgkmcnt(4)
	v_mfma_f32_32x32x16_bf16 v[0:15], v[172:175], v[164:167], v[0:15]
	v_mfma_f32_32x32x16_bf16 v[16:31], v[172:175], v[168:171], v[16:31]
	s_waitcnt lgkmcnt(2)
	v_mfma_f32_32x32x16_bf16 v[32:47], v[176:179], v[180:183], v[32:47]
	s_waitcnt lgkmcnt(1)
	v_mfma_f32_32x32x16_bf16 v[48:63], v[176:179], v[184:187], v[48:63]
	s_waitcnt lgkmcnt(0)
	v_mfma_f32_32x32x16_bf16 v[0:15], v[188:191], v[180:183], v[0:15]
	v_mfma_f32_32x32x16_bf16 v[16:31], v[188:191], v[184:187], v[16:31]
	s_setprio 0
	s_waitcnt vmcnt(0)
	s_barrier
;     ...
;     G_LOAD(x, 0);
;     G_STORE(x, 0);
;     __syncthreads();
;     if (KT > 1) G_LOAD(x, 1);
;     for (int kt = 0; kt < KT; kt += 2) {
;       if (kt + 2 < KT && dummy != 2) G_LOAD(y, kt + 2);
;       G_COMPUTE(0);
;       if (kt + 1 < KT && dummy != 2) G_STORE(x, 1);
;       __syncthreads();
;       if (kt + 1 >= KT) break;
;       if (kt + 3 < KT && dummy != 2) G_LOAD(x, kt + 3);
;       G_COMPUTE(1);
;       if (kt + 2 < KT && dummy != 2) G_STORE(y, 0);
;       __syncthreads();
	s_setprio 1
	ds_read_b128 v[156:159], v196 offset:32768
	ds_read_b128 v[164:167], v200 offset:32768
	ds_read_b128 v[168:171], v200 offset:36864
	ds_read_b128 v[172:175], v196 offset:36864
	ds_read_b128 v[176:179], v197 offset:32768
	ds_read_b128 v[180:183], v201 offset:32768
	ds_read_b128 v[184:187], v201 offset:36864
	ds_read_b128 v[188:191], v197 offset:36864
	s_add_u32 m0, s76, 0x700
	s_nop 0
	global_load_lds_dwordx4 v[138:139], off offset:256
	s_add_u32 m0, s76, 0x1700
	s_nop 0
	global_load_lds_dwordx4 v[142:143], off offset:256
	s_add_u32 m0, s76, 0x2700
	s_nop 0
	global_load_lds_dwordx4 v[144:145], off offset:256
	s_add_u32 m0, s76, 0x3700
	s_nop 0
	global_load_lds_dwordx4 v[152:153], off offset:256
	s_add_u32 m0, s76, 0x4700
	s_nop 0
	global_load_lds_dwordx4 v[140:141], off offset:256
	s_add_u32 m0, s76, 0x5700
	s_nop 0
	global_load_lds_dwordx4 v[146:147], off offset:256
	s_add_u32 m0, s76, 0x6700
	s_nop 0
	global_load_lds_dwordx4 v[148:149], off offset:256
	s_add_u32 m0, s76, 0x7700
	s_nop 0
	global_load_lds_dwordx4 v[150:151], off offset:256
	s_waitcnt lgkmcnt(6)
	v_mfma_f32_32x32x16_bf16 v[32:47], v[156:159], v[164:167], v[32:47]
	s_waitcnt lgkmcnt(5)
	v_mfma_f32_32x32x16_bf16 v[48:63], v[156:159], v[168:171], v[48:63]
	s_waitcnt lgkmcnt(4)
	v_mfma_f32_32x32x16_bf16 v[0:15], v[172:175], v[164:167], v[0:15]
	v_mfma_f32_32x32x16_bf16 v[16:31], v[172:175], v[168:171], v[16:31]
	ds_read_b128 v[156:159], v198 offset:32768
	ds_read_b128 v[164:167], v202 offset:32768
	ds_read_b128 v[168:171], v202 offset:36864
	ds_read_b128 v[172:175], v198 offset:36864
	s_waitcnt lgkmcnt(6)
	v_mfma_f32_32x32x16_bf16 v[32:47], v[176:179], v[180:183], v[32:47]
	s_waitcnt lgkmcnt(5)
	v_mfma_f32_32x32x16_bf16 v[48:63], v[176:179], v[184:187], v[48:63]
	s_waitcnt lgkmcnt(4)
	v_mfma_f32_32x32x16_bf16 v[0:15], v[188:191], v[180:183], v[0:15]
	v_mfma_f32_32x32x16_bf16 v[16:31], v[188:191], v[184:187], v[16:31]
	ds_read_b128 v[176:179], v199 offset:32768
	ds_read_b128 v[180:183], v203 offset:32768
	ds_read_b128 v[184:187], v203 offset:36864
	ds_read_b128 v[188:191], v199 offset:36864
	s_waitcnt lgkmcnt(6)
	v_mfma_f32_32x32x16_bf16 v[32:47], v[156:159], v[164:167], v[32:47]
	s_waitcnt lgkmcnt(5)
	v_mfma_f32_32x32x16_bf16 v[48:63], v[156:159], v[168:171], v[48:63]
	s_waitcnt lgkmcnt(4)
	v_mfma_f32_32x32x16_bf16 v[0:15], v[172:175], v[164:167], v[0:15]
	v_mfma_f32_32x32x16_bf16 v[16:31], v[172:175], v[168:171], v[16:31]
	s_waitcnt lgkmcnt(2)
	v_mfma_f32_32x32x16_bf16 v[32:47], v[176:179], v[180:183], v[32:47]
	s_waitcnt lgkmcnt(1)
	v_mfma_f32_32x32x16_bf16 v[48:63], v[176:179], v[184:187], v[48:63]
	s_waitcnt lgkmcnt(0)
	v_mfma_f32_32x32x16_bf16 v[0:15], v[188:191], v[180:183], v[0:15]
	v_mfma_f32_32x32x16_bf16 v[16:31], v[188:191], v[184:187], v[16:31]
	s_setprio 0
	s_waitcnt vmcnt(0)
	s_barrier
	s_setprio 1
	ds_read_b128 v[156:159], v196
	ds_read_b128 v[164:167], v200
	ds_read_b128 v[168:171], v200 offset:4096
	ds_read_b128 v[172:175], v196 offset:4096
	ds_read_b128 v[176:179], v197
	ds_read_b128 v[180:183], v201
	ds_read_b128 v[184:187], v201 offset:4096
	ds_read_b128 v[188:191], v197 offset:4096
	s_add_u32 m0, s76, 0x8680
	s_nop 0
	global_load_lds_dwordx4 v[138:139], off offset:384
	s_add_u32 m0, s76, 0x9680
	s_nop 0
	global_load_lds_dwordx4 v[142:143], off offset:384
	s_add_u32 m0, s76, 0xa680
	s_nop 0
	global_load_lds_dwordx4 v[144:145], off offset:384
	s_add_u32 m0, s76, 0xb680
	s_nop 0
	global_load_lds_dwordx4 v[152:153], off offset:384
	s_add_u32 m0, s76, 0xc680
	s_nop 0
	global_load_lds_dwordx4 v[140:141], off offset:384
	s_add_u32 m0, s76, 0xd680
	s_nop 0
	global_load_lds_dwordx4 v[146:147], off offset:384
	s_add_u32 m0, s76, 0xe680
	s_nop 0
	global_load_lds_dwordx4 v[148:149], off offset:384
	s_add_u32 m0, s76, 0xf680
	s_nop 0
	global_load_lds_dwordx4 v[150:151], off offset:384
	s_waitcnt lgkmcnt(6)
	v_mfma_f32_32x32x16_bf16 v[32:47], v[156:159], v[164:167], v[32:47]
	s_waitcnt lgkmcnt(5)
	v_mfma_f32_32x32x16_bf16 v[48:63], v[156:159], v[168:171], v[48:63]
	s_waitcnt lgkmcnt(4)
	v_mfma_f32_32x32x16_bf16 v[0:15], v[172:175], v[164:167], v[0:15]
	v_mfma_f32_32x32x16_bf16 v[16:31], v[172:175], v[168:171], v[16:31]
	ds_read_b128 v[156:159], v198
	ds_read_b128 v[164:167], v202
	ds_read_b128 v[168:171], v202 offset:4096
	ds_read_b128 v[172:175], v198 offset:4096
	s_waitcnt lgkmcnt(6)
	v_mfma_f32_32x32x16_bf16 v[32:47], v[176:179], v[180:183], v[32:47]
	s_waitcnt lgkmcnt(5)
	v_mfma_f32_32x32x16_bf16 v[48:63], v[176:179], v[184:187], v[48:63]
	s_waitcnt lgkmcnt(4)
	v_mfma_f32_32x32x16_bf16 v[0:15], v[188:191], v[180:183], v[0:15]
	v_mfma_f32_32x32x16_bf16 v[16:31], v[188:191], v[184:187], v[16:31]
	ds_read_b128 v[176:179], v199
	ds_read_b128 v[180:183], v203
	ds_read_b128 v[184:187], v203 offset:4096
	ds_read_b128 v[188:191], v199 offset:4096
	s_waitcnt lgkmcnt(6)
	v_mfma_f32_32x32x16_bf16 v[32:47], v[156:159], v[164:167], v[32:47]
	s_waitcnt lgkmcnt(5)
	v_mfma_f32_32x32x16_bf16 v[48:63], v[156:159], v[168:171], v[48:63]
	s_waitcnt lgkmcnt(4)
	v_mfma_f32_32x32x16_bf16 v[0:15], v[172:175], v[164:167], v[0:15]
	v_mfma_f32_32x32x16_bf16 v[16:31], v[172:175], v[168:171], v[16:31]
	s_waitcnt lgkmcnt(2)
	v_mfma_f32_32x32x16_bf16 v[32:47], v[176:179], v[180:183], v[32:47]
	s_waitcnt lgkmcnt(1)
	v_mfma_f32_32x32x16_bf16 v[48:63], v[176:179], v[184:187], v[48:63]
	s_waitcnt lgkmcnt(0)
	v_mfma_f32_32x32x16_bf16 v[0:15], v[188:191], v[180:183], v[0:15]
	v_mfma_f32_32x32x16_bf16 v[16:31], v[188:191], v[184:187], v[16:31]
	s_setprio 0
	s_waitcnt vmcnt(0)
	s_barrier
;     ...
;     G_LOAD(x, 0);
;     G_STORE(x, 0);
;     __syncthreads();
;     if (KT > 1) G_LOAD(x, 1);
;     for (int kt = 0; kt < KT; kt += 2) {
;       if (kt + 2 < KT && dummy != 2) G_LOAD(y, kt + 2);
;       G_COMPUTE(0);
;       if (kt + 1 < KT && dummy != 2) G_STORE(x, 1);
;       __syncthreads();
;       if (kt + 1 >= KT) break;
;       if (kt + 3 < KT && dummy != 2) G_LOAD(x, kt + 3);
;       G_COMPUTE(1);
;       if (kt + 2 < KT && dummy != 2) G_STORE(y, 0);
;       __syncthreads();
;     }
	s_setprio 1
	ds_read_b128 v[156:159], v196 offset:32768
	ds_read_b128 v[164:167], v200 offset:32768
	ds_read_b128 v[168:171], v200 offset:36864
	ds_read_b128 v[172:175], v196 offset:36864
	ds_read_b128 v[176:179], v197 offset:32768
	ds_read_b128 v[180:183], v201 offset:32768
	ds_read_b128 v[184:187], v201 offset:36864
	ds_read_b128 v[188:191], v197 offset:36864
	s_add_u32 m0, s76, 0x600
	s_nop 0
	global_load_lds_dwordx4 v[138:139], off offset:512
	s_add_u32 m0, s76, 0x1600
	s_nop 0
	global_load_lds_dwordx4 v[142:143], off offset:512
	s_add_u32 m0, s76, 0x2600
	s_nop 0
	global_load_lds_dwordx4 v[144:145], off offset:512
	s_add_u32 m0, s76, 0x3600
	s_nop 0
	global_load_lds_dwordx4 v[152:153], off offset:512
	s_add_u32 m0, s76, 0x4600
	s_nop 0
	global_load_lds_dwordx4 v[140:141], off offset:512
	s_add_u32 m0, s76, 0x5600
	s_nop 0
	global_load_lds_dwordx4 v[146:147], off offset:512
	s_add_u32 m0, s76, 0x6600
	s_nop 0
	global_load_lds_dwordx4 v[148:149], off offset:512
	s_add_u32 m0, s76, 0x7600
	s_nop 0
	global_load_lds_dwordx4 v[150:151], off offset:512
	s_waitcnt lgkmcnt(6)
	v_mfma_f32_32x32x16_bf16 v[32:47], v[156:159], v[164:167], v[32:47]
	s_waitcnt lgkmcnt(5)
	v_mfma_f32_32x32x16_bf16 v[48:63], v[156:159], v[168:171], v[48:63]
	s_waitcnt lgkmcnt(4)
	v_mfma_f32_32x32x16_bf16 v[0:15], v[172:175], v[164:167], v[0:15]
	v_mfma_f32_32x32x16_bf16 v[16:31], v[172:175], v[168:171], v[16:31]
	ds_read_b128 v[156:159], v198 offset:32768
	ds_read_b128 v[164:167], v202 offset:32768
	ds_read_b128 v[168:171], v202 offset:36864
	ds_read_b128 v[172:175], v198 offset:36864
	s_waitcnt lgkmcnt(6)
	v_mfma_f32_32x32x16_bf16 v[32:47], v[176:179], v[180:183], v[32:47]
	s_waitcnt lgkmcnt(5)
	v_mfma_f32_32x32x16_bf16 v[48:63], v[176:179], v[184:187], v[48:63]
	s_waitcnt lgkmcnt(4)
	v_mfma_f32_32x32x16_bf16 v[0:15], v[188:191], v[180:183], v[0:15]
	v_mfma_f32_32x32x16_bf16 v[16:31], v[188:191], v[184:187], v[16:31]
	ds_read_b128 v[176:179], v199 offset:32768
	ds_read_b128 v[180:183], v203 offset:32768
	ds_read_b128 v[184:187], v203 offset:36864
	ds_read_b128 v[188:191], v199 offset:36864
	s_waitcnt lgkmcnt(6)
	v_mfma_f32_32x32x16_bf16 v[32:47], v[156:159], v[164:167], v[32:47]
	s_waitcnt lgkmcnt(5)
	v_mfma_f32_32x32x16_bf16 v[48:63], v[156:159], v[168:171], v[48:63]
	s_waitcnt lgkmcnt(4)
	v_mfma_f32_32x32x16_bf16 v[0:15], v[172:175], v[164:167], v[0:15]
	v_mfma_f32_32x32x16_bf16 v[16:31], v[172:175], v[168:171], v[16:31]
	s_waitcnt lgkmcnt(2)
	v_mfma_f32_32x32x16_bf16 v[32:47], v[176:179], v[180:183], v[32:47]
	s_waitcnt lgkmcnt(1)
	v_mfma_f32_32x32x16_bf16 v[48:63], v[176:179], v[184:187], v[48:63]
	s_waitcnt lgkmcnt(0)
	v_mfma_f32_32x32x16_bf16 v[0:15], v[188:191], v[180:183], v[0:15]
	v_mfma_f32_32x32x16_bf16 v[16:31], v[188:191], v[184:187], v[16:31]
	s_setprio 0
	s_waitcnt vmcnt(0)
	s_barrier
	s_setprio 1
	ds_read_b128 v[156:159], v196
	ds_read_b128 v[164:167], v200
	ds_read_b128 v[168:171], v200 offset:4096
	ds_read_b128 v[172:175], v196 offset:4096
	ds_read_b128 v[176:179], v197
	ds_read_b128 v[180:183], v201
	ds_read_b128 v[184:187], v201 offset:4096
	ds_read_b128 v[188:191], v197 offset:4096
	s_add_u32 m0, s76, 0x8580
	s_nop 0
	global_load_lds_dwordx4 v[138:139], off offset:640
	s_add_u32 m0, s76, 0x9580
	s_nop 0
	global_load_lds_dwordx4 v[142:143], off offset:640
	s_add_u32 m0, s76, 0xa580
	s_nop 0
	global_load_lds_dwordx4 v[144:145], off offset:640
	s_add_u32 m0, s76, 0xb580
	s_nop 0
	global_load_lds_dwordx4 v[152:153], off offset:640
	s_add_u32 m0, s76, 0xc580
	s_nop 0
	global_load_lds_dwordx4 v[140:141], off offset:640
	s_add_u32 m0, s76, 0xd580
	s_nop 0
	global_load_lds_dwordx4 v[146:147], off offset:640
	s_add_u32 m0, s76, 0xe580
	s_nop 0
	global_load_lds_dwordx4 v[148:149], off offset:640
	s_add_u32 m0, s76, 0xf580
	s_nop 0
	global_load_lds_dwordx4 v[150:151], off offset:640
	s_waitcnt lgkmcnt(6)
	v_mfma_f32_32x32x16_bf16 v[32:47], v[156:159], v[164:167], v[32:47]
	s_waitcnt lgkmcnt(5)
	v_mfma_f32_32x32x16_bf16 v[48:63], v[156:159], v[168:171], v[48:63]
	s_waitcnt lgkmcnt(4)
	v_mfma_f32_32x32x16_bf16 v[0:15], v[172:175], v[164:167], v[0:15]
	v_mfma_f32_32x32x16_bf16 v[16:31], v[172:175], v[168:171], v[16:31]
	ds_read_b128 v[156:159], v198
	ds_read_b128 v[164:167], v202
	ds_read_b128 v[168:171], v202 offset:4096
	ds_read_b128 v[172:175], v198 offset:4096
	s_waitcnt lgkmcnt(6)
	v_mfma_f32_32x32x16_bf16 v[32:47], v[176:179], v[180:183], v[32:47]
	s_waitcnt lgkmcnt(5)
	v_mfma_f32_32x32x16_bf16 v[48:63], v[176:179], v[184:187], v[48:63]
	s_waitcnt lgkmcnt(4)
	v_mfma_f32_32x32x16_bf16 v[0:15], v[188:191], v[180:183], v[0:15]
	v_mfma_f32_32x32x16_bf16 v[16:31], v[188:191], v[184:187], v[16:31]
	ds_read_b128 v[176:179], v199
	ds_read_b128 v[180:183], v203
	ds_read_b128 v[184:187], v203 offset:4096
	ds_read_b128 v[188:191], v199 offset:4096
	s_waitcnt lgkmcnt(6)
	v_mfma_f32_32x32x16_bf16 v[32:47], v[156:159], v[164:167], v[32:47]
	s_waitcnt lgkmcnt(5)
	v_mfma_f32_32x32x16_bf16 v[48:63], v[156:159], v[168:171], v[48:63]
	s_waitcnt lgkmcnt(4)
	v_mfma_f32_32x32x16_bf16 v[0:15], v[172:175], v[164:167], v[0:15]
	v_mfma_f32_32x32x16_bf16 v[16:31], v[172:175], v[168:171], v[16:31]
	s_waitcnt lgkmcnt(2)
	v_mfma_f32_32x32x16_bf16 v[32:47], v[176:179], v[180:183], v[32:47]
	s_waitcnt lgkmcnt(1)
	v_mfma_f32_32x32x16_bf16 v[48:63], v[176:179], v[184:187], v[48:63]
	s_waitcnt lgkmcnt(0)
	v_mfma_f32_32x32x16_bf16 v[0:15], v[188:191], v[180:183], v[0:15]
	v_mfma_f32_32x32x16_bf16 v[16:31], v[188:191], v[184:187], v[16:31]
	s_setprio 0
	s_waitcnt vmcnt(0)
	s_barrier
;     ...
;     G_LOAD(x, 0);
;     G_STORE(x, 0);
;     __syncthreads();
;     if (KT > 1) G_LOAD(x, 1);
;     for (int kt = 0; kt < KT; kt += 2) {
;       if (kt + 2 < KT && dummy != 2) G_LOAD(y, kt + 2);
;       G_COMPUTE(0);
;       if (kt + 1 < KT && dummy != 2) G_STORE(x, 1);
;       __syncthreads();
;       if (kt + 1 >= KT) break;
;       if (kt + 3 < KT && dummy != 2) G_LOAD(x, kt + 3);
;       G_COMPUTE(1);
;       if (kt + 2 < KT && dummy != 2) G_STORE(y, 0);
;       __syncthreads();
;     }
	s_setprio 1
	ds_read_b128 v[156:159], v196 offset:32768
	ds_read_b128 v[164:167], v200 offset:32768
	ds_read_b128 v[168:171], v200 offset:36864
	ds_read_b128 v[172:175], v196 offset:36864
	ds_read_b128 v[176:179], v197 offset:32768
	ds_read_b128 v[180:183], v201 offset:32768
	ds_read_b128 v[184:187], v201 offset:36864
	ds_read_b128 v[188:191], v197 offset:36864
	s_add_u32 m0, s76, 0x500
	s_nop 0
	global_load_lds_dwordx4 v[138:139], off offset:768
	s_add_u32 m0, s76, 0x1500
	s_nop 0
	global_load_lds_dwordx4 v[142:143], off offset:768
	s_add_u32 m0, s76, 0x2500
	s_nop 0
	global_load_lds_dwordx4 v[144:145], off offset:768
	s_add_u32 m0, s76, 0x3500
	s_nop 0
	global_load_lds_dwordx4 v[152:153], off offset:768
	s_add_u32 m0, s76, 0x4500
	s_nop 0
	global_load_lds_dwordx4 v[140:141], off offset:768
	s_add_u32 m0, s76, 0x5500
	s_nop 0
	global_load_lds_dwordx4 v[146:147], off offset:768
	s_add_u32 m0, s76, 0x6500
	s_nop 0
	global_load_lds_dwordx4 v[148:149], off offset:768
	s_add_u32 m0, s76, 0x7500
	s_nop 0
	global_load_lds_dwordx4 v[150:151], off offset:768
	s_waitcnt lgkmcnt(6)
	v_mfma_f32_32x32x16_bf16 v[32:47], v[156:159], v[164:167], v[32:47]
	s_waitcnt lgkmcnt(5)
	v_mfma_f32_32x32x16_bf16 v[48:63], v[156:159], v[168:171], v[48:63]
	s_waitcnt lgkmcnt(4)
	v_mfma_f32_32x32x16_bf16 v[0:15], v[172:175], v[164:167], v[0:15]
	v_mfma_f32_32x32x16_bf16 v[16:31], v[172:175], v[168:171], v[16:31]
	ds_read_b128 v[156:159], v198 offset:32768
	ds_read_b128 v[164:167], v202 offset:32768
	ds_read_b128 v[168:171], v202 offset:36864
	ds_read_b128 v[172:175], v198 offset:36864
	s_waitcnt lgkmcnt(6)
	v_mfma_f32_32x32x16_bf16 v[32:47], v[176:179], v[180:183], v[32:47]
	s_waitcnt lgkmcnt(5)
	v_mfma_f32_32x32x16_bf16 v[48:63], v[176:179], v[184:187], v[48:63]
	s_waitcnt lgkmcnt(4)
	v_mfma_f32_32x32x16_bf16 v[0:15], v[188:191], v[180:183], v[0:15]
	v_mfma_f32_32x32x16_bf16 v[16:31], v[188:191], v[184:187], v[16:31]
	ds_read_b128 v[176:179], v199 offset:32768
	ds_read_b128 v[180:183], v203 offset:32768
	ds_read_b128 v[184:187], v203 offset:36864
	ds_read_b128 v[188:191], v199 offset:36864
	s_waitcnt lgkmcnt(6)
	v_mfma_f32_32x32x16_bf16 v[32:47], v[156:159], v[164:167], v[32:47]
	s_waitcnt lgkmcnt(5)
	v_mfma_f32_32x32x16_bf16 v[48:63], v[156:159], v[168:171], v[48:63]
	s_waitcnt lgkmcnt(4)
	v_mfma_f32_32x32x16_bf16 v[0:15], v[172:175], v[164:167], v[0:15]
	v_mfma_f32_32x32x16_bf16 v[16:31], v[172:175], v[168:171], v[16:31]
	s_waitcnt lgkmcnt(2)
	v_mfma_f32_32x32x16_bf16 v[32:47], v[176:179], v[180:183], v[32:47]
	s_waitcnt lgkmcnt(1)
	v_mfma_f32_32x32x16_bf16 v[48:63], v[176:179], v[184:187], v[48:63]
	s_waitcnt lgkmcnt(0)
	v_mfma_f32_32x32x16_bf16 v[0:15], v[188:191], v[180:183], v[0:15]
	v_mfma_f32_32x32x16_bf16 v[16:31], v[188:191], v[184:187], v[16:31]
	s_setprio 0
	s_waitcnt vmcnt(0)
	s_barrier
	s_setprio 1
	ds_read_b128 v[156:159], v196
	ds_read_b128 v[164:167], v200
	ds_read_b128 v[168:171], v200 offset:4096
	ds_read_b128 v[172:175], v196 offset:4096
	ds_read_b128 v[176:179], v197
	ds_read_b128 v[180:183], v201
	ds_read_b128 v[184:187], v201 offset:4096
	ds_read_b128 v[188:191], v197 offset:4096
	s_add_u32 m0, s76, 0x8480
	s_nop 0
	global_load_lds_dwordx4 v[138:139], off offset:896
	s_add_u32 m0, s76, 0x9480
	s_nop 0
	global_load_lds_dwordx4 v[142:143], off offset:896
	s_add_u32 m0, s76, 0xa480
	s_nop 0
	global_load_lds_dwordx4 v[144:145], off offset:896
	s_add_u32 m0, s76, 0xb480
	s_nop 0
	global_load_lds_dwordx4 v[152:153], off offset:896
	s_add_u32 m0, s76, 0xc480
	s_nop 0
	global_load_lds_dwordx4 v[140:141], off offset:896
	s_add_u32 m0, s76, 0xd480
	s_nop 0
	global_load_lds_dwordx4 v[146:147], off offset:896
	s_add_u32 m0, s76, 0xe480
	s_nop 0
	global_load_lds_dwordx4 v[148:149], off offset:896
	s_add_u32 m0, s76, 0xf480
	s_nop 0
	global_load_lds_dwordx4 v[150:151], off offset:896
	s_waitcnt lgkmcnt(6)
	v_mfma_f32_32x32x16_bf16 v[32:47], v[156:159], v[164:167], v[32:47]
	s_waitcnt lgkmcnt(5)
	v_mfma_f32_32x32x16_bf16 v[48:63], v[156:159], v[168:171], v[48:63]
	s_waitcnt lgkmcnt(4)
	v_mfma_f32_32x32x16_bf16 v[0:15], v[172:175], v[164:167], v[0:15]
	v_mfma_f32_32x32x16_bf16 v[16:31], v[172:175], v[168:171], v[16:31]
	ds_read_b128 v[156:159], v198
	ds_read_b128 v[164:167], v202
	ds_read_b128 v[168:171], v202 offset:4096
	ds_read_b128 v[172:175], v198 offset:4096
	s_waitcnt lgkmcnt(6)
	v_mfma_f32_32x32x16_bf16 v[32:47], v[176:179], v[180:183], v[32:47]
	s_waitcnt lgkmcnt(5)
	v_mfma_f32_32x32x16_bf16 v[48:63], v[176:179], v[184:187], v[48:63]
	s_waitcnt lgkmcnt(4)
	v_mfma_f32_32x32x16_bf16 v[0:15], v[188:191], v[180:183], v[0:15]
	v_mfma_f32_32x32x16_bf16 v[16:31], v[188:191], v[184:187], v[16:31]
	ds_read_b128 v[176:179], v199
	ds_read_b128 v[180:183], v203
	ds_read_b128 v[184:187], v203 offset:4096
	ds_read_b128 v[188:191], v199 offset:4096
	s_waitcnt lgkmcnt(6)
	v_mfma_f32_32x32x16_bf16 v[32:47], v[156:159], v[164:167], v[32:47]
	s_waitcnt lgkmcnt(5)
	v_mfma_f32_32x32x16_bf16 v[48:63], v[156:159], v[168:171], v[48:63]
	s_waitcnt lgkmcnt(4)
	v_mfma_f32_32x32x16_bf16 v[0:15], v[172:175], v[164:167], v[0:15]
	v_mfma_f32_32x32x16_bf16 v[16:31], v[172:175], v[168:171], v[16:31]
	s_waitcnt lgkmcnt(2)
	v_mfma_f32_32x32x16_bf16 v[32:47], v[176:179], v[180:183], v[32:47]
	s_waitcnt lgkmcnt(1)
	v_mfma_f32_32x32x16_bf16 v[48:63], v[176:179], v[184:187], v[48:63]
	s_waitcnt lgkmcnt(0)
	v_mfma_f32_32x32x16_bf16 v[0:15], v[188:191], v[180:183], v[0:15]
	v_mfma_f32_32x32x16_bf16 v[16:31], v[188:191], v[184:187], v[16:31]
	s_setprio 0
	s_waitcnt vmcnt(0)
	s_barrier
;     ...
;     G_LOAD(x, 0);
;     G_STORE(x, 0);
;     __syncthreads();
;     if (KT > 1) G_LOAD(x, 1);
;     for (int kt = 0; kt < KT; kt += 2) {
;       if (kt + 2 < KT && dummy != 2) G_LOAD(y, kt + 2);
;       G_COMPUTE(0);
;       if (kt + 1 < KT && dummy != 2) G_STORE(x, 1);
;       __syncthreads();
;       if (kt + 1 >= KT) break;
;       if (kt + 3 < KT && dummy != 2) G_LOAD(x, kt + 3);
;       G_COMPUTE(1);
;       if (kt + 2 < KT && dummy != 2) G_STORE(y, 0);
;       __syncthreads();
;     }
	s_setprio 1
	ds_read_b128 v[156:159], v196 offset:32768
	ds_read_b128 v[164:167], v200 offset:32768
	ds_read_b128 v[168:171], v200 offset:36864
	ds_read_b128 v[172:175], v196 offset:36864
	ds_read_b128 v[176:179], v197 offset:32768
	ds_read_b128 v[180:183], v201 offset:32768
	ds_read_b128 v[184:187], v201 offset:36864
	ds_read_b128 v[188:191], v197 offset:36864
	s_add_u32 m0, s76, 0x400
	s_nop 0
	global_load_lds_dwordx4 v[138:139], off offset:1024
	s_add_u32 m0, s76, 0x1400
	s_nop 0
	global_load_lds_dwordx4 v[142:143], off offset:1024
	s_add_u32 m0, s76, 0x2400
	s_nop 0
	global_load_lds_dwordx4 v[144:145], off offset:1024
	s_add_u32 m0, s76, 0x3400
	s_nop 0
	global_load_lds_dwordx4 v[152:153], off offset:1024
	s_add_u32 m0, s76, 0x4400
	s_nop 0
	global_load_lds_dwordx4 v[140:141], off offset:1024
	s_add_u32 m0, s76, 0x5400
	s_nop 0
	global_load_lds_dwordx4 v[146:147], off offset:1024
	s_add_u32 m0, s76, 0x6400
	s_nop 0
	global_load_lds_dwordx4 v[148:149], off offset:1024
	s_add_u32 m0, s76, 0x7400
	s_nop 0
	global_load_lds_dwordx4 v[150:151], off offset:1024
	s_waitcnt lgkmcnt(6)
	v_mfma_f32_32x32x16_bf16 v[32:47], v[156:159], v[164:167], v[32:47]
	s_waitcnt lgkmcnt(5)
	v_mfma_f32_32x32x16_bf16 v[48:63], v[156:159], v[168:171], v[48:63]
	s_waitcnt lgkmcnt(4)
	v_mfma_f32_32x32x16_bf16 v[0:15], v[172:175], v[164:167], v[0:15]
	v_mfma_f32_32x32x16_bf16 v[16:31], v[172:175], v[168:171], v[16:31]
	ds_read_b128 v[156:159], v198 offset:32768
	ds_read_b128 v[164:167], v202 offset:32768
	ds_read_b128 v[168:171], v202 offset:36864
	ds_read_b128 v[172:175], v198 offset:36864
	s_waitcnt lgkmcnt(6)
	v_mfma_f32_32x32x16_bf16 v[32:47], v[176:179], v[180:183], v[32:47]
	s_waitcnt lgkmcnt(5)
	v_mfma_f32_32x32x16_bf16 v[48:63], v[176:179], v[184:187], v[48:63]
	s_waitcnt lgkmcnt(4)
	v_mfma_f32_32x32x16_bf16 v[0:15], v[188:191], v[180:183], v[0:15]
	v_mfma_f32_32x32x16_bf16 v[16:31], v[188:191], v[184:187], v[16:31]
	ds_read_b128 v[176:179], v199 offset:32768
	ds_read_b128 v[180:183], v203 offset:32768
	ds_read_b128 v[184:187], v203 offset:36864
	ds_read_b128 v[188:191], v199 offset:36864
	s_waitcnt lgkmcnt(6)
	v_mfma_f32_32x32x16_bf16 v[32:47], v[156:159], v[164:167], v[32:47]
	s_waitcnt lgkmcnt(5)
	v_mfma_f32_32x32x16_bf16 v[48:63], v[156:159], v[168:171], v[48:63]
	s_waitcnt lgkmcnt(4)
	v_mfma_f32_32x32x16_bf16 v[0:15], v[172:175], v[164:167], v[0:15]
	v_mfma_f32_32x32x16_bf16 v[16:31], v[172:175], v[168:171], v[16:31]
	s_waitcnt lgkmcnt(2)
	v_mfma_f32_32x32x16_bf16 v[32:47], v[176:179], v[180:183], v[32:47]
	s_waitcnt lgkmcnt(1)
	v_mfma_f32_32x32x16_bf16 v[48:63], v[176:179], v[184:187], v[48:63]
	s_waitcnt lgkmcnt(0)
	v_mfma_f32_32x32x16_bf16 v[0:15], v[188:191], v[180:183], v[0:15]
	v_mfma_f32_32x32x16_bf16 v[16:31], v[188:191], v[184:187], v[16:31]
	s_setprio 0
	s_waitcnt vmcnt(0)
	s_barrier
	s_setprio 1
	ds_read_b128 v[156:159], v196
	ds_read_b128 v[164:167], v200
	ds_read_b128 v[168:171], v200 offset:4096
	ds_read_b128 v[172:175], v196 offset:4096
	ds_read_b128 v[176:179], v197
	ds_read_b128 v[180:183], v201
	ds_read_b128 v[184:187], v201 offset:4096
	ds_read_b128 v[188:191], v197 offset:4096
	s_add_u32 m0, s76, 0x8380
	s_nop 0
	global_load_lds_dwordx4 v[138:139], off offset:1152
	s_add_u32 m0, s76, 0x9380
	s_nop 0
	global_load_lds_dwordx4 v[142:143], off offset:1152
	s_add_u32 m0, s76, 0xa380
	s_nop 0
	global_load_lds_dwordx4 v[144:145], off offset:1152
	s_add_u32 m0, s76, 0xb380
	s_nop 0
	global_load_lds_dwordx4 v[152:153], off offset:1152
	s_add_u32 m0, s76, 0xc380
	s_nop 0
	global_load_lds_dwordx4 v[140:141], off offset:1152
	s_add_u32 m0, s76, 0xd380
	s_nop 0
	global_load_lds_dwordx4 v[146:147], off offset:1152
	s_add_u32 m0, s76, 0xe380
	s_nop 0
	global_load_lds_dwordx4 v[148:149], off offset:1152
	s_add_u32 m0, s76, 0xf380
	s_nop 0
	global_load_lds_dwordx4 v[150:151], off offset:1152
	s_waitcnt lgkmcnt(6)
	v_mfma_f32_32x32x16_bf16 v[32:47], v[156:159], v[164:167], v[32:47]
	s_waitcnt lgkmcnt(5)
	v_mfma_f32_32x32x16_bf16 v[48:63], v[156:159], v[168:171], v[48:63]
	s_waitcnt lgkmcnt(4)
	v_mfma_f32_32x32x16_bf16 v[0:15], v[172:175], v[164:167], v[0:15]
	v_mfma_f32_32x32x16_bf16 v[16:31], v[172:175], v[168:171], v[16:31]
	ds_read_b128 v[156:159], v198
	ds_read_b128 v[164:167], v202
	ds_read_b128 v[168:171], v202 offset:4096
	ds_read_b128 v[172:175], v198 offset:4096
	s_waitcnt lgkmcnt(6)
	v_mfma_f32_32x32x16_bf16 v[32:47], v[176:179], v[180:183], v[32:47]
	s_waitcnt lgkmcnt(5)
	v_mfma_f32_32x32x16_bf16 v[48:63], v[176:179], v[184:187], v[48:63]
	s_waitcnt lgkmcnt(4)
	v_mfma_f32_32x32x16_bf16 v[0:15], v[188:191], v[180:183], v[0:15]
	v_mfma_f32_32x32x16_bf16 v[16:31], v[188:191], v[184:187], v[16:31]
	ds_read_b128 v[176:179], v199
	ds_read_b128 v[180:183], v203
	ds_read_b128 v[184:187], v203 offset:4096
	ds_read_b128 v[188:191], v199 offset:4096
	s_waitcnt lgkmcnt(6)
	v_mfma_f32_32x32x16_bf16 v[32:47], v[156:159], v[164:167], v[32:47]
	s_waitcnt lgkmcnt(5)
	v_mfma_f32_32x32x16_bf16 v[48:63], v[156:159], v[168:171], v[48:63]
	s_waitcnt lgkmcnt(4)
	v_mfma_f32_32x32x16_bf16 v[0:15], v[172:175], v[164:167], v[0:15]
	v_mfma_f32_32x32x16_bf16 v[16:31], v[172:175], v[168:171], v[16:31]
	s_waitcnt lgkmcnt(2)
	v_mfma_f32_32x32x16_bf16 v[32:47], v[176:179], v[180:183], v[32:47]
	s_waitcnt lgkmcnt(1)
	v_mfma_f32_32x32x16_bf16 v[48:63], v[176:179], v[184:187], v[48:63]
	s_waitcnt lgkmcnt(0)
	v_mfma_f32_32x32x16_bf16 v[0:15], v[188:191], v[180:183], v[0:15]
	v_mfma_f32_32x32x16_bf16 v[16:31], v[188:191], v[184:187], v[16:31]
	s_setprio 0
	s_waitcnt vmcnt(0)
	s_barrier
;     ...
;     G_LOAD(x, 0);
;     G_STORE(x, 0);
;     __syncthreads();
;     if (KT > 1) G_LOAD(x, 1);
;     for (int kt = 0; kt < KT; kt += 2) {
;       if (kt + 2 < KT && dummy != 2) G_LOAD(y, kt + 2);
;       G_COMPUTE(0);
;       if (kt + 1 < KT && dummy != 2) G_STORE(x, 1);
;       __syncthreads();
;       if (kt + 1 >= KT) break;
;       if (kt + 3 < KT && dummy != 2) G_LOAD(x, kt + 3);
;       G_COMPUTE(1);
;       if (kt + 2 < KT && dummy != 2) G_STORE(y, 0);
;       __syncthreads();
;     }
	s_setprio 1
	ds_read_b128 v[156:159], v196 offset:32768
	ds_read_b128 v[164:167], v200 offset:32768
	ds_read_b128 v[168:171], v200 offset:36864
	ds_read_b128 v[172:175], v196 offset:36864
	ds_read_b128 v[176:179], v197 offset:32768
	ds_read_b128 v[180:183], v201 offset:32768
	ds_read_b128 v[184:187], v201 offset:36864
	ds_read_b128 v[188:191], v197 offset:36864
	s_add_u32 m0, s76, 0x300
	s_nop 0
	global_load_lds_dwordx4 v[138:139], off offset:1280
	s_add_u32 m0, s76, 0x1300
	s_nop 0
	global_load_lds_dwordx4 v[142:143], off offset:1280
	s_add_u32 m0, s76, 0x2300
	s_nop 0
	global_load_lds_dwordx4 v[144:145], off offset:1280
	s_add_u32 m0, s76, 0x3300
	s_nop 0
	global_load_lds_dwordx4 v[152:153], off offset:1280
	s_add_u32 m0, s76, 0x4300
	s_nop 0
	global_load_lds_dwordx4 v[140:141], off offset:1280
	s_add_u32 m0, s76, 0x5300
	s_nop 0
	global_load_lds_dwordx4 v[146:147], off offset:1280
	s_add_u32 m0, s76, 0x6300
	s_nop 0
	global_load_lds_dwordx4 v[148:149], off offset:1280
	s_add_u32 m0, s76, 0x7300
	s_nop 0
	global_load_lds_dwordx4 v[150:151], off offset:1280
	s_waitcnt lgkmcnt(6)
	v_mfma_f32_32x32x16_bf16 v[32:47], v[156:159], v[164:167], v[32:47]
	s_waitcnt lgkmcnt(5)
	v_mfma_f32_32x32x16_bf16 v[48:63], v[156:159], v[168:171], v[48:63]
	s_waitcnt lgkmcnt(4)
	v_mfma_f32_32x32x16_bf16 v[0:15], v[172:175], v[164:167], v[0:15]
	v_mfma_f32_32x32x16_bf16 v[16:31], v[172:175], v[168:171], v[16:31]
	ds_read_b128 v[156:159], v198 offset:32768
	ds_read_b128 v[164:167], v202 offset:32768
	ds_read_b128 v[168:171], v202 offset:36864
	ds_read_b128 v[172:175], v198 offset:36864
	s_waitcnt lgkmcnt(6)
	v_mfma_f32_32x32x16_bf16 v[32:47], v[176:179], v[180:183], v[32:47]
	s_waitcnt lgkmcnt(5)
	v_mfma_f32_32x32x16_bf16 v[48:63], v[176:179], v[184:187], v[48:63]
	s_waitcnt lgkmcnt(4)
	v_mfma_f32_32x32x16_bf16 v[0:15], v[188:191], v[180:183], v[0:15]
	v_mfma_f32_32x32x16_bf16 v[16:31], v[188:191], v[184:187], v[16:31]
	ds_read_b128 v[176:179], v199 offset:32768
	ds_read_b128 v[180:183], v203 offset:32768
	ds_read_b128 v[184:187], v203 offset:36864
	ds_read_b128 v[188:191], v199 offset:36864
	s_waitcnt lgkmcnt(6)
	v_mfma_f32_32x32x16_bf16 v[32:47], v[156:159], v[164:167], v[32:47]
	s_waitcnt lgkmcnt(5)
	v_mfma_f32_32x32x16_bf16 v[48:63], v[156:159], v[168:171], v[48:63]
	s_waitcnt lgkmcnt(4)
	v_mfma_f32_32x32x16_bf16 v[0:15], v[172:175], v[164:167], v[0:15]
	v_mfma_f32_32x32x16_bf16 v[16:31], v[172:175], v[168:171], v[16:31]
	s_waitcnt lgkmcnt(2)
	v_mfma_f32_32x32x16_bf16 v[32:47], v[176:179], v[180:183], v[32:47]
	s_waitcnt lgkmcnt(1)
	v_mfma_f32_32x32x16_bf16 v[48:63], v[176:179], v[184:187], v[48:63]
	s_waitcnt lgkmcnt(0)
	v_mfma_f32_32x32x16_bf16 v[0:15], v[188:191], v[180:183], v[0:15]
	v_mfma_f32_32x32x16_bf16 v[16:31], v[188:191], v[184:187], v[16:31]
	s_setprio 0
	s_waitcnt vmcnt(0)
	s_barrier
	s_setprio 1
	ds_read_b128 v[156:159], v196
	ds_read_b128 v[164:167], v200
	ds_read_b128 v[168:171], v200 offset:4096
	ds_read_b128 v[172:175], v196 offset:4096
	ds_read_b128 v[176:179], v197
	ds_read_b128 v[180:183], v201
	ds_read_b128 v[184:187], v201 offset:4096
	ds_read_b128 v[188:191], v197 offset:4096
	s_add_u32 m0, s76, 0x8280
	s_nop 0
	global_load_lds_dwordx4 v[138:139], off offset:1408
	s_add_u32 m0, s76, 0x9280
	s_nop 0
	global_load_lds_dwordx4 v[142:143], off offset:1408
	s_add_u32 m0, s76, 0xa280
	s_nop 0
	global_load_lds_dwordx4 v[144:145], off offset:1408
	s_add_u32 m0, s76, 0xb280
	s_nop 0
	global_load_lds_dwordx4 v[152:153], off offset:1408
	s_add_u32 m0, s76, 0xc280
	s_nop 0
	global_load_lds_dwordx4 v[140:141], off offset:1408
	s_add_u32 m0, s76, 0xd280
	s_nop 0
	global_load_lds_dwordx4 v[146:147], off offset:1408
	s_add_u32 m0, s76, 0xe280
	s_nop 0
	global_load_lds_dwordx4 v[148:149], off offset:1408
	s_add_u32 m0, s76, 0xf280
	s_nop 0
	global_load_lds_dwordx4 v[150:151], off offset:1408
	s_waitcnt lgkmcnt(6)
	v_mfma_f32_32x32x16_bf16 v[32:47], v[156:159], v[164:167], v[32:47]
	s_waitcnt lgkmcnt(5)
	v_mfma_f32_32x32x16_bf16 v[48:63], v[156:159], v[168:171], v[48:63]
	s_waitcnt lgkmcnt(4)
	v_mfma_f32_32x32x16_bf16 v[0:15], v[172:175], v[164:167], v[0:15]
	v_mfma_f32_32x32x16_bf16 v[16:31], v[172:175], v[168:171], v[16:31]
	ds_read_b128 v[156:159], v198
	ds_read_b128 v[164:167], v202
	ds_read_b128 v[168:171], v202 offset:4096
	ds_read_b128 v[172:175], v198 offset:4096
	s_waitcnt lgkmcnt(6)
	v_mfma_f32_32x32x16_bf16 v[32:47], v[176:179], v[180:183], v[32:47]
	s_waitcnt lgkmcnt(5)
	v_mfma_f32_32x32x16_bf16 v[48:63], v[176:179], v[184:187], v[48:63]
	s_waitcnt lgkmcnt(4)
	v_mfma_f32_32x32x16_bf16 v[0:15], v[188:191], v[180:183], v[0:15]
	v_mfma_f32_32x32x16_bf16 v[16:31], v[188:191], v[184:187], v[16:31]
	ds_read_b128 v[176:179], v199
	ds_read_b128 v[180:183], v203
	ds_read_b128 v[184:187], v203 offset:4096
	ds_read_b128 v[188:191], v199 offset:4096
	s_waitcnt lgkmcnt(6)
	v_mfma_f32_32x32x16_bf16 v[32:47], v[156:159], v[164:167], v[32:47]
	s_waitcnt lgkmcnt(5)
	v_mfma_f32_32x32x16_bf16 v[48:63], v[156:159], v[168:171], v[48:63]
	s_waitcnt lgkmcnt(4)
	v_mfma_f32_32x32x16_bf16 v[0:15], v[172:175], v[164:167], v[0:15]
	v_mfma_f32_32x32x16_bf16 v[16:31], v[172:175], v[168:171], v[16:31]
	s_waitcnt lgkmcnt(2)
	v_mfma_f32_32x32x16_bf16 v[32:47], v[176:179], v[180:183], v[32:47]
	s_waitcnt lgkmcnt(1)
	v_mfma_f32_32x32x16_bf16 v[48:63], v[176:179], v[184:187], v[48:63]
	s_waitcnt lgkmcnt(0)
	v_mfma_f32_32x32x16_bf16 v[0:15], v[188:191], v[180:183], v[0:15]
	v_mfma_f32_32x32x16_bf16 v[16:31], v[188:191], v[184:187], v[16:31]
	s_setprio 0
	s_waitcnt vmcnt(0)
	s_barrier
;     ...
;     G_LOAD(x, 0);
;     G_STORE(x, 0);
;     __syncthreads();
;     if (KT > 1) G_LOAD(x, 1);
;     for (int kt = 0; kt < KT; kt += 2) {
;       if (kt + 2 < KT && dummy != 2) G_LOAD(y, kt + 2);
;       G_COMPUTE(0);
;       if (kt + 1 < KT && dummy != 2) G_STORE(x, 1);
;       __syncthreads();
;       if (kt + 1 >= KT) break;
;       if (kt + 3 < KT && dummy != 2) G_LOAD(x, kt + 3);
;       G_COMPUTE(1);
;       if (kt + 2 < KT && dummy != 2) G_STORE(y, 0);
;       __syncthreads();
;     }
	s_setprio 1
	ds_read_b128 v[156:159], v196 offset:32768
	ds_read_b128 v[164:167], v200 offset:32768
	ds_read_b128 v[168:171], v200 offset:36864
	ds_read_b128 v[172:175], v196 offset:36864
	ds_read_b128 v[176:179], v197 offset:32768
	ds_read_b128 v[180:183], v201 offset:32768
	ds_read_b128 v[184:187], v201 offset:36864
	ds_read_b128 v[188:191], v197 offset:36864
	s_add_u32 m0, s76, 0x200
	s_nop 0
	global_load_lds_dwordx4 v[138:139], off offset:1536
	s_add_u32 m0, s76, 0x1200
	s_nop 0
	global_load_lds_dwordx4 v[142:143], off offset:1536
	s_add_u32 m0, s76, 0x2200
	s_nop 0
	global_load_lds_dwordx4 v[144:145], off offset:1536
	s_add_u32 m0, s76, 0x3200
	s_nop 0
	global_load_lds_dwordx4 v[152:153], off offset:1536
	s_add_u32 m0, s76, 0x4200
	s_nop 0
	global_load_lds_dwordx4 v[140:141], off offset:1536
	s_add_u32 m0, s76, 0x5200
	s_nop 0
	global_load_lds_dwordx4 v[146:147], off offset:1536
	s_add_u32 m0, s76, 0x6200
	s_nop 0
	global_load_lds_dwordx4 v[148:149], off offset:1536
	s_add_u32 m0, s76, 0x7200
	s_nop 0
	global_load_lds_dwordx4 v[150:151], off offset:1536
	s_waitcnt lgkmcnt(6)
	v_mfma_f32_32x32x16_bf16 v[32:47], v[156:159], v[164:167], v[32:47]
	s_waitcnt lgkmcnt(5)
	v_mfma_f32_32x32x16_bf16 v[48:63], v[156:159], v[168:171], v[48:63]
	s_waitcnt lgkmcnt(4)
	v_mfma_f32_32x32x16_bf16 v[0:15], v[172:175], v[164:167], v[0:15]
	v_mfma_f32_32x32x16_bf16 v[16:31], v[172:175], v[168:171], v[16:31]
	ds_read_b128 v[156:159], v198 offset:32768
	ds_read_b128 v[164:167], v202 offset:32768
	ds_read_b128 v[168:171], v202 offset:36864
	ds_read_b128 v[172:175], v198 offset:36864
	s_waitcnt lgkmcnt(6)
	v_mfma_f32_32x32x16_bf16 v[32:47], v[176:179], v[180:183], v[32:47]
	s_waitcnt lgkmcnt(5)
	v_mfma_f32_32x32x16_bf16 v[48:63], v[176:179], v[184:187], v[48:63]
	s_waitcnt lgkmcnt(4)
	v_mfma_f32_32x32x16_bf16 v[0:15], v[188:191], v[180:183], v[0:15]
	v_mfma_f32_32x32x16_bf16 v[16:31], v[188:191], v[184:187], v[16:31]
	ds_read_b128 v[176:179], v199 offset:32768
	ds_read_b128 v[180:183], v203 offset:32768
	ds_read_b128 v[184:187], v203 offset:36864
	ds_read_b128 v[188:191], v199 offset:36864
	s_waitcnt lgkmcnt(6)
	v_mfma_f32_32x32x16_bf16 v[32:47], v[156:159], v[164:167], v[32:47]
	s_waitcnt lgkmcnt(5)
	v_mfma_f32_32x32x16_bf16 v[48:63], v[156:159], v[168:171], v[48:63]
	s_waitcnt lgkmcnt(4)
	v_mfma_f32_32x32x16_bf16 v[0:15], v[172:175], v[164:167], v[0:15]
	v_mfma_f32_32x32x16_bf16 v[16:31], v[172:175], v[168:171], v[16:31]
	s_waitcnt lgkmcnt(2)
	v_mfma_f32_32x32x16_bf16 v[32:47], v[176:179], v[180:183], v[32:47]
	s_waitcnt lgkmcnt(1)
	v_mfma_f32_32x32x16_bf16 v[48:63], v[176:179], v[184:187], v[48:63]
	s_waitcnt lgkmcnt(0)
	v_mfma_f32_32x32x16_bf16 v[0:15], v[188:191], v[180:183], v[0:15]
	v_mfma_f32_32x32x16_bf16 v[16:31], v[188:191], v[184:187], v[16:31]
	s_setprio 0
	s_waitcnt vmcnt(0)
	s_barrier
	s_setprio 1
	ds_read_b128 v[156:159], v196
	ds_read_b128 v[164:167], v200
	ds_read_b128 v[168:171], v200 offset:4096
	ds_read_b128 v[172:175], v196 offset:4096
	ds_read_b128 v[176:179], v197
	ds_read_b128 v[180:183], v201
	ds_read_b128 v[184:187], v201 offset:4096
	ds_read_b128 v[188:191], v197 offset:4096
	s_add_u32 m0, s76, 0x8180
	s_nop 0
	global_load_lds_dwordx4 v[138:139], off offset:1664
	s_add_u32 m0, s76, 0x9180
	s_nop 0
	global_load_lds_dwordx4 v[142:143], off offset:1664
	s_add_u32 m0, s76, 0xa180
	s_nop 0
	global_load_lds_dwordx4 v[144:145], off offset:1664
	s_add_u32 m0, s76, 0xb180
	s_nop 0
	global_load_lds_dwordx4 v[152:153], off offset:1664
	s_add_u32 m0, s76, 0xc180
	s_nop 0
	global_load_lds_dwordx4 v[140:141], off offset:1664
	s_add_u32 m0, s76, 0xd180
	s_nop 0
	global_load_lds_dwordx4 v[146:147], off offset:1664
	s_add_u32 m0, s76, 0xe180
	s_nop 0
	global_load_lds_dwordx4 v[148:149], off offset:1664
	s_add_u32 m0, s76, 0xf180
	s_nop 0
	global_load_lds_dwordx4 v[150:151], off offset:1664
	s_waitcnt lgkmcnt(6)
	v_mfma_f32_32x32x16_bf16 v[32:47], v[156:159], v[164:167], v[32:47]
	s_waitcnt lgkmcnt(5)
	v_mfma_f32_32x32x16_bf16 v[48:63], v[156:159], v[168:171], v[48:63]
	s_waitcnt lgkmcnt(4)
	v_mfma_f32_32x32x16_bf16 v[0:15], v[172:175], v[164:167], v[0:15]
	v_mfma_f32_32x32x16_bf16 v[16:31], v[172:175], v[168:171], v[16:31]
	ds_read_b128 v[156:159], v198
	ds_read_b128 v[164:167], v202
	ds_read_b128 v[168:171], v202 offset:4096
	ds_read_b128 v[172:175], v198 offset:4096
	s_waitcnt lgkmcnt(6)
	v_mfma_f32_32x32x16_bf16 v[32:47], v[176:179], v[180:183], v[32:47]
	s_waitcnt lgkmcnt(5)
	v_mfma_f32_32x32x16_bf16 v[48:63], v[176:179], v[184:187], v[48:63]
	s_waitcnt lgkmcnt(4)
	v_mfma_f32_32x32x16_bf16 v[0:15], v[188:191], v[180:183], v[0:15]
	v_mfma_f32_32x32x16_bf16 v[16:31], v[188:191], v[184:187], v[16:31]
	ds_read_b128 v[176:179], v199
	ds_read_b128 v[180:183], v203
	ds_read_b128 v[184:187], v203 offset:4096
	ds_read_b128 v[188:191], v199 offset:4096
	s_waitcnt lgkmcnt(6)
	v_mfma_f32_32x32x16_bf16 v[32:47], v[156:159], v[164:167], v[32:47]
	s_waitcnt lgkmcnt(5)
	v_mfma_f32_32x32x16_bf16 v[48:63], v[156:159], v[168:171], v[48:63]
	s_waitcnt lgkmcnt(4)
	v_mfma_f32_32x32x16_bf16 v[0:15], v[172:175], v[164:167], v[0:15]
	v_mfma_f32_32x32x16_bf16 v[16:31], v[172:175], v[168:171], v[16:31]
	s_waitcnt lgkmcnt(2)
	v_mfma_f32_32x32x16_bf16 v[32:47], v[176:179], v[180:183], v[32:47]
	s_waitcnt lgkmcnt(1)
	v_mfma_f32_32x32x16_bf16 v[48:63], v[176:179], v[184:187], v[48:63]
	s_waitcnt lgkmcnt(0)
	v_mfma_f32_32x32x16_bf16 v[0:15], v[188:191], v[180:183], v[0:15]
	v_mfma_f32_32x32x16_bf16 v[16:31], v[188:191], v[184:187], v[16:31]
	s_setprio 0
	s_waitcnt vmcnt(0)
	s_barrier
;     ...
;     G_LOAD(x, 0);
;     G_STORE(x, 0);
;     __syncthreads();
;     if (KT > 1) G_LOAD(x, 1);
;     for (int kt = 0; kt < KT; kt += 2) {
;       if (kt + 2 < KT && dummy != 2) G_LOAD(y, kt + 2);
;       G_COMPUTE(0);
;       if (kt + 1 < KT && dummy != 2) G_STORE(x, 1);
;       __syncthreads();
;       if (kt + 1 >= KT) break;
;       if (kt + 3 < KT && dummy != 2) G_LOAD(x, kt + 3);
;       G_COMPUTE(1);
;       if (kt + 2 < KT && dummy != 2) G_STORE(y, 0);
;       __syncthreads();
;     }
	s_setprio 1
	ds_read_b128 v[156:159], v196 offset:32768
	ds_read_b128 v[164:167], v200 offset:32768
	ds_read_b128 v[168:171], v200 offset:36864
	ds_read_b128 v[172:175], v196 offset:36864
	ds_read_b128 v[176:179], v197 offset:32768
	ds_read_b128 v[180:183], v201 offset:32768
	ds_read_b128 v[184:187], v201 offset:36864
	ds_read_b128 v[188:191], v197 offset:36864
	s_add_u32 m0, s76, 0x100
	s_nop 0
	global_load_lds_dwordx4 v[138:139], off offset:1792
	s_add_u32 m0, s76, 0x1100
	s_nop 0
	global_load_lds_dwordx4 v[142:143], off offset:1792
	s_add_u32 m0, s76, 0x2100
	s_nop 0
	global_load_lds_dwordx4 v[144:145], off offset:1792
	s_add_u32 m0, s76, 0x3100
	s_nop 0
	global_load_lds_dwordx4 v[152:153], off offset:1792
	s_add_u32 m0, s76, 0x4100
	s_nop 0
	global_load_lds_dwordx4 v[140:141], off offset:1792
	s_add_u32 m0, s76, 0x5100
	s_nop 0
	global_load_lds_dwordx4 v[146:147], off offset:1792
	s_add_u32 m0, s76, 0x6100
	s_nop 0
	global_load_lds_dwordx4 v[148:149], off offset:1792
	s_add_u32 m0, s76, 0x7100
	s_nop 0
	global_load_lds_dwordx4 v[150:151], off offset:1792
	s_waitcnt lgkmcnt(6)
	v_mfma_f32_32x32x16_bf16 v[32:47], v[156:159], v[164:167], v[32:47]
	s_waitcnt lgkmcnt(5)
	v_mfma_f32_32x32x16_bf16 v[48:63], v[156:159], v[168:171], v[48:63]
	s_waitcnt lgkmcnt(4)
	v_mfma_f32_32x32x16_bf16 v[0:15], v[172:175], v[164:167], v[0:15]
	v_mfma_f32_32x32x16_bf16 v[16:31], v[172:175], v[168:171], v[16:31]
	ds_read_b128 v[156:159], v198 offset:32768
	ds_read_b128 v[164:167], v202 offset:32768
	ds_read_b128 v[168:171], v202 offset:36864
	ds_read_b128 v[172:175], v198 offset:36864
	s_waitcnt lgkmcnt(6)
	v_mfma_f32_32x32x16_bf16 v[32:47], v[176:179], v[180:183], v[32:47]
	s_waitcnt lgkmcnt(5)
	v_mfma_f32_32x32x16_bf16 v[48:63], v[176:179], v[184:187], v[48:63]
	s_waitcnt lgkmcnt(4)
	v_mfma_f32_32x32x16_bf16 v[0:15], v[188:191], v[180:183], v[0:15]
	v_mfma_f32_32x32x16_bf16 v[16:31], v[188:191], v[184:187], v[16:31]
	ds_read_b128 v[176:179], v199 offset:32768
	ds_read_b128 v[180:183], v203 offset:32768
	ds_read_b128 v[184:187], v203 offset:36864
	ds_read_b128 v[188:191], v199 offset:36864
	s_waitcnt lgkmcnt(6)
	v_mfma_f32_32x32x16_bf16 v[32:47], v[156:159], v[164:167], v[32:47]
	s_waitcnt lgkmcnt(5)
	v_mfma_f32_32x32x16_bf16 v[48:63], v[156:159], v[168:171], v[48:63]
	s_waitcnt lgkmcnt(4)
	v_mfma_f32_32x32x16_bf16 v[0:15], v[172:175], v[164:167], v[0:15]
	v_mfma_f32_32x32x16_bf16 v[16:31], v[172:175], v[168:171], v[16:31]
	s_waitcnt lgkmcnt(2)
	v_mfma_f32_32x32x16_bf16 v[32:47], v[176:179], v[180:183], v[32:47]
	s_waitcnt lgkmcnt(1)
	v_mfma_f32_32x32x16_bf16 v[48:63], v[176:179], v[184:187], v[48:63]
	s_waitcnt lgkmcnt(0)
	v_mfma_f32_32x32x16_bf16 v[0:15], v[188:191], v[180:183], v[0:15]
	v_mfma_f32_32x32x16_bf16 v[16:31], v[188:191], v[184:187], v[16:31]
	s_setprio 0
	s_waitcnt vmcnt(0)
	s_barrier
	s_setprio 1
	ds_read_b128 v[156:159], v196
	ds_read_b128 v[164:167], v200
	ds_read_b128 v[168:171], v200 offset:4096
	ds_read_b128 v[172:175], v196 offset:4096
	ds_read_b128 v[176:179], v197
	ds_read_b128 v[180:183], v201
	ds_read_b128 v[184:187], v201 offset:4096
	ds_read_b128 v[188:191], v197 offset:4096
	s_add_u32 m0, s76, 0x8080
	s_nop 0
	global_load_lds_dwordx4 v[138:139], off offset:1920
	s_add_u32 m0, s76, 0x9080
	s_nop 0
	global_load_lds_dwordx4 v[142:143], off offset:1920
	s_add_u32 m0, s76, 0xa080
	s_nop 0
	global_load_lds_dwordx4 v[144:145], off offset:1920
	s_add_u32 m0, s76, 0xb080
	s_nop 0
	global_load_lds_dwordx4 v[152:153], off offset:1920
	s_add_u32 m0, s76, 0xc080
	s_nop 0
	global_load_lds_dwordx4 v[140:141], off offset:1920
	s_add_u32 m0, s76, 0xd080
	s_nop 0
	global_load_lds_dwordx4 v[146:147], off offset:1920
	s_add_u32 m0, s76, 0xe080
	s_nop 0
	global_load_lds_dwordx4 v[148:149], off offset:1920
	s_add_u32 m0, s76, 0xf080
	s_nop 0
	global_load_lds_dwordx4 v[150:151], off offset:1920
	s_waitcnt lgkmcnt(6)
	v_mfma_f32_32x32x16_bf16 v[32:47], v[156:159], v[164:167], v[32:47]
	s_waitcnt lgkmcnt(5)
	v_mfma_f32_32x32x16_bf16 v[48:63], v[156:159], v[168:171], v[48:63]
	s_waitcnt lgkmcnt(4)
	v_mfma_f32_32x32x16_bf16 v[0:15], v[172:175], v[164:167], v[0:15]
	v_mfma_f32_32x32x16_bf16 v[16:31], v[172:175], v[168:171], v[16:31]
	ds_read_b128 v[156:159], v198
	ds_read_b128 v[164:167], v202
	ds_read_b128 v[168:171], v202 offset:4096
	ds_read_b128 v[172:175], v198 offset:4096
	s_waitcnt lgkmcnt(6)
	v_mfma_f32_32x32x16_bf16 v[32:47], v[176:179], v[180:183], v[32:47]
	s_waitcnt lgkmcnt(5)
	v_mfma_f32_32x32x16_bf16 v[48:63], v[176:179], v[184:187], v[48:63]
	s_waitcnt lgkmcnt(4)
	v_mfma_f32_32x32x16_bf16 v[0:15], v[188:191], v[180:183], v[0:15]
	v_mfma_f32_32x32x16_bf16 v[16:31], v[188:191], v[184:187], v[16:31]
	ds_read_b128 v[176:179], v199
	ds_read_b128 v[180:183], v203
	ds_read_b128 v[184:187], v203 offset:4096
	ds_read_b128 v[188:191], v199 offset:4096
	s_waitcnt lgkmcnt(6)
	v_mfma_f32_32x32x16_bf16 v[32:47], v[156:159], v[164:167], v[32:47]
	s_waitcnt lgkmcnt(5)
	v_mfma_f32_32x32x16_bf16 v[48:63], v[156:159], v[168:171], v[48:63]
	s_waitcnt lgkmcnt(4)
	v_mfma_f32_32x32x16_bf16 v[0:15], v[172:175], v[164:167], v[0:15]
	v_mfma_f32_32x32x16_bf16 v[16:31], v[172:175], v[168:171], v[16:31]
	s_waitcnt lgkmcnt(2)
	v_mfma_f32_32x32x16_bf16 v[32:47], v[176:179], v[180:183], v[32:47]
	s_waitcnt lgkmcnt(1)
	v_mfma_f32_32x32x16_bf16 v[48:63], v[176:179], v[184:187], v[48:63]
	s_waitcnt lgkmcnt(0)
	v_mfma_f32_32x32x16_bf16 v[0:15], v[188:191], v[180:183], v[0:15]
	v_mfma_f32_32x32x16_bf16 v[16:31], v[188:191], v[184:187], v[16:31]
	s_setprio 0
	s_waitcnt vmcnt(0)
	s_barrier
; DI unsigned pack2(float a, float b) { f32v2 v = {a, b}; bf16v2 r = __builtin_convertvector(v, bf16v2); return __builtin_bit_cast(unsigned, r); }
;     ...
;       const int hb = (n0e >> 7) * 64 + (cb >> 6) * 32 + (cb & 31);
;       const bool odd = (cb & 1) != 0;
; #pragma unroll
;       for (int mi = 0; mi < 2; ++mi)
; #pragma unroll
;         for (int i = 0; i < 16; i += 2) {
;           const float u0 = acc[mi][0][i], g0 = acc[mi][1][i], u1 = acc[mi][0][i + 1], g1 = acc[mi][1][i + 1];
;           const float a = u0 * __builtin_amdgcn_rcpf(1.f + __expf(-u0)) * g0, b2 = u1 * __builtin_amdgcn_rcpf(1.f + __expf(-u1)) * g1;
;           const float recv = dpp_f(odd ? a : b2, 0);
;           const int row = m0e + rb + mi * 32 + (i & 3) + 8 * (i >> 2) + (odd ? 1 : 0);
;           const unsigned w = odd ? pack2(recv, b2) : pack2(a, recv);
;           __builtin_nontemporal_store(w, (unsigned*)(P.pbuf + (size_t)row * DFF + (hb & ~1)));
;         }
	s_setprio 1
	ds_read_b128 v[156:159], v196 offset:32768
	ds_read_b128 v[164:167], v200 offset:32768
	ds_read_b128 v[168:171], v200 offset:36864
	ds_read_b128 v[172:175], v196 offset:36864
	ds_read_b128 v[176:179], v197 offset:32768
	ds_read_b128 v[180:183], v201 offset:32768
	ds_read_b128 v[184:187], v201 offset:36864
	ds_read_b128 v[188:191], v197 offset:36864
	s_waitcnt lgkmcnt(6)
	v_mfma_f32_32x32x16_bf16 v[32:47], v[156:159], v[164:167], v[32:47]
	s_waitcnt lgkmcnt(5)
	v_mfma_f32_32x32x16_bf16 v[48:63], v[156:159], v[168:171], v[48:63]
	s_waitcnt lgkmcnt(4)
	v_mfma_f32_32x32x16_bf16 v[0:15], v[172:175], v[164:167], v[0:15]
	v_mfma_f32_32x32x16_bf16 v[16:31], v[172:175], v[168:171], v[16:31]
	ds_read_b128 v[156:159], v198 offset:32768
	ds_read_b128 v[164:167], v202 offset:32768
	ds_read_b128 v[168:171], v202 offset:36864
	ds_read_b128 v[172:175], v198 offset:36864
	s_waitcnt lgkmcnt(6)
	v_mfma_f32_32x32x16_bf16 v[32:47], v[176:179], v[180:183], v[32:47]
	s_waitcnt lgkmcnt(5)
	v_mfma_f32_32x32x16_bf16 v[48:63], v[176:179], v[184:187], v[48:63]
	s_waitcnt lgkmcnt(4)
	v_mfma_f32_32x32x16_bf16 v[0:15], v[188:191], v[180:183], v[0:15]
	v_mfma_f32_32x32x16_bf16 v[16:31], v[188:191], v[184:187], v[16:31]
	ds_read_b128 v[176:179], v199 offset:32768
	ds_read_b128 v[180:183], v203 offset:32768
	ds_read_b128 v[184:187], v203 offset:36864
	ds_read_b128 v[188:191], v199 offset:36864
	s_waitcnt lgkmcnt(6)
	v_mfma_f32_32x32x16_bf16 v[32:47], v[156:159], v[164:167], v[32:47]
	s_waitcnt lgkmcnt(5)
	v_mfma_f32_32x32x16_bf16 v[48:63], v[156:159], v[168:171], v[48:63]
	s_waitcnt lgkmcnt(4)
	v_mfma_f32_32x32x16_bf16 v[0:15], v[172:175], v[164:167], v[0:15]
	v_mfma_f32_32x32x16_bf16 v[16:31], v[172:175], v[168:171], v[16:31]
	s_waitcnt lgkmcnt(2)
	v_mfma_f32_32x32x16_bf16 v[32:47], v[176:179], v[180:183], v[32:47]
	s_waitcnt lgkmcnt(1)
	v_mfma_f32_32x32x16_bf16 v[48:63], v[176:179], v[184:187], v[48:63]
	s_waitcnt lgkmcnt(0)
	v_mfma_f32_32x32x16_bf16 v[0:15], v[188:191], v[180:183], v[0:15]
	v_mfma_f32_32x32x16_bf16 v[16:31], v[188:191], v[184:187], v[16:31]
	s_setprio 0
	s_nop 4
	v_mul_f32_e32 v67, 0xbfb8aa3b, v32
	v_exp_f32_e32 v67, v67
	s_barrier
	v_add_f32_e32 v67, 1.0, v67
	v_rcp_f32_e32 v67, v67
	v_mov_b32_e32 v65, v155
	v_mov_b32_e32 v66, v96
	v_mul_f32_e32 v32, v32, v67
	v_mul_f32_e32 v32, v48, v32
	v_mul_f32_e32 v48, 0xbfb8aa3b, v33
	v_exp_f32_e32 v48, v48
	s_ashr_i32 s1, s1, 1
	v_ashrrev_i32_e32 v64, 1, v66
	v_add_f32_e32 v48, 1.0, v48
	v_rcp_f32_e32 v48, v48
	s_andn2_b32 s1, s1, 63
	v_and_b32_e32 v64, 0xffffffe0, v64
	v_add_u32_e32 v64, s1, v64
	v_and_or_b32 v64, v66, 30, v64
	v_and_b32_e32 v66, 1, v66
	v_mul_f32_e32 v33, v33, v48
	v_cmp_eq_u32_e32 vcc, 0, v66
	v_mul_f32_e32 v33, v49, v33
	v_add3_u32 v66, v65, s0, v66
	v_cndmask_b32_e32 v48, v32, v33, vcc
	v_ashrrev_i32_e32 v65, 31, v64
	v_lshl_add_u64 v[64:65], v[64:65], 1, s[64:65]
	v_mov_b32_dpp v48, v48 quad_perm:[1,0,3,2] row_mask:0xf bank_mask:0xf bound_ctrl:1
	v_cndmask_b32_e32 v33, v33, v48, vcc
	v_cndmask_b32_e32 v32, v48, v32, vcc
	s_movk_i32 s3, 0x1600
	v_cvt_pk_bf16_f32 v48, v32, v33
	v_mad_i64_i32 v[32:33], s[0:1], v66, s3, v[64:65]
	global_store_dword v[32:33], v48, off nt
	v_mul_f32_e32 v32, 0xbfb8aa3b, v34
	v_mul_f32_e32 v33, 0xbfb8aa3b, v35
	v_exp_f32_e32 v32, v32
	v_exp_f32_e32 v33, v33
	v_add_f32_e32 v32, 1.0, v32
	v_add_f32_e32 v33, 1.0, v33
	v_rcp_f32_e32 v32, v32
	v_rcp_f32_e32 v33, v33
	v_mul_f32_e32 v32, v34, v32
	v_mul_f32_e32 v33, v35, v33
	v_mul_f32_e32 v32, v50, v32
	v_mul_f32_e32 v33, v51, v33
	v_cndmask_b32_e32 v34, v32, v33, vcc
	v_add_u32_e32 v35, 2, v66
	s_nop 0
	v_mov_b32_dpp v34, v34 quad_perm:[1,0,3,2] row_mask:0xf bank_mask:0xf bound_ctrl:1
	v_cndmask_b32_e32 v33, v33, v34, vcc
	v_cndmask_b32_e32 v32, v34, v32, vcc
	v_cvt_pk_bf16_f32 v34, v32, v33
	v_mad_i64_i32 v[32:33], s[0:1], v35, s3, v[64:65]
	global_store_dword v[32:33], v34, off nt
	v_mul_f32_e32 v32, 0xbfb8aa3b, v36
	v_mul_f32_e32 v33, 0xbfb8aa3b, v37
	v_exp_f32_e32 v32, v32
	v_exp_f32_e32 v33, v33
	v_add_u32_e32 v35, 8, v66
	v_add_f32_e32 v32, 1.0, v32
	v_add_f32_e32 v33, 1.0, v33
	v_rcp_f32_e32 v32, v32
	v_rcp_f32_e32 v33, v33
	v_mul_f32_e32 v32, v36, v32
	v_mul_f32_e32 v33, v37, v33
	v_mul_f32_e32 v32, v52, v32
	v_mul_f32_e32 v33, v53, v33
	v_cndmask_b32_e32 v34, v32, v33, vcc
	s_nop 1
	v_mov_b32_dpp v34, v34 quad_perm:[1,0,3,2] row_mask:0xf bank_mask:0xf bound_ctrl:1
	v_cndmask_b32_e32 v33, v33, v34, vcc
	v_cndmask_b32_e32 v32, v34, v32, vcc
	v_cvt_pk_bf16_f32 v34, v32, v33
	v_mad_i64_i32 v[32:33], s[0:1], v35, s3, v[64:65]
	global_store_dword v[32:33], v34, off nt
	v_mul_f32_e32 v32, 0xbfb8aa3b, v38
	v_mul_f32_e32 v33, 0xbfb8aa3b, v39
	v_exp_f32_e32 v32, v32
	v_exp_f32_e32 v33, v33
	v_add_u32_e32 v35, 10, v66
	v_add_f32_e32 v32, 1.0, v32
	v_add_f32_e32 v33, 1.0, v33
	v_rcp_f32_e32 v32, v32
	v_rcp_f32_e32 v33, v33
	v_mul_f32_e32 v32, v38, v32
	v_mul_f32_e32 v33, v39, v33
	v_mul_f32_e32 v32, v54, v32
	v_mul_f32_e32 v33, v55, v33
	v_cndmask_b32_e32 v34, v32, v33, vcc
	s_nop 1
	v_mov_b32_dpp v34, v34 quad_perm:[1,0,3,2] row_mask:0xf bank_mask:0xf bound_ctrl:1
	v_cndmask_b32_e32 v33, v33, v34, vcc
	v_cndmask_b32_e32 v32, v34, v32, vcc
	v_cvt_pk_bf16_f32 v34, v32, v33
	v_mad_i64_i32 v[32:33], s[0:1], v35, s3, v[64:65]
	global_store_dword v[32:33], v34, off nt
	v_mul_f32_e32 v32, 0xbfb8aa3b, v40
	v_mul_f32_e32 v33, 0xbfb8aa3b, v41
	v_exp_f32_e32 v32, v32
	v_exp_f32_e32 v33, v33
	v_add_u32_e32 v35, 16, v66
	v_add_f32_e32 v32, 1.0, v32
	v_add_f32_e32 v33, 1.0, v33
	v_rcp_f32_e32 v32, v32
	v_rcp_f32_e32 v33, v33
	v_mul_f32_e32 v32, v40, v32
	v_mul_f32_e32 v33, v41, v33
	v_mul_f32_e32 v32, v56, v32
; DI unsigned pack2(float a, float b) { f32v2 v = {a, b}; bf16v2 r = __builtin_convertvector(v, bf16v2); return __builtin_bit_cast(unsigned, r); }
;     ...
;       const int hb = (n0e >> 7) * 64 + (cb >> 6) * 32 + (cb & 31);
;       const bool odd = (cb & 1) != 0;
; #pragma unroll
;       for (int mi = 0; mi < 2; ++mi)
; #pragma unroll
;         for (int i = 0; i < 16; i += 2) {
;           const float u0 = acc[mi][0][i], g0 = acc[mi][1][i], u1 = acc[mi][0][i + 1], g1 = acc[mi][1][i + 1];
;           const float a = u0 * __builtin_amdgcn_rcpf(1.f + __expf(-u0)) * g0, b2 = u1 * __builtin_amdgcn_rcpf(1.f + __expf(-u1)) * g1;
;           const float recv = dpp_f(odd ? a : b2, 0);
;           const int row = m0e + rb + mi * 32 + (i & 3) + 8 * (i >> 2) + (odd ? 1 : 0);
;           const unsigned w = odd ? pack2(recv, b2) : pack2(a, recv);
;           __builtin_nontemporal_store(w, (unsigned*)(P.pbuf + (size_t)row * DFF + (hb & ~1)));
;         }
	v_mul_f32_e32 v33, v57, v33
	v_cndmask_b32_e32 v34, v32, v33, vcc
	s_nop 1
	v_mov_b32_dpp v34, v34 quad_perm:[1,0,3,2] row_mask:0xf bank_mask:0xf bound_ctrl:1
	v_cndmask_b32_e32 v33, v33, v34, vcc
	v_cndmask_b32_e32 v32, v34, v32, vcc
	v_cvt_pk_bf16_f32 v34, v32, v33
	v_mad_i64_i32 v[32:33], s[0:1], v35, s3, v[64:65]
	global_store_dword v[32:33], v34, off nt
	v_mul_f32_e32 v32, 0xbfb8aa3b, v42
	v_mul_f32_e32 v33, 0xbfb8aa3b, v43
	v_exp_f32_e32 v32, v32
	v_exp_f32_e32 v33, v33
	v_add_u32_e32 v35, 18, v66
	v_add_f32_e32 v32, 1.0, v32
	v_add_f32_e32 v33, 1.0, v33
	v_rcp_f32_e32 v32, v32
	v_rcp_f32_e32 v33, v33
	v_mul_f32_e32 v32, v42, v32
	v_mul_f32_e32 v33, v43, v33
	v_mul_f32_e32 v32, v58, v32
	v_mul_f32_e32 v33, v59, v33
	v_cndmask_b32_e32 v34, v32, v33, vcc
	s_nop 1
	v_mov_b32_dpp v34, v34 quad_perm:[1,0,3,2] row_mask:0xf bank_mask:0xf bound_ctrl:1
	v_cndmask_b32_e32 v33, v33, v34, vcc
	v_cndmask_b32_e32 v32, v34, v32, vcc
	v_cvt_pk_bf16_f32 v34, v32, v33
	v_mad_i64_i32 v[32:33], s[0:1], v35, s3, v[64:65]
	global_store_dword v[32:33], v34, off nt
	v_mul_f32_e32 v32, 0xbfb8aa3b, v44
	v_mul_f32_e32 v33, 0xbfb8aa3b, v45
	v_exp_f32_e32 v32, v32
	v_exp_f32_e32 v33, v33
	v_add_u32_e32 v35, 24, v66
	v_add_f32_e32 v32, 1.0, v32
	v_add_f32_e32 v33, 1.0, v33
	v_rcp_f32_e32 v32, v32
	v_rcp_f32_e32 v33, v33
	v_mul_f32_e32 v32, v44, v32
	v_mul_f32_e32 v33, v45, v33
	v_mul_f32_e32 v32, v60, v32
	v_mul_f32_e32 v33, v61, v33
	v_cndmask_b32_e32 v34, v32, v33, vcc
	s_nop 1
	v_mov_b32_dpp v34, v34 quad_perm:[1,0,3,2] row_mask:0xf bank_mask:0xf bound_ctrl:1
	v_cndmask_b32_e32 v33, v33, v34, vcc
	v_cndmask_b32_e32 v32, v34, v32, vcc
	v_cvt_pk_bf16_f32 v34, v32, v33
	v_mad_i64_i32 v[32:33], s[0:1], v35, s3, v[64:65]
	global_store_dword v[32:33], v34, off nt
	v_mul_f32_e32 v32, 0xbfb8aa3b, v46
	v_mul_f32_e32 v33, 0xbfb8aa3b, v47
	v_exp_f32_e32 v32, v32
	v_exp_f32_e32 v33, v33
	v_add_u32_e32 v35, 26, v66
	v_add_f32_e32 v32, 1.0, v32
	v_add_f32_e32 v33, 1.0, v33
	v_rcp_f32_e32 v32, v32
	v_rcp_f32_e32 v33, v33
	v_mul_f32_e32 v32, v46, v32
	v_mul_f32_e32 v33, v47, v33
	v_mul_f32_e32 v32, v62, v32
	v_mul_f32_e32 v33, v63, v33
	v_cndmask_b32_e32 v34, v32, v33, vcc
	s_nop 1
	v_mov_b32_dpp v34, v34 quad_perm:[1,0,3,2] row_mask:0xf bank_mask:0xf bound_ctrl:1
	v_cndmask_b32_e32 v33, v33, v34, vcc
	v_cndmask_b32_e32 v32, v34, v32, vcc
	v_cvt_pk_bf16_f32 v34, v32, v33
	v_mad_i64_i32 v[32:33], s[0:1], v35, s3, v[64:65]
	global_store_dword v[32:33], v34, off nt
	v_mul_f32_e32 v33, 0xbfb8aa3b, v0
	v_exp_f32_e32 v33, v33
	v_add_u32_e32 v32, 32, v66
	v_add_f32_e32 v33, 1.0, v33
	v_rcp_f32_e32 v33, v33
	s_nop 0
	v_mul_f32_e32 v0, v0, v33
	v_mul_f32_e32 v0, v16, v0
	v_mul_f32_e32 v16, 0xbfb8aa3b, v1
	v_exp_f32_e32 v16, v16
	s_nop 0
	v_add_f32_e32 v16, 1.0, v16
	v_rcp_f32_e32 v16, v16
	s_nop 0
	v_mul_f32_e32 v1, v1, v16
	v_mul_f32_e32 v1, v17, v1
	v_cndmask_b32_e32 v16, v0, v1, vcc
	s_nop 1
	v_mov_b32_dpp v16, v16 quad_perm:[1,0,3,2] row_mask:0xf bank_mask:0xf bound_ctrl:1
	v_cndmask_b32_e32 v1, v1, v16, vcc
	v_cndmask_b32_e32 v0, v16, v0, vcc
	v_cvt_pk_bf16_f32 v16, v0, v1
	v_mad_i64_i32 v[0:1], s[0:1], v32, s3, v[64:65]
	global_store_dword v[0:1], v16, off nt
	v_mul_f32_e32 v0, 0xbfb8aa3b, v2
	v_mul_f32_e32 v1, 0xbfb8aa3b, v3
	v_exp_f32_e32 v0, v0
	v_exp_f32_e32 v1, v1
	v_add_f32_e32 v0, 1.0, v0
	v_add_f32_e32 v1, 1.0, v1
	v_rcp_f32_e32 v0, v0
	v_rcp_f32_e32 v1, v1
	v_mul_f32_e32 v0, v2, v0
	v_mul_f32_e32 v1, v3, v1
	v_mul_f32_e32 v0, v18, v0
	v_mul_f32_e32 v1, v19, v1
	v_cndmask_b32_e32 v2, v0, v1, vcc
	v_add_u32_e32 v3, 34, v66
	s_nop 0
	v_mov_b32_dpp v2, v2 quad_perm:[1,0,3,2] row_mask:0xf bank_mask:0xf bound_ctrl:1
	v_cndmask_b32_e32 v1, v1, v2, vcc
	v_cndmask_b32_e32 v0, v2, v0, vcc
	v_cvt_pk_bf16_f32 v2, v0, v1
	v_mad_i64_i32 v[0:1], s[0:1], v3, s3, v[64:65]
	global_store_dword v[0:1], v2, off nt
	v_mul_f32_e32 v0, 0xbfb8aa3b, v4
	v_mul_f32_e32 v1, 0xbfb8aa3b, v5
	v_exp_f32_e32 v0, v0
	v_exp_f32_e32 v1, v1
; DI unsigned pack2(float a, float b) { f32v2 v = {a, b}; bf16v2 r = __builtin_convertvector(v, bf16v2); return __builtin_bit_cast(unsigned, r); }
;     ...
;       const int hb = (n0e >> 7) * 64 + (cb >> 6) * 32 + (cb & 31);
;       const bool odd = (cb & 1) != 0;
; #pragma unroll
;       for (int mi = 0; mi < 2; ++mi)
; #pragma unroll
;         for (int i = 0; i < 16; i += 2) {
;           const float u0 = acc[mi][0][i], g0 = acc[mi][1][i], u1 = acc[mi][0][i + 1], g1 = acc[mi][1][i + 1];
;           const float a = u0 * __builtin_amdgcn_rcpf(1.f + __expf(-u0)) * g0, b2 = u1 * __builtin_amdgcn_rcpf(1.f + __expf(-u1)) * g1;
;           const float recv = dpp_f(odd ? a : b2, 0);
;           const int row = m0e + rb + mi * 32 + (i & 3) + 8 * (i >> 2) + (odd ? 1 : 0);
;           const unsigned w = odd ? pack2(recv, b2) : pack2(a, recv);
;           __builtin_nontemporal_store(w, (unsigned*)(P.pbuf + (size_t)row * DFF + (hb & ~1)));
;         }
	v_add_u32_e32 v3, 40, v66
	v_add_f32_e32 v0, 1.0, v0
	v_add_f32_e32 v1, 1.0, v1
	v_rcp_f32_e32 v0, v0
	v_rcp_f32_e32 v1, v1
	v_mul_f32_e32 v0, v4, v0
	v_mul_f32_e32 v1, v5, v1
	v_mul_f32_e32 v0, v20, v0
	v_mul_f32_e32 v1, v21, v1
	v_cndmask_b32_e32 v2, v0, v1, vcc
	s_nop 1
	v_mov_b32_dpp v2, v2 quad_perm:[1,0,3,2] row_mask:0xf bank_mask:0xf bound_ctrl:1
	v_cndmask_b32_e32 v1, v1, v2, vcc
	v_cndmask_b32_e32 v0, v2, v0, vcc
	v_cvt_pk_bf16_f32 v2, v0, v1
	v_mad_i64_i32 v[0:1], s[0:1], v3, s3, v[64:65]
	global_store_dword v[0:1], v2, off nt
	v_mul_f32_e32 v0, 0xbfb8aa3b, v6
	v_mul_f32_e32 v1, 0xbfb8aa3b, v7
	v_exp_f32_e32 v0, v0
	v_exp_f32_e32 v1, v1
	v_add_u32_e32 v3, 42, v66
	v_add_f32_e32 v0, 1.0, v0
	v_add_f32_e32 v1, 1.0, v1
	v_rcp_f32_e32 v0, v0
	v_rcp_f32_e32 v1, v1
	v_mul_f32_e32 v0, v6, v0
	v_mul_f32_e32 v1, v7, v1
	v_mul_f32_e32 v0, v22, v0
	v_mul_f32_e32 v1, v23, v1
	v_cndmask_b32_e32 v2, v0, v1, vcc
	s_nop 1
	v_mov_b32_dpp v2, v2 quad_perm:[1,0,3,2] row_mask:0xf bank_mask:0xf bound_ctrl:1
	v_cndmask_b32_e32 v1, v1, v2, vcc
	v_cndmask_b32_e32 v0, v2, v0, vcc
	v_cvt_pk_bf16_f32 v2, v0, v1
	v_mad_i64_i32 v[0:1], s[0:1], v3, s3, v[64:65]
	global_store_dword v[0:1], v2, off nt
	v_mul_f32_e32 v0, 0xbfb8aa3b, v8
	v_mul_f32_e32 v1, 0xbfb8aa3b, v9
	v_exp_f32_e32 v0, v0
	v_exp_f32_e32 v1, v1
	v_add_u32_e32 v3, 48, v66
	v_add_f32_e32 v0, 1.0, v0
	v_add_f32_e32 v1, 1.0, v1
	v_rcp_f32_e32 v0, v0
	v_rcp_f32_e32 v1, v1
	v_mul_f32_e32 v0, v8, v0
	v_mul_f32_e32 v1, v9, v1
	v_mul_f32_e32 v0, v24, v0
	v_mul_f32_e32 v1, v25, v1
	v_cndmask_b32_e32 v2, v0, v1, vcc
	s_nop 1
	v_mov_b32_dpp v2, v2 quad_perm:[1,0,3,2] row_mask:0xf bank_mask:0xf bound_ctrl:1
	v_cndmask_b32_e32 v1, v1, v2, vcc
	v_cndmask_b32_e32 v0, v2, v0, vcc
	v_cvt_pk_bf16_f32 v2, v0, v1
	v_mad_i64_i32 v[0:1], s[0:1], v3, s3, v[64:65]
	global_store_dword v[0:1], v2, off nt
	v_mul_f32_e32 v0, 0xbfb8aa3b, v10
	v_mul_f32_e32 v1, 0xbfb8aa3b, v11
	v_exp_f32_e32 v0, v0
	v_exp_f32_e32 v1, v1
	v_add_u32_e32 v3, 50, v66
	v_add_f32_e32 v0, 1.0, v0
	v_add_f32_e32 v1, 1.0, v1
	v_rcp_f32_e32 v0, v0
	v_rcp_f32_e32 v1, v1
	v_mul_f32_e32 v0, v10, v0
	v_mul_f32_e32 v1, v11, v1
	v_mul_f32_e32 v0, v26, v0
	v_mul_f32_e32 v1, v27, v1
	v_cndmask_b32_e32 v2, v0, v1, vcc
	s_nop 1
	v_mov_b32_dpp v2, v2 quad_perm:[1,0,3,2] row_mask:0xf bank_mask:0xf bound_ctrl:1
	v_cndmask_b32_e32 v1, v1, v2, vcc
	v_cndmask_b32_e32 v0, v2, v0, vcc
	v_cvt_pk_bf16_f32 v2, v0, v1
	v_mad_i64_i32 v[0:1], s[0:1], v3, s3, v[64:65]
	global_store_dword v[0:1], v2, off nt
	v_mul_f32_e32 v0, 0xbfb8aa3b, v12
	v_mul_f32_e32 v1, 0xbfb8aa3b, v13
	v_exp_f32_e32 v0, v0
	v_exp_f32_e32 v1, v1
	v_add_u32_e32 v3, 56, v66
	v_add_f32_e32 v0, 1.0, v0
	v_add_f32_e32 v1, 1.0, v1
	v_rcp_f32_e32 v0, v0
	v_rcp_f32_e32 v1, v1
	v_mul_f32_e32 v0, v12, v0
	v_mul_f32_e32 v1, v13, v1
	v_mul_f32_e32 v0, v28, v0
	v_mul_f32_e32 v1, v29, v1
	v_cndmask_b32_e32 v2, v0, v1, vcc
	s_nop 1
	v_mov_b32_dpp v2, v2 quad_perm:[1,0,3,2] row_mask:0xf bank_mask:0xf bound_ctrl:1
	v_cndmask_b32_e32 v1, v1, v2, vcc
	v_cndmask_b32_e32 v0, v2, v0, vcc
	v_cvt_pk_bf16_f32 v2, v0, v1
	v_mad_i64_i32 v[0:1], s[0:1], v3, s3, v[64:65]
	global_store_dword v[0:1], v2, off nt
	v_mul_f32_e32 v0, 0xbfb8aa3b, v14
	v_mul_f32_e32 v1, 0xbfb8aa3b, v15
	v_exp_f32_e32 v0, v0
	v_exp_f32_e32 v1, v1
	v_add_u32_e32 v3, 58, v66
	v_add_f32_e32 v0, 1.0, v0
	v_add_f32_e32 v1, 1.0, v1
	v_rcp_f32_e32 v0, v0
	v_rcp_f32_e32 v1, v1
	v_mul_f32_e32 v0, v14, v0
	v_mul_f32_e32 v1, v15, v1
	v_mul_f32_e32 v0, v30, v0
	v_mul_f32_e32 v1, v31, v1
	v_cndmask_b32_e32 v2, v0, v1, vcc
	s_nop 1
	v_mov_b32_dpp v2, v2 quad_perm:[1,0,3,2] row_mask:0xf bank_mask:0xf bound_ctrl:1
	v_cndmask_b32_e32 v1, v1, v2, vcc
	v_cndmask_b32_e32 v0, v2, v0, vcc
	v_cvt_pk_bf16_f32 v2, v0, v1
	v_mad_i64_i32 v[0:1], s[0:1], v3, s3, v[64:65]
	v_readlane_b32 s0, v252, 30
	s_add_i32 s2, s2, s0
	v_readlane_b32 s0, v252, 47
	s_cmp_ge_i32 s2, s0
	global_store_dword v[0:1], v2, off nt
	s_cbranch_scc1 .LBB0_202

;     ...
;     const u16* Ag = A + (size_t)(m0 + lrow) * K + lkc * 8;
;     const u16* Bg = Bt + (size_t)(n0 + lrow) * K + lkc * 8;
;     const size_t K32 = (size_t)32 * K;
;     uint4 xa0, xa1, xa2, xa3, xb0, xb1, xb2, xb3;
;     uint4 ya0, ya1, ya2, ya3, yb0, yb1, yb2, yb3;
;     ...
;     G_LOAD(x, 0);
;     G_STORE(x, 0);
;     __syncthreads();
;     if (KT > 1) G_LOAD(x, 1);
;     for (int kt = 0; kt < KT; kt += 2) {
;       if (kt + 2 < KT && dummy != 2) G_LOAD(y, kt + 2);
;       G_COMPUTE(0);
.LBB0_235:
	v_readlane_b32 s0, v252, 34
	s_or_b32 s14, s14, s0
	v_readlane_b32 s0, v252, 28
	v_readlane_b32 s1, v252, 29
	s_and_b64 s[0:1], s[0:1], exec
	s_cselect_b32 s0, s14, s3
	s_lshl_b32 s14, s0, 7
	s_lshl_b32 s0, s2, 7
	v_add_u32_e32 v0, s14, v154
	v_ashrrev_i32_e32 v1, 31, v0
	v_lshlrev_b64 v[0:1], 11, v[0:1]
	v_lshl_add_u64 v[138:139], v[130:131], 0, v[0:1]
	v_add_u32_e32 v0, s0, v154
	v_ashrrev_i32_e32 v1, 31, v0
	v_lshlrev_b64 v[0:1], 11, v[0:1]
	v_lshl_add_u64 v[140:141], v[132:133], 0, v[0:1]
	v_and_b32_e32 v194, 7, v206
	v_bfe_u32 v195, v206, 4, 3
	v_xor_b32_e32 v195, v195, v194
	v_sub_u32_e32 v195, v195, v194
	v_lshlrev_b32_e32 v192, 4, v195
	v_ashrrev_i32_e32 v193, 31, v192
	v_lshl_add_u64 v[138:139], v[138:139], 0, v[192:193]
	v_lshl_add_u64 v[140:141], v[140:141], 0, v[192:193]
	s_mov_b64 s[78:79], 0x10000
	v_lshl_add_u64 v[142:143], v[138:139], 0, s[78:79]
	v_lshl_add_u64 v[146:147], v[140:141], 0, s[78:79]
	s_mov_b64 s[78:79], 0x20000
	v_lshl_add_u64 v[144:145], v[138:139], 0, s[78:79]
	v_lshl_add_u64 v[148:149], v[140:141], 0, s[78:79]
	s_mov_b64 s[78:79], 0x30000
	v_lshl_add_u64 v[152:153], v[138:139], 0, s[78:79]
	v_lshl_add_u64 v[150:151], v[140:141], 0, s[78:79]
	v_lshrrev_b32_e32 v194, 6, v206
	v_lshlrev_b32_e32 v194, 10, v194
	s_nop 0
	v_readfirstlane_b32 s88, v194
	v_bfe_u32 v195, v206, 1, 3
	v_bfe_u32 v194, v206, 5, 1
	v_and_b32_e32 v192, 1, v195
	v_xor_b32_e32 v194, v194, v192
	v_lshrrev_b32_e32 v195, 1, v195
	v_and_b32_e32 v192, 31, v206
	v_lshrrev_b32_e32 v193, 7, v206
	v_lshl_add_u32 v193, v193, 6, v192
	v_lshlrev_b32_e32 v193, 7, v193
	v_lshl_add_u32 v193, v194, 4, v193
	v_add_u32_e32 v193, 2048, v193
	v_bfe_u32 v172, v206, 6, 1
	v_lshl_add_u32 v172, v172, 6, v192
	v_lshlrev_b32_e32 v172, 7, v172
	v_lshl_add_u32 v172, v194, 4, v172
	v_add_u32_e32 v172, 18432, v172
	v_xor_b32_e32 v192, 0, v195
	v_lshl_add_u32 v196, v192, 5, v193
	v_lshl_add_u32 v200, v192, 5, v172
	v_xor_b32_e32 v192, 1, v195
	v_lshl_add_u32 v197, v192, 5, v193
	v_lshl_add_u32 v201, v192, 5, v172
	v_xor_b32_e32 v192, 2, v195
	v_lshl_add_u32 v198, v192, 5, v193
	v_lshl_add_u32 v202, v192, 5, v172
	v_xor_b32_e32 v192, 3, v195
	v_lshl_add_u32 v199, v192, 5, v193
	v_lshl_add_u32 v203, v192, 5, v172
	s_add_u32 m0, s88, 0x800
	s_nop 0
	global_load_lds_dwordx4 v[138:139], off
	s_add_u32 m0, s88, 0x1800
	s_nop 0
	global_load_lds_dwordx4 v[142:143], off
	s_add_u32 m0, s88, 0x2800
	s_nop 0
	global_load_lds_dwordx4 v[144:145], off
	s_add_u32 m0, s88, 0x3800
	s_nop 0
	global_load_lds_dwordx4 v[152:153], off
	s_add_u32 m0, s88, 0x4800
	s_nop 0
	global_load_lds_dwordx4 v[140:141], off
	s_add_u32 m0, s88, 0x5800
	s_nop 0
	global_load_lds_dwordx4 v[146:147], off
	s_add_u32 m0, s88, 0x6800
	s_nop 0
	global_load_lds_dwordx4 v[148:149], off
	s_add_u32 m0, s88, 0x7800
	s_nop 0
	global_load_lds_dwordx4 v[150:151], off
	s_waitcnt vmcnt(0)
	s_barrier
	s_setprio 1
	ds_read_b128 v[156:159], v196
	ds_read_b128 v[164:167], v200
	ds_read_b128 v[168:171], v200 offset:4096
	ds_read_b128 v[172:175], v196 offset:4096
	ds_read_b128 v[176:179], v197
	ds_read_b128 v[180:183], v201
	ds_read_b128 v[184:187], v201 offset:4096
	ds_read_b128 v[188:191], v197 offset:4096
	s_add_u32 m0, s88, 0x8780
	s_nop 0
	global_load_lds_dwordx4 v[138:139], off offset:128
	s_add_u32 m0, s88, 0x9780
	s_nop 0
	global_load_lds_dwordx4 v[142:143], off offset:128
	s_add_u32 m0, s88, 0xa780
	s_nop 0
	global_load_lds_dwordx4 v[144:145], off offset:128
	s_add_u32 m0, s88, 0xb780
	s_nop 0
	global_load_lds_dwordx4 v[152:153], off offset:128
	s_add_u32 m0, s88, 0xc780
	s_nop 0
	global_load_lds_dwordx4 v[140:141], off offset:128
	s_add_u32 m0, s88, 0xd780
	s_nop 0
	global_load_lds_dwordx4 v[146:147], off offset:128
	s_add_u32 m0, s88, 0xe780
	s_nop 0
	global_load_lds_dwordx4 v[148:149], off offset:128
	s_add_u32 m0, s88, 0xf780
	s_nop 0
	global_load_lds_dwordx4 v[150:151], off offset:128
	s_waitcnt lgkmcnt(6)
	v_mfma_f32_32x32x16_bf16 v[48:63], v[156:159], v[164:167], 0
	s_waitcnt lgkmcnt(5)
	v_mfma_f32_32x32x16_bf16 v[32:47], v[156:159], v[168:171], 0
	s_waitcnt lgkmcnt(4)
	v_mfma_f32_32x32x16_bf16 v[16:31], v[172:175], v[164:167], 0
	v_mfma_f32_32x32x16_bf16 v[0:15], v[172:175], v[168:171], 0
	ds_read_b128 v[156:159], v198
	ds_read_b128 v[164:167], v202
	ds_read_b128 v[168:171], v202 offset:4096
	ds_read_b128 v[172:175], v198 offset:4096
	s_waitcnt lgkmcnt(6)
	v_mfma_f32_32x32x16_bf16 v[48:63], v[176:179], v[180:183], v[48:63]
	s_waitcnt lgkmcnt(5)
	v_mfma_f32_32x32x16_bf16 v[32:47], v[176:179], v[184:187], v[32:47]
	s_waitcnt lgkmcnt(4)
	v_mfma_f32_32x32x16_bf16 v[16:31], v[188:191], v[180:183], v[16:31]
	v_mfma_f32_32x32x16_bf16 v[0:15], v[188:191], v[184:187], v[0:15]
	ds_read_b128 v[176:179], v199
	ds_read_b128 v[180:183], v203
	ds_read_b128 v[184:187], v203 offset:4096
	ds_read_b128 v[188:191], v199 offset:4096
	s_waitcnt lgkmcnt(6)
	v_mfma_f32_32x32x16_bf16 v[48:63], v[156:159], v[164:167], v[48:63]
	s_waitcnt lgkmcnt(5)
	v_mfma_f32_32x32x16_bf16 v[32:47], v[156:159], v[168:171], v[32:47]
	s_waitcnt lgkmcnt(4)
	v_mfma_f32_32x32x16_bf16 v[16:31], v[172:175], v[164:167], v[16:31]
	v_mfma_f32_32x32x16_bf16 v[0:15], v[172:175], v[168:171], v[0:15]
	s_waitcnt lgkmcnt(2)
	v_mfma_f32_32x32x16_bf16 v[48:63], v[176:179], v[180:183], v[48:63]
	s_waitcnt lgkmcnt(1)
	v_mfma_f32_32x32x16_bf16 v[32:47], v[176:179], v[184:187], v[32:47]
	s_waitcnt lgkmcnt(0)
	v_mfma_f32_32x32x16_bf16 v[16:31], v[188:191], v[180:183], v[16:31]
	v_mfma_f32_32x32x16_bf16 v[0:15], v[188:191], v[184:187], v[0:15]
	s_setprio 0
	s_waitcnt vmcnt(0)
	s_barrier
;     ...
;     G_LOAD(x, 0);
;     G_STORE(x, 0);
;     __syncthreads();
;     if (KT > 1) G_LOAD(x, 1);
;     for (int kt = 0; kt < KT; kt += 2) {
;       if (kt + 2 < KT && dummy != 2) G_LOAD(y, kt + 2);
;       G_COMPUTE(0);
;       if (kt + 1 < KT && dummy != 2) G_STORE(x, 1);
;       __syncthreads();
;       if (kt + 1 >= KT) break;
;       if (kt + 3 < KT && dummy != 2) G_LOAD(x, kt + 3);
;       G_COMPUTE(1);
;       if (kt + 2 < KT && dummy != 2) G_STORE(y, 0);
;       __syncthreads();
;     }
	s_setprio 1
	ds_read_b128 v[156:159], v196 offset:32768
	ds_read_b128 v[164:167], v200 offset:32768
	ds_read_b128 v[168:171], v200 offset:36864
	ds_read_b128 v[172:175], v196 offset:36864
	ds_read_b128 v[176:179], v197 offset:32768
	ds_read_b128 v[180:183], v201 offset:32768
	ds_read_b128 v[184:187], v201 offset:36864
	ds_read_b128 v[188:191], v197 offset:36864
	s_add_u32 m0, s88, 0x700
	s_nop 0
	global_load_lds_dwordx4 v[138:139], off offset:256
	s_add_u32 m0, s88, 0x1700
	s_nop 0
	global_load_lds_dwordx4 v[142:143], off offset:256
	s_add_u32 m0, s88, 0x2700
	s_nop 0
	global_load_lds_dwordx4 v[144:145], off offset:256
	s_add_u32 m0, s88, 0x3700
	s_nop 0
	global_load_lds_dwordx4 v[152:153], off offset:256
	s_add_u32 m0, s88, 0x4700
	s_nop 0
	global_load_lds_dwordx4 v[140:141], off offset:256
	s_add_u32 m0, s88, 0x5700
	s_nop 0
	global_load_lds_dwordx4 v[146:147], off offset:256
	s_add_u32 m0, s88, 0x6700
	s_nop 0
	global_load_lds_dwordx4 v[148:149], off offset:256
	s_add_u32 m0, s88, 0x7700
	s_nop 0
	global_load_lds_dwordx4 v[150:151], off offset:256
	s_waitcnt lgkmcnt(6)
	v_mfma_f32_32x32x16_bf16 v[48:63], v[156:159], v[164:167], v[48:63]
	s_waitcnt lgkmcnt(5)
	v_mfma_f32_32x32x16_bf16 v[32:47], v[156:159], v[168:171], v[32:47]
	s_waitcnt lgkmcnt(4)
	v_mfma_f32_32x32x16_bf16 v[16:31], v[172:175], v[164:167], v[16:31]
	v_mfma_f32_32x32x16_bf16 v[0:15], v[172:175], v[168:171], v[0:15]
	ds_read_b128 v[156:159], v198 offset:32768
	ds_read_b128 v[164:167], v202 offset:32768
	ds_read_b128 v[168:171], v202 offset:36864
	ds_read_b128 v[172:175], v198 offset:36864
	s_waitcnt lgkmcnt(6)
	v_mfma_f32_32x32x16_bf16 v[48:63], v[176:179], v[180:183], v[48:63]
	s_waitcnt lgkmcnt(5)
	v_mfma_f32_32x32x16_bf16 v[32:47], v[176:179], v[184:187], v[32:47]
	s_waitcnt lgkmcnt(4)
	v_mfma_f32_32x32x16_bf16 v[16:31], v[188:191], v[180:183], v[16:31]
	v_mfma_f32_32x32x16_bf16 v[0:15], v[188:191], v[184:187], v[0:15]
	ds_read_b128 v[176:179], v199 offset:32768
	ds_read_b128 v[180:183], v203 offset:32768
	ds_read_b128 v[184:187], v203 offset:36864
	ds_read_b128 v[188:191], v199 offset:36864
	s_waitcnt lgkmcnt(6)
	v_mfma_f32_32x32x16_bf16 v[48:63], v[156:159], v[164:167], v[48:63]
	s_waitcnt lgkmcnt(5)
	v_mfma_f32_32x32x16_bf16 v[32:47], v[156:159], v[168:171], v[32:47]
	s_waitcnt lgkmcnt(4)
	v_mfma_f32_32x32x16_bf16 v[16:31], v[172:175], v[164:167], v[16:31]
	v_mfma_f32_32x32x16_bf16 v[0:15], v[172:175], v[168:171], v[0:15]
	s_waitcnt lgkmcnt(2)
	v_mfma_f32_32x32x16_bf16 v[48:63], v[176:179], v[180:183], v[48:63]
	s_waitcnt lgkmcnt(1)
	v_mfma_f32_32x32x16_bf16 v[32:47], v[176:179], v[184:187], v[32:47]
	s_waitcnt lgkmcnt(0)
	v_mfma_f32_32x32x16_bf16 v[16:31], v[188:191], v[180:183], v[16:31]
	v_mfma_f32_32x32x16_bf16 v[0:15], v[188:191], v[184:187], v[0:15]
	s_setprio 0
	s_waitcnt vmcnt(0)
	s_barrier
	s_setprio 1
	ds_read_b128 v[156:159], v196
	ds_read_b128 v[164:167], v200
	ds_read_b128 v[168:171], v200 offset:4096
	ds_read_b128 v[172:175], v196 offset:4096
	ds_read_b128 v[176:179], v197
	ds_read_b128 v[180:183], v201
	ds_read_b128 v[184:187], v201 offset:4096
	ds_read_b128 v[188:191], v197 offset:4096
	s_add_u32 m0, s88, 0x8680
	s_nop 0
	global_load_lds_dwordx4 v[138:139], off offset:384
	s_add_u32 m0, s88, 0x9680
	s_nop 0
	global_load_lds_dwordx4 v[142:143], off offset:384
	s_add_u32 m0, s88, 0xa680
	s_nop 0
	global_load_lds_dwordx4 v[144:145], off offset:384
	s_add_u32 m0, s88, 0xb680
	s_nop 0
	global_load_lds_dwordx4 v[152:153], off offset:384
	s_add_u32 m0, s88, 0xc680
	s_nop 0
	global_load_lds_dwordx4 v[140:141], off offset:384
	s_add_u32 m0, s88, 0xd680
	s_nop 0
	global_load_lds_dwordx4 v[146:147], off offset:384
	s_add_u32 m0, s88, 0xe680
	s_nop 0
	global_load_lds_dwordx4 v[148:149], off offset:384
	s_add_u32 m0, s88, 0xf680
	s_nop 0
	global_load_lds_dwordx4 v[150:151], off offset:384
	s_waitcnt lgkmcnt(6)
	v_mfma_f32_32x32x16_bf16 v[48:63], v[156:159], v[164:167], v[48:63]
	s_waitcnt lgkmcnt(5)
	v_mfma_f32_32x32x16_bf16 v[32:47], v[156:159], v[168:171], v[32:47]
	s_waitcnt lgkmcnt(4)
	v_mfma_f32_32x32x16_bf16 v[16:31], v[172:175], v[164:167], v[16:31]
	v_mfma_f32_32x32x16_bf16 v[0:15], v[172:175], v[168:171], v[0:15]
	ds_read_b128 v[156:159], v198
	ds_read_b128 v[164:167], v202
	ds_read_b128 v[168:171], v202 offset:4096
	ds_read_b128 v[172:175], v198 offset:4096
	s_waitcnt lgkmcnt(6)
	v_mfma_f32_32x32x16_bf16 v[48:63], v[176:179], v[180:183], v[48:63]
	s_waitcnt lgkmcnt(5)
	v_mfma_f32_32x32x16_bf16 v[32:47], v[176:179], v[184:187], v[32:47]
	s_waitcnt lgkmcnt(4)
	v_mfma_f32_32x32x16_bf16 v[16:31], v[188:191], v[180:183], v[16:31]
	v_mfma_f32_32x32x16_bf16 v[0:15], v[188:191], v[184:187], v[0:15]
	ds_read_b128 v[176:179], v199
	ds_read_b128 v[180:183], v203
	ds_read_b128 v[184:187], v203 offset:4096
	ds_read_b128 v[188:191], v199 offset:4096
	s_waitcnt lgkmcnt(6)
	v_mfma_f32_32x32x16_bf16 v[48:63], v[156:159], v[164:167], v[48:63]
	s_waitcnt lgkmcnt(5)
	v_mfma_f32_32x32x16_bf16 v[32:47], v[156:159], v[168:171], v[32:47]
	s_waitcnt lgkmcnt(4)
	v_mfma_f32_32x32x16_bf16 v[16:31], v[172:175], v[164:167], v[16:31]
	v_mfma_f32_32x32x16_bf16 v[0:15], v[172:175], v[168:171], v[0:15]
	s_waitcnt lgkmcnt(2)
	v_mfma_f32_32x32x16_bf16 v[48:63], v[176:179], v[180:183], v[48:63]
	s_waitcnt lgkmcnt(1)
	v_mfma_f32_32x32x16_bf16 v[32:47], v[176:179], v[184:187], v[32:47]
	s_waitcnt lgkmcnt(0)
	v_mfma_f32_32x32x16_bf16 v[16:31], v[188:191], v[180:183], v[16:31]
	v_mfma_f32_32x32x16_bf16 v[0:15], v[188:191], v[184:187], v[0:15]
	s_setprio 0
	s_waitcnt vmcnt(0)
	s_barrier
;     ...
;     G_LOAD(x, 0);
;     G_STORE(x, 0);
;     __syncthreads();
;     if (KT > 1) G_LOAD(x, 1);
;     for (int kt = 0; kt < KT; kt += 2) {
;       if (kt + 2 < KT && dummy != 2) G_LOAD(y, kt + 2);
;       G_COMPUTE(0);
;       if (kt + 1 < KT && dummy != 2) G_STORE(x, 1);
;       __syncthreads();
;       if (kt + 1 >= KT) break;
;       if (kt + 3 < KT && dummy != 2) G_LOAD(x, kt + 3);
;       G_COMPUTE(1);
;       if (kt + 2 < KT && dummy != 2) G_STORE(y, 0);
;       __syncthreads();
;     }
	s_setprio 1
	ds_read_b128 v[156:159], v196 offset:32768
	ds_read_b128 v[164:167], v200 offset:32768
	ds_read_b128 v[168:171], v200 offset:36864
	ds_read_b128 v[172:175], v196 offset:36864
	ds_read_b128 v[176:179], v197 offset:32768
	ds_read_b128 v[180:183], v201 offset:32768
	ds_read_b128 v[184:187], v201 offset:36864
	ds_read_b128 v[188:191], v197 offset:36864
	s_add_u32 m0, s88, 0x600
	s_nop 0
	global_load_lds_dwordx4 v[138:139], off offset:512
	s_add_u32 m0, s88, 0x1600
	s_nop 0
	global_load_lds_dwordx4 v[142:143], off offset:512
	s_add_u32 m0, s88, 0x2600
	s_nop 0
	global_load_lds_dwordx4 v[144:145], off offset:512
	s_add_u32 m0, s88, 0x3600
	s_nop 0
	global_load_lds_dwordx4 v[152:153], off offset:512
	s_add_u32 m0, s88, 0x4600
	s_nop 0
	global_load_lds_dwordx4 v[140:141], off offset:512
	s_add_u32 m0, s88, 0x5600
	s_nop 0
	global_load_lds_dwordx4 v[146:147], off offset:512
	s_add_u32 m0, s88, 0x6600
	s_nop 0
	global_load_lds_dwordx4 v[148:149], off offset:512
	s_add_u32 m0, s88, 0x7600
	s_nop 0
	global_load_lds_dwordx4 v[150:151], off offset:512
	s_waitcnt lgkmcnt(6)
	v_mfma_f32_32x32x16_bf16 v[48:63], v[156:159], v[164:167], v[48:63]
	s_waitcnt lgkmcnt(5)
	v_mfma_f32_32x32x16_bf16 v[32:47], v[156:159], v[168:171], v[32:47]
	s_waitcnt lgkmcnt(4)
	v_mfma_f32_32x32x16_bf16 v[16:31], v[172:175], v[164:167], v[16:31]
	v_mfma_f32_32x32x16_bf16 v[0:15], v[172:175], v[168:171], v[0:15]
	ds_read_b128 v[156:159], v198 offset:32768
	ds_read_b128 v[164:167], v202 offset:32768
	ds_read_b128 v[168:171], v202 offset:36864
	ds_read_b128 v[172:175], v198 offset:36864
	s_waitcnt lgkmcnt(6)
	v_mfma_f32_32x32x16_bf16 v[48:63], v[176:179], v[180:183], v[48:63]
	s_waitcnt lgkmcnt(5)
	v_mfma_f32_32x32x16_bf16 v[32:47], v[176:179], v[184:187], v[32:47]
	s_waitcnt lgkmcnt(4)
	v_mfma_f32_32x32x16_bf16 v[16:31], v[188:191], v[180:183], v[16:31]
	v_mfma_f32_32x32x16_bf16 v[0:15], v[188:191], v[184:187], v[0:15]
	ds_read_b128 v[176:179], v199 offset:32768
	ds_read_b128 v[180:183], v203 offset:32768
	ds_read_b128 v[184:187], v203 offset:36864
	ds_read_b128 v[188:191], v199 offset:36864
	s_waitcnt lgkmcnt(6)
	v_mfma_f32_32x32x16_bf16 v[48:63], v[156:159], v[164:167], v[48:63]
	s_waitcnt lgkmcnt(5)
	v_mfma_f32_32x32x16_bf16 v[32:47], v[156:159], v[168:171], v[32:47]
	s_waitcnt lgkmcnt(4)
	v_mfma_f32_32x32x16_bf16 v[16:31], v[172:175], v[164:167], v[16:31]
	v_mfma_f32_32x32x16_bf16 v[0:15], v[172:175], v[168:171], v[0:15]
	s_waitcnt lgkmcnt(2)
	v_mfma_f32_32x32x16_bf16 v[48:63], v[176:179], v[180:183], v[48:63]
	s_waitcnt lgkmcnt(1)
	v_mfma_f32_32x32x16_bf16 v[32:47], v[176:179], v[184:187], v[32:47]
	s_waitcnt lgkmcnt(0)
	v_mfma_f32_32x32x16_bf16 v[16:31], v[188:191], v[180:183], v[16:31]
	v_mfma_f32_32x32x16_bf16 v[0:15], v[188:191], v[184:187], v[0:15]
	s_setprio 0
	s_waitcnt vmcnt(0)
	s_barrier
	s_setprio 1
	ds_read_b128 v[156:159], v196
	ds_read_b128 v[164:167], v200
	ds_read_b128 v[168:171], v200 offset:4096
	ds_read_b128 v[172:175], v196 offset:4096
	ds_read_b128 v[176:179], v197
	ds_read_b128 v[180:183], v201
	ds_read_b128 v[184:187], v201 offset:4096
	ds_read_b128 v[188:191], v197 offset:4096
	s_add_u32 m0, s88, 0x8580
	s_nop 0
	global_load_lds_dwordx4 v[138:139], off offset:640
	s_add_u32 m0, s88, 0x9580
	s_nop 0
	global_load_lds_dwordx4 v[142:143], off offset:640
	s_add_u32 m0, s88, 0xa580
	s_nop 0
	global_load_lds_dwordx4 v[144:145], off offset:640
	s_add_u32 m0, s88, 0xb580
	s_nop 0
	global_load_lds_dwordx4 v[152:153], off offset:640
	s_add_u32 m0, s88, 0xc580
	s_nop 0
	global_load_lds_dwordx4 v[140:141], off offset:640
	s_add_u32 m0, s88, 0xd580
	s_nop 0
	global_load_lds_dwordx4 v[146:147], off offset:640
	s_add_u32 m0, s88, 0xe580
	s_nop 0
	global_load_lds_dwordx4 v[148:149], off offset:640
	s_add_u32 m0, s88, 0xf580
	s_nop 0
	global_load_lds_dwordx4 v[150:151], off offset:640
	s_waitcnt lgkmcnt(6)
	v_mfma_f32_32x32x16_bf16 v[48:63], v[156:159], v[164:167], v[48:63]
	s_waitcnt lgkmcnt(5)
	v_mfma_f32_32x32x16_bf16 v[32:47], v[156:159], v[168:171], v[32:47]
	s_waitcnt lgkmcnt(4)
	v_mfma_f32_32x32x16_bf16 v[16:31], v[172:175], v[164:167], v[16:31]
	v_mfma_f32_32x32x16_bf16 v[0:15], v[172:175], v[168:171], v[0:15]
	ds_read_b128 v[156:159], v198
	ds_read_b128 v[164:167], v202
	ds_read_b128 v[168:171], v202 offset:4096
	ds_read_b128 v[172:175], v198 offset:4096
	s_waitcnt lgkmcnt(6)
	v_mfma_f32_32x32x16_bf16 v[48:63], v[176:179], v[180:183], v[48:63]
	s_waitcnt lgkmcnt(5)
	v_mfma_f32_32x32x16_bf16 v[32:47], v[176:179], v[184:187], v[32:47]
	s_waitcnt lgkmcnt(4)
	v_mfma_f32_32x32x16_bf16 v[16:31], v[188:191], v[180:183], v[16:31]
	v_mfma_f32_32x32x16_bf16 v[0:15], v[188:191], v[184:187], v[0:15]
	ds_read_b128 v[176:179], v199
	ds_read_b128 v[180:183], v203
	ds_read_b128 v[184:187], v203 offset:4096
	ds_read_b128 v[188:191], v199 offset:4096
	s_waitcnt lgkmcnt(6)
	v_mfma_f32_32x32x16_bf16 v[48:63], v[156:159], v[164:167], v[48:63]
	s_waitcnt lgkmcnt(5)
	v_mfma_f32_32x32x16_bf16 v[32:47], v[156:159], v[168:171], v[32:47]
	s_waitcnt lgkmcnt(4)
	v_mfma_f32_32x32x16_bf16 v[16:31], v[172:175], v[164:167], v[16:31]
	v_mfma_f32_32x32x16_bf16 v[0:15], v[172:175], v[168:171], v[0:15]
	s_waitcnt lgkmcnt(2)
	v_mfma_f32_32x32x16_bf16 v[48:63], v[176:179], v[180:183], v[48:63]
	s_waitcnt lgkmcnt(1)
	v_mfma_f32_32x32x16_bf16 v[32:47], v[176:179], v[184:187], v[32:47]
	s_waitcnt lgkmcnt(0)
	v_mfma_f32_32x32x16_bf16 v[16:31], v[188:191], v[180:183], v[16:31]
	v_mfma_f32_32x32x16_bf16 v[0:15], v[188:191], v[184:187], v[0:15]
	s_setprio 0
	s_waitcnt vmcnt(0)
	s_barrier
;     ...
;     G_LOAD(x, 0);
;     G_STORE(x, 0);
;     __syncthreads();
;     if (KT > 1) G_LOAD(x, 1);
;     for (int kt = 0; kt < KT; kt += 2) {
;       if (kt + 2 < KT && dummy != 2) G_LOAD(y, kt + 2);
;       G_COMPUTE(0);
;       if (kt + 1 < KT && dummy != 2) G_STORE(x, 1);
;       __syncthreads();
;       if (kt + 1 >= KT) break;
;       if (kt + 3 < KT && dummy != 2) G_LOAD(x, kt + 3);
;       G_COMPUTE(1);
;       if (kt + 2 < KT && dummy != 2) G_STORE(y, 0);
;       __syncthreads();
;     }
	s_setprio 1
	ds_read_b128 v[156:159], v196 offset:32768
	ds_read_b128 v[164:167], v200 offset:32768
	ds_read_b128 v[168:171], v200 offset:36864
	ds_read_b128 v[172:175], v196 offset:36864
	ds_read_b128 v[176:179], v197 offset:32768
	ds_read_b128 v[180:183], v201 offset:32768
	ds_read_b128 v[184:187], v201 offset:36864
	ds_read_b128 v[188:191], v197 offset:36864
	s_add_u32 m0, s88, 0x500
	s_nop 0
	global_load_lds_dwordx4 v[138:139], off offset:768
	s_add_u32 m0, s88, 0x1500
	s_nop 0
	global_load_lds_dwordx4 v[142:143], off offset:768
	s_add_u32 m0, s88, 0x2500
	s_nop 0
	global_load_lds_dwordx4 v[144:145], off offset:768
	s_add_u32 m0, s88, 0x3500
	s_nop 0
	global_load_lds_dwordx4 v[152:153], off offset:768
	s_add_u32 m0, s88, 0x4500
	s_nop 0
	global_load_lds_dwordx4 v[140:141], off offset:768
	s_add_u32 m0, s88, 0x5500
	s_nop 0
	global_load_lds_dwordx4 v[146:147], off offset:768
	s_add_u32 m0, s88, 0x6500
	s_nop 0
	global_load_lds_dwordx4 v[148:149], off offset:768
	s_add_u32 m0, s88, 0x7500
	s_nop 0
	global_load_lds_dwordx4 v[150:151], off offset:768
	s_waitcnt lgkmcnt(6)
	v_mfma_f32_32x32x16_bf16 v[48:63], v[156:159], v[164:167], v[48:63]
	s_waitcnt lgkmcnt(5)
	v_mfma_f32_32x32x16_bf16 v[32:47], v[156:159], v[168:171], v[32:47]
	s_waitcnt lgkmcnt(4)
	v_mfma_f32_32x32x16_bf16 v[16:31], v[172:175], v[164:167], v[16:31]
	v_mfma_f32_32x32x16_bf16 v[0:15], v[172:175], v[168:171], v[0:15]
	ds_read_b128 v[156:159], v198 offset:32768
	ds_read_b128 v[164:167], v202 offset:32768
	ds_read_b128 v[168:171], v202 offset:36864
	ds_read_b128 v[172:175], v198 offset:36864
	s_waitcnt lgkmcnt(6)
	v_mfma_f32_32x32x16_bf16 v[48:63], v[176:179], v[180:183], v[48:63]
	s_waitcnt lgkmcnt(5)
	v_mfma_f32_32x32x16_bf16 v[32:47], v[176:179], v[184:187], v[32:47]
	s_waitcnt lgkmcnt(4)
	v_mfma_f32_32x32x16_bf16 v[16:31], v[188:191], v[180:183], v[16:31]
	v_mfma_f32_32x32x16_bf16 v[0:15], v[188:191], v[184:187], v[0:15]
	ds_read_b128 v[176:179], v199 offset:32768
	ds_read_b128 v[180:183], v203 offset:32768
	ds_read_b128 v[184:187], v203 offset:36864
	ds_read_b128 v[188:191], v199 offset:36864
	s_waitcnt lgkmcnt(6)
	v_mfma_f32_32x32x16_bf16 v[48:63], v[156:159], v[164:167], v[48:63]
	s_waitcnt lgkmcnt(5)
	v_mfma_f32_32x32x16_bf16 v[32:47], v[156:159], v[168:171], v[32:47]
	s_waitcnt lgkmcnt(4)
	v_mfma_f32_32x32x16_bf16 v[16:31], v[172:175], v[164:167], v[16:31]
	v_mfma_f32_32x32x16_bf16 v[0:15], v[172:175], v[168:171], v[0:15]
	s_waitcnt lgkmcnt(2)
	v_mfma_f32_32x32x16_bf16 v[48:63], v[176:179], v[180:183], v[48:63]
	s_waitcnt lgkmcnt(1)
	v_mfma_f32_32x32x16_bf16 v[32:47], v[176:179], v[184:187], v[32:47]
	s_waitcnt lgkmcnt(0)
	v_mfma_f32_32x32x16_bf16 v[16:31], v[188:191], v[180:183], v[16:31]
	v_mfma_f32_32x32x16_bf16 v[0:15], v[188:191], v[184:187], v[0:15]
	s_setprio 0
	s_waitcnt vmcnt(0)
	s_barrier
	s_setprio 1
	ds_read_b128 v[156:159], v196
	ds_read_b128 v[164:167], v200
	ds_read_b128 v[168:171], v200 offset:4096
	ds_read_b128 v[172:175], v196 offset:4096
	ds_read_b128 v[176:179], v197
	ds_read_b128 v[180:183], v201
	ds_read_b128 v[184:187], v201 offset:4096
	ds_read_b128 v[188:191], v197 offset:4096
	s_add_u32 m0, s88, 0x8480
	s_nop 0
	global_load_lds_dwordx4 v[138:139], off offset:896
	s_add_u32 m0, s88, 0x9480
	s_nop 0
	global_load_lds_dwordx4 v[142:143], off offset:896
	s_add_u32 m0, s88, 0xa480
	s_nop 0
	global_load_lds_dwordx4 v[144:145], off offset:896
	s_add_u32 m0, s88, 0xb480
	s_nop 0
	global_load_lds_dwordx4 v[152:153], off offset:896
	s_add_u32 m0, s88, 0xc480
	s_nop 0
	global_load_lds_dwordx4 v[140:141], off offset:896
	s_add_u32 m0, s88, 0xd480
	s_nop 0
	global_load_lds_dwordx4 v[146:147], off offset:896
	s_add_u32 m0, s88, 0xe480
	s_nop 0
	global_load_lds_dwordx4 v[148:149], off offset:896
	s_add_u32 m0, s88, 0xf480
	s_nop 0
	global_load_lds_dwordx4 v[150:151], off offset:896
	s_waitcnt lgkmcnt(6)
	v_mfma_f32_32x32x16_bf16 v[48:63], v[156:159], v[164:167], v[48:63]
	s_waitcnt lgkmcnt(5)
	v_mfma_f32_32x32x16_bf16 v[32:47], v[156:159], v[168:171], v[32:47]
	s_waitcnt lgkmcnt(4)
	v_mfma_f32_32x32x16_bf16 v[16:31], v[172:175], v[164:167], v[16:31]
	v_mfma_f32_32x32x16_bf16 v[0:15], v[172:175], v[168:171], v[0:15]
	ds_read_b128 v[156:159], v198
	ds_read_b128 v[164:167], v202
	ds_read_b128 v[168:171], v202 offset:4096
	ds_read_b128 v[172:175], v198 offset:4096
	s_waitcnt lgkmcnt(6)
	v_mfma_f32_32x32x16_bf16 v[48:63], v[176:179], v[180:183], v[48:63]
	s_waitcnt lgkmcnt(5)
	v_mfma_f32_32x32x16_bf16 v[32:47], v[176:179], v[184:187], v[32:47]
	s_waitcnt lgkmcnt(4)
	v_mfma_f32_32x32x16_bf16 v[16:31], v[188:191], v[180:183], v[16:31]
	v_mfma_f32_32x32x16_bf16 v[0:15], v[188:191], v[184:187], v[0:15]
	ds_read_b128 v[176:179], v199
	ds_read_b128 v[180:183], v203
	ds_read_b128 v[184:187], v203 offset:4096
	ds_read_b128 v[188:191], v199 offset:4096
	s_waitcnt lgkmcnt(6)
	v_mfma_f32_32x32x16_bf16 v[48:63], v[156:159], v[164:167], v[48:63]
	s_waitcnt lgkmcnt(5)
	v_mfma_f32_32x32x16_bf16 v[32:47], v[156:159], v[168:171], v[32:47]
	s_waitcnt lgkmcnt(4)
	v_mfma_f32_32x32x16_bf16 v[16:31], v[172:175], v[164:167], v[16:31]
	v_mfma_f32_32x32x16_bf16 v[0:15], v[172:175], v[168:171], v[0:15]
	s_waitcnt lgkmcnt(2)
	v_mfma_f32_32x32x16_bf16 v[48:63], v[176:179], v[180:183], v[48:63]
	s_waitcnt lgkmcnt(1)
	v_mfma_f32_32x32x16_bf16 v[32:47], v[176:179], v[184:187], v[32:47]
	s_waitcnt lgkmcnt(0)
	v_mfma_f32_32x32x16_bf16 v[16:31], v[188:191], v[180:183], v[16:31]
	v_mfma_f32_32x32x16_bf16 v[0:15], v[188:191], v[184:187], v[0:15]
	s_setprio 0
	s_waitcnt vmcnt(0)
	s_barrier
;     ...
;     G_LOAD(x, 0);
;     G_STORE(x, 0);
;     __syncthreads();
;     if (KT > 1) G_LOAD(x, 1);
;     for (int kt = 0; kt < KT; kt += 2) {
;       if (kt + 2 < KT && dummy != 2) G_LOAD(y, kt + 2);
;       G_COMPUTE(0);
;       if (kt + 1 < KT && dummy != 2) G_STORE(x, 1);
;       __syncthreads();
;       if (kt + 1 >= KT) break;
;       if (kt + 3 < KT && dummy != 2) G_LOAD(x, kt + 3);
;       G_COMPUTE(1);
;       if (kt + 2 < KT && dummy != 2) G_STORE(y, 0);
;       __syncthreads();
;     }
	s_setprio 1
	ds_read_b128 v[156:159], v196 offset:32768
	ds_read_b128 v[164:167], v200 offset:32768
	ds_read_b128 v[168:171], v200 offset:36864
	ds_read_b128 v[172:175], v196 offset:36864
	ds_read_b128 v[176:179], v197 offset:32768
	ds_read_b128 v[180:183], v201 offset:32768
	ds_read_b128 v[184:187], v201 offset:36864
	ds_read_b128 v[188:191], v197 offset:36864
	s_add_u32 m0, s88, 0x400
	s_nop 0
	global_load_lds_dwordx4 v[138:139], off offset:1024
	s_add_u32 m0, s88, 0x1400
	s_nop 0
	global_load_lds_dwordx4 v[142:143], off offset:1024
	s_add_u32 m0, s88, 0x2400
	s_nop 0
	global_load_lds_dwordx4 v[144:145], off offset:1024
	s_add_u32 m0, s88, 0x3400
	s_nop 0
	global_load_lds_dwordx4 v[152:153], off offset:1024
	s_add_u32 m0, s88, 0x4400
	s_nop 0
	global_load_lds_dwordx4 v[140:141], off offset:1024
	s_add_u32 m0, s88, 0x5400
	s_nop 0
	global_load_lds_dwordx4 v[146:147], off offset:1024
	s_add_u32 m0, s88, 0x6400
	s_nop 0
	global_load_lds_dwordx4 v[148:149], off offset:1024
	s_add_u32 m0, s88, 0x7400
	s_nop 0
	global_load_lds_dwordx4 v[150:151], off offset:1024
	s_waitcnt lgkmcnt(6)
	v_mfma_f32_32x32x16_bf16 v[48:63], v[156:159], v[164:167], v[48:63]
	s_waitcnt lgkmcnt(5)
	v_mfma_f32_32x32x16_bf16 v[32:47], v[156:159], v[168:171], v[32:47]
	s_waitcnt lgkmcnt(4)
	v_mfma_f32_32x32x16_bf16 v[16:31], v[172:175], v[164:167], v[16:31]
	v_mfma_f32_32x32x16_bf16 v[0:15], v[172:175], v[168:171], v[0:15]
	ds_read_b128 v[156:159], v198 offset:32768
	ds_read_b128 v[164:167], v202 offset:32768
	ds_read_b128 v[168:171], v202 offset:36864
	ds_read_b128 v[172:175], v198 offset:36864
	s_waitcnt lgkmcnt(6)
	v_mfma_f32_32x32x16_bf16 v[48:63], v[176:179], v[180:183], v[48:63]
	s_waitcnt lgkmcnt(5)
	v_mfma_f32_32x32x16_bf16 v[32:47], v[176:179], v[184:187], v[32:47]
	s_waitcnt lgkmcnt(4)
	v_mfma_f32_32x32x16_bf16 v[16:31], v[188:191], v[180:183], v[16:31]
	v_mfma_f32_32x32x16_bf16 v[0:15], v[188:191], v[184:187], v[0:15]
	ds_read_b128 v[176:179], v199 offset:32768
	ds_read_b128 v[180:183], v203 offset:32768
	ds_read_b128 v[184:187], v203 offset:36864
	ds_read_b128 v[188:191], v199 offset:36864
	s_waitcnt lgkmcnt(6)
	v_mfma_f32_32x32x16_bf16 v[48:63], v[156:159], v[164:167], v[48:63]
	s_waitcnt lgkmcnt(5)
	v_mfma_f32_32x32x16_bf16 v[32:47], v[156:159], v[168:171], v[32:47]
	s_waitcnt lgkmcnt(4)
	v_mfma_f32_32x32x16_bf16 v[16:31], v[172:175], v[164:167], v[16:31]
	v_mfma_f32_32x32x16_bf16 v[0:15], v[172:175], v[168:171], v[0:15]
	s_waitcnt lgkmcnt(2)
	v_mfma_f32_32x32x16_bf16 v[48:63], v[176:179], v[180:183], v[48:63]
	s_waitcnt lgkmcnt(1)
	v_mfma_f32_32x32x16_bf16 v[32:47], v[176:179], v[184:187], v[32:47]
	s_waitcnt lgkmcnt(0)
	v_mfma_f32_32x32x16_bf16 v[16:31], v[188:191], v[180:183], v[16:31]
	v_mfma_f32_32x32x16_bf16 v[0:15], v[188:191], v[184:187], v[0:15]
	s_setprio 0
	s_waitcnt vmcnt(0)
	s_barrier
	s_setprio 1
	ds_read_b128 v[156:159], v196
	ds_read_b128 v[164:167], v200
	ds_read_b128 v[168:171], v200 offset:4096
	ds_read_b128 v[172:175], v196 offset:4096
	ds_read_b128 v[176:179], v197
	ds_read_b128 v[180:183], v201
	ds_read_b128 v[184:187], v201 offset:4096
	ds_read_b128 v[188:191], v197 offset:4096
	s_add_u32 m0, s88, 0x8380
	s_nop 0
	global_load_lds_dwordx4 v[138:139], off offset:1152
	s_add_u32 m0, s88, 0x9380
	s_nop 0
	global_load_lds_dwordx4 v[142:143], off offset:1152
	s_add_u32 m0, s88, 0xa380
	s_nop 0
	global_load_lds_dwordx4 v[144:145], off offset:1152
	s_add_u32 m0, s88, 0xb380
	s_nop 0
	global_load_lds_dwordx4 v[152:153], off offset:1152
	s_add_u32 m0, s88, 0xc380
	s_nop 0
	global_load_lds_dwordx4 v[140:141], off offset:1152
	s_add_u32 m0, s88, 0xd380
	s_nop 0
	global_load_lds_dwordx4 v[146:147], off offset:1152
	s_add_u32 m0, s88, 0xe380
	s_nop 0
	global_load_lds_dwordx4 v[148:149], off offset:1152
	s_add_u32 m0, s88, 0xf380
	s_nop 0
	global_load_lds_dwordx4 v[150:151], off offset:1152
	s_waitcnt lgkmcnt(6)
	v_mfma_f32_32x32x16_bf16 v[48:63], v[156:159], v[164:167], v[48:63]
	s_waitcnt lgkmcnt(5)
	v_mfma_f32_32x32x16_bf16 v[32:47], v[156:159], v[168:171], v[32:47]
	s_waitcnt lgkmcnt(4)
	v_mfma_f32_32x32x16_bf16 v[16:31], v[172:175], v[164:167], v[16:31]
	v_mfma_f32_32x32x16_bf16 v[0:15], v[172:175], v[168:171], v[0:15]
	ds_read_b128 v[156:159], v198
	ds_read_b128 v[164:167], v202
	ds_read_b128 v[168:171], v202 offset:4096
	ds_read_b128 v[172:175], v198 offset:4096
	s_waitcnt lgkmcnt(6)
	v_mfma_f32_32x32x16_bf16 v[48:63], v[176:179], v[180:183], v[48:63]
	s_waitcnt lgkmcnt(5)
	v_mfma_f32_32x32x16_bf16 v[32:47], v[176:179], v[184:187], v[32:47]
	s_waitcnt lgkmcnt(4)
	v_mfma_f32_32x32x16_bf16 v[16:31], v[188:191], v[180:183], v[16:31]
	v_mfma_f32_32x32x16_bf16 v[0:15], v[188:191], v[184:187], v[0:15]
	ds_read_b128 v[176:179], v199
	ds_read_b128 v[180:183], v203
	ds_read_b128 v[184:187], v203 offset:4096
	ds_read_b128 v[188:191], v199 offset:4096
	s_waitcnt lgkmcnt(6)
	v_mfma_f32_32x32x16_bf16 v[48:63], v[156:159], v[164:167], v[48:63]
	s_waitcnt lgkmcnt(5)
	v_mfma_f32_32x32x16_bf16 v[32:47], v[156:159], v[168:171], v[32:47]
	s_waitcnt lgkmcnt(4)
	v_mfma_f32_32x32x16_bf16 v[16:31], v[172:175], v[164:167], v[16:31]
	v_mfma_f32_32x32x16_bf16 v[0:15], v[172:175], v[168:171], v[0:15]
	s_waitcnt lgkmcnt(2)
	v_mfma_f32_32x32x16_bf16 v[48:63], v[176:179], v[180:183], v[48:63]
	s_waitcnt lgkmcnt(1)
	v_mfma_f32_32x32x16_bf16 v[32:47], v[176:179], v[184:187], v[32:47]
	s_waitcnt lgkmcnt(0)
	v_mfma_f32_32x32x16_bf16 v[16:31], v[188:191], v[180:183], v[16:31]
	v_mfma_f32_32x32x16_bf16 v[0:15], v[188:191], v[184:187], v[0:15]
	s_setprio 0
	s_waitcnt vmcnt(0)
	s_barrier
;     ...
;     G_LOAD(x, 0);
;     G_STORE(x, 0);
;     __syncthreads();
;     if (KT > 1) G_LOAD(x, 1);
;     for (int kt = 0; kt < KT; kt += 2) {
;       if (kt + 2 < KT && dummy != 2) G_LOAD(y, kt + 2);
;       G_COMPUTE(0);
;       if (kt + 1 < KT && dummy != 2) G_STORE(x, 1);
;       __syncthreads();
;       if (kt + 1 >= KT) break;
;       if (kt + 3 < KT && dummy != 2) G_LOAD(x, kt + 3);
;       G_COMPUTE(1);
;       if (kt + 2 < KT && dummy != 2) G_STORE(y, 0);
;       __syncthreads();
;     }
	s_setprio 1
	ds_read_b128 v[156:159], v196 offset:32768
	ds_read_b128 v[164:167], v200 offset:32768
	ds_read_b128 v[168:171], v200 offset:36864
	ds_read_b128 v[172:175], v196 offset:36864
	ds_read_b128 v[176:179], v197 offset:32768
	ds_read_b128 v[180:183], v201 offset:32768
	ds_read_b128 v[184:187], v201 offset:36864
	ds_read_b128 v[188:191], v197 offset:36864
	s_add_u32 m0, s88, 0x300
	s_nop 0
	global_load_lds_dwordx4 v[138:139], off offset:1280
	s_add_u32 m0, s88, 0x1300
	s_nop 0
	global_load_lds_dwordx4 v[142:143], off offset:1280
	s_add_u32 m0, s88, 0x2300
	s_nop 0
	global_load_lds_dwordx4 v[144:145], off offset:1280
	s_add_u32 m0, s88, 0x3300
	s_nop 0
	global_load_lds_dwordx4 v[152:153], off offset:1280
	s_add_u32 m0, s88, 0x4300
	s_nop 0
	global_load_lds_dwordx4 v[140:141], off offset:1280
	s_add_u32 m0, s88, 0x5300
	s_nop 0
	global_load_lds_dwordx4 v[146:147], off offset:1280
	s_add_u32 m0, s88, 0x6300
	s_nop 0
	global_load_lds_dwordx4 v[148:149], off offset:1280
	s_add_u32 m0, s88, 0x7300
	s_nop 0
	global_load_lds_dwordx4 v[150:151], off offset:1280
	s_waitcnt lgkmcnt(6)
	v_mfma_f32_32x32x16_bf16 v[48:63], v[156:159], v[164:167], v[48:63]
	s_waitcnt lgkmcnt(5)
	v_mfma_f32_32x32x16_bf16 v[32:47], v[156:159], v[168:171], v[32:47]
	s_waitcnt lgkmcnt(4)
	v_mfma_f32_32x32x16_bf16 v[16:31], v[172:175], v[164:167], v[16:31]
	v_mfma_f32_32x32x16_bf16 v[0:15], v[172:175], v[168:171], v[0:15]
	ds_read_b128 v[156:159], v198 offset:32768
	ds_read_b128 v[164:167], v202 offset:32768
	ds_read_b128 v[168:171], v202 offset:36864
	ds_read_b128 v[172:175], v198 offset:36864
	s_waitcnt lgkmcnt(6)
	v_mfma_f32_32x32x16_bf16 v[48:63], v[176:179], v[180:183], v[48:63]
	s_waitcnt lgkmcnt(5)
	v_mfma_f32_32x32x16_bf16 v[32:47], v[176:179], v[184:187], v[32:47]
	s_waitcnt lgkmcnt(4)
	v_mfma_f32_32x32x16_bf16 v[16:31], v[188:191], v[180:183], v[16:31]
	v_mfma_f32_32x32x16_bf16 v[0:15], v[188:191], v[184:187], v[0:15]
	ds_read_b128 v[176:179], v199 offset:32768
	ds_read_b128 v[180:183], v203 offset:32768
	ds_read_b128 v[184:187], v203 offset:36864
	ds_read_b128 v[188:191], v199 offset:36864
	s_waitcnt lgkmcnt(6)
	v_mfma_f32_32x32x16_bf16 v[48:63], v[156:159], v[164:167], v[48:63]
	s_waitcnt lgkmcnt(5)
	v_mfma_f32_32x32x16_bf16 v[32:47], v[156:159], v[168:171], v[32:47]
	s_waitcnt lgkmcnt(4)
	v_mfma_f32_32x32x16_bf16 v[16:31], v[172:175], v[164:167], v[16:31]
	v_mfma_f32_32x32x16_bf16 v[0:15], v[172:175], v[168:171], v[0:15]
	s_waitcnt lgkmcnt(2)
	v_mfma_f32_32x32x16_bf16 v[48:63], v[176:179], v[180:183], v[48:63]
	s_waitcnt lgkmcnt(1)
	v_mfma_f32_32x32x16_bf16 v[32:47], v[176:179], v[184:187], v[32:47]
	s_waitcnt lgkmcnt(0)
	v_mfma_f32_32x32x16_bf16 v[16:31], v[188:191], v[180:183], v[16:31]
	v_mfma_f32_32x32x16_bf16 v[0:15], v[188:191], v[184:187], v[0:15]
	s_setprio 0
	s_waitcnt vmcnt(0)
	s_barrier
	s_setprio 1
	ds_read_b128 v[156:159], v196
	ds_read_b128 v[164:167], v200
	ds_read_b128 v[168:171], v200 offset:4096
	ds_read_b128 v[172:175], v196 offset:4096
	ds_read_b128 v[176:179], v197
	ds_read_b128 v[180:183], v201
	ds_read_b128 v[184:187], v201 offset:4096
	ds_read_b128 v[188:191], v197 offset:4096
	s_add_u32 m0, s88, 0x8280
	s_nop 0
	global_load_lds_dwordx4 v[138:139], off offset:1408
	s_add_u32 m0, s88, 0x9280
	s_nop 0
	global_load_lds_dwordx4 v[142:143], off offset:1408
	s_add_u32 m0, s88, 0xa280
	s_nop 0
	global_load_lds_dwordx4 v[144:145], off offset:1408
	s_add_u32 m0, s88, 0xb280
	s_nop 0
	global_load_lds_dwordx4 v[152:153], off offset:1408
	s_add_u32 m0, s88, 0xc280
	s_nop 0
	global_load_lds_dwordx4 v[140:141], off offset:1408
	s_add_u32 m0, s88, 0xd280
	s_nop 0
	global_load_lds_dwordx4 v[146:147], off offset:1408
	s_add_u32 m0, s88, 0xe280
	s_nop 0
	global_load_lds_dwordx4 v[148:149], off offset:1408
	s_add_u32 m0, s88, 0xf280
	s_nop 0
	global_load_lds_dwordx4 v[150:151], off offset:1408
	s_waitcnt lgkmcnt(6)
	v_mfma_f32_32x32x16_bf16 v[48:63], v[156:159], v[164:167], v[48:63]
	s_waitcnt lgkmcnt(5)
	v_mfma_f32_32x32x16_bf16 v[32:47], v[156:159], v[168:171], v[32:47]
	s_waitcnt lgkmcnt(4)
	v_mfma_f32_32x32x16_bf16 v[16:31], v[172:175], v[164:167], v[16:31]
	v_mfma_f32_32x32x16_bf16 v[0:15], v[172:175], v[168:171], v[0:15]
	ds_read_b128 v[156:159], v198
	ds_read_b128 v[164:167], v202
	ds_read_b128 v[168:171], v202 offset:4096
	ds_read_b128 v[172:175], v198 offset:4096
	s_waitcnt lgkmcnt(6)
	v_mfma_f32_32x32x16_bf16 v[48:63], v[176:179], v[180:183], v[48:63]
	s_waitcnt lgkmcnt(5)
	v_mfma_f32_32x32x16_bf16 v[32:47], v[176:179], v[184:187], v[32:47]
	s_waitcnt lgkmcnt(4)
	v_mfma_f32_32x32x16_bf16 v[16:31], v[188:191], v[180:183], v[16:31]
	v_mfma_f32_32x32x16_bf16 v[0:15], v[188:191], v[184:187], v[0:15]
	ds_read_b128 v[176:179], v199
	ds_read_b128 v[180:183], v203
	ds_read_b128 v[184:187], v203 offset:4096
	ds_read_b128 v[188:191], v199 offset:4096
	s_waitcnt lgkmcnt(6)
	v_mfma_f32_32x32x16_bf16 v[48:63], v[156:159], v[164:167], v[48:63]
	s_waitcnt lgkmcnt(5)
	v_mfma_f32_32x32x16_bf16 v[32:47], v[156:159], v[168:171], v[32:47]
	s_waitcnt lgkmcnt(4)
	v_mfma_f32_32x32x16_bf16 v[16:31], v[172:175], v[164:167], v[16:31]
	v_mfma_f32_32x32x16_bf16 v[0:15], v[172:175], v[168:171], v[0:15]
	s_waitcnt lgkmcnt(2)
	v_mfma_f32_32x32x16_bf16 v[48:63], v[176:179], v[180:183], v[48:63]
	s_waitcnt lgkmcnt(1)
	v_mfma_f32_32x32x16_bf16 v[32:47], v[176:179], v[184:187], v[32:47]
	s_waitcnt lgkmcnt(0)
	v_mfma_f32_32x32x16_bf16 v[16:31], v[188:191], v[180:183], v[16:31]
	v_mfma_f32_32x32x16_bf16 v[0:15], v[188:191], v[184:187], v[0:15]
	s_setprio 0
	s_waitcnt vmcnt(0)
	s_barrier
;     ...
;     G_LOAD(x, 0);
;     G_STORE(x, 0);
;     __syncthreads();
;     if (KT > 1) G_LOAD(x, 1);
;     for (int kt = 0; kt < KT; kt += 2) {
;       if (kt + 2 < KT && dummy != 2) G_LOAD(y, kt + 2);
;       G_COMPUTE(0);
;       if (kt + 1 < KT && dummy != 2) G_STORE(x, 1);
;       __syncthreads();
;       if (kt + 1 >= KT) break;
;       if (kt + 3 < KT && dummy != 2) G_LOAD(x, kt + 3);
;       G_COMPUTE(1);
;       if (kt + 2 < KT && dummy != 2) G_STORE(y, 0);
;       __syncthreads();
;     }
	s_setprio 1
	ds_read_b128 v[156:159], v196 offset:32768
	ds_read_b128 v[164:167], v200 offset:32768
	ds_read_b128 v[168:171], v200 offset:36864
	ds_read_b128 v[172:175], v196 offset:36864
	ds_read_b128 v[176:179], v197 offset:32768
	ds_read_b128 v[180:183], v201 offset:32768
	ds_read_b128 v[184:187], v201 offset:36864
	ds_read_b128 v[188:191], v197 offset:36864
	s_add_u32 m0, s88, 0x200
	s_nop 0
	global_load_lds_dwordx4 v[138:139], off offset:1536
	s_add_u32 m0, s88, 0x1200
	s_nop 0
	global_load_lds_dwordx4 v[142:143], off offset:1536
	s_add_u32 m0, s88, 0x2200
	s_nop 0
	global_load_lds_dwordx4 v[144:145], off offset:1536
	s_add_u32 m0, s88, 0x3200
	s_nop 0
	global_load_lds_dwordx4 v[152:153], off offset:1536
	s_add_u32 m0, s88, 0x4200
	s_nop 0
	global_load_lds_dwordx4 v[140:141], off offset:1536
	s_add_u32 m0, s88, 0x5200
	s_nop 0
	global_load_lds_dwordx4 v[146:147], off offset:1536
	s_add_u32 m0, s88, 0x6200
	s_nop 0
	global_load_lds_dwordx4 v[148:149], off offset:1536
	s_add_u32 m0, s88, 0x7200
	s_nop 0
	global_load_lds_dwordx4 v[150:151], off offset:1536
	s_waitcnt lgkmcnt(6)
	v_mfma_f32_32x32x16_bf16 v[48:63], v[156:159], v[164:167], v[48:63]
	s_waitcnt lgkmcnt(5)
	v_mfma_f32_32x32x16_bf16 v[32:47], v[156:159], v[168:171], v[32:47]
	s_waitcnt lgkmcnt(4)
	v_mfma_f32_32x32x16_bf16 v[16:31], v[172:175], v[164:167], v[16:31]
	v_mfma_f32_32x32x16_bf16 v[0:15], v[172:175], v[168:171], v[0:15]
	ds_read_b128 v[156:159], v198 offset:32768
	ds_read_b128 v[164:167], v202 offset:32768
	ds_read_b128 v[168:171], v202 offset:36864
	ds_read_b128 v[172:175], v198 offset:36864
	s_waitcnt lgkmcnt(6)
	v_mfma_f32_32x32x16_bf16 v[48:63], v[176:179], v[180:183], v[48:63]
	s_waitcnt lgkmcnt(5)
	v_mfma_f32_32x32x16_bf16 v[32:47], v[176:179], v[184:187], v[32:47]
	s_waitcnt lgkmcnt(4)
	v_mfma_f32_32x32x16_bf16 v[16:31], v[188:191], v[180:183], v[16:31]
	v_mfma_f32_32x32x16_bf16 v[0:15], v[188:191], v[184:187], v[0:15]
	ds_read_b128 v[176:179], v199 offset:32768
	ds_read_b128 v[180:183], v203 offset:32768
	ds_read_b128 v[184:187], v203 offset:36864
	ds_read_b128 v[188:191], v199 offset:36864
	s_waitcnt lgkmcnt(6)
	v_mfma_f32_32x32x16_bf16 v[48:63], v[156:159], v[164:167], v[48:63]
	s_waitcnt lgkmcnt(5)
	v_mfma_f32_32x32x16_bf16 v[32:47], v[156:159], v[168:171], v[32:47]
	s_waitcnt lgkmcnt(4)
	v_mfma_f32_32x32x16_bf16 v[16:31], v[172:175], v[164:167], v[16:31]
	v_mfma_f32_32x32x16_bf16 v[0:15], v[172:175], v[168:171], v[0:15]
	s_waitcnt lgkmcnt(2)
	v_mfma_f32_32x32x16_bf16 v[48:63], v[176:179], v[180:183], v[48:63]
	s_waitcnt lgkmcnt(1)
	v_mfma_f32_32x32x16_bf16 v[32:47], v[176:179], v[184:187], v[32:47]
	s_waitcnt lgkmcnt(0)
	v_mfma_f32_32x32x16_bf16 v[16:31], v[188:191], v[180:183], v[16:31]
	v_mfma_f32_32x32x16_bf16 v[0:15], v[188:191], v[184:187], v[0:15]
	s_setprio 0
	s_waitcnt vmcnt(0)
	s_barrier
	s_setprio 1
	ds_read_b128 v[156:159], v196
	ds_read_b128 v[164:167], v200
	ds_read_b128 v[168:171], v200 offset:4096
	ds_read_b128 v[172:175], v196 offset:4096
	ds_read_b128 v[176:179], v197
	ds_read_b128 v[180:183], v201
	ds_read_b128 v[184:187], v201 offset:4096
	ds_read_b128 v[188:191], v197 offset:4096
	s_add_u32 m0, s88, 0x8180
	s_nop 0
	global_load_lds_dwordx4 v[138:139], off offset:1664
	s_add_u32 m0, s88, 0x9180
	s_nop 0
	global_load_lds_dwordx4 v[142:143], off offset:1664
	s_add_u32 m0, s88, 0xa180
	s_nop 0
	global_load_lds_dwordx4 v[144:145], off offset:1664
	s_add_u32 m0, s88, 0xb180
	s_nop 0
	global_load_lds_dwordx4 v[152:153], off offset:1664
	s_add_u32 m0, s88, 0xc180
	s_nop 0
	global_load_lds_dwordx4 v[140:141], off offset:1664
	s_add_u32 m0, s88, 0xd180
	s_nop 0
	global_load_lds_dwordx4 v[146:147], off offset:1664
	s_add_u32 m0, s88, 0xe180
	s_nop 0
	global_load_lds_dwordx4 v[148:149], off offset:1664
	s_add_u32 m0, s88, 0xf180
	s_nop 0
	global_load_lds_dwordx4 v[150:151], off offset:1664
	s_waitcnt lgkmcnt(6)
	v_mfma_f32_32x32x16_bf16 v[48:63], v[156:159], v[164:167], v[48:63]
	s_waitcnt lgkmcnt(5)
	v_mfma_f32_32x32x16_bf16 v[32:47], v[156:159], v[168:171], v[32:47]
	s_waitcnt lgkmcnt(4)
	v_mfma_f32_32x32x16_bf16 v[16:31], v[172:175], v[164:167], v[16:31]
	v_mfma_f32_32x32x16_bf16 v[0:15], v[172:175], v[168:171], v[0:15]
	ds_read_b128 v[156:159], v198
	ds_read_b128 v[164:167], v202
	ds_read_b128 v[168:171], v202 offset:4096
	ds_read_b128 v[172:175], v198 offset:4096
	s_waitcnt lgkmcnt(6)
	v_mfma_f32_32x32x16_bf16 v[48:63], v[176:179], v[180:183], v[48:63]
	s_waitcnt lgkmcnt(5)
	v_mfma_f32_32x32x16_bf16 v[32:47], v[176:179], v[184:187], v[32:47]
	s_waitcnt lgkmcnt(4)
	v_mfma_f32_32x32x16_bf16 v[16:31], v[188:191], v[180:183], v[16:31]
	v_mfma_f32_32x32x16_bf16 v[0:15], v[188:191], v[184:187], v[0:15]
	ds_read_b128 v[176:179], v199
	ds_read_b128 v[180:183], v203
	ds_read_b128 v[184:187], v203 offset:4096
	ds_read_b128 v[188:191], v199 offset:4096
	s_waitcnt lgkmcnt(6)
	v_mfma_f32_32x32x16_bf16 v[48:63], v[156:159], v[164:167], v[48:63]
	s_waitcnt lgkmcnt(5)
	v_mfma_f32_32x32x16_bf16 v[32:47], v[156:159], v[168:171], v[32:47]
	s_waitcnt lgkmcnt(4)
	v_mfma_f32_32x32x16_bf16 v[16:31], v[172:175], v[164:167], v[16:31]
	v_mfma_f32_32x32x16_bf16 v[0:15], v[172:175], v[168:171], v[0:15]
	s_waitcnt lgkmcnt(2)
	v_mfma_f32_32x32x16_bf16 v[48:63], v[176:179], v[180:183], v[48:63]
	s_waitcnt lgkmcnt(1)
	v_mfma_f32_32x32x16_bf16 v[32:47], v[176:179], v[184:187], v[32:47]
	s_waitcnt lgkmcnt(0)
	v_mfma_f32_32x32x16_bf16 v[16:31], v[188:191], v[180:183], v[16:31]
	v_mfma_f32_32x32x16_bf16 v[0:15], v[188:191], v[184:187], v[0:15]
	s_setprio 0
	s_waitcnt vmcnt(0)
	s_barrier
;     ...
;     G_LOAD(x, 0);
;     G_STORE(x, 0);
;     __syncthreads();
;     if (KT > 1) G_LOAD(x, 1);
;     for (int kt = 0; kt < KT; kt += 2) {
;       if (kt + 2 < KT && dummy != 2) G_LOAD(y, kt + 2);
;       G_COMPUTE(0);
;       if (kt + 1 < KT && dummy != 2) G_STORE(x, 1);
;       __syncthreads();
;       if (kt + 1 >= KT) break;
;       if (kt + 3 < KT && dummy != 2) G_LOAD(x, kt + 3);
;       G_COMPUTE(1);
;       if (kt + 2 < KT && dummy != 2) G_STORE(y, 0);
;       __syncthreads();
;     }
	s_setprio 1
	ds_read_b128 v[156:159], v196 offset:32768
	ds_read_b128 v[164:167], v200 offset:32768
	ds_read_b128 v[168:171], v200 offset:36864
	ds_read_b128 v[172:175], v196 offset:36864
	ds_read_b128 v[176:179], v197 offset:32768
	ds_read_b128 v[180:183], v201 offset:32768
	ds_read_b128 v[184:187], v201 offset:36864
	ds_read_b128 v[188:191], v197 offset:36864
	s_add_u32 m0, s88, 0x100
	s_nop 0
	global_load_lds_dwordx4 v[138:139], off offset:1792
	s_add_u32 m0, s88, 0x1100
	s_nop 0
	global_load_lds_dwordx4 v[142:143], off offset:1792
	s_add_u32 m0, s88, 0x2100
	s_nop 0
	global_load_lds_dwordx4 v[144:145], off offset:1792
	s_add_u32 m0, s88, 0x3100
	s_nop 0
	global_load_lds_dwordx4 v[152:153], off offset:1792
	s_add_u32 m0, s88, 0x4100
	s_nop 0
	global_load_lds_dwordx4 v[140:141], off offset:1792
	s_add_u32 m0, s88, 0x5100
	s_nop 0
	global_load_lds_dwordx4 v[146:147], off offset:1792
	s_add_u32 m0, s88, 0x6100
	s_nop 0
	global_load_lds_dwordx4 v[148:149], off offset:1792
	s_add_u32 m0, s88, 0x7100
	s_nop 0
	global_load_lds_dwordx4 v[150:151], off offset:1792
	s_waitcnt lgkmcnt(6)
	v_mfma_f32_32x32x16_bf16 v[48:63], v[156:159], v[164:167], v[48:63]
	s_waitcnt lgkmcnt(5)
	v_mfma_f32_32x32x16_bf16 v[32:47], v[156:159], v[168:171], v[32:47]
	s_waitcnt lgkmcnt(4)
	v_mfma_f32_32x32x16_bf16 v[16:31], v[172:175], v[164:167], v[16:31]
	v_mfma_f32_32x32x16_bf16 v[0:15], v[172:175], v[168:171], v[0:15]
	ds_read_b128 v[156:159], v198 offset:32768
	ds_read_b128 v[164:167], v202 offset:32768
	ds_read_b128 v[168:171], v202 offset:36864
	ds_read_b128 v[172:175], v198 offset:36864
	s_waitcnt lgkmcnt(6)
	v_mfma_f32_32x32x16_bf16 v[48:63], v[176:179], v[180:183], v[48:63]
	s_waitcnt lgkmcnt(5)
	v_mfma_f32_32x32x16_bf16 v[32:47], v[176:179], v[184:187], v[32:47]
	s_waitcnt lgkmcnt(4)
	v_mfma_f32_32x32x16_bf16 v[16:31], v[188:191], v[180:183], v[16:31]
	v_mfma_f32_32x32x16_bf16 v[0:15], v[188:191], v[184:187], v[0:15]
	ds_read_b128 v[176:179], v199 offset:32768
	ds_read_b128 v[180:183], v203 offset:32768
	ds_read_b128 v[184:187], v203 offset:36864
	ds_read_b128 v[188:191], v199 offset:36864
	s_waitcnt lgkmcnt(6)
	v_mfma_f32_32x32x16_bf16 v[48:63], v[156:159], v[164:167], v[48:63]
	s_waitcnt lgkmcnt(5)
	v_mfma_f32_32x32x16_bf16 v[32:47], v[156:159], v[168:171], v[32:47]
	s_waitcnt lgkmcnt(4)
	v_mfma_f32_32x32x16_bf16 v[16:31], v[172:175], v[164:167], v[16:31]
	v_mfma_f32_32x32x16_bf16 v[0:15], v[172:175], v[168:171], v[0:15]
	s_waitcnt lgkmcnt(2)
	v_mfma_f32_32x32x16_bf16 v[48:63], v[176:179], v[180:183], v[48:63]
	s_waitcnt lgkmcnt(1)
	v_mfma_f32_32x32x16_bf16 v[32:47], v[176:179], v[184:187], v[32:47]
	s_waitcnt lgkmcnt(0)
	v_mfma_f32_32x32x16_bf16 v[16:31], v[188:191], v[180:183], v[16:31]
	v_mfma_f32_32x32x16_bf16 v[0:15], v[188:191], v[184:187], v[0:15]
	s_setprio 0
	s_waitcnt vmcnt(0)
	s_barrier
	s_setprio 1
	ds_read_b128 v[156:159], v196
	ds_read_b128 v[164:167], v200
	ds_read_b128 v[168:171], v200 offset:4096
	ds_read_b128 v[172:175], v196 offset:4096
	ds_read_b128 v[176:179], v197
	ds_read_b128 v[180:183], v201
	ds_read_b128 v[184:187], v201 offset:4096
	ds_read_b128 v[188:191], v197 offset:4096
	s_add_u32 m0, s88, 0x8080
	s_nop 0
	global_load_lds_dwordx4 v[138:139], off offset:1920
	s_add_u32 m0, s88, 0x9080
	s_nop 0
	global_load_lds_dwordx4 v[142:143], off offset:1920
	s_add_u32 m0, s88, 0xa080
	s_nop 0
	global_load_lds_dwordx4 v[144:145], off offset:1920
	s_add_u32 m0, s88, 0xb080
	s_nop 0
	global_load_lds_dwordx4 v[152:153], off offset:1920
	s_add_u32 m0, s88, 0xc080
	s_nop 0
	global_load_lds_dwordx4 v[140:141], off offset:1920
	s_add_u32 m0, s88, 0xd080
	s_nop 0
	global_load_lds_dwordx4 v[146:147], off offset:1920
	s_add_u32 m0, s88, 0xe080
	s_nop 0
	global_load_lds_dwordx4 v[148:149], off offset:1920
	s_add_u32 m0, s88, 0xf080
	s_nop 0
	global_load_lds_dwordx4 v[150:151], off offset:1920
	s_waitcnt lgkmcnt(6)
	v_mfma_f32_32x32x16_bf16 v[48:63], v[156:159], v[164:167], v[48:63]
	s_waitcnt lgkmcnt(5)
	v_mfma_f32_32x32x16_bf16 v[32:47], v[156:159], v[168:171], v[32:47]
	s_waitcnt lgkmcnt(4)
	v_mfma_f32_32x32x16_bf16 v[16:31], v[172:175], v[164:167], v[16:31]
	v_mfma_f32_32x32x16_bf16 v[0:15], v[172:175], v[168:171], v[0:15]
	ds_read_b128 v[156:159], v198
	ds_read_b128 v[164:167], v202
	ds_read_b128 v[168:171], v202 offset:4096
	ds_read_b128 v[172:175], v198 offset:4096
	s_waitcnt lgkmcnt(6)
	v_mfma_f32_32x32x16_bf16 v[48:63], v[176:179], v[180:183], v[48:63]
	s_waitcnt lgkmcnt(5)
	v_mfma_f32_32x32x16_bf16 v[32:47], v[176:179], v[184:187], v[32:47]
	s_waitcnt lgkmcnt(4)
	v_mfma_f32_32x32x16_bf16 v[16:31], v[188:191], v[180:183], v[16:31]
	v_mfma_f32_32x32x16_bf16 v[0:15], v[188:191], v[184:187], v[0:15]
	ds_read_b128 v[176:179], v199
	ds_read_b128 v[180:183], v203
	ds_read_b128 v[184:187], v203 offset:4096
	ds_read_b128 v[188:191], v199 offset:4096
	s_waitcnt lgkmcnt(6)
	v_mfma_f32_32x32x16_bf16 v[48:63], v[156:159], v[164:167], v[48:63]
	s_waitcnt lgkmcnt(5)
	v_mfma_f32_32x32x16_bf16 v[32:47], v[156:159], v[168:171], v[32:47]
	s_waitcnt lgkmcnt(4)
	v_mfma_f32_32x32x16_bf16 v[16:31], v[172:175], v[164:167], v[16:31]
	v_mfma_f32_32x32x16_bf16 v[0:15], v[172:175], v[168:171], v[0:15]
	s_waitcnt lgkmcnt(2)
	v_mfma_f32_32x32x16_bf16 v[48:63], v[176:179], v[180:183], v[48:63]
	s_waitcnt lgkmcnt(1)
	v_mfma_f32_32x32x16_bf16 v[32:47], v[176:179], v[184:187], v[32:47]
	s_waitcnt lgkmcnt(0)
	v_mfma_f32_32x32x16_bf16 v[16:31], v[188:191], v[180:183], v[16:31]
	v_mfma_f32_32x32x16_bf16 v[0:15], v[188:191], v[184:187], v[0:15]
	s_setprio 0
	s_waitcnt vmcnt(0)
	s_barrier
;     ...
;     } else if (EPI == EPI_RES1 || EPI == EPI_RES2) {
;       const int b = m0e / TALL, t0 = m0e - b * TALL;
;       const bool isctx = t0 < CTX;
;       float* xb = isctx ? P.zctx + ((size_t)(b * CTX + t0)) * D : P.out + ((size_t)(b * SEQ + t0 - CTX)) * D;
;       const float* g = P.mod + ((size_t)(l * 17 + (isctx ? 16 : b))) * 6144 + (EPI == EPI_RES1 ? 2 * D : 5 * D);
;       const float* xs = (EPI == EPI_RES1 && l == 0) ? (isctx ? P.ctx + ((size_t)(b * CTX + t0)) * D : P.x + ((size_t)(b * SEQ + t0 - CTX)) * D) : xb;
;       const float gv0 = g[n0e + cb], gv1 = g[n0e + cb + 32];
;       const bool haveln = !(EPI == EPI_RES1 && l == 0);
;       const float* lgp = (EPI == EPI_RES1) ? P.post2_g + (size_t)(l > 0 ? l - 1 : 0) * D : P.post1_g + (size_t)l * D;
;       const float* lbp = (EPI == EPI_RES1) ? P.post2_b + (size_t)(l > 0 ? l - 1 : 0) * D : P.post1_b + (size_t)l * D;
;       const float lg0 = lgp[n0e + cb], lg1 = lgp[n0e + cb + 32], lb0 = lbp[n0e + cb], lb1 = lbp[n0e + cb + 32];
	s_setprio 1
	ds_read_b128 v[156:159], v196 offset:32768
	ds_read_b128 v[164:167], v200 offset:32768
	ds_read_b128 v[168:171], v200 offset:36864
	ds_read_b128 v[172:175], v196 offset:36864
	ds_read_b128 v[176:179], v197 offset:32768
	ds_read_b128 v[180:183], v201 offset:32768
	ds_read_b128 v[184:187], v201 offset:36864
	ds_read_b128 v[188:191], v197 offset:36864
	s_waitcnt lgkmcnt(6)
	v_mfma_f32_32x32x16_bf16 v[48:63], v[156:159], v[164:167], v[48:63]
	s_waitcnt lgkmcnt(5)
	v_mfma_f32_32x32x16_bf16 v[32:47], v[156:159], v[168:171], v[32:47]
	s_waitcnt lgkmcnt(4)
	v_mfma_f32_32x32x16_bf16 v[16:31], v[172:175], v[164:167], v[16:31]
	v_mfma_f32_32x32x16_bf16 v[0:15], v[172:175], v[168:171], v[0:15]
	ds_read_b128 v[156:159], v198 offset:32768
	ds_read_b128 v[164:167], v202 offset:32768
	ds_read_b128 v[168:171], v202 offset:36864
	ds_read_b128 v[172:175], v198 offset:36864
	s_waitcnt lgkmcnt(6)
	v_mfma_f32_32x32x16_bf16 v[48:63], v[176:179], v[180:183], v[48:63]
	s_waitcnt lgkmcnt(5)
	v_mfma_f32_32x32x16_bf16 v[32:47], v[176:179], v[184:187], v[32:47]
	s_waitcnt lgkmcnt(4)
	v_mfma_f32_32x32x16_bf16 v[16:31], v[188:191], v[180:183], v[16:31]
	v_mfma_f32_32x32x16_bf16 v[0:15], v[188:191], v[184:187], v[0:15]
	ds_read_b128 v[176:179], v199 offset:32768
	ds_read_b128 v[180:183], v203 offset:32768
	ds_read_b128 v[184:187], v203 offset:36864
	ds_read_b128 v[188:191], v199 offset:36864
	s_waitcnt lgkmcnt(6)
	v_mfma_f32_32x32x16_bf16 v[48:63], v[156:159], v[164:167], v[48:63]
	s_waitcnt lgkmcnt(5)
	v_mfma_f32_32x32x16_bf16 v[32:47], v[156:159], v[168:171], v[32:47]
	s_waitcnt lgkmcnt(4)
	v_mfma_f32_32x32x16_bf16 v[16:31], v[172:175], v[164:167], v[16:31]
	v_mfma_f32_32x32x16_bf16 v[0:15], v[172:175], v[168:171], v[0:15]
	s_waitcnt lgkmcnt(2)
	v_mfma_f32_32x32x16_bf16 v[48:63], v[176:179], v[180:183], v[48:63]
	s_waitcnt lgkmcnt(1)
	v_mfma_f32_32x32x16_bf16 v[32:47], v[176:179], v[184:187], v[32:47]
	s_waitcnt lgkmcnt(0)
	v_mfma_f32_32x32x16_bf16 v[16:31], v[188:191], v[180:183], v[16:31]
	v_mfma_f32_32x32x16_bf16 v[0:15], v[188:191], v[184:187], v[0:15]
	s_setprio 0
	s_barrier
	s_mul_hi_i32 s1, s14, 0x38e38e39
	s_lshr_b32 s2, s1, 31
	s_ashr_i32 s1, s1, 9
	s_add_i32 s1, s1, s2
	s_mul_i32 s15, s1, 0xfffff700
	s_add_i32 s15, s15, s14
	s_cmpk_gt_i32 s15, 0xff
	s_cselect_b64 s[76:77], -1, 0
	v_mov_b32_e32 v78, v155
	v_mov_b32_e32 v72, v96
	s_and_b64 vcc, exec, s[76:77]
	s_cbranch_vccz .LBB0_237
	s_lshl_b32 s2, s1, 11
	v_readlane_b32 s16, v253, 0
	s_add_i32 s2, s2, s15
	v_readlane_b32 s26, v253, 10
	v_readlane_b32 s27, v253, 11
	s_add_i32 s34, s2, 0xffffff00
	v_readlane_b32 s17, v253, 1
	v_readlane_b32 s18, v253, 2
	v_readlane_b32 s19, v253, 3
	v_readlane_b32 s20, v253, 4
	v_readlane_b32 s21, v253, 5
	v_readlane_b32 s22, v253, 6
	v_readlane_b32 s23, v253, 7
	v_readlane_b32 s24, v253, 8
	v_readlane_b32 s25, v253, 9
	v_readlane_b32 s28, v253, 12
	v_readlane_b32 s29, v253, 13
	v_readlane_b32 s30, v253, 14
	v_readlane_b32 s31, v253, 15
	s_mov_b64 s[2:3], s[26:27]
	s_mov_b32 s16, s1
	s_cbranch_execz .LBB0_238
	s_branch .LBB0_239

;     ...
;     const int mi_ = swz ? (mq * 8 + (bid & 7)) : mq;
;     const int mt = latent_only ? ((mi_ >> 4) * 18 + 2 + (mi_ & 15)) : mi_;
;     const int m0 = mt * 128, n0 = nt * 128;
;     f32x16 acc[2][2];
; #pragma unroll
;     for (int a = 0; a < 2; ++a)
; #pragma unroll
;       for (int b = 0; b < 2; ++b)
; #pragma unroll
;         for (int i = 0; i < 16; ++i) acc[a][b][i] = 0.f;
;     const u16* Ag = A + (size_t)(m0 + lrow) * K + lkc * 8;
;     const u16* Bg = Bt + (size_t)(n0 + lrow) * K + lkc * 8;
;     const size_t K32 = (size_t)32 * K;
;     uint4 xa0, xa1, xa2, xa3, xb0, xb1, xb2, xb3;
;     uint4 ya0, ya1, ya2, ya3, yb0, yb1, yb2, yb3;
;     ...
;     G_LOAD(x, 0);
;     G_STORE(x, 0);
;     __syncthreads();
;     if (KT > 1) G_LOAD(x, 1);
;     for (int kt = 0; kt < KT; kt += 2) {
;       if (kt + 2 < KT && dummy != 2) G_LOAD(y, kt + 2);
;       G_COMPUTE(0);
.LBB0_257:
	v_readlane_b32 s0, v252, 34
	s_or_b32 s4, s4, s0
	v_readlane_b32 s0, v252, 28
	v_readlane_b32 s1, v252, 29
	s_and_b64 s[0:1], s[0:1], exec
	s_cselect_b32 s0, s4, s3
	s_lshr_b32 s1, s0, 4
	s_mul_i32 s1, s1, 18
	s_and_b32 s0, s0, 15
	s_add_i32 s0, s0, s1
	s_lshl_b32 s0, s0, 7
	s_add_i32 s11, s0, 0x100
	s_lshl_b32 s0, s2, 7
	v_add_u32_e32 v0, s11, v154
	v_ashrrev_i32_e32 v1, 31, v0
	v_lshlrev_b64 v[0:1], 11, v[0:1]
	v_lshl_add_u64 v[138:139], v[130:131], 0, v[0:1]
	v_add_u32_e32 v0, s0, v154
	v_ashrrev_i32_e32 v1, 31, v0
	v_lshlrev_b64 v[0:1], 11, v[0:1]
	v_lshl_add_u64 v[140:141], v[132:133], 0, v[0:1]
	v_and_b32_e32 v204, 7, v206
	v_bfe_u32 v205, v206, 4, 3
	v_xor_b32_e32 v205, v205, v204
	v_sub_u32_e32 v205, v205, v204
	v_lshlrev_b32_e32 v198, 4, v205
	v_ashrrev_i32_e32 v199, 31, v198
	v_lshl_add_u64 v[138:139], v[138:139], 0, v[198:199]
	v_lshl_add_u64 v[140:141], v[140:141], 0, v[198:199]
	s_mov_b64 s[78:79], 0x10000
	v_lshl_add_u64 v[142:143], v[138:139], 0, s[78:79]
	v_lshl_add_u64 v[146:147], v[140:141], 0, s[78:79]
	s_mov_b64 s[78:79], 0x20000
	v_lshl_add_u64 v[144:145], v[138:139], 0, s[78:79]
	v_lshl_add_u64 v[148:149], v[140:141], 0, s[78:79]
	s_mov_b64 s[78:79], 0x30000
	v_lshl_add_u64 v[152:153], v[138:139], 0, s[78:79]
	v_lshl_add_u64 v[150:151], v[140:141], 0, s[78:79]
	v_lshrrev_b32_e32 v204, 6, v206
	v_lshlrev_b32_e32 v204, 10, v204
	s_nop 0
	v_readfirstlane_b32 s76, v204
	v_bfe_u32 v205, v206, 1, 3
	v_bfe_u32 v204, v206, 5, 1
	v_and_b32_e32 v198, 1, v205
	v_xor_b32_e32 v204, v204, v198
	v_lshrrev_b32_e32 v205, 1, v205
	v_and_b32_e32 v198, 31, v206
	v_lshrrev_b32_e32 v199, 7, v206
	v_lshl_add_u32 v199, v199, 6, v198
	v_lshlrev_b32_e32 v199, 7, v199
	v_lshl_add_u32 v199, v204, 4, v199
	v_add_u32_e32 v199, 2048, v199
	v_bfe_u32 v200, v206, 6, 1
	v_lshl_add_u32 v200, v200, 6, v198
	v_lshlrev_b32_e32 v200, 7, v200
	v_lshl_add_u32 v200, v204, 4, v200
	v_add_u32_e32 v200, 18432, v200
	v_xor_b32_e32 v198, 0, v205
	v_lshl_add_u32 v240, v198, 5, v199
	v_lshl_add_u32 v244, v198, 5, v200
	v_xor_b32_e32 v198, 1, v205
	v_lshl_add_u32 v241, v198, 5, v199
	v_lshl_add_u32 v245, v198, 5, v200
	v_xor_b32_e32 v198, 2, v205
	v_lshl_add_u32 v242, v198, 5, v199
	v_lshl_add_u32 v246, v198, 5, v200
	v_xor_b32_e32 v198, 3, v205
	v_lshl_add_u32 v243, v198, 5, v199
	v_lshl_add_u32 v247, v198, 5, v200
	s_add_u32 m0, s76, 0x800
	s_nop 0
	global_load_lds_dwordx4 v[138:139], off
	s_add_u32 m0, s76, 0x1800
	s_nop 0
	global_load_lds_dwordx4 v[142:143], off
	s_add_u32 m0, s76, 0x2800
	s_nop 0
	global_load_lds_dwordx4 v[144:145], off
	s_add_u32 m0, s76, 0x3800
	s_nop 0
	global_load_lds_dwordx4 v[152:153], off
	s_add_u32 m0, s76, 0x4800
	s_nop 0
	global_load_lds_dwordx4 v[140:141], off
	s_add_u32 m0, s76, 0x5800
	s_nop 0
	global_load_lds_dwordx4 v[146:147], off
	s_add_u32 m0, s76, 0x6800
	s_nop 0
	global_load_lds_dwordx4 v[148:149], off
	s_add_u32 m0, s76, 0x7800
	s_nop 0
	global_load_lds_dwordx4 v[150:151], off
	s_waitcnt vmcnt(0)
	s_barrier
	s_setprio 1
	ds_read_b128 v[156:159], v240
	ds_read_b128 v[164:167], v244
	ds_read_b128 v[168:171], v244 offset:4096
	ds_read_b128 v[200:203], v240 offset:4096
	ds_read_b128 v[224:227], v241
	ds_read_b128 v[228:231], v245
	ds_read_b128 v[232:235], v245 offset:4096
	ds_read_b128 v[236:239], v241 offset:4096
	s_add_u32 m0, s76, 0x8780
	s_nop 0
	global_load_lds_dwordx4 v[138:139], off offset:128
	s_add_u32 m0, s76, 0x9780
	s_nop 0
	global_load_lds_dwordx4 v[142:143], off offset:128
	s_add_u32 m0, s76, 0xa780
	s_nop 0
	global_load_lds_dwordx4 v[144:145], off offset:128
	s_add_u32 m0, s76, 0xb780
	s_nop 0
	global_load_lds_dwordx4 v[152:153], off offset:128
	s_add_u32 m0, s76, 0xc780
	s_nop 0
	global_load_lds_dwordx4 v[140:141], off offset:128
	s_add_u32 m0, s76, 0xd780
	s_nop 0
	global_load_lds_dwordx4 v[146:147], off offset:128
	s_add_u32 m0, s76, 0xe780
	s_nop 0
	global_load_lds_dwordx4 v[148:149], off offset:128
	s_add_u32 m0, s76, 0xf780
	s_nop 0
	global_load_lds_dwordx4 v[150:151], off offset:128
	s_waitcnt lgkmcnt(6)
	v_mfma_f32_32x32x16_bf16 v[48:63], v[156:159], v[164:167], 0
	s_waitcnt lgkmcnt(5)
	v_mfma_f32_32x32x16_bf16 v[32:47], v[156:159], v[168:171], 0
	s_waitcnt lgkmcnt(4)
	v_mfma_f32_32x32x16_bf16 v[16:31], v[200:203], v[164:167], 0
	v_mfma_f32_32x32x16_bf16 v[0:15], v[200:203], v[168:171], 0
	ds_read_b128 v[156:159], v242
	ds_read_b128 v[164:167], v246
	ds_read_b128 v[168:171], v246 offset:4096
	ds_read_b128 v[200:203], v242 offset:4096
	s_waitcnt lgkmcnt(6)
	v_mfma_f32_32x32x16_bf16 v[48:63], v[224:227], v[228:231], v[48:63]
	s_waitcnt lgkmcnt(5)
	v_mfma_f32_32x32x16_bf16 v[32:47], v[224:227], v[232:235], v[32:47]
	s_waitcnt lgkmcnt(4)
	v_mfma_f32_32x32x16_bf16 v[16:31], v[236:239], v[228:231], v[16:31]
	v_mfma_f32_32x32x16_bf16 v[0:15], v[236:239], v[232:235], v[0:15]
	ds_read_b128 v[224:227], v243
	ds_read_b128 v[228:231], v247
	ds_read_b128 v[232:235], v247 offset:4096
	ds_read_b128 v[236:239], v243 offset:4096
	s_waitcnt lgkmcnt(6)
	v_mfma_f32_32x32x16_bf16 v[48:63], v[156:159], v[164:167], v[48:63]
	s_waitcnt lgkmcnt(5)
	v_mfma_f32_32x32x16_bf16 v[32:47], v[156:159], v[168:171], v[32:47]
	s_waitcnt lgkmcnt(4)
	v_mfma_f32_32x32x16_bf16 v[16:31], v[200:203], v[164:167], v[16:31]
	v_mfma_f32_32x32x16_bf16 v[0:15], v[200:203], v[168:171], v[0:15]
	s_waitcnt lgkmcnt(2)
	v_mfma_f32_32x32x16_bf16 v[48:63], v[224:227], v[228:231], v[48:63]
	s_waitcnt lgkmcnt(1)
	v_mfma_f32_32x32x16_bf16 v[32:47], v[224:227], v[232:235], v[32:47]
	s_waitcnt lgkmcnt(0)
	v_mfma_f32_32x32x16_bf16 v[16:31], v[236:239], v[228:231], v[16:31]
	v_mfma_f32_32x32x16_bf16 v[0:15], v[236:239], v[232:235], v[0:15]
	s_setprio 0
	s_waitcnt vmcnt(0)
	s_barrier
;     ...
;     G_LOAD(x, 0);
;     G_STORE(x, 0);
;     __syncthreads();
;     if (KT > 1) G_LOAD(x, 1);
;     for (int kt = 0; kt < KT; kt += 2) {
;       if (kt + 2 < KT && dummy != 2) G_LOAD(y, kt + 2);
;       G_COMPUTE(0);
;       if (kt + 1 < KT && dummy != 2) G_STORE(x, 1);
;       __syncthreads();
;       if (kt + 1 >= KT) break;
;       if (kt + 3 < KT && dummy != 2) G_LOAD(x, kt + 3);
;       G_COMPUTE(1);
;       if (kt + 2 < KT && dummy != 2) G_STORE(y, 0);
;       __syncthreads();
;     }
	s_setprio 1
	ds_read_b128 v[156:159], v240 offset:32768
	ds_read_b128 v[164:167], v244 offset:32768
	ds_read_b128 v[168:171], v244 offset:36864
	ds_read_b128 v[200:203], v240 offset:36864
	ds_read_b128 v[224:227], v241 offset:32768
	ds_read_b128 v[228:231], v245 offset:32768
	ds_read_b128 v[232:235], v245 offset:36864
	ds_read_b128 v[236:239], v241 offset:36864
	s_add_u32 m0, s76, 0x700
	s_nop 0
	global_load_lds_dwordx4 v[138:139], off offset:256
	s_add_u32 m0, s76, 0x1700
	s_nop 0
	global_load_lds_dwordx4 v[142:143], off offset:256
	s_add_u32 m0, s76, 0x2700
	s_nop 0
	global_load_lds_dwordx4 v[144:145], off offset:256
	s_add_u32 m0, s76, 0x3700
	s_nop 0
	global_load_lds_dwordx4 v[152:153], off offset:256
	s_add_u32 m0, s76, 0x4700
	s_nop 0
	global_load_lds_dwordx4 v[140:141], off offset:256
	s_add_u32 m0, s76, 0x5700
	s_nop 0
	global_load_lds_dwordx4 v[146:147], off offset:256
	s_add_u32 m0, s76, 0x6700
	s_nop 0
	global_load_lds_dwordx4 v[148:149], off offset:256
	s_add_u32 m0, s76, 0x7700
	s_nop 0
	global_load_lds_dwordx4 v[150:151], off offset:256
	s_waitcnt lgkmcnt(6)
	v_mfma_f32_32x32x16_bf16 v[48:63], v[156:159], v[164:167], v[48:63]
	s_waitcnt lgkmcnt(5)
	v_mfma_f32_32x32x16_bf16 v[32:47], v[156:159], v[168:171], v[32:47]
	s_waitcnt lgkmcnt(4)
	v_mfma_f32_32x32x16_bf16 v[16:31], v[200:203], v[164:167], v[16:31]
	v_mfma_f32_32x32x16_bf16 v[0:15], v[200:203], v[168:171], v[0:15]
	ds_read_b128 v[156:159], v242 offset:32768
	ds_read_b128 v[164:167], v246 offset:32768
	ds_read_b128 v[168:171], v246 offset:36864
	ds_read_b128 v[200:203], v242 offset:36864
	s_waitcnt lgkmcnt(6)
	v_mfma_f32_32x32x16_bf16 v[48:63], v[224:227], v[228:231], v[48:63]
	s_waitcnt lgkmcnt(5)
	v_mfma_f32_32x32x16_bf16 v[32:47], v[224:227], v[232:235], v[32:47]
	s_waitcnt lgkmcnt(4)
	v_mfma_f32_32x32x16_bf16 v[16:31], v[236:239], v[228:231], v[16:31]
	v_mfma_f32_32x32x16_bf16 v[0:15], v[236:239], v[232:235], v[0:15]
	ds_read_b128 v[224:227], v243 offset:32768
	ds_read_b128 v[228:231], v247 offset:32768
	ds_read_b128 v[232:235], v247 offset:36864
	ds_read_b128 v[236:239], v243 offset:36864
	s_waitcnt lgkmcnt(6)
	v_mfma_f32_32x32x16_bf16 v[48:63], v[156:159], v[164:167], v[48:63]
	s_waitcnt lgkmcnt(5)
	v_mfma_f32_32x32x16_bf16 v[32:47], v[156:159], v[168:171], v[32:47]
	s_waitcnt lgkmcnt(4)
	v_mfma_f32_32x32x16_bf16 v[16:31], v[200:203], v[164:167], v[16:31]
	v_mfma_f32_32x32x16_bf16 v[0:15], v[200:203], v[168:171], v[0:15]
	s_waitcnt lgkmcnt(2)
	v_mfma_f32_32x32x16_bf16 v[48:63], v[224:227], v[228:231], v[48:63]
	s_waitcnt lgkmcnt(1)
	v_mfma_f32_32x32x16_bf16 v[32:47], v[224:227], v[232:235], v[32:47]
	s_waitcnt lgkmcnt(0)
	v_mfma_f32_32x32x16_bf16 v[16:31], v[236:239], v[228:231], v[16:31]
	v_mfma_f32_32x32x16_bf16 v[0:15], v[236:239], v[232:235], v[0:15]
	s_setprio 0
	s_waitcnt vmcnt(0)
	s_barrier
	s_setprio 1
	ds_read_b128 v[156:159], v240
	ds_read_b128 v[164:167], v244
	ds_read_b128 v[168:171], v244 offset:4096
	ds_read_b128 v[200:203], v240 offset:4096
	ds_read_b128 v[224:227], v241
	ds_read_b128 v[228:231], v245
	ds_read_b128 v[232:235], v245 offset:4096
	ds_read_b128 v[236:239], v241 offset:4096
	s_add_u32 m0, s76, 0x8680
	s_nop 0
	global_load_lds_dwordx4 v[138:139], off offset:384
	s_add_u32 m0, s76, 0x9680
	s_nop 0
	global_load_lds_dwordx4 v[142:143], off offset:384
	s_add_u32 m0, s76, 0xa680
	s_nop 0
	global_load_lds_dwordx4 v[144:145], off offset:384
	s_add_u32 m0, s76, 0xb680
	s_nop 0
	global_load_lds_dwordx4 v[152:153], off offset:384
	s_add_u32 m0, s76, 0xc680
	s_nop 0
	global_load_lds_dwordx4 v[140:141], off offset:384
	s_add_u32 m0, s76, 0xd680
	s_nop 0
	global_load_lds_dwordx4 v[146:147], off offset:384
	s_add_u32 m0, s76, 0xe680
	s_nop 0
	global_load_lds_dwordx4 v[148:149], off offset:384
	s_add_u32 m0, s76, 0xf680
	s_nop 0
	global_load_lds_dwordx4 v[150:151], off offset:384
	s_waitcnt lgkmcnt(6)
	v_mfma_f32_32x32x16_bf16 v[48:63], v[156:159], v[164:167], v[48:63]
	s_waitcnt lgkmcnt(5)
	v_mfma_f32_32x32x16_bf16 v[32:47], v[156:159], v[168:171], v[32:47]
	s_waitcnt lgkmcnt(4)
	v_mfma_f32_32x32x16_bf16 v[16:31], v[200:203], v[164:167], v[16:31]
	v_mfma_f32_32x32x16_bf16 v[0:15], v[200:203], v[168:171], v[0:15]
	ds_read_b128 v[156:159], v242
	ds_read_b128 v[164:167], v246
	ds_read_b128 v[168:171], v246 offset:4096
	ds_read_b128 v[200:203], v242 offset:4096
	s_waitcnt lgkmcnt(6)
	v_mfma_f32_32x32x16_bf16 v[48:63], v[224:227], v[228:231], v[48:63]
	s_waitcnt lgkmcnt(5)
	v_mfma_f32_32x32x16_bf16 v[32:47], v[224:227], v[232:235], v[32:47]
	s_waitcnt lgkmcnt(4)
	v_mfma_f32_32x32x16_bf16 v[16:31], v[236:239], v[228:231], v[16:31]
	v_mfma_f32_32x32x16_bf16 v[0:15], v[236:239], v[232:235], v[0:15]
	ds_read_b128 v[224:227], v243
	ds_read_b128 v[228:231], v247
	ds_read_b128 v[232:235], v247 offset:4096
	ds_read_b128 v[236:239], v243 offset:4096
	s_waitcnt lgkmcnt(6)
	v_mfma_f32_32x32x16_bf16 v[48:63], v[156:159], v[164:167], v[48:63]
	s_waitcnt lgkmcnt(5)
	v_mfma_f32_32x32x16_bf16 v[32:47], v[156:159], v[168:171], v[32:47]
	s_waitcnt lgkmcnt(4)
	v_mfma_f32_32x32x16_bf16 v[16:31], v[200:203], v[164:167], v[16:31]
	v_mfma_f32_32x32x16_bf16 v[0:15], v[200:203], v[168:171], v[0:15]
	s_waitcnt lgkmcnt(2)
	v_mfma_f32_32x32x16_bf16 v[48:63], v[224:227], v[228:231], v[48:63]
	s_waitcnt lgkmcnt(1)
	v_mfma_f32_32x32x16_bf16 v[32:47], v[224:227], v[232:235], v[32:47]
	s_waitcnt lgkmcnt(0)
	v_mfma_f32_32x32x16_bf16 v[16:31], v[236:239], v[228:231], v[16:31]
	v_mfma_f32_32x32x16_bf16 v[0:15], v[236:239], v[232:235], v[0:15]
	s_setprio 0
	s_waitcnt vmcnt(0)
	s_barrier
;     ...
;     G_LOAD(x, 0);
;     G_STORE(x, 0);
;     __syncthreads();
;     if (KT > 1) G_LOAD(x, 1);
;     for (int kt = 0; kt < KT; kt += 2) {
;       if (kt + 2 < KT && dummy != 2) G_LOAD(y, kt + 2);
;       G_COMPUTE(0);
;       if (kt + 1 < KT && dummy != 2) G_STORE(x, 1);
;       __syncthreads();
;       if (kt + 1 >= KT) break;
;       if (kt + 3 < KT && dummy != 2) G_LOAD(x, kt + 3);
;       G_COMPUTE(1);
;       if (kt + 2 < KT && dummy != 2) G_STORE(y, 0);
;       __syncthreads();
	s_setprio 1
	ds_read_b128 v[156:159], v240 offset:32768
	ds_read_b128 v[164:167], v244 offset:32768
	ds_read_b128 v[168:171], v244 offset:36864
	ds_read_b128 v[200:203], v240 offset:36864
	ds_read_b128 v[224:227], v241 offset:32768
	ds_read_b128 v[228:231], v245 offset:32768
	ds_read_b128 v[232:235], v245 offset:36864
	ds_read_b128 v[236:239], v241 offset:36864
	s_add_u32 m0, s76, 0x600
	s_nop 0
	global_load_lds_dwordx4 v[138:139], off offset:512
	s_add_u32 m0, s76, 0x1600
	s_nop 0
	global_load_lds_dwordx4 v[142:143], off offset:512
	s_add_u32 m0, s76, 0x2600
	s_nop 0
	global_load_lds_dwordx4 v[144:145], off offset:512
	s_add_u32 m0, s76, 0x3600
	s_nop 0
	global_load_lds_dwordx4 v[152:153], off offset:512
	s_add_u32 m0, s76, 0x4600
	s_nop 0
	global_load_lds_dwordx4 v[140:141], off offset:512
	s_add_u32 m0, s76, 0x5600
	s_nop 0
	global_load_lds_dwordx4 v[146:147], off offset:512
	s_add_u32 m0, s76, 0x6600
	s_nop 0
	global_load_lds_dwordx4 v[148:149], off offset:512
	s_add_u32 m0, s76, 0x7600
	s_nop 0
	global_load_lds_dwordx4 v[150:151], off offset:512
	s_waitcnt lgkmcnt(6)
	v_mfma_f32_32x32x16_bf16 v[48:63], v[156:159], v[164:167], v[48:63]
	s_waitcnt lgkmcnt(5)
	v_mfma_f32_32x32x16_bf16 v[32:47], v[156:159], v[168:171], v[32:47]
	s_waitcnt lgkmcnt(4)
	v_mfma_f32_32x32x16_bf16 v[16:31], v[200:203], v[164:167], v[16:31]
	v_mfma_f32_32x32x16_bf16 v[0:15], v[200:203], v[168:171], v[0:15]
	ds_read_b128 v[156:159], v242 offset:32768
	ds_read_b128 v[164:167], v246 offset:32768
	ds_read_b128 v[168:171], v246 offset:36864
	ds_read_b128 v[200:203], v242 offset:36864
	s_waitcnt lgkmcnt(6)
	v_mfma_f32_32x32x16_bf16 v[48:63], v[224:227], v[228:231], v[48:63]
	s_waitcnt lgkmcnt(5)
	v_mfma_f32_32x32x16_bf16 v[32:47], v[224:227], v[232:235], v[32:47]
	s_waitcnt lgkmcnt(4)
	v_mfma_f32_32x32x16_bf16 v[16:31], v[236:239], v[228:231], v[16:31]
	v_mfma_f32_32x32x16_bf16 v[0:15], v[236:239], v[232:235], v[0:15]
	ds_read_b128 v[224:227], v243 offset:32768
	ds_read_b128 v[228:231], v247 offset:32768
	ds_read_b128 v[232:235], v247 offset:36864
	ds_read_b128 v[236:239], v243 offset:36864
	s_waitcnt lgkmcnt(6)
	v_mfma_f32_32x32x16_bf16 v[48:63], v[156:159], v[164:167], v[48:63]
	s_waitcnt lgkmcnt(5)
	v_mfma_f32_32x32x16_bf16 v[32:47], v[156:159], v[168:171], v[32:47]
	s_waitcnt lgkmcnt(4)
	v_mfma_f32_32x32x16_bf16 v[16:31], v[200:203], v[164:167], v[16:31]
	v_mfma_f32_32x32x16_bf16 v[0:15], v[200:203], v[168:171], v[0:15]
	s_waitcnt lgkmcnt(2)
	v_mfma_f32_32x32x16_bf16 v[48:63], v[224:227], v[228:231], v[48:63]
	s_waitcnt lgkmcnt(1)
	v_mfma_f32_32x32x16_bf16 v[32:47], v[224:227], v[232:235], v[32:47]
	s_waitcnt lgkmcnt(0)
	v_mfma_f32_32x32x16_bf16 v[16:31], v[236:239], v[228:231], v[16:31]
	v_mfma_f32_32x32x16_bf16 v[0:15], v[236:239], v[232:235], v[0:15]
	s_setprio 0
	s_waitcnt vmcnt(0)
	s_barrier
	s_setprio 1
	ds_read_b128 v[156:159], v240
	ds_read_b128 v[164:167], v244
	ds_read_b128 v[168:171], v244 offset:4096
	ds_read_b128 v[200:203], v240 offset:4096
	ds_read_b128 v[224:227], v241
	ds_read_b128 v[228:231], v245
	ds_read_b128 v[232:235], v245 offset:4096
	ds_read_b128 v[236:239], v241 offset:4096
	s_add_u32 m0, s76, 0x8580
	s_nop 0
	global_load_lds_dwordx4 v[138:139], off offset:640
	s_add_u32 m0, s76, 0x9580
	s_nop 0
	global_load_lds_dwordx4 v[142:143], off offset:640
	s_add_u32 m0, s76, 0xa580
	s_nop 0
	global_load_lds_dwordx4 v[144:145], off offset:640
	s_add_u32 m0, s76, 0xb580
	s_nop 0
	global_load_lds_dwordx4 v[152:153], off offset:640
	s_add_u32 m0, s76, 0xc580
	s_nop 0
	global_load_lds_dwordx4 v[140:141], off offset:640
	s_add_u32 m0, s76, 0xd580
	s_nop 0
	global_load_lds_dwordx4 v[146:147], off offset:640
	s_add_u32 m0, s76, 0xe580
	s_nop 0
	global_load_lds_dwordx4 v[148:149], off offset:640
	s_add_u32 m0, s76, 0xf580
	s_nop 0
	global_load_lds_dwordx4 v[150:151], off offset:640
	s_waitcnt lgkmcnt(6)
	v_mfma_f32_32x32x16_bf16 v[48:63], v[156:159], v[164:167], v[48:63]
	s_waitcnt lgkmcnt(5)
	v_mfma_f32_32x32x16_bf16 v[32:47], v[156:159], v[168:171], v[32:47]
	s_waitcnt lgkmcnt(4)
	v_mfma_f32_32x32x16_bf16 v[16:31], v[200:203], v[164:167], v[16:31]
	v_mfma_f32_32x32x16_bf16 v[0:15], v[200:203], v[168:171], v[0:15]
	ds_read_b128 v[156:159], v242
	ds_read_b128 v[164:167], v246
	ds_read_b128 v[168:171], v246 offset:4096
	ds_read_b128 v[200:203], v242 offset:4096
	s_waitcnt lgkmcnt(6)
	v_mfma_f32_32x32x16_bf16 v[48:63], v[224:227], v[228:231], v[48:63]
	s_waitcnt lgkmcnt(5)
	v_mfma_f32_32x32x16_bf16 v[32:47], v[224:227], v[232:235], v[32:47]
	s_waitcnt lgkmcnt(4)
	v_mfma_f32_32x32x16_bf16 v[16:31], v[236:239], v[228:231], v[16:31]
	v_mfma_f32_32x32x16_bf16 v[0:15], v[236:239], v[232:235], v[0:15]
	ds_read_b128 v[224:227], v243
	ds_read_b128 v[228:231], v247
	ds_read_b128 v[232:235], v247 offset:4096
	ds_read_b128 v[236:239], v243 offset:4096
	s_waitcnt lgkmcnt(6)
	v_mfma_f32_32x32x16_bf16 v[48:63], v[156:159], v[164:167], v[48:63]
	s_waitcnt lgkmcnt(5)
	v_mfma_f32_32x32x16_bf16 v[32:47], v[156:159], v[168:171], v[32:47]
	s_waitcnt lgkmcnt(4)
	v_mfma_f32_32x32x16_bf16 v[16:31], v[200:203], v[164:167], v[16:31]
	v_mfma_f32_32x32x16_bf16 v[0:15], v[200:203], v[168:171], v[0:15]
	s_waitcnt lgkmcnt(2)
	v_mfma_f32_32x32x16_bf16 v[48:63], v[224:227], v[228:231], v[48:63]
	s_waitcnt lgkmcnt(1)
	v_mfma_f32_32x32x16_bf16 v[32:47], v[224:227], v[232:235], v[32:47]
	s_waitcnt lgkmcnt(0)
	v_mfma_f32_32x32x16_bf16 v[16:31], v[236:239], v[228:231], v[16:31]
	v_mfma_f32_32x32x16_bf16 v[0:15], v[236:239], v[232:235], v[0:15]
	s_setprio 0
	s_waitcnt vmcnt(0)
	s_barrier
;     ...
;     G_LOAD(x, 0);
;     G_STORE(x, 0);
;     __syncthreads();
;     if (KT > 1) G_LOAD(x, 1);
;     for (int kt = 0; kt < KT; kt += 2) {
;       if (kt + 2 < KT && dummy != 2) G_LOAD(y, kt + 2);
;       G_COMPUTE(0);
;       if (kt + 1 < KT && dummy != 2) G_STORE(x, 1);
;       __syncthreads();
;       if (kt + 1 >= KT) break;
;       if (kt + 3 < KT && dummy != 2) G_LOAD(x, kt + 3);
;       G_COMPUTE(1);
;       if (kt + 2 < KT && dummy != 2) G_STORE(y, 0);
;       __syncthreads();
	s_setprio 1
	ds_read_b128 v[156:159], v240 offset:32768
	ds_read_b128 v[164:167], v244 offset:32768
	ds_read_b128 v[168:171], v244 offset:36864
	ds_read_b128 v[200:203], v240 offset:36864
	ds_read_b128 v[224:227], v241 offset:32768
	ds_read_b128 v[228:231], v245 offset:32768
	ds_read_b128 v[232:235], v245 offset:36864
	ds_read_b128 v[236:239], v241 offset:36864
	s_add_u32 m0, s76, 0x500
	s_nop 0
	global_load_lds_dwordx4 v[138:139], off offset:768
	s_add_u32 m0, s76, 0x1500
	s_nop 0
	global_load_lds_dwordx4 v[142:143], off offset:768
	s_add_u32 m0, s76, 0x2500
	s_nop 0
	global_load_lds_dwordx4 v[144:145], off offset:768
	s_add_u32 m0, s76, 0x3500
	s_nop 0
	global_load_lds_dwordx4 v[152:153], off offset:768
	s_add_u32 m0, s76, 0x4500
	s_nop 0
	global_load_lds_dwordx4 v[140:141], off offset:768
	s_add_u32 m0, s76, 0x5500
	s_nop 0
	global_load_lds_dwordx4 v[146:147], off offset:768
	s_add_u32 m0, s76, 0x6500
	s_nop 0
	global_load_lds_dwordx4 v[148:149], off offset:768
	s_add_u32 m0, s76, 0x7500
	s_nop 0
	global_load_lds_dwordx4 v[150:151], off offset:768
	s_waitcnt lgkmcnt(6)
	v_mfma_f32_32x32x16_bf16 v[48:63], v[156:159], v[164:167], v[48:63]
	s_waitcnt lgkmcnt(5)
	v_mfma_f32_32x32x16_bf16 v[32:47], v[156:159], v[168:171], v[32:47]
	s_waitcnt lgkmcnt(4)
	v_mfma_f32_32x32x16_bf16 v[16:31], v[200:203], v[164:167], v[16:31]
	v_mfma_f32_32x32x16_bf16 v[0:15], v[200:203], v[168:171], v[0:15]
	ds_read_b128 v[156:159], v242 offset:32768
	ds_read_b128 v[164:167], v246 offset:32768
	ds_read_b128 v[168:171], v246 offset:36864
	ds_read_b128 v[200:203], v242 offset:36864
	s_waitcnt lgkmcnt(6)
	v_mfma_f32_32x32x16_bf16 v[48:63], v[224:227], v[228:231], v[48:63]
	s_waitcnt lgkmcnt(5)
	v_mfma_f32_32x32x16_bf16 v[32:47], v[224:227], v[232:235], v[32:47]
	s_waitcnt lgkmcnt(4)
	v_mfma_f32_32x32x16_bf16 v[16:31], v[236:239], v[228:231], v[16:31]
	v_mfma_f32_32x32x16_bf16 v[0:15], v[236:239], v[232:235], v[0:15]
	ds_read_b128 v[224:227], v243 offset:32768
	ds_read_b128 v[228:231], v247 offset:32768
	ds_read_b128 v[232:235], v247 offset:36864
	ds_read_b128 v[236:239], v243 offset:36864
	s_waitcnt lgkmcnt(6)
	v_mfma_f32_32x32x16_bf16 v[48:63], v[156:159], v[164:167], v[48:63]
	s_waitcnt lgkmcnt(5)
	v_mfma_f32_32x32x16_bf16 v[32:47], v[156:159], v[168:171], v[32:47]
	s_waitcnt lgkmcnt(4)
	v_mfma_f32_32x32x16_bf16 v[16:31], v[200:203], v[164:167], v[16:31]
	v_mfma_f32_32x32x16_bf16 v[0:15], v[200:203], v[168:171], v[0:15]
	s_waitcnt lgkmcnt(2)
	v_mfma_f32_32x32x16_bf16 v[48:63], v[224:227], v[228:231], v[48:63]
	s_waitcnt lgkmcnt(1)
	v_mfma_f32_32x32x16_bf16 v[32:47], v[224:227], v[232:235], v[32:47]
	s_waitcnt lgkmcnt(0)
	v_mfma_f32_32x32x16_bf16 v[16:31], v[236:239], v[228:231], v[16:31]
	v_mfma_f32_32x32x16_bf16 v[0:15], v[236:239], v[232:235], v[0:15]
	s_setprio 0
	s_waitcnt vmcnt(0)
	s_barrier
	s_setprio 1
	ds_read_b128 v[156:159], v240
	ds_read_b128 v[164:167], v244
	ds_read_b128 v[168:171], v244 offset:4096
	ds_read_b128 v[200:203], v240 offset:4096
	ds_read_b128 v[224:227], v241
	ds_read_b128 v[228:231], v245
	ds_read_b128 v[232:235], v245 offset:4096
	ds_read_b128 v[236:239], v241 offset:4096
	s_add_u32 m0, s76, 0x8480
	s_nop 0
	global_load_lds_dwordx4 v[138:139], off offset:896
	s_add_u32 m0, s76, 0x9480
	s_nop 0
	global_load_lds_dwordx4 v[142:143], off offset:896
	s_add_u32 m0, s76, 0xa480
	s_nop 0
	global_load_lds_dwordx4 v[144:145], off offset:896
	s_add_u32 m0, s76, 0xb480
	s_nop 0
	global_load_lds_dwordx4 v[152:153], off offset:896
	s_add_u32 m0, s76, 0xc480
	s_nop 0
	global_load_lds_dwordx4 v[140:141], off offset:896
	s_add_u32 m0, s76, 0xd480
	s_nop 0
	global_load_lds_dwordx4 v[146:147], off offset:896
	s_add_u32 m0, s76, 0xe480
	s_nop 0
	global_load_lds_dwordx4 v[148:149], off offset:896
	s_add_u32 m0, s76, 0xf480
	s_nop 0
	global_load_lds_dwordx4 v[150:151], off offset:896
	s_waitcnt lgkmcnt(6)
	v_mfma_f32_32x32x16_bf16 v[48:63], v[156:159], v[164:167], v[48:63]
	s_waitcnt lgkmcnt(5)
	v_mfma_f32_32x32x16_bf16 v[32:47], v[156:159], v[168:171], v[32:47]
	s_waitcnt lgkmcnt(4)
	v_mfma_f32_32x32x16_bf16 v[16:31], v[200:203], v[164:167], v[16:31]
	v_mfma_f32_32x32x16_bf16 v[0:15], v[200:203], v[168:171], v[0:15]
	ds_read_b128 v[156:159], v242
	ds_read_b128 v[164:167], v246
	ds_read_b128 v[168:171], v246 offset:4096
	ds_read_b128 v[200:203], v242 offset:4096
	s_waitcnt lgkmcnt(6)
	v_mfma_f32_32x32x16_bf16 v[48:63], v[224:227], v[228:231], v[48:63]
	s_waitcnt lgkmcnt(5)
	v_mfma_f32_32x32x16_bf16 v[32:47], v[224:227], v[232:235], v[32:47]
	s_waitcnt lgkmcnt(4)
	v_mfma_f32_32x32x16_bf16 v[16:31], v[236:239], v[228:231], v[16:31]
	v_mfma_f32_32x32x16_bf16 v[0:15], v[236:239], v[232:235], v[0:15]
	ds_read_b128 v[224:227], v243
	ds_read_b128 v[228:231], v247
	ds_read_b128 v[232:235], v247 offset:4096
	ds_read_b128 v[236:239], v243 offset:4096
	s_waitcnt lgkmcnt(6)
	v_mfma_f32_32x32x16_bf16 v[48:63], v[156:159], v[164:167], v[48:63]
	s_waitcnt lgkmcnt(5)
	v_mfma_f32_32x32x16_bf16 v[32:47], v[156:159], v[168:171], v[32:47]
	s_waitcnt lgkmcnt(4)
	v_mfma_f32_32x32x16_bf16 v[16:31], v[200:203], v[164:167], v[16:31]
	v_mfma_f32_32x32x16_bf16 v[0:15], v[200:203], v[168:171], v[0:15]
	s_waitcnt lgkmcnt(2)
	v_mfma_f32_32x32x16_bf16 v[48:63], v[224:227], v[228:231], v[48:63]
	s_waitcnt lgkmcnt(1)
	v_mfma_f32_32x32x16_bf16 v[32:47], v[224:227], v[232:235], v[32:47]
	s_waitcnt lgkmcnt(0)
	v_mfma_f32_32x32x16_bf16 v[16:31], v[236:239], v[228:231], v[16:31]
	v_mfma_f32_32x32x16_bf16 v[0:15], v[236:239], v[232:235], v[0:15]
	s_setprio 0
	s_waitcnt vmcnt(0)
	s_barrier
;     ...
;     G_LOAD(x, 0);
;     G_STORE(x, 0);
;     __syncthreads();
;     if (KT > 1) G_LOAD(x, 1);
;     for (int kt = 0; kt < KT; kt += 2) {
;       if (kt + 2 < KT && dummy != 2) G_LOAD(y, kt + 2);
;       G_COMPUTE(0);
;       if (kt + 1 < KT && dummy != 2) G_STORE(x, 1);
;       __syncthreads();
;       if (kt + 1 >= KT) break;
;       if (kt + 3 < KT && dummy != 2) G_LOAD(x, kt + 3);
;       G_COMPUTE(1);
;       if (kt + 2 < KT && dummy != 2) G_STORE(y, 0);
;       __syncthreads();
	s_setprio 1
	ds_read_b128 v[156:159], v240 offset:32768
	ds_read_b128 v[164:167], v244 offset:32768
	ds_read_b128 v[168:171], v244 offset:36864
	ds_read_b128 v[200:203], v240 offset:36864
	ds_read_b128 v[224:227], v241 offset:32768
	ds_read_b128 v[228:231], v245 offset:32768
	ds_read_b128 v[232:235], v245 offset:36864
	ds_read_b128 v[236:239], v241 offset:36864
	s_add_u32 m0, s76, 0x400
	s_nop 0
	global_load_lds_dwordx4 v[138:139], off offset:1024
	s_add_u32 m0, s76, 0x1400
	s_nop 0
	global_load_lds_dwordx4 v[142:143], off offset:1024
	s_add_u32 m0, s76, 0x2400
	s_nop 0
	global_load_lds_dwordx4 v[144:145], off offset:1024
	s_add_u32 m0, s76, 0x3400
	s_nop 0
	global_load_lds_dwordx4 v[152:153], off offset:1024
	s_add_u32 m0, s76, 0x4400
	s_nop 0
	global_load_lds_dwordx4 v[140:141], off offset:1024
	s_add_u32 m0, s76, 0x5400
	s_nop 0
	global_load_lds_dwordx4 v[146:147], off offset:1024
	s_add_u32 m0, s76, 0x6400
	s_nop 0
	global_load_lds_dwordx4 v[148:149], off offset:1024
	s_add_u32 m0, s76, 0x7400
	s_nop 0
	global_load_lds_dwordx4 v[150:151], off offset:1024
	s_waitcnt lgkmcnt(6)
	v_mfma_f32_32x32x16_bf16 v[48:63], v[156:159], v[164:167], v[48:63]
	s_waitcnt lgkmcnt(5)
	v_mfma_f32_32x32x16_bf16 v[32:47], v[156:159], v[168:171], v[32:47]
	s_waitcnt lgkmcnt(4)
	v_mfma_f32_32x32x16_bf16 v[16:31], v[200:203], v[164:167], v[16:31]
	v_mfma_f32_32x32x16_bf16 v[0:15], v[200:203], v[168:171], v[0:15]
	ds_read_b128 v[156:159], v242 offset:32768
	ds_read_b128 v[164:167], v246 offset:32768
	ds_read_b128 v[168:171], v246 offset:36864
	ds_read_b128 v[200:203], v242 offset:36864
	s_waitcnt lgkmcnt(6)
	v_mfma_f32_32x32x16_bf16 v[48:63], v[224:227], v[228:231], v[48:63]
	s_waitcnt lgkmcnt(5)
	v_mfma_f32_32x32x16_bf16 v[32:47], v[224:227], v[232:235], v[32:47]
	s_waitcnt lgkmcnt(4)
	v_mfma_f32_32x32x16_bf16 v[16:31], v[236:239], v[228:231], v[16:31]
	v_mfma_f32_32x32x16_bf16 v[0:15], v[236:239], v[232:235], v[0:15]
	ds_read_b128 v[224:227], v243 offset:32768
	ds_read_b128 v[228:231], v247 offset:32768
	ds_read_b128 v[232:235], v247 offset:36864
	ds_read_b128 v[236:239], v243 offset:36864
	s_waitcnt lgkmcnt(6)
	v_mfma_f32_32x32x16_bf16 v[48:63], v[156:159], v[164:167], v[48:63]
	s_waitcnt lgkmcnt(5)
	v_mfma_f32_32x32x16_bf16 v[32:47], v[156:159], v[168:171], v[32:47]
	s_waitcnt lgkmcnt(4)
	v_mfma_f32_32x32x16_bf16 v[16:31], v[200:203], v[164:167], v[16:31]
	v_mfma_f32_32x32x16_bf16 v[0:15], v[200:203], v[168:171], v[0:15]
	s_waitcnt lgkmcnt(2)
	v_mfma_f32_32x32x16_bf16 v[48:63], v[224:227], v[228:231], v[48:63]
	s_waitcnt lgkmcnt(1)
	v_mfma_f32_32x32x16_bf16 v[32:47], v[224:227], v[232:235], v[32:47]
	s_waitcnt lgkmcnt(0)
	v_mfma_f32_32x32x16_bf16 v[16:31], v[236:239], v[228:231], v[16:31]
	v_mfma_f32_32x32x16_bf16 v[0:15], v[236:239], v[232:235], v[0:15]
	s_setprio 0
	s_waitcnt vmcnt(0)
	s_barrier
	s_setprio 1
	ds_read_b128 v[156:159], v240
	ds_read_b128 v[164:167], v244
	ds_read_b128 v[168:171], v244 offset:4096
	ds_read_b128 v[200:203], v240 offset:4096
	ds_read_b128 v[224:227], v241
	ds_read_b128 v[228:231], v245
	ds_read_b128 v[232:235], v245 offset:4096
	ds_read_b128 v[236:239], v241 offset:4096
	s_add_u32 m0, s76, 0x8380
	s_nop 0
	global_load_lds_dwordx4 v[138:139], off offset:1152
	s_add_u32 m0, s76, 0x9380
	s_nop 0
	global_load_lds_dwordx4 v[142:143], off offset:1152
	s_add_u32 m0, s76, 0xa380
	s_nop 0
	global_load_lds_dwordx4 v[144:145], off offset:1152
	s_add_u32 m0, s76, 0xb380
	s_nop 0
	global_load_lds_dwordx4 v[152:153], off offset:1152
	s_add_u32 m0, s76, 0xc380
	s_nop 0
	global_load_lds_dwordx4 v[140:141], off offset:1152
	s_add_u32 m0, s76, 0xd380
	s_nop 0
	global_load_lds_dwordx4 v[146:147], off offset:1152
	s_add_u32 m0, s76, 0xe380
	s_nop 0
	global_load_lds_dwordx4 v[148:149], off offset:1152
	s_add_u32 m0, s76, 0xf380
	s_nop 0
	global_load_lds_dwordx4 v[150:151], off offset:1152
	s_waitcnt lgkmcnt(6)
	v_mfma_f32_32x32x16_bf16 v[48:63], v[156:159], v[164:167], v[48:63]
	s_waitcnt lgkmcnt(5)
	v_mfma_f32_32x32x16_bf16 v[32:47], v[156:159], v[168:171], v[32:47]
	s_waitcnt lgkmcnt(4)
	v_mfma_f32_32x32x16_bf16 v[16:31], v[200:203], v[164:167], v[16:31]
	v_mfma_f32_32x32x16_bf16 v[0:15], v[200:203], v[168:171], v[0:15]
	ds_read_b128 v[156:159], v242
	ds_read_b128 v[164:167], v246
	ds_read_b128 v[168:171], v246 offset:4096
	ds_read_b128 v[200:203], v242 offset:4096
	s_waitcnt lgkmcnt(6)
	v_mfma_f32_32x32x16_bf16 v[48:63], v[224:227], v[228:231], v[48:63]
	s_waitcnt lgkmcnt(5)
	v_mfma_f32_32x32x16_bf16 v[32:47], v[224:227], v[232:235], v[32:47]
	s_waitcnt lgkmcnt(4)
	v_mfma_f32_32x32x16_bf16 v[16:31], v[236:239], v[228:231], v[16:31]
	v_mfma_f32_32x32x16_bf16 v[0:15], v[236:239], v[232:235], v[0:15]
	ds_read_b128 v[224:227], v243
	ds_read_b128 v[228:231], v247
	ds_read_b128 v[232:235], v247 offset:4096
	ds_read_b128 v[236:239], v243 offset:4096
	s_waitcnt lgkmcnt(6)
	v_mfma_f32_32x32x16_bf16 v[48:63], v[156:159], v[164:167], v[48:63]
	s_waitcnt lgkmcnt(5)
	v_mfma_f32_32x32x16_bf16 v[32:47], v[156:159], v[168:171], v[32:47]
	s_waitcnt lgkmcnt(4)
	v_mfma_f32_32x32x16_bf16 v[16:31], v[200:203], v[164:167], v[16:31]
	v_mfma_f32_32x32x16_bf16 v[0:15], v[200:203], v[168:171], v[0:15]
	s_waitcnt lgkmcnt(2)
	v_mfma_f32_32x32x16_bf16 v[48:63], v[224:227], v[228:231], v[48:63]
	s_waitcnt lgkmcnt(1)
	v_mfma_f32_32x32x16_bf16 v[32:47], v[224:227], v[232:235], v[32:47]
	s_waitcnt lgkmcnt(0)
	v_mfma_f32_32x32x16_bf16 v[16:31], v[236:239], v[228:231], v[16:31]
	v_mfma_f32_32x32x16_bf16 v[0:15], v[236:239], v[232:235], v[0:15]
	s_setprio 0
	s_waitcnt vmcnt(0)
	s_barrier
;     ...
;     G_LOAD(x, 0);
;     G_STORE(x, 0);
;     __syncthreads();
;     if (KT > 1) G_LOAD(x, 1);
;     for (int kt = 0; kt < KT; kt += 2) {
;       if (kt + 2 < KT && dummy != 2) G_LOAD(y, kt + 2);
;       G_COMPUTE(0);
;       if (kt + 1 < KT && dummy != 2) G_STORE(x, 1);
;       __syncthreads();
;       if (kt + 1 >= KT) break;
;       if (kt + 3 < KT && dummy != 2) G_LOAD(x, kt + 3);
;       G_COMPUTE(1);
;       if (kt + 2 < KT && dummy != 2) G_STORE(y, 0);
;       __syncthreads();
	s_setprio 1
	ds_read_b128 v[156:159], v240 offset:32768
	ds_read_b128 v[164:167], v244 offset:32768
	ds_read_b128 v[168:171], v244 offset:36864
	ds_read_b128 v[200:203], v240 offset:36864
	ds_read_b128 v[224:227], v241 offset:32768
	ds_read_b128 v[228:231], v245 offset:32768
	ds_read_b128 v[232:235], v245 offset:36864
	ds_read_b128 v[236:239], v241 offset:36864
	s_add_u32 m0, s76, 0x300
	s_nop 0
	global_load_lds_dwordx4 v[138:139], off offset:1280
	s_add_u32 m0, s76, 0x1300
	s_nop 0
	global_load_lds_dwordx4 v[142:143], off offset:1280
	s_add_u32 m0, s76, 0x2300
	s_nop 0
	global_load_lds_dwordx4 v[144:145], off offset:1280
	s_add_u32 m0, s76, 0x3300
	s_nop 0
	global_load_lds_dwordx4 v[152:153], off offset:1280
	s_add_u32 m0, s76, 0x4300
	s_nop 0
	global_load_lds_dwordx4 v[140:141], off offset:1280
	s_add_u32 m0, s76, 0x5300
	s_nop 0
	global_load_lds_dwordx4 v[146:147], off offset:1280
	s_add_u32 m0, s76, 0x6300
	s_nop 0
	global_load_lds_dwordx4 v[148:149], off offset:1280
	s_add_u32 m0, s76, 0x7300
	s_nop 0
	global_load_lds_dwordx4 v[150:151], off offset:1280
	s_waitcnt lgkmcnt(6)
	v_mfma_f32_32x32x16_bf16 v[48:63], v[156:159], v[164:167], v[48:63]
	s_waitcnt lgkmcnt(5)
	v_mfma_f32_32x32x16_bf16 v[32:47], v[156:159], v[168:171], v[32:47]
	s_waitcnt lgkmcnt(4)
	v_mfma_f32_32x32x16_bf16 v[16:31], v[200:203], v[164:167], v[16:31]
	v_mfma_f32_32x32x16_bf16 v[0:15], v[200:203], v[168:171], v[0:15]
	ds_read_b128 v[156:159], v242 offset:32768
	ds_read_b128 v[164:167], v246 offset:32768
	ds_read_b128 v[168:171], v246 offset:36864
	ds_read_b128 v[200:203], v242 offset:36864
	s_waitcnt lgkmcnt(6)
	v_mfma_f32_32x32x16_bf16 v[48:63], v[224:227], v[228:231], v[48:63]
	s_waitcnt lgkmcnt(5)
	v_mfma_f32_32x32x16_bf16 v[32:47], v[224:227], v[232:235], v[32:47]
	s_waitcnt lgkmcnt(4)
	v_mfma_f32_32x32x16_bf16 v[16:31], v[236:239], v[228:231], v[16:31]
	v_mfma_f32_32x32x16_bf16 v[0:15], v[236:239], v[232:235], v[0:15]
	ds_read_b128 v[224:227], v243 offset:32768
	ds_read_b128 v[228:231], v247 offset:32768
	ds_read_b128 v[232:235], v247 offset:36864
	ds_read_b128 v[236:239], v243 offset:36864
	s_waitcnt lgkmcnt(6)
	v_mfma_f32_32x32x16_bf16 v[48:63], v[156:159], v[164:167], v[48:63]
	s_waitcnt lgkmcnt(5)
	v_mfma_f32_32x32x16_bf16 v[32:47], v[156:159], v[168:171], v[32:47]
	s_waitcnt lgkmcnt(4)
	v_mfma_f32_32x32x16_bf16 v[16:31], v[200:203], v[164:167], v[16:31]
	v_mfma_f32_32x32x16_bf16 v[0:15], v[200:203], v[168:171], v[0:15]
	s_waitcnt lgkmcnt(2)
	v_mfma_f32_32x32x16_bf16 v[48:63], v[224:227], v[228:231], v[48:63]
	s_waitcnt lgkmcnt(1)
	v_mfma_f32_32x32x16_bf16 v[32:47], v[224:227], v[232:235], v[32:47]
	s_waitcnt lgkmcnt(0)
	v_mfma_f32_32x32x16_bf16 v[16:31], v[236:239], v[228:231], v[16:31]
	v_mfma_f32_32x32x16_bf16 v[0:15], v[236:239], v[232:235], v[0:15]
	s_setprio 0
	s_waitcnt vmcnt(0)
	s_barrier
	s_setprio 1
	ds_read_b128 v[156:159], v240
	ds_read_b128 v[164:167], v244
	ds_read_b128 v[168:171], v244 offset:4096
	ds_read_b128 v[200:203], v240 offset:4096
	ds_read_b128 v[224:227], v241
	ds_read_b128 v[228:231], v245
	ds_read_b128 v[232:235], v245 offset:4096
	ds_read_b128 v[236:239], v241 offset:4096
	s_add_u32 m0, s76, 0x8280
	s_nop 0
	global_load_lds_dwordx4 v[138:139], off offset:1408
	s_add_u32 m0, s76, 0x9280
	s_nop 0
	global_load_lds_dwordx4 v[142:143], off offset:1408
	s_add_u32 m0, s76, 0xa280
	s_nop 0
	global_load_lds_dwordx4 v[144:145], off offset:1408
	s_add_u32 m0, s76, 0xb280
	s_nop 0
	global_load_lds_dwordx4 v[152:153], off offset:1408
	s_add_u32 m0, s76, 0xc280
	s_nop 0
	global_load_lds_dwordx4 v[140:141], off offset:1408
	s_add_u32 m0, s76, 0xd280
	s_nop 0
	global_load_lds_dwordx4 v[146:147], off offset:1408
	s_add_u32 m0, s76, 0xe280
	s_nop 0
	global_load_lds_dwordx4 v[148:149], off offset:1408
	s_add_u32 m0, s76, 0xf280
	s_nop 0
	global_load_lds_dwordx4 v[150:151], off offset:1408
	s_waitcnt lgkmcnt(6)
	v_mfma_f32_32x32x16_bf16 v[48:63], v[156:159], v[164:167], v[48:63]
	s_waitcnt lgkmcnt(5)
	v_mfma_f32_32x32x16_bf16 v[32:47], v[156:159], v[168:171], v[32:47]
	s_waitcnt lgkmcnt(4)
	v_mfma_f32_32x32x16_bf16 v[16:31], v[200:203], v[164:167], v[16:31]
	v_mfma_f32_32x32x16_bf16 v[0:15], v[200:203], v[168:171], v[0:15]
	ds_read_b128 v[156:159], v242
	ds_read_b128 v[164:167], v246
	ds_read_b128 v[168:171], v246 offset:4096
	ds_read_b128 v[200:203], v242 offset:4096
	s_waitcnt lgkmcnt(6)
	v_mfma_f32_32x32x16_bf16 v[48:63], v[224:227], v[228:231], v[48:63]
	s_waitcnt lgkmcnt(5)
	v_mfma_f32_32x32x16_bf16 v[32:47], v[224:227], v[232:235], v[32:47]
	s_waitcnt lgkmcnt(4)
	v_mfma_f32_32x32x16_bf16 v[16:31], v[236:239], v[228:231], v[16:31]
	v_mfma_f32_32x32x16_bf16 v[0:15], v[236:239], v[232:235], v[0:15]
	ds_read_b128 v[224:227], v243
	ds_read_b128 v[228:231], v247
	ds_read_b128 v[232:235], v247 offset:4096
	ds_read_b128 v[236:239], v243 offset:4096
	s_waitcnt lgkmcnt(6)
	v_mfma_f32_32x32x16_bf16 v[48:63], v[156:159], v[164:167], v[48:63]
	s_waitcnt lgkmcnt(5)
	v_mfma_f32_32x32x16_bf16 v[32:47], v[156:159], v[168:171], v[32:47]
	s_waitcnt lgkmcnt(4)
	v_mfma_f32_32x32x16_bf16 v[16:31], v[200:203], v[164:167], v[16:31]
	v_mfma_f32_32x32x16_bf16 v[0:15], v[200:203], v[168:171], v[0:15]
	s_waitcnt lgkmcnt(2)
	v_mfma_f32_32x32x16_bf16 v[48:63], v[224:227], v[228:231], v[48:63]
	s_waitcnt lgkmcnt(1)
	v_mfma_f32_32x32x16_bf16 v[32:47], v[224:227], v[232:235], v[32:47]
	s_waitcnt lgkmcnt(0)
	v_mfma_f32_32x32x16_bf16 v[16:31], v[236:239], v[228:231], v[16:31]
	v_mfma_f32_32x32x16_bf16 v[0:15], v[236:239], v[232:235], v[0:15]
	s_setprio 0
	s_waitcnt vmcnt(0)
	s_barrier
;     ...
;     G_LOAD(x, 0);
;     G_STORE(x, 0);
;     __syncthreads();
;     if (KT > 1) G_LOAD(x, 1);
;     for (int kt = 0; kt < KT; kt += 2) {
;       if (kt + 2 < KT && dummy != 2) G_LOAD(y, kt + 2);
;       G_COMPUTE(0);
;       if (kt + 1 < KT && dummy != 2) G_STORE(x, 1);
;       __syncthreads();
;       if (kt + 1 >= KT) break;
;       if (kt + 3 < KT && dummy != 2) G_LOAD(x, kt + 3);
;       G_COMPUTE(1);
;       if (kt + 2 < KT && dummy != 2) G_STORE(y, 0);
;       __syncthreads();
	s_setprio 1
	ds_read_b128 v[156:159], v240 offset:32768
	ds_read_b128 v[164:167], v244 offset:32768
	ds_read_b128 v[168:171], v244 offset:36864
	ds_read_b128 v[200:203], v240 offset:36864
	ds_read_b128 v[224:227], v241 offset:32768
	ds_read_b128 v[228:231], v245 offset:32768
	ds_read_b128 v[232:235], v245 offset:36864
	ds_read_b128 v[236:239], v241 offset:36864
	s_add_u32 m0, s76, 0x200
	s_nop 0
	global_load_lds_dwordx4 v[138:139], off offset:1536
	s_add_u32 m0, s76, 0x1200
	s_nop 0
	global_load_lds_dwordx4 v[142:143], off offset:1536
	s_add_u32 m0, s76, 0x2200
	s_nop 0
	global_load_lds_dwordx4 v[144:145], off offset:1536
	s_add_u32 m0, s76, 0x3200
	s_nop 0
	global_load_lds_dwordx4 v[152:153], off offset:1536
	s_add_u32 m0, s76, 0x4200
	s_nop 0
	global_load_lds_dwordx4 v[140:141], off offset:1536
	s_add_u32 m0, s76, 0x5200
	s_nop 0
	global_load_lds_dwordx4 v[146:147], off offset:1536
	s_add_u32 m0, s76, 0x6200
	s_nop 0
	global_load_lds_dwordx4 v[148:149], off offset:1536
	s_add_u32 m0, s76, 0x7200
	s_nop 0
	global_load_lds_dwordx4 v[150:151], off offset:1536
	s_waitcnt lgkmcnt(6)
	v_mfma_f32_32x32x16_bf16 v[48:63], v[156:159], v[164:167], v[48:63]
	s_waitcnt lgkmcnt(5)
	v_mfma_f32_32x32x16_bf16 v[32:47], v[156:159], v[168:171], v[32:47]
	s_waitcnt lgkmcnt(4)
	v_mfma_f32_32x32x16_bf16 v[16:31], v[200:203], v[164:167], v[16:31]
	v_mfma_f32_32x32x16_bf16 v[0:15], v[200:203], v[168:171], v[0:15]
	ds_read_b128 v[156:159], v242 offset:32768
	ds_read_b128 v[164:167], v246 offset:32768
	ds_read_b128 v[168:171], v246 offset:36864
	ds_read_b128 v[200:203], v242 offset:36864
	s_waitcnt lgkmcnt(6)
	v_mfma_f32_32x32x16_bf16 v[48:63], v[224:227], v[228:231], v[48:63]
	s_waitcnt lgkmcnt(5)
	v_mfma_f32_32x32x16_bf16 v[32:47], v[224:227], v[232:235], v[32:47]
	s_waitcnt lgkmcnt(4)
	v_mfma_f32_32x32x16_bf16 v[16:31], v[236:239], v[228:231], v[16:31]
	v_mfma_f32_32x32x16_bf16 v[0:15], v[236:239], v[232:235], v[0:15]
	ds_read_b128 v[224:227], v243 offset:32768
	ds_read_b128 v[228:231], v247 offset:32768
	ds_read_b128 v[232:235], v247 offset:36864
	ds_read_b128 v[236:239], v243 offset:36864
	s_waitcnt lgkmcnt(6)
	v_mfma_f32_32x32x16_bf16 v[48:63], v[156:159], v[164:167], v[48:63]
	s_waitcnt lgkmcnt(5)
	v_mfma_f32_32x32x16_bf16 v[32:47], v[156:159], v[168:171], v[32:47]
	s_waitcnt lgkmcnt(4)
	v_mfma_f32_32x32x16_bf16 v[16:31], v[200:203], v[164:167], v[16:31]
	v_mfma_f32_32x32x16_bf16 v[0:15], v[200:203], v[168:171], v[0:15]
	s_waitcnt lgkmcnt(2)
	v_mfma_f32_32x32x16_bf16 v[48:63], v[224:227], v[228:231], v[48:63]
	s_waitcnt lgkmcnt(1)
	v_mfma_f32_32x32x16_bf16 v[32:47], v[224:227], v[232:235], v[32:47]
	s_waitcnt lgkmcnt(0)
	v_mfma_f32_32x32x16_bf16 v[16:31], v[236:239], v[228:231], v[16:31]
	v_mfma_f32_32x32x16_bf16 v[0:15], v[236:239], v[232:235], v[0:15]
	s_setprio 0
	s_waitcnt vmcnt(0)
	s_barrier
	s_setprio 1
	ds_read_b128 v[156:159], v240
	ds_read_b128 v[164:167], v244
	ds_read_b128 v[168:171], v244 offset:4096
	ds_read_b128 v[200:203], v240 offset:4096
	ds_read_b128 v[224:227], v241
	ds_read_b128 v[228:231], v245
	ds_read_b128 v[232:235], v245 offset:4096
	ds_read_b128 v[236:239], v241 offset:4096
	s_add_u32 m0, s76, 0x8180
	s_nop 0
	global_load_lds_dwordx4 v[138:139], off offset:1664
	s_add_u32 m0, s76, 0x9180
	s_nop 0
	global_load_lds_dwordx4 v[142:143], off offset:1664
	s_add_u32 m0, s76, 0xa180
	s_nop 0
	global_load_lds_dwordx4 v[144:145], off offset:1664
	s_add_u32 m0, s76, 0xb180
	s_nop 0
	global_load_lds_dwordx4 v[152:153], off offset:1664
	s_add_u32 m0, s76, 0xc180
	s_nop 0
	global_load_lds_dwordx4 v[140:141], off offset:1664
	s_add_u32 m0, s76, 0xd180
	s_nop 0
	global_load_lds_dwordx4 v[146:147], off offset:1664
	s_add_u32 m0, s76, 0xe180
	s_nop 0
	global_load_lds_dwordx4 v[148:149], off offset:1664
	s_add_u32 m0, s76, 0xf180
	s_nop 0
	global_load_lds_dwordx4 v[150:151], off offset:1664
	s_waitcnt lgkmcnt(6)
	v_mfma_f32_32x32x16_bf16 v[48:63], v[156:159], v[164:167], v[48:63]
	s_waitcnt lgkmcnt(5)
	v_mfma_f32_32x32x16_bf16 v[32:47], v[156:159], v[168:171], v[32:47]
	s_waitcnt lgkmcnt(4)
	v_mfma_f32_32x32x16_bf16 v[16:31], v[200:203], v[164:167], v[16:31]
	v_mfma_f32_32x32x16_bf16 v[0:15], v[200:203], v[168:171], v[0:15]
	ds_read_b128 v[156:159], v242
	ds_read_b128 v[164:167], v246
	ds_read_b128 v[168:171], v246 offset:4096
	ds_read_b128 v[200:203], v242 offset:4096
	s_waitcnt lgkmcnt(6)
	v_mfma_f32_32x32x16_bf16 v[48:63], v[224:227], v[228:231], v[48:63]
	s_waitcnt lgkmcnt(5)
	v_mfma_f32_32x32x16_bf16 v[32:47], v[224:227], v[232:235], v[32:47]
	s_waitcnt lgkmcnt(4)
	v_mfma_f32_32x32x16_bf16 v[16:31], v[236:239], v[228:231], v[16:31]
	v_mfma_f32_32x32x16_bf16 v[0:15], v[236:239], v[232:235], v[0:15]
	ds_read_b128 v[224:227], v243
	ds_read_b128 v[228:231], v247
	ds_read_b128 v[232:235], v247 offset:4096
	ds_read_b128 v[236:239], v243 offset:4096
	s_waitcnt lgkmcnt(6)
	v_mfma_f32_32x32x16_bf16 v[48:63], v[156:159], v[164:167], v[48:63]
	s_waitcnt lgkmcnt(5)
	v_mfma_f32_32x32x16_bf16 v[32:47], v[156:159], v[168:171], v[32:47]
	s_waitcnt lgkmcnt(4)
	v_mfma_f32_32x32x16_bf16 v[16:31], v[200:203], v[164:167], v[16:31]
	v_mfma_f32_32x32x16_bf16 v[0:15], v[200:203], v[168:171], v[0:15]
	s_waitcnt lgkmcnt(2)
	v_mfma_f32_32x32x16_bf16 v[48:63], v[224:227], v[228:231], v[48:63]
	s_waitcnt lgkmcnt(1)
	v_mfma_f32_32x32x16_bf16 v[32:47], v[224:227], v[232:235], v[32:47]
	s_waitcnt lgkmcnt(0)
	v_mfma_f32_32x32x16_bf16 v[16:31], v[236:239], v[228:231], v[16:31]
	v_mfma_f32_32x32x16_bf16 v[0:15], v[236:239], v[232:235], v[0:15]
	s_setprio 0
	s_waitcnt vmcnt(0)
	s_barrier
;     ...
;     G_LOAD(x, 0);
;     G_STORE(x, 0);
;     __syncthreads();
;     if (KT > 1) G_LOAD(x, 1);
;     for (int kt = 0; kt < KT; kt += 2) {
;       if (kt + 2 < KT && dummy != 2) G_LOAD(y, kt + 2);
;       G_COMPUTE(0);
;       if (kt + 1 < KT && dummy != 2) G_STORE(x, 1);
;       __syncthreads();
;       if (kt + 1 >= KT) break;
;       if (kt + 3 < KT && dummy != 2) G_LOAD(x, kt + 3);
;       G_COMPUTE(1);
;       if (kt + 2 < KT && dummy != 2) G_STORE(y, 0);
;       __syncthreads();
	s_setprio 1
	ds_read_b128 v[156:159], v240 offset:32768
	ds_read_b128 v[164:167], v244 offset:32768
	ds_read_b128 v[168:171], v244 offset:36864
	ds_read_b128 v[200:203], v240 offset:36864
	ds_read_b128 v[224:227], v241 offset:32768
	ds_read_b128 v[228:231], v245 offset:32768
	ds_read_b128 v[232:235], v245 offset:36864
	ds_read_b128 v[236:239], v241 offset:36864
	s_add_u32 m0, s76, 0x100
	s_nop 0
	global_load_lds_dwordx4 v[138:139], off offset:1792
	s_add_u32 m0, s76, 0x1100
	s_nop 0
	global_load_lds_dwordx4 v[142:143], off offset:1792
	s_add_u32 m0, s76, 0x2100
	s_nop 0
	global_load_lds_dwordx4 v[144:145], off offset:1792
	s_add_u32 m0, s76, 0x3100
	s_nop 0
	global_load_lds_dwordx4 v[152:153], off offset:1792
	s_add_u32 m0, s76, 0x4100
	s_nop 0
	global_load_lds_dwordx4 v[140:141], off offset:1792
	s_add_u32 m0, s76, 0x5100
	s_nop 0
	global_load_lds_dwordx4 v[146:147], off offset:1792
	s_add_u32 m0, s76, 0x6100
	s_nop 0
	global_load_lds_dwordx4 v[148:149], off offset:1792
	s_add_u32 m0, s76, 0x7100
	s_nop 0
	global_load_lds_dwordx4 v[150:151], off offset:1792
	s_waitcnt lgkmcnt(6)
	v_mfma_f32_32x32x16_bf16 v[48:63], v[156:159], v[164:167], v[48:63]
	s_waitcnt lgkmcnt(5)
	v_mfma_f32_32x32x16_bf16 v[32:47], v[156:159], v[168:171], v[32:47]
	s_waitcnt lgkmcnt(4)
	v_mfma_f32_32x32x16_bf16 v[16:31], v[200:203], v[164:167], v[16:31]
	v_mfma_f32_32x32x16_bf16 v[0:15], v[200:203], v[168:171], v[0:15]
	ds_read_b128 v[156:159], v242 offset:32768
	ds_read_b128 v[164:167], v246 offset:32768
	ds_read_b128 v[168:171], v246 offset:36864
	ds_read_b128 v[200:203], v242 offset:36864
	s_waitcnt lgkmcnt(6)
	v_mfma_f32_32x32x16_bf16 v[48:63], v[224:227], v[228:231], v[48:63]
	s_waitcnt lgkmcnt(5)
	v_mfma_f32_32x32x16_bf16 v[32:47], v[224:227], v[232:235], v[32:47]
	s_waitcnt lgkmcnt(4)
	v_mfma_f32_32x32x16_bf16 v[16:31], v[236:239], v[228:231], v[16:31]
	v_mfma_f32_32x32x16_bf16 v[0:15], v[236:239], v[232:235], v[0:15]
	ds_read_b128 v[224:227], v243 offset:32768
	ds_read_b128 v[228:231], v247 offset:32768
	ds_read_b128 v[232:235], v247 offset:36864
	ds_read_b128 v[236:239], v243 offset:36864
	s_waitcnt lgkmcnt(6)
	v_mfma_f32_32x32x16_bf16 v[48:63], v[156:159], v[164:167], v[48:63]
	s_waitcnt lgkmcnt(5)
	v_mfma_f32_32x32x16_bf16 v[32:47], v[156:159], v[168:171], v[32:47]
	s_waitcnt lgkmcnt(4)
	v_mfma_f32_32x32x16_bf16 v[16:31], v[200:203], v[164:167], v[16:31]
	v_mfma_f32_32x32x16_bf16 v[0:15], v[200:203], v[168:171], v[0:15]
	s_waitcnt lgkmcnt(2)
	v_mfma_f32_32x32x16_bf16 v[48:63], v[224:227], v[228:231], v[48:63]
	s_waitcnt lgkmcnt(1)
	v_mfma_f32_32x32x16_bf16 v[32:47], v[224:227], v[232:235], v[32:47]
	s_waitcnt lgkmcnt(0)
	v_mfma_f32_32x32x16_bf16 v[16:31], v[236:239], v[228:231], v[16:31]
	v_mfma_f32_32x32x16_bf16 v[0:15], v[236:239], v[232:235], v[0:15]
	s_setprio 0
	s_waitcnt vmcnt(0)
	s_barrier
	s_setprio 1
	ds_read_b128 v[156:159], v240
	ds_read_b128 v[164:167], v244
	ds_read_b128 v[168:171], v244 offset:4096
	ds_read_b128 v[200:203], v240 offset:4096
	ds_read_b128 v[224:227], v241
	ds_read_b128 v[228:231], v245
	ds_read_b128 v[232:235], v245 offset:4096
	ds_read_b128 v[236:239], v241 offset:4096
	s_add_u32 m0, s76, 0x8080
	s_nop 0
	global_load_lds_dwordx4 v[138:139], off offset:1920
	s_add_u32 m0, s76, 0x9080
	s_nop 0
	global_load_lds_dwordx4 v[142:143], off offset:1920
	s_add_u32 m0, s76, 0xa080
	s_nop 0
	global_load_lds_dwordx4 v[144:145], off offset:1920
	s_add_u32 m0, s76, 0xb080
	s_nop 0
	global_load_lds_dwordx4 v[152:153], off offset:1920
	s_add_u32 m0, s76, 0xc080
	s_nop 0
	global_load_lds_dwordx4 v[140:141], off offset:1920
	s_add_u32 m0, s76, 0xd080
	s_nop 0
	global_load_lds_dwordx4 v[146:147], off offset:1920
	s_add_u32 m0, s76, 0xe080
	s_nop 0
	global_load_lds_dwordx4 v[148:149], off offset:1920
	s_add_u32 m0, s76, 0xf080
	s_nop 0
	global_load_lds_dwordx4 v[150:151], off offset:1920
	s_waitcnt lgkmcnt(6)
	v_mfma_f32_32x32x16_bf16 v[48:63], v[156:159], v[164:167], v[48:63]
	s_waitcnt lgkmcnt(5)
	v_mfma_f32_32x32x16_bf16 v[32:47], v[156:159], v[168:171], v[32:47]
	s_waitcnt lgkmcnt(4)
	v_mfma_f32_32x32x16_bf16 v[16:31], v[200:203], v[164:167], v[16:31]
	v_mfma_f32_32x32x16_bf16 v[0:15], v[200:203], v[168:171], v[0:15]
	ds_read_b128 v[156:159], v242
	ds_read_b128 v[164:167], v246
	ds_read_b128 v[168:171], v246 offset:4096
	ds_read_b128 v[200:203], v242 offset:4096
	s_waitcnt lgkmcnt(6)
	v_mfma_f32_32x32x16_bf16 v[48:63], v[224:227], v[228:231], v[48:63]
	s_waitcnt lgkmcnt(5)
	v_mfma_f32_32x32x16_bf16 v[32:47], v[224:227], v[232:235], v[32:47]
	s_waitcnt lgkmcnt(4)
	v_mfma_f32_32x32x16_bf16 v[16:31], v[236:239], v[228:231], v[16:31]
	v_mfma_f32_32x32x16_bf16 v[0:15], v[236:239], v[232:235], v[0:15]
	ds_read_b128 v[224:227], v243
	ds_read_b128 v[228:231], v247
	ds_read_b128 v[232:235], v247 offset:4096
	ds_read_b128 v[236:239], v243 offset:4096
	s_waitcnt lgkmcnt(6)
	v_mfma_f32_32x32x16_bf16 v[48:63], v[156:159], v[164:167], v[48:63]
	s_waitcnt lgkmcnt(5)
	v_mfma_f32_32x32x16_bf16 v[32:47], v[156:159], v[168:171], v[32:47]
	s_waitcnt lgkmcnt(4)
	v_mfma_f32_32x32x16_bf16 v[16:31], v[200:203], v[164:167], v[16:31]
	v_mfma_f32_32x32x16_bf16 v[0:15], v[200:203], v[168:171], v[0:15]
	s_waitcnt lgkmcnt(2)
	v_mfma_f32_32x32x16_bf16 v[48:63], v[224:227], v[228:231], v[48:63]
	s_waitcnt lgkmcnt(1)
	v_mfma_f32_32x32x16_bf16 v[32:47], v[224:227], v[232:235], v[32:47]
	s_waitcnt lgkmcnt(0)
	v_mfma_f32_32x32x16_bf16 v[16:31], v[236:239], v[228:231], v[16:31]
	v_mfma_f32_32x32x16_bf16 v[0:15], v[236:239], v[232:235], v[0:15]
	s_setprio 0
	s_waitcnt vmcnt(0)
	s_barrier
;     ...
;       const int b = m0e / TALL, t0 = m0e - b * TALL;
;       const bool isctx = t0 < CTX;
;       float* xb = isctx ? P.zctx + ((size_t)(b * CTX + t0)) * D : P.out + ((size_t)(b * SEQ + t0 - CTX)) * D;
;       const float* g = P.mod + ((size_t)(l * 17 + (isctx ? 16 : b))) * 6144 + (EPI == EPI_RES1 ? 2 * D : 5 * D);
;       const float* xs = (EPI == EPI_RES1 && l == 0) ? (isctx ? P.ctx + ((size_t)(b * CTX + t0)) * D : P.x + ((size_t)(b * SEQ + t0 - CTX)) * D) : xb;
;       const float gv0 = g[n0e + cb], gv1 = g[n0e + cb + 32];
	s_setprio 1
	ds_read_b128 v[156:159], v240 offset:32768
	ds_read_b128 v[164:167], v244 offset:32768
	ds_read_b128 v[168:171], v244 offset:36864
	ds_read_b128 v[200:203], v240 offset:36864
	ds_read_b128 v[224:227], v241 offset:32768
	ds_read_b128 v[228:231], v245 offset:32768
	ds_read_b128 v[232:235], v245 offset:36864
	ds_read_b128 v[236:239], v241 offset:36864
	s_waitcnt lgkmcnt(6)
	v_mfma_f32_32x32x16_bf16 v[48:63], v[156:159], v[164:167], v[48:63]
	s_waitcnt lgkmcnt(5)
	v_mfma_f32_32x32x16_bf16 v[32:47], v[156:159], v[168:171], v[32:47]
	s_waitcnt lgkmcnt(4)
	v_mfma_f32_32x32x16_bf16 v[16:31], v[200:203], v[164:167], v[16:31]
	v_mfma_f32_32x32x16_bf16 v[0:15], v[200:203], v[168:171], v[0:15]
	ds_read_b128 v[156:159], v242 offset:32768
	ds_read_b128 v[164:167], v246 offset:32768
	ds_read_b128 v[168:171], v246 offset:36864
	ds_read_b128 v[200:203], v242 offset:36864
	s_waitcnt lgkmcnt(6)
	v_mfma_f32_32x32x16_bf16 v[48:63], v[224:227], v[228:231], v[48:63]
	s_waitcnt lgkmcnt(5)
	v_mfma_f32_32x32x16_bf16 v[32:47], v[224:227], v[232:235], v[32:47]
	s_waitcnt lgkmcnt(4)
	v_mfma_f32_32x32x16_bf16 v[16:31], v[236:239], v[228:231], v[16:31]
	v_mfma_f32_32x32x16_bf16 v[0:15], v[236:239], v[232:235], v[0:15]
	ds_read_b128 v[224:227], v243 offset:32768
	ds_read_b128 v[228:231], v247 offset:32768
	ds_read_b128 v[232:235], v247 offset:36864
	ds_read_b128 v[236:239], v243 offset:36864
	s_waitcnt lgkmcnt(6)
	v_mfma_f32_32x32x16_bf16 v[48:63], v[156:159], v[164:167], v[48:63]
	s_waitcnt lgkmcnt(5)
	v_mfma_f32_32x32x16_bf16 v[32:47], v[156:159], v[168:171], v[32:47]
	s_waitcnt lgkmcnt(4)
	v_mfma_f32_32x32x16_bf16 v[16:31], v[200:203], v[164:167], v[16:31]
	v_mfma_f32_32x32x16_bf16 v[0:15], v[200:203], v[168:171], v[0:15]
	s_waitcnt lgkmcnt(2)
	v_mfma_f32_32x32x16_bf16 v[48:63], v[224:227], v[228:231], v[48:63]
	s_waitcnt lgkmcnt(1)
	v_mfma_f32_32x32x16_bf16 v[32:47], v[224:227], v[232:235], v[32:47]
	s_waitcnt lgkmcnt(0)
	v_mfma_f32_32x32x16_bf16 v[16:31], v[236:239], v[228:231], v[16:31]
	v_mfma_f32_32x32x16_bf16 v[0:15], v[236:239], v[232:235], v[0:15]
	s_setprio 0
	s_barrier
	s_mul_hi_i32 s1, s11, 0x38e38e39
	s_lshr_b32 s2, s1, 31
	s_ashr_i32 s1, s1, 9
	s_add_i32 s1, s1, s2
	s_mul_i32 s12, s1, 0xfffff700
	s_add_i32 s12, s12, s11
	v_mov_b32_e32 v64, v155
	v_mov_b32_e32 v66, v96
	s_cmpk_gt_i32 s12, 0xff
	s_mov_b64 s[6:7], -1
	s_cbranch_scc0 .LBB0_259
	s_lshl_b32 s2, s1, 11
	s_add_i32 s2, s2, s12
	s_addk_i32 s2, 0xff00
	s_ashr_i32 s3, s2, 31
	v_readlane_b32 s16, v253, 0
	s_lshl_b64 s[2:3], s[2:3], 12
	v_readlane_b32 s26, v253, 10
	v_readlane_b32 s27, v253, 11
	s_add_u32 s2, s26, s2
	s_addc_u32 s3, s27, s3
	s_add_i32 s4, s1, 51
	v_readlane_b32 s17, v253, 1
	v_readlane_b32 s18, v253, 2
	v_readlane_b32 s19, v253, 3
	v_readlane_b32 s20, v253, 4
	v_readlane_b32 s21, v253, 5
	v_readlane_b32 s22, v253, 6
	v_readlane_b32 s23, v253, 7
	v_readlane_b32 s24, v253, 8
	v_readlane_b32 s25, v253, 9
	v_readlane_b32 s28, v253, 12
	v_readlane_b32 s29, v253, 13
	v_readlane_b32 s30, v253, 14
	v_readlane_b32 s31, v253, 15
	s_mul_hi_i32 s5, s4, 0x1800
	s_mulk_i32 s4, 0x1800
	s_mov_b64 s[6:7], 0

; DI float bf2f(u16 v) { return __uint_as_float(((unsigned)v) << 16); }
;     ...
;       *(uint4*)(raw + (1 + (tid >> 5)) * 256 + vec * 8) = rg0;
;       *(uint4*)(raw + (9 + (tid >> 5)) * 256 + vec * 8) = rg1;
;       *(uint4*)(raw + (17 + (tid >> 5)) * 256 + vec * 8) = rg2;
;       *(uint4*)(raw + (25 + (tid >> 5)) * 256 + vec * 8) = rg3;
;       if (tid < 64) *(uint4*)(raw + ((tid >> 5) ? 33 : 0) * 256 + vec * 8) = rg4;
;       __syncthreads();
;       if (!(pm & 2)) {
;         float pv[34];
; #pragma unroll
;         for (int j = 0; j < 34; ++j) pv[j] = bf2f(raw[j * 256 + c]);
;         if (wv < 3) {
;           float* pdst = prep + (wv == 0 ? 256 + c : (wv == 1 ? 192 + (c - 64) : 320 + (c - 128)));
; #pragma unroll
;           for (int j = 0; j < 32; ++j) {
;             const float psv = pv[j + 1] + mu * (0.5f * (pv[j] + pv[j + 2]) - pv[j + 1]);
.LBB0_365:
	s_andn2_b64 vcc, exec, s[34:35]
	s_cbranch_vccnz .LBB0_350
	s_waitcnt vmcnt(3)
	ds_write_b128 v136, v[24:27] offset:49664
	s_waitcnt vmcnt(2)
	ds_write_b128 v136, v[28:31] offset:53760
	s_waitcnt vmcnt(1)
	ds_write_b128 v136, v[32:35] offset:57856
	s_waitcnt vmcnt(1)
	ds_write_b128 v136, v[36:39] offset:61952
	s_and_saveexec_b64 s[12:13], s[0:1]
	ds_write_b128 v137, v[40:43] offset:49152
	s_or_b64 exec, exec, s[12:13]
	s_waitcnt lgkmcnt(0)
	s_barrier
	ds_read_u16 v24, v138 offset:49152
	ds_read_u16 v25, v138 offset:49664
	ds_read_u16 v26, v138 offset:50176
	ds_read_u16 v27, v138 offset:50688
	ds_read_u16 v28, v138 offset:51200
	ds_read_u16 v29, v138 offset:51712
	ds_read_u16 v30, v138 offset:52224
	ds_read_u16 v31, v138 offset:52736
	ds_read_u16 v32, v138 offset:53248
	ds_read_u16 v33, v138 offset:53760
	ds_read_u16 v34, v138 offset:54272
	ds_read_u16 v35, v138 offset:54784
	ds_read_u16 v36, v138 offset:55296
	ds_read_u16 v37, v138 offset:55808
	ds_read_u16 v38, v138 offset:56320
	s_waitcnt lgkmcnt(14)
	v_lshlrev_b32_e32 v60, 16, v24
	ds_read_u16 v39, v138 offset:56832
	s_waitcnt lgkmcnt(14)
	v_lshlrev_b32_e32 v59, 16, v25
	ds_read_u16 v40, v138 offset:57344
	s_waitcnt lgkmcnt(14)
	v_lshlrev_b32_e32 v58, 16, v26
	ds_read_u16 v41, v138 offset:57856
	s_waitcnt lgkmcnt(14)
	v_lshlrev_b32_e32 v56, 16, v27
	ds_read_u16 v42, v138 offset:58368
	s_waitcnt lgkmcnt(14)
	v_lshlrev_b32_e32 v54, 16, v28
	ds_read_u16 v43, v138 offset:58880
	s_waitcnt lgkmcnt(14)
	v_lshlrev_b32_e32 v52, 16, v29
	ds_read_u16 v62, v138 offset:59392
	s_waitcnt lgkmcnt(14)
	v_lshlrev_b32_e32 v49, 16, v30
	ds_read_u16 v63, v138 offset:59904
	s_waitcnt lgkmcnt(14)
	v_lshlrev_b32_e32 v46, 16, v31
	ds_read_u16 v64, v138 offset:60416
	s_waitcnt lgkmcnt(14)
	v_lshlrev_b32_e32 v57, 16, v32
	ds_read_u16 v65, v138 offset:60928
	s_waitcnt lgkmcnt(14)
	v_lshlrev_b32_e32 v55, 16, v33
	ds_read_u16 v66, v138 offset:61440
	s_waitcnt lgkmcnt(14)
	v_lshlrev_b32_e32 v53, 16, v34
	ds_read_u16 v67, v138 offset:61952
	s_waitcnt lgkmcnt(14)
	v_lshlrev_b32_e32 v50, 16, v35
	ds_read_u16 v68, v138 offset:62464
	s_waitcnt lgkmcnt(14)
	v_lshlrev_b32_e32 v47, 16, v36
	ds_read_u16 v69, v138 offset:62976
	s_waitcnt lgkmcnt(14)
	v_lshlrev_b32_e32 v44, 16, v37
	ds_read_u16 v70, v138 offset:63488
	s_waitcnt lgkmcnt(14)
	v_lshlrev_b32_e32 v13, 16, v38
	ds_read_u16 v71, v138 offset:64000
	s_waitcnt lgkmcnt(14)
	v_lshlrev_b32_e32 v10, 16, v39
	ds_read_u16 v72, v138 offset:64512
	s_waitcnt lgkmcnt(14)
	v_lshlrev_b32_e32 v51, 16, v40
	ds_read_u16 v73, v138 offset:65024
	s_waitcnt lgkmcnt(14)
	v_lshlrev_b32_e32 v48, 16, v41
	ds_read_u16 v74, v139 offset:16384
	s_waitcnt lgkmcnt(14)
	v_lshlrev_b32_e32 v45, 16, v42
	ds_read_u16 v75, v139 offset:16896
	s_waitcnt lgkmcnt(14)
	v_lshlrev_b32_e32 v14, 16, v43
	s_waitcnt lgkmcnt(13)
	v_lshlrev_b32_e32 v11, 16, v62
	s_waitcnt lgkmcnt(12)
	v_lshlrev_b32_e32 v8, 16, v63
	s_waitcnt lgkmcnt(11)
	v_lshlrev_b32_e32 v6, 16, v64
	s_waitcnt lgkmcnt(10)
	v_lshlrev_b32_e32 v3, 16, v65
	s_waitcnt lgkmcnt(9)
	v_lshlrev_b32_e32 v15, 16, v66
	s_waitcnt lgkmcnt(8)
	v_lshlrev_b32_e32 v12, 16, v67
	s_waitcnt lgkmcnt(7)
	v_lshlrev_b32_e32 v9, 16, v68
	s_waitcnt lgkmcnt(6)
	v_lshlrev_b32_e32 v7, 16, v69
	s_waitcnt lgkmcnt(5)
	v_lshlrev_b32_e32 v4, 16, v70
	s_waitcnt lgkmcnt(4)
	v_lshlrev_b32_e32 v5, 16, v71
	s_waitcnt lgkmcnt(3)
	v_lshlrev_b32_e32 v2, 16, v72
	s_waitcnt lgkmcnt(2)
	v_lshlrev_b32_e32 v1, 16, v73
	s_waitcnt lgkmcnt(1)
	v_lshlrev_b32_e32 v0, 16, v74
	s_waitcnt lgkmcnt(0)
	v_lshlrev_b32_e32 v61, 16, v75
	v_add_f32_e32 v60, v60, v58
	v_add_f32_e32 v62, v59, v56
	v_add_f32_e32 v63, v58, v54
	v_add_f32_e32 v64, v56, v52
	v_add_f32_e32 v65, v54, v49
	v_add_f32_e32 v66, v52, v46
	v_add_f32_e32 v67, v49, v57
	v_add_f32_e32 v68, v46, v55
	v_add_f32_e32 v69, v57, v53
	v_add_f32_e32 v70, v55, v50
	v_add_f32_e32 v71, v53, v47
	v_add_f32_e32 v72, v50, v44
	v_add_f32_e32 v73, v47, v13
	v_add_f32_e32 v74, v44, v10
	v_add_f32_e32 v75, v13, v51
	v_add_f32_e32 v76, v10, v48
	v_add_f32_e32 v92, v51, v45
	v_add_f32_e32 v93, v48, v14
	v_add_f32_e32 v94, v45, v11
	v_add_f32_e32 v95, v14, v8
	v_add_f32_e32 v96, v11, v6
	v_add_f32_e32 v98, v8, v3
	v_add_f32_e32 v99, v6, v15
	v_add_f32_e32 v100, v3, v12
	v_add_f32_e32 v101, v15, v9
	v_add_f32_e32 v102, v12, v7
	v_add_f32_e32 v103, v9, v4
	v_add_f32_e32 v104, v7, v5
	v_add_f32_e32 v105, v4, v2
	v_add_f32_e32 v106, v5, v1
	v_add_f32_e32 v107, v2, v0
	v_add_f32_e32 v108, v1, v61
	s_mov_b64 s[12:13], -1
	s_andn2_b64 vcc, exec, s[88:89]
	v_fma_f32 v91, v60, 0.5, -v59
	v_fma_f32 v90, v62, 0.5, -v58
	v_fma_f32 v89, v63, 0.5, -v56
	v_fma_f32 v88, v64, 0.5, -v54
	v_fma_f32 v87, v65, 0.5, -v52
	v_fma_f32 v86, v66, 0.5, -v49
	v_fma_f32 v85, v67, 0.5, -v46
	v_fma_f32 v84, v68, 0.5, -v57
	v_fma_f32 v83, v69, 0.5, -v55
	v_fma_f32 v82, v70, 0.5, -v53
	v_fma_f32 v81, v71, 0.5, -v50
	v_fma_f32 v80, v72, 0.5, -v47
	v_fma_f32 v79, v73, 0.5, -v44
	v_fma_f32 v78, v74, 0.5, -v13
	v_fma_f32 v77, v75, 0.5, -v10
	v_fma_f32 v76, v76, 0.5, -v51
	v_fma_f32 v75, v92, 0.5, -v48
	v_fma_f32 v74, v93, 0.5, -v45
	v_fma_f32 v73, v94, 0.5, -v14
	v_fma_f32 v72, v95, 0.5, -v11
	v_fma_f32 v71, v96, 0.5, -v8
	v_fma_f32 v70, v98, 0.5, -v6
	v_fma_f32 v69, v99, 0.5, -v3
	v_fma_f32 v68, v100, 0.5, -v15
	v_fma_f32 v67, v101, 0.5, -v12
	v_fma_f32 v66, v102, 0.5, -v9
	v_fma_f32 v65, v103, 0.5, -v7
	v_fma_f32 v64, v104, 0.5, -v4
	v_fma_f32 v63, v105, 0.5, -v5
	v_fma_f32 v62, v106, 0.5, -v2
	v_fma_f32 v61, v107, 0.5, -v1
	v_fma_f32 v60, v108, 0.5, -v0
	s_cbranch_vccnz .LBB0_370
; DI u16 f2bf(float x) { unsigned u = __float_as_uint(x); u += 0x7fffu + ((u >> 16) & 1u); return (u16)(u >> 16); }
;     ...
;           u16* tdst = ((c < 224) ? twb : tab) + ((c - 192) & 31);
; #pragma unroll
;           for (int j = 0; j < 32; ++j) {
;             const float psv = pv[j + 1] + mu * (0.5f * (pv[j] + pv[j + 2]) - pv[j + 1]);
;             const float th = 1.f - 2.f * __builtin_amdgcn_rcpf(__expf(2.f * psv) + 1.f);
;             tdst[(dir ? 31 - j : j) * 40] = f2bf((c < 224) ? th : psv);
;           }
	s_movk_i32 s12, 0x7fff
	v_fma_f32 v24, v123, v91, v59
	v_fma_f32 v26, v123, v90, v58
	v_fma_f32 v28, v123, v89, v56
	v_fma_f32 v30, v123, v88, v54
	v_fma_f32 v32, v123, v87, v52
	v_fma_f32 v34, v123, v86, v49
	v_fma_f32 v36, v123, v85, v46
	v_fma_f32 v38, v123, v84, v57
	v_add_f32_e32 v25, v24, v24
	v_add_f32_e32 v27, v26, v26
	v_add_f32_e32 v29, v28, v28
	v_add_f32_e32 v31, v30, v30
	v_add_f32_e32 v33, v32, v32
	v_add_f32_e32 v35, v34, v34
	v_add_f32_e32 v37, v36, v36
	v_add_f32_e32 v39, v38, v38
	v_mul_f32_e32 v25, 0x3fb8aa3b, v25
	v_mul_f32_e32 v27, 0x3fb8aa3b, v27
	v_mul_f32_e32 v29, 0x3fb8aa3b, v29
	v_mul_f32_e32 v31, 0x3fb8aa3b, v31
	v_mul_f32_e32 v33, 0x3fb8aa3b, v33
	v_mul_f32_e32 v35, 0x3fb8aa3b, v35
	v_mul_f32_e32 v37, 0x3fb8aa3b, v37
	v_mul_f32_e32 v39, 0x3fb8aa3b, v39
	v_exp_f32_e32 v25, v25
	v_exp_f32_e32 v27, v27
	v_exp_f32_e32 v29, v29
	v_exp_f32_e32 v31, v31
	v_exp_f32_e32 v33, v33
	v_exp_f32_e32 v35, v35
	v_exp_f32_e32 v37, v37
	v_exp_f32_e32 v39, v39
	v_add_f32_e32 v25, 1.0, v25
	v_add_f32_e32 v27, 1.0, v27
	v_add_f32_e32 v29, 1.0, v29
	v_add_f32_e32 v31, 1.0, v31
	v_add_f32_e32 v33, 1.0, v33
	v_add_f32_e32 v35, 1.0, v35
	v_add_f32_e32 v37, 1.0, v37
	v_add_f32_e32 v39, 1.0, v39
	v_rcp_f32_e32 v25, v25
	v_rcp_f32_e32 v27, v27
	v_rcp_f32_e32 v29, v29
	v_rcp_f32_e32 v31, v31
	v_rcp_f32_e32 v33, v33
	v_rcp_f32_e32 v35, v35
	v_rcp_f32_e32 v37, v37
	v_rcp_f32_e32 v39, v39
	v_fma_f32 v25, v25, -2.0, 1.0
	v_fma_f32 v27, v27, -2.0, 1.0
	v_fma_f32 v29, v29, -2.0, 1.0
	v_fma_f32 v31, v31, -2.0, 1.0
	v_fma_f32 v33, v33, -2.0, 1.0
	v_fma_f32 v35, v35, -2.0, 1.0
	v_fma_f32 v37, v37, -2.0, 1.0
	v_fma_f32 v39, v39, -2.0, 1.0
	v_cndmask_b32_e64 v24, v24, v25, s[6:7]
	v_cndmask_b32_e64 v26, v26, v27, s[6:7]
	v_cndmask_b32_e64 v28, v28, v29, s[6:7]
	v_cndmask_b32_e64 v30, v30, v31, s[6:7]
	v_cndmask_b32_e64 v32, v32, v33, s[6:7]
	v_cndmask_b32_e64 v34, v34, v35, s[6:7]
	v_cndmask_b32_e64 v36, v36, v37, s[6:7]
	v_cndmask_b32_e64 v38, v38, v39, s[6:7]
	v_bfe_u32 v25, v24, 16, 1
	v_bfe_u32 v27, v26, 16, 1
	v_bfe_u32 v29, v28, 16, 1
	v_bfe_u32 v31, v30, 16, 1
	v_bfe_u32 v33, v32, 16, 1
	v_bfe_u32 v35, v34, 16, 1
	v_bfe_u32 v37, v36, 16, 1
	v_bfe_u32 v39, v38, 16, 1
	v_add3_u32 v24, v24, v25, s12
	v_add3_u32 v26, v26, v27, s12
	v_add3_u32 v28, v28, v29, s12
	v_add3_u32 v30, v30, v31, s12
	v_add3_u32 v32, v32, v33, s12
	v_add3_u32 v34, v34, v35, s12
	v_add3_u32 v36, v36, v37, s12
	v_add3_u32 v38, v38, v39, s12
	v_add_u32_e32 v25, s95, v140
	v_add_u32_e32 v27, s97, v140
	v_add_u32_e32 v29, s28, v140
	v_add_u32_e32 v31, s29, v140
	v_add_u32_e32 v33, s17, v140
	v_add_u32_e32 v35, s18, v140
	v_add_u32_e32 v37, s19, v140
	v_add_u32_e32 v39, s20, v140
	ds_write_b16_d16_hi v25, v24
	ds_write_b16_d16_hi v27, v26
	ds_write_b16_d16_hi v29, v28
	ds_write_b16_d16_hi v31, v30
	ds_write_b16_d16_hi v33, v32
	ds_write_b16_d16_hi v35, v34
	ds_write_b16_d16_hi v37, v36
	ds_write_b16_d16_hi v39, v38
	v_fma_f32 v24, v123, v83, v55
	v_fma_f32 v26, v123, v82, v53
	v_fma_f32 v28, v123, v81, v50
	v_fma_f32 v30, v123, v80, v47
	v_fma_f32 v32, v123, v79, v44
	v_fma_f32 v34, v123, v78, v13
	v_fma_f32 v36, v123, v77, v10
	v_fma_f32 v38, v123, v76, v51
	v_add_f32_e32 v25, v24, v24
	v_add_f32_e32 v27, v26, v26
	v_add_f32_e32 v29, v28, v28
	v_add_f32_e32 v31, v30, v30
	v_add_f32_e32 v33, v32, v32
	v_add_f32_e32 v35, v34, v34
	v_add_f32_e32 v37, v36, v36
	v_add_f32_e32 v39, v38, v38
	v_mul_f32_e32 v25, 0x3fb8aa3b, v25
	v_mul_f32_e32 v27, 0x3fb8aa3b, v27
	v_mul_f32_e32 v29, 0x3fb8aa3b, v29
	v_mul_f32_e32 v31, 0x3fb8aa3b, v31
	v_mul_f32_e32 v33, 0x3fb8aa3b, v33
	v_mul_f32_e32 v35, 0x3fb8aa3b, v35
	v_mul_f32_e32 v37, 0x3fb8aa3b, v37
	v_mul_f32_e32 v39, 0x3fb8aa3b, v39
	v_exp_f32_e32 v25, v25
	v_exp_f32_e32 v27, v27
	v_exp_f32_e32 v29, v29
	v_exp_f32_e32 v31, v31
	v_exp_f32_e32 v33, v33
	v_exp_f32_e32 v35, v35
	v_exp_f32_e32 v37, v37
	v_exp_f32_e32 v39, v39
	v_add_f32_e32 v25, 1.0, v25
	v_add_f32_e32 v27, 1.0, v27
	v_add_f32_e32 v29, 1.0, v29
	v_add_f32_e32 v31, 1.0, v31
	v_add_f32_e32 v33, 1.0, v33
	v_add_f32_e32 v35, 1.0, v35
	v_add_f32_e32 v37, 1.0, v37
	v_add_f32_e32 v39, 1.0, v39
	v_rcp_f32_e32 v25, v25
	v_rcp_f32_e32 v27, v27
	v_rcp_f32_e32 v29, v29
	v_rcp_f32_e32 v31, v31
	v_rcp_f32_e32 v33, v33
	v_rcp_f32_e32 v35, v35
	v_rcp_f32_e32 v37, v37
	v_rcp_f32_e32 v39, v39
	v_fma_f32 v25, v25, -2.0, 1.0
	v_fma_f32 v27, v27, -2.0, 1.0
	v_fma_f32 v29, v29, -2.0, 1.0
	v_fma_f32 v31, v31, -2.0, 1.0
	v_fma_f32 v33, v33, -2.0, 1.0
	v_fma_f32 v35, v35, -2.0, 1.0
	v_fma_f32 v37, v37, -2.0, 1.0
	v_fma_f32 v39, v39, -2.0, 1.0
	v_cndmask_b32_e64 v24, v24, v25, s[6:7]
	v_cndmask_b32_e64 v26, v26, v27, s[6:7]
	v_cndmask_b32_e64 v28, v28, v29, s[6:7]
	v_cndmask_b32_e64 v30, v30, v31, s[6:7]
	v_cndmask_b32_e64 v32, v32, v33, s[6:7]
	v_cndmask_b32_e64 v34, v34, v35, s[6:7]
	v_cndmask_b32_e64 v36, v36, v37, s[6:7]
	v_cndmask_b32_e64 v38, v38, v39, s[6:7]
	v_bfe_u32 v25, v24, 16, 1
	v_bfe_u32 v27, v26, 16, 1
	v_bfe_u32 v29, v28, 16, 1
	v_bfe_u32 v31, v30, 16, 1
	v_bfe_u32 v33, v32, 16, 1
	v_bfe_u32 v35, v34, 16, 1
	v_bfe_u32 v37, v36, 16, 1
	v_bfe_u32 v39, v38, 16, 1
	v_add3_u32 v24, v24, v25, s12
	v_add3_u32 v26, v26, v27, s12
	v_add3_u32 v28, v28, v29, s12
	v_add3_u32 v30, v30, v31, s12
	v_add3_u32 v32, v32, v33, s12
	v_add3_u32 v34, v34, v35, s12
	v_add3_u32 v36, v36, v37, s12
	v_add3_u32 v38, v38, v39, s12
	v_add_u32_e32 v25, s21, v140
	v_add_u32_e32 v27, s96, v140
	v_add_u32_e32 v29, s82, v140
	v_add_u32_e32 v31, s22, v140
	v_add_u32_e32 v33, s23, v140
	v_add_u32_e32 v35, s24, v140
	v_add_u32_e32 v37, s83, v140
	v_add_u32_e32 v39, s33, v140
	ds_write_b16_d16_hi v25, v24
	ds_write_b16_d16_hi v27, v26
; DI u16 f2bf(float x) { unsigned u = __float_as_uint(x); u += 0x7fffu + ((u >> 16) & 1u); return (u16)(u >> 16); }
;     ...
;           u16* tdst = ((c < 224) ? twb : tab) + ((c - 192) & 31);
; #pragma unroll
;           for (int j = 0; j < 32; ++j) {
;             const float psv = pv[j + 1] + mu * (0.5f * (pv[j] + pv[j + 2]) - pv[j + 1]);
;             const float th = 1.f - 2.f * __builtin_amdgcn_rcpf(__expf(2.f * psv) + 1.f);
;             tdst[(dir ? 31 - j : j) * 40] = f2bf((c < 224) ? th : psv);
;           }
	ds_write_b16_d16_hi v29, v28
	ds_write_b16_d16_hi v31, v30
	ds_write_b16_d16_hi v33, v32
	ds_write_b16_d16_hi v35, v34
	ds_write_b16_d16_hi v37, v36
	ds_write_b16_d16_hi v39, v38
	v_fma_f32 v24, v123, v75, v48
	v_fma_f32 v26, v123, v74, v45
	v_fma_f32 v28, v123, v73, v14
	v_fma_f32 v30, v123, v72, v11
	v_fma_f32 v32, v123, v71, v8
	v_fma_f32 v34, v123, v70, v6
	v_fma_f32 v36, v123, v69, v3
	v_fma_f32 v38, v123, v68, v15
	v_add_f32_e32 v25, v24, v24
	v_add_f32_e32 v27, v26, v26
	v_add_f32_e32 v29, v28, v28
	v_add_f32_e32 v31, v30, v30
	v_add_f32_e32 v33, v32, v32
	v_add_f32_e32 v35, v34, v34
	v_add_f32_e32 v37, v36, v36
	v_add_f32_e32 v39, v38, v38
	v_mul_f32_e32 v25, 0x3fb8aa3b, v25
	v_mul_f32_e32 v27, 0x3fb8aa3b, v27
	v_mul_f32_e32 v29, 0x3fb8aa3b, v29
	v_mul_f32_e32 v31, 0x3fb8aa3b, v31
	v_mul_f32_e32 v33, 0x3fb8aa3b, v33
	v_mul_f32_e32 v35, 0x3fb8aa3b, v35
	v_mul_f32_e32 v37, 0x3fb8aa3b, v37
	v_mul_f32_e32 v39, 0x3fb8aa3b, v39
	v_exp_f32_e32 v25, v25
	v_exp_f32_e32 v27, v27
	v_exp_f32_e32 v29, v29
	v_exp_f32_e32 v31, v31
	v_exp_f32_e32 v33, v33
	v_exp_f32_e32 v35, v35
	v_exp_f32_e32 v37, v37
	v_exp_f32_e32 v39, v39
	v_add_f32_e32 v25, 1.0, v25
	v_add_f32_e32 v27, 1.0, v27
	v_add_f32_e32 v29, 1.0, v29
	v_add_f32_e32 v31, 1.0, v31
	v_add_f32_e32 v33, 1.0, v33
	v_add_f32_e32 v35, 1.0, v35
	v_add_f32_e32 v37, 1.0, v37
	v_add_f32_e32 v39, 1.0, v39
	v_rcp_f32_e32 v25, v25
	v_rcp_f32_e32 v27, v27
	v_rcp_f32_e32 v29, v29
	v_rcp_f32_e32 v31, v31
	v_rcp_f32_e32 v33, v33
	v_rcp_f32_e32 v35, v35
	v_rcp_f32_e32 v37, v37
	v_rcp_f32_e32 v39, v39
	v_fma_f32 v25, v25, -2.0, 1.0
	v_fma_f32 v27, v27, -2.0, 1.0
	v_fma_f32 v29, v29, -2.0, 1.0
	v_fma_f32 v31, v31, -2.0, 1.0
	v_fma_f32 v33, v33, -2.0, 1.0
	v_fma_f32 v35, v35, -2.0, 1.0
	v_fma_f32 v37, v37, -2.0, 1.0
	v_fma_f32 v39, v39, -2.0, 1.0
	v_cndmask_b32_e64 v24, v24, v25, s[6:7]
	v_cndmask_b32_e64 v26, v26, v27, s[6:7]
	v_cndmask_b32_e64 v28, v28, v29, s[6:7]
	v_cndmask_b32_e64 v30, v30, v31, s[6:7]
	v_cndmask_b32_e64 v32, v32, v33, s[6:7]
	v_cndmask_b32_e64 v34, v34, v35, s[6:7]
	v_cndmask_b32_e64 v36, v36, v37, s[6:7]
	v_cndmask_b32_e64 v38, v38, v39, s[6:7]
	v_bfe_u32 v25, v24, 16, 1
	v_bfe_u32 v27, v26, 16, 1
	v_bfe_u32 v29, v28, 16, 1
	v_bfe_u32 v31, v30, 16, 1
	v_bfe_u32 v33, v32, 16, 1
	v_bfe_u32 v35, v34, 16, 1
	v_bfe_u32 v37, v36, 16, 1
	v_bfe_u32 v39, v38, 16, 1
	v_add3_u32 v24, v24, v25, s12
	v_add3_u32 v26, v26, v27, s12
	v_add3_u32 v28, v28, v29, s12
	v_add3_u32 v30, v30, v31, s12
	v_add3_u32 v32, v32, v33, s12
	v_add3_u32 v34, v34, v35, s12
	v_add3_u32 v36, v36, v37, s12
	v_add3_u32 v38, v38, v39, s12
	v_add_u32_e32 v25, s52, v140
	v_add_u32_e32 v27, s36, v140
	v_add_u32_e32 v29, s37, v140
	v_add_u32_e32 v31, s38, v140
	v_add_u32_e32 v33, s39, v140
	v_add_u32_e32 v35, s40, v140
	v_add_u32_e32 v37, s41, v140
	v_add_u32_e32 v39, s42, v140
	ds_write_b16_d16_hi v25, v24
	ds_write_b16_d16_hi v27, v26
	ds_write_b16_d16_hi v29, v28
	ds_write_b16_d16_hi v31, v30
	ds_write_b16_d16_hi v33, v32
	ds_write_b16_d16_hi v35, v34
	ds_write_b16_d16_hi v37, v36
	ds_write_b16_d16_hi v39, v38
	v_fma_f32 v24, v123, v67, v12
	v_fma_f32 v26, v123, v66, v9
	v_fma_f32 v28, v123, v65, v7
	v_fma_f32 v30, v123, v64, v4
	v_fma_f32 v32, v123, v63, v5
	v_fma_f32 v34, v123, v62, v2
	v_fma_f32 v36, v123, v61, v1
	v_fma_f32 v38, v123, v60, v0
	v_add_f32_e32 v25, v24, v24
	v_add_f32_e32 v27, v26, v26
	v_add_f32_e32 v29, v28, v28
	v_add_f32_e32 v31, v30, v30
	v_add_f32_e32 v33, v32, v32
	v_add_f32_e32 v35, v34, v34
	v_add_f32_e32 v37, v36, v36
	v_add_f32_e32 v39, v38, v38
	v_mul_f32_e32 v25, 0x3fb8aa3b, v25
	v_mul_f32_e32 v27, 0x3fb8aa3b, v27
	v_mul_f32_e32 v29, 0x3fb8aa3b, v29
	v_mul_f32_e32 v31, 0x3fb8aa3b, v31
	v_mul_f32_e32 v33, 0x3fb8aa3b, v33
	v_mul_f32_e32 v35, 0x3fb8aa3b, v35
	v_mul_f32_e32 v37, 0x3fb8aa3b, v37
	v_mul_f32_e32 v39, 0x3fb8aa3b, v39
	v_exp_f32_e32 v25, v25
	v_exp_f32_e32 v27, v27
	v_exp_f32_e32 v29, v29
	v_exp_f32_e32 v31, v31
	v_exp_f32_e32 v33, v33
	v_exp_f32_e32 v35, v35
	v_exp_f32_e32 v37, v37
	v_exp_f32_e32 v39, v39
	v_add_f32_e32 v25, 1.0, v25
	v_add_f32_e32 v27, 1.0, v27
	v_add_f32_e32 v29, 1.0, v29
	v_add_f32_e32 v31, 1.0, v31
	v_add_f32_e32 v33, 1.0, v33
	v_add_f32_e32 v35, 1.0, v35
	v_add_f32_e32 v37, 1.0, v37
	v_add_f32_e32 v39, 1.0, v39
	v_rcp_f32_e32 v25, v25
	v_rcp_f32_e32 v27, v27
	v_rcp_f32_e32 v29, v29
	v_rcp_f32_e32 v31, v31
	v_rcp_f32_e32 v33, v33
	v_rcp_f32_e32 v35, v35
	v_rcp_f32_e32 v37, v37
	v_rcp_f32_e32 v39, v39
	v_fma_f32 v25, v25, -2.0, 1.0
	v_fma_f32 v27, v27, -2.0, 1.0
	v_fma_f32 v29, v29, -2.0, 1.0
	v_fma_f32 v31, v31, -2.0, 1.0
	v_fma_f32 v33, v33, -2.0, 1.0
	v_fma_f32 v35, v35, -2.0, 1.0
	v_fma_f32 v37, v37, -2.0, 1.0
	v_fma_f32 v39, v39, -2.0, 1.0
	v_cndmask_b32_e64 v24, v24, v25, s[6:7]
	v_cndmask_b32_e64 v26, v26, v27, s[6:7]
	v_cndmask_b32_e64 v28, v28, v29, s[6:7]
	v_cndmask_b32_e64 v30, v30, v31, s[6:7]
	v_cndmask_b32_e64 v32, v32, v33, s[6:7]
	v_cndmask_b32_e64 v34, v34, v35, s[6:7]
	v_cndmask_b32_e64 v36, v36, v37, s[6:7]
	v_cndmask_b32_e64 v38, v38, v39, s[6:7]
	v_bfe_u32 v25, v24, 16, 1
	v_bfe_u32 v27, v26, 16, 1
	v_bfe_u32 v29, v28, 16, 1
	v_bfe_u32 v31, v30, 16, 1
	v_bfe_u32 v33, v32, 16, 1
	v_bfe_u32 v35, v34, 16, 1
	v_bfe_u32 v37, v36, 16, 1
	v_bfe_u32 v39, v38, 16, 1
	v_add3_u32 v24, v24, v25, s12
	v_add3_u32 v26, v26, v27, s12
	v_add3_u32 v28, v28, v29, s12
	v_add3_u32 v30, v30, v31, s12
	v_add3_u32 v32, v32, v33, s12
	v_add3_u32 v34, v34, v35, s12
	v_add3_u32 v36, v36, v37, s12
	v_add3_u32 v38, v38, v39, s12
	v_add_u32_e32 v25, s43, v140
	v_add_u32_e32 v27, s44, v140
	v_add_u32_e32 v29, s45, v140
	v_add_u32_e32 v31, s46, v140
	v_add_u32_e32 v33, s47, v140
	v_add_u32_e32 v35, s48, v140
	v_add_u32_e32 v37, s49, v140
	v_add_u32_e32 v39, s50, v140
	ds_write_b16_d16_hi v25, v24
	ds_write_b16_d16_hi v27, v26
	ds_write_b16_d16_hi v29, v28
	ds_write_b16_d16_hi v31, v30
	ds_write_b16_d16_hi v33, v32
	ds_write_b16_d16_hi v35, v34
	ds_write_b16_d16_hi v37, v36
	ds_write_b16_d16_hi v39, v38
	s_mov_b64 s[12:13], 0

.LBB0_426:
	s_and_b32 s3, s3, 1
	s_mul_i32 s5, s3, 0x2400
	v_add_u32_e32 v227, s5, v171
	ds_read_b128 v[130:133], v227
	ds_read_b128 v[136:139], v227 offset:32
	ds_read_b128 v[140:143], v227 offset:4608
	ds_read_b128 v[144:147], v227 offset:4640
	v_xor_b32_e32 v64, 0x80000000, v225
	v_mov_b32_e32 v65, v64
	v_mov_b32_e32 v66, v64
	v_mov_b32_e32 v67, v64
	v_mov_b32_e32 v68, v64
	v_mov_b32_e32 v69, v64
	v_mov_b32_e32 v70, v64
	v_mov_b32_e32 v71, v64
	v_mov_b32_e32 v72, v64
	v_mov_b32_e32 v73, v64
	v_mov_b32_e32 v74, v64
	v_mov_b32_e32 v75, v64
	v_mov_b32_e32 v76, v64
	v_mov_b32_e32 v77, v64
	v_mov_b32_e32 v78, v64
	v_mov_b32_e32 v79, v64
	s_mov_b32 s5, 0x41000000
	s_waitcnt lgkmcnt(3)
	v_mfma_f32_32x32x16_bf16 v[80:95], v[130:133], v[98:101], v[64:79]
	s_waitcnt lgkmcnt(2)
	v_mfma_f32_32x32x16_bf16 v[80:95], v[136:139], v[102:105], v[80:95]
	s_waitcnt lgkmcnt(1)
	v_mfma_f32_32x32x16_bf16 v[64:79], v[140:143], v[98:101], v[64:79]
	s_waitcnt lgkmcnt(0)
	v_mfma_f32_32x32x16_bf16 v[64:79], v[144:147], v[102:105], v[64:79]
	s_nop 7
	v_max_f32_e32 v134, v81, v81
	v_max_f32_e32 v135, v80, v80
	v_max_f32_e32 v134, v135, v134
	v_max3_f32 v134, v134, v82, v83
	v_max3_f32 v130, v134, v84, v85
	v_max3_f32 v130, v130, v86, v87
	v_max3_f32 v130, v130, v88, v89
	v_max3_f32 v130, v130, v90, v91
	v_max3_f32 v130, v130, v92, v93
	v_max3_f32 v130, v130, v94, v95
	v_max3_f32 v130, v130, v64, v65
	v_max3_f32 v130, v130, v66, v67
	v_max3_f32 v130, v130, v68, v69
	v_max3_f32 v130, v130, v70, v71
	v_max3_f32 v130, v130, v72, v73
	v_max3_f32 v130, v130, v74, v75
	v_max3_f32 v130, v130, v76, v77
	v_max3_f32 v130, v130, v78, v79
	v_mov_b32_e32 v131, v130
	s_nop 1
	v_permlane32_swap_b32_e32 v130, v131
	v_max_f32_e32 v131, v131, v131
	v_max_f32_e32 v130, v130, v130
	v_max_f32_e32 v130, v130, v131
	v_cmp_lt_f32_e32 vcc, s5, v130
	s_cbranch_vccz .LBB0_428
	v_max_f32_e32 v130, v130, v130
	v_max_f32_e32 v130, 0, v130
	v_exp_f32_e64 v132, -v130
	v_add_f32_e32 v225, v225, v130
	v_pk_add_f32 v[80:81], v[80:81], v[130:131] op_sel_hi:[1,0] neg_lo:[0,1] neg_hi:[0,1]
	v_pk_add_f32 v[82:83], v[82:83], v[130:131] op_sel_hi:[1,0] neg_lo:[0,1] neg_hi:[0,1]
	v_mul_f32_e32 v172, v172, v132
	v_pk_add_f32 v[84:85], v[84:85], v[130:131] op_sel_hi:[1,0] neg_lo:[0,1] neg_hi:[0,1]
	v_pk_add_f32 v[86:87], v[86:87], v[130:131] op_sel_hi:[1,0] neg_lo:[0,1] neg_hi:[0,1]
	v_pk_add_f32 v[88:89], v[88:89], v[130:131] op_sel_hi:[1,0] neg_lo:[0,1] neg_hi:[0,1]
	v_pk_add_f32 v[90:91], v[90:91], v[130:131] op_sel_hi:[1,0] neg_lo:[0,1] neg_hi:[0,1]
	v_pk_add_f32 v[92:93], v[92:93], v[130:131] op_sel_hi:[1,0] neg_lo:[0,1] neg_hi:[0,1]
	v_pk_add_f32 v[94:95], v[94:95], v[130:131] op_sel_hi:[1,0] neg_lo:[0,1] neg_hi:[0,1]
	v_pk_add_f32 v[64:65], v[64:65], v[130:131] op_sel_hi:[1,0] neg_lo:[0,1] neg_hi:[0,1]
	v_pk_add_f32 v[66:67], v[66:67], v[130:131] op_sel_hi:[1,0] neg_lo:[0,1] neg_hi:[0,1]
	v_pk_add_f32 v[68:69], v[68:69], v[130:131] op_sel_hi:[1,0] neg_lo:[0,1] neg_hi:[0,1]
	v_pk_add_f32 v[70:71], v[70:71], v[130:131] op_sel_hi:[1,0] neg_lo:[0,1] neg_hi:[0,1]
	v_pk_add_f32 v[72:73], v[72:73], v[130:131] op_sel_hi:[1,0] neg_lo:[0,1] neg_hi:[0,1]
	v_pk_add_f32 v[74:75], v[74:75], v[130:131] op_sel_hi:[1,0] neg_lo:[0,1] neg_hi:[0,1]
	v_pk_add_f32 v[76:77], v[76:77], v[130:131] op_sel_hi:[1,0] neg_lo:[0,1] neg_hi:[0,1]
	v_pk_add_f32 v[78:79], v[78:79], v[130:131] op_sel_hi:[1,0] neg_lo:[0,1] neg_hi:[0,1]
	v_pk_mul_f32 v[14:15], v[14:15], v[132:133] op_sel_hi:[1,0]
	v_pk_mul_f32 v[12:13], v[12:13], v[132:133] op_sel_hi:[1,0]
	v_pk_mul_f32 v[10:11], v[10:11], v[132:133] op_sel_hi:[1,0]
	v_pk_mul_f32 v[8:9], v[8:9], v[132:133] op_sel_hi:[1,0]
	v_pk_mul_f32 v[6:7], v[6:7], v[132:133] op_sel_hi:[1,0]
	v_pk_mul_f32 v[4:5], v[4:5], v[132:133] op_sel_hi:[1,0]
	v_pk_mul_f32 v[2:3], v[2:3], v[132:133] op_sel_hi:[1,0]
	v_pk_mul_f32 v[0:1], v[0:1], v[132:133] op_sel_hi:[1,0]
	v_pk_mul_f32 v[30:31], v[30:31], v[132:133] op_sel_hi:[1,0]
	v_pk_mul_f32 v[28:29], v[28:29], v[132:133] op_sel_hi:[1,0]
	v_pk_mul_f32 v[26:27], v[26:27], v[132:133] op_sel_hi:[1,0]
	v_pk_mul_f32 v[24:25], v[24:25], v[132:133] op_sel_hi:[1,0]
	v_pk_mul_f32 v[22:23], v[22:23], v[132:133] op_sel_hi:[1,0]
	v_pk_mul_f32 v[20:21], v[20:21], v[132:133] op_sel_hi:[1,0]
	v_pk_mul_f32 v[18:19], v[18:19], v[132:133] op_sel_hi:[1,0]
	v_pk_mul_f32 v[16:17], v[16:17], v[132:133] op_sel_hi:[1,0]

;     ...
;     const u16* Ag = A + (size_t)(m0 + lrow) * K + lkc * 8;
;     const u16* Bg = Bt + (size_t)(n0 + lrow) * K + lkc * 8;
;     const size_t K32 = (size_t)32 * K;
;     uint4 xa0, xa1, xa2, xa3, xb0, xb1, xb2, xb3;
;     uint4 ya0, ya1, ya2, ya3, yb0, yb1, yb2, yb3;
;     ...
;     G_LOAD(x, 0);
;     G_STORE(x, 0);
;     __syncthreads();
;     if (KT > 1) G_LOAD(x, 1);
;     for (int kt = 0; kt < KT; kt += 2) {
;       if (kt + 2 < KT && dummy != 2) G_LOAD(y, kt + 2);
;       G_COMPUTE(0);
;       if (kt + 1 < KT && dummy != 2) G_STORE(x, 1);
;       __syncthreads();
.LBB0_574:
	s_lshl_b32 s0, s3, 3
	v_readlane_b32 s1, v252, 34
	s_or_b32 s4, s0, s1
	v_readlane_b32 s0, v252, 28
	v_readlane_b32 s1, v252, 29
	s_and_b64 s[0:1], s[0:1], exec
	s_cselect_b32 s0, s4, s3
	s_lshl_b32 s9, s0, 7
	s_lshl_b32 s4, s2, 7
	v_add_u32_e32 v0, s9, v154
	v_ashrrev_i32_e32 v1, 31, v0
	v_lshlrev_b64 v[0:1], 11, v[0:1]
	v_lshl_add_u64 v[138:139], v[130:131], 0, v[0:1]
	v_add_u32_e32 v0, s4, v154
	v_ashrrev_i32_e32 v1, 31, v0
	v_lshlrev_b64 v[0:1], 11, v[0:1]
	v_lshl_add_u64 v[140:141], v[132:133], 0, v[0:1]
	v_and_b32_e32 v194, 7, v206
	v_bfe_u32 v195, v206, 4, 3
	v_xor_b32_e32 v195, v195, v194
	v_sub_u32_e32 v195, v195, v194
	v_lshlrev_b32_e32 v192, 4, v195
	v_ashrrev_i32_e32 v193, 31, v192
	v_lshl_add_u64 v[138:139], v[138:139], 0, v[192:193]
	v_lshl_add_u64 v[140:141], v[140:141], 0, v[192:193]
	s_mov_b64 s[78:79], 0x10000
	v_lshl_add_u64 v[142:143], v[138:139], 0, s[78:79]
	v_lshl_add_u64 v[146:147], v[140:141], 0, s[78:79]
	s_mov_b64 s[78:79], 0x20000
	v_lshl_add_u64 v[144:145], v[138:139], 0, s[78:79]
	v_lshl_add_u64 v[148:149], v[140:141], 0, s[78:79]
	s_mov_b64 s[78:79], 0x30000
	v_lshl_add_u64 v[152:153], v[138:139], 0, s[78:79]
	v_lshl_add_u64 v[150:151], v[140:141], 0, s[78:79]
	v_lshrrev_b32_e32 v194, 6, v206
	v_lshlrev_b32_e32 v194, 10, v194
	s_nop 0
	v_readfirstlane_b32 s76, v194
	v_bfe_u32 v195, v206, 1, 3
	v_bfe_u32 v194, v206, 5, 1
	v_and_b32_e32 v192, 1, v195
	v_xor_b32_e32 v194, v194, v192
	v_lshrrev_b32_e32 v195, 1, v195
	v_and_b32_e32 v192, 31, v206
	v_lshrrev_b32_e32 v193, 7, v206
	v_lshl_add_u32 v193, v193, 6, v192
	v_lshlrev_b32_e32 v193, 7, v193
	v_lshl_add_u32 v193, v194, 4, v193
	v_add_u32_e32 v193, 2048, v193
	v_bfe_u32 v172, v206, 6, 1
	v_lshl_add_u32 v172, v172, 6, v192
	v_lshlrev_b32_e32 v172, 7, v172
	v_lshl_add_u32 v172, v194, 4, v172
	v_add_u32_e32 v172, 18432, v172
	v_xor_b32_e32 v192, 0, v195
	v_lshl_add_u32 v196, v192, 5, v193
	v_lshl_add_u32 v200, v192, 5, v172
	v_xor_b32_e32 v192, 1, v195
	v_lshl_add_u32 v197, v192, 5, v193
	v_lshl_add_u32 v201, v192, 5, v172
	v_xor_b32_e32 v192, 2, v195
	v_lshl_add_u32 v198, v192, 5, v193
	v_lshl_add_u32 v202, v192, 5, v172
	v_xor_b32_e32 v192, 3, v195
	v_lshl_add_u32 v199, v192, 5, v193
	v_lshl_add_u32 v203, v192, 5, v172
	s_add_u32 m0, s76, 0x800
	s_nop 0
	global_load_lds_dwordx4 v[138:139], off
	s_add_u32 m0, s76, 0x1800
	s_nop 0
	global_load_lds_dwordx4 v[142:143], off
	s_add_u32 m0, s76, 0x2800
	s_nop 0
	global_load_lds_dwordx4 v[144:145], off
	s_add_u32 m0, s76, 0x3800
	s_nop 0
	global_load_lds_dwordx4 v[152:153], off
	s_add_u32 m0, s76, 0x4800
	s_nop 0
	global_load_lds_dwordx4 v[140:141], off
	s_add_u32 m0, s76, 0x5800
	s_nop 0
	global_load_lds_dwordx4 v[146:147], off
	s_add_u32 m0, s76, 0x6800
	s_nop 0
	global_load_lds_dwordx4 v[148:149], off
	s_add_u32 m0, s76, 0x7800
	s_nop 0
	global_load_lds_dwordx4 v[150:151], off
	s_waitcnt vmcnt(0)
	s_barrier
	s_setprio 1
	ds_read_b128 v[156:159], v196
	ds_read_b128 v[164:167], v200
	ds_read_b128 v[168:171], v200 offset:4096
	ds_read_b128 v[172:175], v196 offset:4096
	ds_read_b128 v[176:179], v197
	ds_read_b128 v[180:183], v201
	ds_read_b128 v[184:187], v201 offset:4096
	ds_read_b128 v[188:191], v197 offset:4096
	s_add_u32 m0, s76, 0x8780
	s_nop 0
	global_load_lds_dwordx4 v[138:139], off offset:128
	s_add_u32 m0, s76, 0x9780
	s_nop 0
	global_load_lds_dwordx4 v[142:143], off offset:128
	s_add_u32 m0, s76, 0xa780
	s_nop 0
	global_load_lds_dwordx4 v[144:145], off offset:128
	s_add_u32 m0, s76, 0xb780
	s_nop 0
	global_load_lds_dwordx4 v[152:153], off offset:128
	s_add_u32 m0, s76, 0xc780
	s_nop 0
	global_load_lds_dwordx4 v[140:141], off offset:128
	s_add_u32 m0, s76, 0xd780
	s_nop 0
	global_load_lds_dwordx4 v[146:147], off offset:128
	s_add_u32 m0, s76, 0xe780
	s_nop 0
	global_load_lds_dwordx4 v[148:149], off offset:128
	s_add_u32 m0, s76, 0xf780
	s_nop 0
	global_load_lds_dwordx4 v[150:151], off offset:128
	s_waitcnt lgkmcnt(6)
	v_mfma_f32_32x32x16_bf16 v[48:63], v[156:159], v[164:167], 0
	s_waitcnt lgkmcnt(5)
	v_mfma_f32_32x32x16_bf16 v[32:47], v[156:159], v[168:171], 0
	s_waitcnt lgkmcnt(4)
	v_mfma_f32_32x32x16_bf16 v[16:31], v[172:175], v[164:167], 0
	v_mfma_f32_32x32x16_bf16 v[0:15], v[172:175], v[168:171], 0
	ds_read_b128 v[156:159], v198
	ds_read_b128 v[164:167], v202
	ds_read_b128 v[168:171], v202 offset:4096
	ds_read_b128 v[172:175], v198 offset:4096
	s_waitcnt lgkmcnt(6)
	v_mfma_f32_32x32x16_bf16 v[48:63], v[176:179], v[180:183], v[48:63]
	s_waitcnt lgkmcnt(5)
	v_mfma_f32_32x32x16_bf16 v[32:47], v[176:179], v[184:187], v[32:47]
	s_waitcnt lgkmcnt(4)
	v_mfma_f32_32x32x16_bf16 v[16:31], v[188:191], v[180:183], v[16:31]
	v_mfma_f32_32x32x16_bf16 v[0:15], v[188:191], v[184:187], v[0:15]
	ds_read_b128 v[176:179], v199
	ds_read_b128 v[180:183], v203
	ds_read_b128 v[184:187], v203 offset:4096
	ds_read_b128 v[188:191], v199 offset:4096
	s_waitcnt lgkmcnt(6)
	v_mfma_f32_32x32x16_bf16 v[48:63], v[156:159], v[164:167], v[48:63]
	s_waitcnt lgkmcnt(5)
	v_mfma_f32_32x32x16_bf16 v[32:47], v[156:159], v[168:171], v[32:47]
	s_waitcnt lgkmcnt(4)
	v_mfma_f32_32x32x16_bf16 v[16:31], v[172:175], v[164:167], v[16:31]
	v_mfma_f32_32x32x16_bf16 v[0:15], v[172:175], v[168:171], v[0:15]
	s_waitcnt lgkmcnt(2)
	v_mfma_f32_32x32x16_bf16 v[48:63], v[176:179], v[180:183], v[48:63]
	s_waitcnt lgkmcnt(1)
	v_mfma_f32_32x32x16_bf16 v[32:47], v[176:179], v[184:187], v[32:47]
	s_waitcnt lgkmcnt(0)
	v_mfma_f32_32x32x16_bf16 v[16:31], v[188:191], v[180:183], v[16:31]
	v_mfma_f32_32x32x16_bf16 v[0:15], v[188:191], v[184:187], v[0:15]
	s_setprio 0
	s_waitcnt vmcnt(0)
	s_barrier
;     ...
;     G_LOAD(x, 0);
;     G_STORE(x, 0);
;     __syncthreads();
;     if (KT > 1) G_LOAD(x, 1);
;     for (int kt = 0; kt < KT; kt += 2) {
;       if (kt + 2 < KT && dummy != 2) G_LOAD(y, kt + 2);
;       G_COMPUTE(0);
;       if (kt + 1 < KT && dummy != 2) G_STORE(x, 1);
;       __syncthreads();
;       if (kt + 1 >= KT) break;
;       if (kt + 3 < KT && dummy != 2) G_LOAD(x, kt + 3);
;       G_COMPUTE(1);
;       if (kt + 2 < KT && dummy != 2) G_STORE(y, 0);
;       __syncthreads();
	s_setprio 1
	ds_read_b128 v[156:159], v196 offset:32768
	ds_read_b128 v[164:167], v200 offset:32768
	ds_read_b128 v[168:171], v200 offset:36864
	ds_read_b128 v[172:175], v196 offset:36864
	ds_read_b128 v[176:179], v197 offset:32768
	ds_read_b128 v[180:183], v201 offset:32768
	ds_read_b128 v[184:187], v201 offset:36864
	ds_read_b128 v[188:191], v197 offset:36864
	s_add_u32 m0, s76, 0x700
	s_nop 0
	global_load_lds_dwordx4 v[138:139], off offset:256
	s_add_u32 m0, s76, 0x1700
	s_nop 0
	global_load_lds_dwordx4 v[142:143], off offset:256
	s_add_u32 m0, s76, 0x2700
	s_nop 0
	global_load_lds_dwordx4 v[144:145], off offset:256
	s_add_u32 m0, s76, 0x3700
	s_nop 0
	global_load_lds_dwordx4 v[152:153], off offset:256
	s_add_u32 m0, s76, 0x4700
	s_nop 0
	global_load_lds_dwordx4 v[140:141], off offset:256
	s_add_u32 m0, s76, 0x5700
	s_nop 0
	global_load_lds_dwordx4 v[146:147], off offset:256
	s_add_u32 m0, s76, 0x6700
	s_nop 0
	global_load_lds_dwordx4 v[148:149], off offset:256
	s_add_u32 m0, s76, 0x7700
	s_nop 0
	global_load_lds_dwordx4 v[150:151], off offset:256
	s_waitcnt lgkmcnt(6)
	v_mfma_f32_32x32x16_bf16 v[48:63], v[156:159], v[164:167], v[48:63]
	s_waitcnt lgkmcnt(5)
	v_mfma_f32_32x32x16_bf16 v[32:47], v[156:159], v[168:171], v[32:47]
	s_waitcnt lgkmcnt(4)
	v_mfma_f32_32x32x16_bf16 v[16:31], v[172:175], v[164:167], v[16:31]
	v_mfma_f32_32x32x16_bf16 v[0:15], v[172:175], v[168:171], v[0:15]
	ds_read_b128 v[156:159], v198 offset:32768
	ds_read_b128 v[164:167], v202 offset:32768
	ds_read_b128 v[168:171], v202 offset:36864
	ds_read_b128 v[172:175], v198 offset:36864
	s_waitcnt lgkmcnt(6)
	v_mfma_f32_32x32x16_bf16 v[48:63], v[176:179], v[180:183], v[48:63]
	s_waitcnt lgkmcnt(5)
	v_mfma_f32_32x32x16_bf16 v[32:47], v[176:179], v[184:187], v[32:47]
	s_waitcnt lgkmcnt(4)
	v_mfma_f32_32x32x16_bf16 v[16:31], v[188:191], v[180:183], v[16:31]
	v_mfma_f32_32x32x16_bf16 v[0:15], v[188:191], v[184:187], v[0:15]
	ds_read_b128 v[176:179], v199 offset:32768
	ds_read_b128 v[180:183], v203 offset:32768
	ds_read_b128 v[184:187], v203 offset:36864
	ds_read_b128 v[188:191], v199 offset:36864
	s_waitcnt lgkmcnt(6)
	v_mfma_f32_32x32x16_bf16 v[48:63], v[156:159], v[164:167], v[48:63]
	s_waitcnt lgkmcnt(5)
	v_mfma_f32_32x32x16_bf16 v[32:47], v[156:159], v[168:171], v[32:47]
	s_waitcnt lgkmcnt(4)
	v_mfma_f32_32x32x16_bf16 v[16:31], v[172:175], v[164:167], v[16:31]
	v_mfma_f32_32x32x16_bf16 v[0:15], v[172:175], v[168:171], v[0:15]
	s_waitcnt lgkmcnt(2)
	v_mfma_f32_32x32x16_bf16 v[48:63], v[176:179], v[180:183], v[48:63]
	s_waitcnt lgkmcnt(1)
	v_mfma_f32_32x32x16_bf16 v[32:47], v[176:179], v[184:187], v[32:47]
	s_waitcnt lgkmcnt(0)
	v_mfma_f32_32x32x16_bf16 v[16:31], v[188:191], v[180:183], v[16:31]
	v_mfma_f32_32x32x16_bf16 v[0:15], v[188:191], v[184:187], v[0:15]
	s_setprio 0
	s_waitcnt vmcnt(0)
	s_barrier
	s_setprio 1
	ds_read_b128 v[156:159], v196
	ds_read_b128 v[164:167], v200
	ds_read_b128 v[168:171], v200 offset:4096
	ds_read_b128 v[172:175], v196 offset:4096
	ds_read_b128 v[176:179], v197
	ds_read_b128 v[180:183], v201
	ds_read_b128 v[184:187], v201 offset:4096
	ds_read_b128 v[188:191], v197 offset:4096
	s_add_u32 m0, s76, 0x8680
	s_nop 0
	global_load_lds_dwordx4 v[138:139], off offset:384
	s_add_u32 m0, s76, 0x9680
	s_nop 0
	global_load_lds_dwordx4 v[142:143], off offset:384
	s_add_u32 m0, s76, 0xa680
	s_nop 0
	global_load_lds_dwordx4 v[144:145], off offset:384
	s_add_u32 m0, s76, 0xb680
	s_nop 0
	global_load_lds_dwordx4 v[152:153], off offset:384
	s_add_u32 m0, s76, 0xc680
	s_nop 0
	global_load_lds_dwordx4 v[140:141], off offset:384
	s_add_u32 m0, s76, 0xd680
	s_nop 0
	global_load_lds_dwordx4 v[146:147], off offset:384
	s_add_u32 m0, s76, 0xe680
	s_nop 0
	global_load_lds_dwordx4 v[148:149], off offset:384
	s_add_u32 m0, s76, 0xf680
	s_nop 0
	global_load_lds_dwordx4 v[150:151], off offset:384
	s_waitcnt lgkmcnt(6)
	v_mfma_f32_32x32x16_bf16 v[48:63], v[156:159], v[164:167], v[48:63]
	s_waitcnt lgkmcnt(5)
	v_mfma_f32_32x32x16_bf16 v[32:47], v[156:159], v[168:171], v[32:47]
	s_waitcnt lgkmcnt(4)
	v_mfma_f32_32x32x16_bf16 v[16:31], v[172:175], v[164:167], v[16:31]
	v_mfma_f32_32x32x16_bf16 v[0:15], v[172:175], v[168:171], v[0:15]
	ds_read_b128 v[156:159], v198
	ds_read_b128 v[164:167], v202
	ds_read_b128 v[168:171], v202 offset:4096
	ds_read_b128 v[172:175], v198 offset:4096
	s_waitcnt lgkmcnt(6)
	v_mfma_f32_32x32x16_bf16 v[48:63], v[176:179], v[180:183], v[48:63]
	s_waitcnt lgkmcnt(5)
	v_mfma_f32_32x32x16_bf16 v[32:47], v[176:179], v[184:187], v[32:47]
	s_waitcnt lgkmcnt(4)
	v_mfma_f32_32x32x16_bf16 v[16:31], v[188:191], v[180:183], v[16:31]
	v_mfma_f32_32x32x16_bf16 v[0:15], v[188:191], v[184:187], v[0:15]
	ds_read_b128 v[176:179], v199
	ds_read_b128 v[180:183], v203
	ds_read_b128 v[184:187], v203 offset:4096
	ds_read_b128 v[188:191], v199 offset:4096
	s_waitcnt lgkmcnt(6)
	v_mfma_f32_32x32x16_bf16 v[48:63], v[156:159], v[164:167], v[48:63]
	s_waitcnt lgkmcnt(5)
	v_mfma_f32_32x32x16_bf16 v[32:47], v[156:159], v[168:171], v[32:47]
	s_waitcnt lgkmcnt(4)
	v_mfma_f32_32x32x16_bf16 v[16:31], v[172:175], v[164:167], v[16:31]
	v_mfma_f32_32x32x16_bf16 v[0:15], v[172:175], v[168:171], v[0:15]
	s_waitcnt lgkmcnt(2)
	v_mfma_f32_32x32x16_bf16 v[48:63], v[176:179], v[180:183], v[48:63]
	s_waitcnt lgkmcnt(1)
	v_mfma_f32_32x32x16_bf16 v[32:47], v[176:179], v[184:187], v[32:47]
	s_waitcnt lgkmcnt(0)
	v_mfma_f32_32x32x16_bf16 v[16:31], v[188:191], v[180:183], v[16:31]
	v_mfma_f32_32x32x16_bf16 v[0:15], v[188:191], v[184:187], v[0:15]
	s_setprio 0
	s_waitcnt vmcnt(0)
	s_barrier
;     ...
;     G_LOAD(x, 0);
;     G_STORE(x, 0);
;     __syncthreads();
;     if (KT > 1) G_LOAD(x, 1);
;     for (int kt = 0; kt < KT; kt += 2) {
;       if (kt + 2 < KT && dummy != 2) G_LOAD(y, kt + 2);
;       G_COMPUTE(0);
;       if (kt + 1 < KT && dummy != 2) G_STORE(x, 1);
;       __syncthreads();
;       if (kt + 1 >= KT) break;
;       if (kt + 3 < KT && dummy != 2) G_LOAD(x, kt + 3);
;       G_COMPUTE(1);
;       if (kt + 2 < KT && dummy != 2) G_STORE(y, 0);
;       __syncthreads();
	s_setprio 1
	ds_read_b128 v[156:159], v196 offset:32768
	ds_read_b128 v[164:167], v200 offset:32768
	ds_read_b128 v[168:171], v200 offset:36864
	ds_read_b128 v[172:175], v196 offset:36864
	ds_read_b128 v[176:179], v197 offset:32768
	ds_read_b128 v[180:183], v201 offset:32768
	ds_read_b128 v[184:187], v201 offset:36864
	ds_read_b128 v[188:191], v197 offset:36864
	s_add_u32 m0, s76, 0x600
	s_nop 0
	global_load_lds_dwordx4 v[138:139], off offset:512
	s_add_u32 m0, s76, 0x1600
	s_nop 0
	global_load_lds_dwordx4 v[142:143], off offset:512
	s_add_u32 m0, s76, 0x2600
	s_nop 0
	global_load_lds_dwordx4 v[144:145], off offset:512
	s_add_u32 m0, s76, 0x3600
	s_nop 0
	global_load_lds_dwordx4 v[152:153], off offset:512
	s_add_u32 m0, s76, 0x4600
	s_nop 0
	global_load_lds_dwordx4 v[140:141], off offset:512
	s_add_u32 m0, s76, 0x5600
	s_nop 0
	global_load_lds_dwordx4 v[146:147], off offset:512
	s_add_u32 m0, s76, 0x6600
	s_nop 0
	global_load_lds_dwordx4 v[148:149], off offset:512
	s_add_u32 m0, s76, 0x7600
	s_nop 0
	global_load_lds_dwordx4 v[150:151], off offset:512
	s_waitcnt lgkmcnt(6)
	v_mfma_f32_32x32x16_bf16 v[48:63], v[156:159], v[164:167], v[48:63]
	s_waitcnt lgkmcnt(5)
	v_mfma_f32_32x32x16_bf16 v[32:47], v[156:159], v[168:171], v[32:47]
	s_waitcnt lgkmcnt(4)
	v_mfma_f32_32x32x16_bf16 v[16:31], v[172:175], v[164:167], v[16:31]
	v_mfma_f32_32x32x16_bf16 v[0:15], v[172:175], v[168:171], v[0:15]
	ds_read_b128 v[156:159], v198 offset:32768
	ds_read_b128 v[164:167], v202 offset:32768
	ds_read_b128 v[168:171], v202 offset:36864
	ds_read_b128 v[172:175], v198 offset:36864
	s_waitcnt lgkmcnt(6)
	v_mfma_f32_32x32x16_bf16 v[48:63], v[176:179], v[180:183], v[48:63]
	s_waitcnt lgkmcnt(5)
	v_mfma_f32_32x32x16_bf16 v[32:47], v[176:179], v[184:187], v[32:47]
	s_waitcnt lgkmcnt(4)
	v_mfma_f32_32x32x16_bf16 v[16:31], v[188:191], v[180:183], v[16:31]
	v_mfma_f32_32x32x16_bf16 v[0:15], v[188:191], v[184:187], v[0:15]
	ds_read_b128 v[176:179], v199 offset:32768
	ds_read_b128 v[180:183], v203 offset:32768
	ds_read_b128 v[184:187], v203 offset:36864
	ds_read_b128 v[188:191], v199 offset:36864
	s_waitcnt lgkmcnt(6)
	v_mfma_f32_32x32x16_bf16 v[48:63], v[156:159], v[164:167], v[48:63]
	s_waitcnt lgkmcnt(5)
	v_mfma_f32_32x32x16_bf16 v[32:47], v[156:159], v[168:171], v[32:47]
	s_waitcnt lgkmcnt(4)
	v_mfma_f32_32x32x16_bf16 v[16:31], v[172:175], v[164:167], v[16:31]
	v_mfma_f32_32x32x16_bf16 v[0:15], v[172:175], v[168:171], v[0:15]
	s_waitcnt lgkmcnt(2)
	v_mfma_f32_32x32x16_bf16 v[48:63], v[176:179], v[180:183], v[48:63]
	s_waitcnt lgkmcnt(1)
	v_mfma_f32_32x32x16_bf16 v[32:47], v[176:179], v[184:187], v[32:47]
	s_waitcnt lgkmcnt(0)
	v_mfma_f32_32x32x16_bf16 v[16:31], v[188:191], v[180:183], v[16:31]
	v_mfma_f32_32x32x16_bf16 v[0:15], v[188:191], v[184:187], v[0:15]
	s_setprio 0
	s_waitcnt vmcnt(0)
	s_barrier
	s_setprio 1
	ds_read_b128 v[156:159], v196
	ds_read_b128 v[164:167], v200
	ds_read_b128 v[168:171], v200 offset:4096
	ds_read_b128 v[172:175], v196 offset:4096
	ds_read_b128 v[176:179], v197
	ds_read_b128 v[180:183], v201
	ds_read_b128 v[184:187], v201 offset:4096
	ds_read_b128 v[188:191], v197 offset:4096
	s_add_u32 m0, s76, 0x8580
	s_nop 0
	global_load_lds_dwordx4 v[138:139], off offset:640
	s_add_u32 m0, s76, 0x9580
	s_nop 0
	global_load_lds_dwordx4 v[142:143], off offset:640
	s_add_u32 m0, s76, 0xa580
	s_nop 0
	global_load_lds_dwordx4 v[144:145], off offset:640
	s_add_u32 m0, s76, 0xb580
	s_nop 0
	global_load_lds_dwordx4 v[152:153], off offset:640
	s_add_u32 m0, s76, 0xc580
	s_nop 0
	global_load_lds_dwordx4 v[140:141], off offset:640
	s_add_u32 m0, s76, 0xd580
	s_nop 0
	global_load_lds_dwordx4 v[146:147], off offset:640
	s_add_u32 m0, s76, 0xe580
	s_nop 0
	global_load_lds_dwordx4 v[148:149], off offset:640
	s_add_u32 m0, s76, 0xf580
	s_nop 0
	global_load_lds_dwordx4 v[150:151], off offset:640
	s_waitcnt lgkmcnt(6)
	v_mfma_f32_32x32x16_bf16 v[48:63], v[156:159], v[164:167], v[48:63]
	s_waitcnt lgkmcnt(5)
	v_mfma_f32_32x32x16_bf16 v[32:47], v[156:159], v[168:171], v[32:47]
	s_waitcnt lgkmcnt(4)
	v_mfma_f32_32x32x16_bf16 v[16:31], v[172:175], v[164:167], v[16:31]
	v_mfma_f32_32x32x16_bf16 v[0:15], v[172:175], v[168:171], v[0:15]
	ds_read_b128 v[156:159], v198
	ds_read_b128 v[164:167], v202
	ds_read_b128 v[168:171], v202 offset:4096
	ds_read_b128 v[172:175], v198 offset:4096
	s_waitcnt lgkmcnt(6)
	v_mfma_f32_32x32x16_bf16 v[48:63], v[176:179], v[180:183], v[48:63]
	s_waitcnt lgkmcnt(5)
	v_mfma_f32_32x32x16_bf16 v[32:47], v[176:179], v[184:187], v[32:47]
	s_waitcnt lgkmcnt(4)
	v_mfma_f32_32x32x16_bf16 v[16:31], v[188:191], v[180:183], v[16:31]
	v_mfma_f32_32x32x16_bf16 v[0:15], v[188:191], v[184:187], v[0:15]
	ds_read_b128 v[176:179], v199
	ds_read_b128 v[180:183], v203
	ds_read_b128 v[184:187], v203 offset:4096
	ds_read_b128 v[188:191], v199 offset:4096
	s_waitcnt lgkmcnt(6)
	v_mfma_f32_32x32x16_bf16 v[48:63], v[156:159], v[164:167], v[48:63]
	s_waitcnt lgkmcnt(5)
	v_mfma_f32_32x32x16_bf16 v[32:47], v[156:159], v[168:171], v[32:47]
	s_waitcnt lgkmcnt(4)
	v_mfma_f32_32x32x16_bf16 v[16:31], v[172:175], v[164:167], v[16:31]
	v_mfma_f32_32x32x16_bf16 v[0:15], v[172:175], v[168:171], v[0:15]
	s_waitcnt lgkmcnt(2)
	v_mfma_f32_32x32x16_bf16 v[48:63], v[176:179], v[180:183], v[48:63]
	s_waitcnt lgkmcnt(1)
	v_mfma_f32_32x32x16_bf16 v[32:47], v[176:179], v[184:187], v[32:47]
	s_waitcnt lgkmcnt(0)
	v_mfma_f32_32x32x16_bf16 v[16:31], v[188:191], v[180:183], v[16:31]
	v_mfma_f32_32x32x16_bf16 v[0:15], v[188:191], v[184:187], v[0:15]
	s_setprio 0
	s_waitcnt vmcnt(0)
	s_barrier
;     ...
;     G_LOAD(x, 0);
;     G_STORE(x, 0);
;     __syncthreads();
;     if (KT > 1) G_LOAD(x, 1);
;     for (int kt = 0; kt < KT; kt += 2) {
;       if (kt + 2 < KT && dummy != 2) G_LOAD(y, kt + 2);
;       G_COMPUTE(0);
;       if (kt + 1 < KT && dummy != 2) G_STORE(x, 1);
;       __syncthreads();
;       if (kt + 1 >= KT) break;
;       if (kt + 3 < KT && dummy != 2) G_LOAD(x, kt + 3);
;       G_COMPUTE(1);
;       if (kt + 2 < KT && dummy != 2) G_STORE(y, 0);
;       __syncthreads();
	s_setprio 1
	ds_read_b128 v[156:159], v196 offset:32768
	ds_read_b128 v[164:167], v200 offset:32768
	ds_read_b128 v[168:171], v200 offset:36864
	ds_read_b128 v[172:175], v196 offset:36864
	ds_read_b128 v[176:179], v197 offset:32768
	ds_read_b128 v[180:183], v201 offset:32768
	ds_read_b128 v[184:187], v201 offset:36864
	ds_read_b128 v[188:191], v197 offset:36864
	s_add_u32 m0, s76, 0x500
	s_nop 0
	global_load_lds_dwordx4 v[138:139], off offset:768
	s_add_u32 m0, s76, 0x1500
	s_nop 0
	global_load_lds_dwordx4 v[142:143], off offset:768
	s_add_u32 m0, s76, 0x2500
	s_nop 0
	global_load_lds_dwordx4 v[144:145], off offset:768
	s_add_u32 m0, s76, 0x3500
	s_nop 0
	global_load_lds_dwordx4 v[152:153], off offset:768
	s_add_u32 m0, s76, 0x4500
	s_nop 0
	global_load_lds_dwordx4 v[140:141], off offset:768
	s_add_u32 m0, s76, 0x5500
	s_nop 0
	global_load_lds_dwordx4 v[146:147], off offset:768
	s_add_u32 m0, s76, 0x6500
	s_nop 0
	global_load_lds_dwordx4 v[148:149], off offset:768
	s_add_u32 m0, s76, 0x7500
	s_nop 0
	global_load_lds_dwordx4 v[150:151], off offset:768
	s_waitcnt lgkmcnt(6)
	v_mfma_f32_32x32x16_bf16 v[48:63], v[156:159], v[164:167], v[48:63]
	s_waitcnt lgkmcnt(5)
	v_mfma_f32_32x32x16_bf16 v[32:47], v[156:159], v[168:171], v[32:47]
	s_waitcnt lgkmcnt(4)
	v_mfma_f32_32x32x16_bf16 v[16:31], v[172:175], v[164:167], v[16:31]
	v_mfma_f32_32x32x16_bf16 v[0:15], v[172:175], v[168:171], v[0:15]
	ds_read_b128 v[156:159], v198 offset:32768
	ds_read_b128 v[164:167], v202 offset:32768
	ds_read_b128 v[168:171], v202 offset:36864
	ds_read_b128 v[172:175], v198 offset:36864
	s_waitcnt lgkmcnt(6)
	v_mfma_f32_32x32x16_bf16 v[48:63], v[176:179], v[180:183], v[48:63]
	s_waitcnt lgkmcnt(5)
	v_mfma_f32_32x32x16_bf16 v[32:47], v[176:179], v[184:187], v[32:47]
	s_waitcnt lgkmcnt(4)
	v_mfma_f32_32x32x16_bf16 v[16:31], v[188:191], v[180:183], v[16:31]
	v_mfma_f32_32x32x16_bf16 v[0:15], v[188:191], v[184:187], v[0:15]
	ds_read_b128 v[176:179], v199 offset:32768
	ds_read_b128 v[180:183], v203 offset:32768
	ds_read_b128 v[184:187], v203 offset:36864
	ds_read_b128 v[188:191], v199 offset:36864
	s_waitcnt lgkmcnt(6)
	v_mfma_f32_32x32x16_bf16 v[48:63], v[156:159], v[164:167], v[48:63]
	s_waitcnt lgkmcnt(5)
	v_mfma_f32_32x32x16_bf16 v[32:47], v[156:159], v[168:171], v[32:47]
	s_waitcnt lgkmcnt(4)
	v_mfma_f32_32x32x16_bf16 v[16:31], v[172:175], v[164:167], v[16:31]
	v_mfma_f32_32x32x16_bf16 v[0:15], v[172:175], v[168:171], v[0:15]
	s_waitcnt lgkmcnt(2)
	v_mfma_f32_32x32x16_bf16 v[48:63], v[176:179], v[180:183], v[48:63]
	s_waitcnt lgkmcnt(1)
	v_mfma_f32_32x32x16_bf16 v[32:47], v[176:179], v[184:187], v[32:47]
	s_waitcnt lgkmcnt(0)
	v_mfma_f32_32x32x16_bf16 v[16:31], v[188:191], v[180:183], v[16:31]
	v_mfma_f32_32x32x16_bf16 v[0:15], v[188:191], v[184:187], v[0:15]
	s_setprio 0
	s_waitcnt vmcnt(0)
	s_barrier
	s_setprio 1
	ds_read_b128 v[156:159], v196
	ds_read_b128 v[164:167], v200
	ds_read_b128 v[168:171], v200 offset:4096
	ds_read_b128 v[172:175], v196 offset:4096
	ds_read_b128 v[176:179], v197
	ds_read_b128 v[180:183], v201
	ds_read_b128 v[184:187], v201 offset:4096
	ds_read_b128 v[188:191], v197 offset:4096
	s_add_u32 m0, s76, 0x8480
	s_nop 0
	global_load_lds_dwordx4 v[138:139], off offset:896
	s_add_u32 m0, s76, 0x9480
	s_nop 0
	global_load_lds_dwordx4 v[142:143], off offset:896
	s_add_u32 m0, s76, 0xa480
	s_nop 0
	global_load_lds_dwordx4 v[144:145], off offset:896
	s_add_u32 m0, s76, 0xb480
	s_nop 0
	global_load_lds_dwordx4 v[152:153], off offset:896
	s_add_u32 m0, s76, 0xc480
	s_nop 0
	global_load_lds_dwordx4 v[140:141], off offset:896
	s_add_u32 m0, s76, 0xd480
	s_nop 0
	global_load_lds_dwordx4 v[146:147], off offset:896
	s_add_u32 m0, s76, 0xe480
	s_nop 0
	global_load_lds_dwordx4 v[148:149], off offset:896
	s_add_u32 m0, s76, 0xf480
	s_nop 0
	global_load_lds_dwordx4 v[150:151], off offset:896
	s_waitcnt lgkmcnt(6)
	v_mfma_f32_32x32x16_bf16 v[48:63], v[156:159], v[164:167], v[48:63]
	s_waitcnt lgkmcnt(5)
	v_mfma_f32_32x32x16_bf16 v[32:47], v[156:159], v[168:171], v[32:47]
	s_waitcnt lgkmcnt(4)
	v_mfma_f32_32x32x16_bf16 v[16:31], v[172:175], v[164:167], v[16:31]
	v_mfma_f32_32x32x16_bf16 v[0:15], v[172:175], v[168:171], v[0:15]
	ds_read_b128 v[156:159], v198
	ds_read_b128 v[164:167], v202
	ds_read_b128 v[168:171], v202 offset:4096
	ds_read_b128 v[172:175], v198 offset:4096
	s_waitcnt lgkmcnt(6)
	v_mfma_f32_32x32x16_bf16 v[48:63], v[176:179], v[180:183], v[48:63]
	s_waitcnt lgkmcnt(5)
	v_mfma_f32_32x32x16_bf16 v[32:47], v[176:179], v[184:187], v[32:47]
	s_waitcnt lgkmcnt(4)
	v_mfma_f32_32x32x16_bf16 v[16:31], v[188:191], v[180:183], v[16:31]
	v_mfma_f32_32x32x16_bf16 v[0:15], v[188:191], v[184:187], v[0:15]
	ds_read_b128 v[176:179], v199
	ds_read_b128 v[180:183], v203
	ds_read_b128 v[184:187], v203 offset:4096
	ds_read_b128 v[188:191], v199 offset:4096
	s_waitcnt lgkmcnt(6)
	v_mfma_f32_32x32x16_bf16 v[48:63], v[156:159], v[164:167], v[48:63]
	s_waitcnt lgkmcnt(5)
	v_mfma_f32_32x32x16_bf16 v[32:47], v[156:159], v[168:171], v[32:47]
	s_waitcnt lgkmcnt(4)
	v_mfma_f32_32x32x16_bf16 v[16:31], v[172:175], v[164:167], v[16:31]
	v_mfma_f32_32x32x16_bf16 v[0:15], v[172:175], v[168:171], v[0:15]
	s_waitcnt lgkmcnt(2)
	v_mfma_f32_32x32x16_bf16 v[48:63], v[176:179], v[180:183], v[48:63]
	s_waitcnt lgkmcnt(1)
	v_mfma_f32_32x32x16_bf16 v[32:47], v[176:179], v[184:187], v[32:47]
	s_waitcnt lgkmcnt(0)
	v_mfma_f32_32x32x16_bf16 v[16:31], v[188:191], v[180:183], v[16:31]
	v_mfma_f32_32x32x16_bf16 v[0:15], v[188:191], v[184:187], v[0:15]
	s_setprio 0
	s_waitcnt vmcnt(0)
	s_barrier
;     ...
;     G_LOAD(x, 0);
;     G_STORE(x, 0);
;     __syncthreads();
;     if (KT > 1) G_LOAD(x, 1);
;     for (int kt = 0; kt < KT; kt += 2) {
;       if (kt + 2 < KT && dummy != 2) G_LOAD(y, kt + 2);
;       G_COMPUTE(0);
;       if (kt + 1 < KT && dummy != 2) G_STORE(x, 1);
;       __syncthreads();
;       if (kt + 1 >= KT) break;
;       if (kt + 3 < KT && dummy != 2) G_LOAD(x, kt + 3);
;       G_COMPUTE(1);
;       if (kt + 2 < KT && dummy != 2) G_STORE(y, 0);
;       __syncthreads();
	s_setprio 1
	ds_read_b128 v[156:159], v196 offset:32768
	ds_read_b128 v[164:167], v200 offset:32768
	ds_read_b128 v[168:171], v200 offset:36864
	ds_read_b128 v[172:175], v196 offset:36864
	ds_read_b128 v[176:179], v197 offset:32768
	ds_read_b128 v[180:183], v201 offset:32768
	ds_read_b128 v[184:187], v201 offset:36864
	ds_read_b128 v[188:191], v197 offset:36864
	s_add_u32 m0, s76, 0x400
	s_nop 0
	global_load_lds_dwordx4 v[138:139], off offset:1024
	s_add_u32 m0, s76, 0x1400
	s_nop 0
	global_load_lds_dwordx4 v[142:143], off offset:1024
	s_add_u32 m0, s76, 0x2400
	s_nop 0
	global_load_lds_dwordx4 v[144:145], off offset:1024
	s_add_u32 m0, s76, 0x3400
	s_nop 0
	global_load_lds_dwordx4 v[152:153], off offset:1024
	s_add_u32 m0, s76, 0x4400
	s_nop 0
	global_load_lds_dwordx4 v[140:141], off offset:1024
	s_add_u32 m0, s76, 0x5400
	s_nop 0
	global_load_lds_dwordx4 v[146:147], off offset:1024
	s_add_u32 m0, s76, 0x6400
	s_nop 0
	global_load_lds_dwordx4 v[148:149], off offset:1024
	s_add_u32 m0, s76, 0x7400
	s_nop 0
	global_load_lds_dwordx4 v[150:151], off offset:1024
	s_waitcnt lgkmcnt(6)
	v_mfma_f32_32x32x16_bf16 v[48:63], v[156:159], v[164:167], v[48:63]
	s_waitcnt lgkmcnt(5)
	v_mfma_f32_32x32x16_bf16 v[32:47], v[156:159], v[168:171], v[32:47]
	s_waitcnt lgkmcnt(4)
	v_mfma_f32_32x32x16_bf16 v[16:31], v[172:175], v[164:167], v[16:31]
	v_mfma_f32_32x32x16_bf16 v[0:15], v[172:175], v[168:171], v[0:15]
	ds_read_b128 v[156:159], v198 offset:32768
	ds_read_b128 v[164:167], v202 offset:32768
	ds_read_b128 v[168:171], v202 offset:36864
	ds_read_b128 v[172:175], v198 offset:36864
	s_waitcnt lgkmcnt(6)
	v_mfma_f32_32x32x16_bf16 v[48:63], v[176:179], v[180:183], v[48:63]
	s_waitcnt lgkmcnt(5)
	v_mfma_f32_32x32x16_bf16 v[32:47], v[176:179], v[184:187], v[32:47]
	s_waitcnt lgkmcnt(4)
	v_mfma_f32_32x32x16_bf16 v[16:31], v[188:191], v[180:183], v[16:31]
	v_mfma_f32_32x32x16_bf16 v[0:15], v[188:191], v[184:187], v[0:15]
	ds_read_b128 v[176:179], v199 offset:32768
	ds_read_b128 v[180:183], v203 offset:32768
	ds_read_b128 v[184:187], v203 offset:36864
	ds_read_b128 v[188:191], v199 offset:36864
	s_waitcnt lgkmcnt(6)
	v_mfma_f32_32x32x16_bf16 v[48:63], v[156:159], v[164:167], v[48:63]
	s_waitcnt lgkmcnt(5)
	v_mfma_f32_32x32x16_bf16 v[32:47], v[156:159], v[168:171], v[32:47]
	s_waitcnt lgkmcnt(4)
	v_mfma_f32_32x32x16_bf16 v[16:31], v[172:175], v[164:167], v[16:31]
	v_mfma_f32_32x32x16_bf16 v[0:15], v[172:175], v[168:171], v[0:15]
	s_waitcnt lgkmcnt(2)
	v_mfma_f32_32x32x16_bf16 v[48:63], v[176:179], v[180:183], v[48:63]
	s_waitcnt lgkmcnt(1)
	v_mfma_f32_32x32x16_bf16 v[32:47], v[176:179], v[184:187], v[32:47]
	s_waitcnt lgkmcnt(0)
	v_mfma_f32_32x32x16_bf16 v[16:31], v[188:191], v[180:183], v[16:31]
	v_mfma_f32_32x32x16_bf16 v[0:15], v[188:191], v[184:187], v[0:15]
	s_setprio 0
	s_waitcnt vmcnt(0)
	s_barrier
	s_setprio 1
	ds_read_b128 v[156:159], v196
	ds_read_b128 v[164:167], v200
	ds_read_b128 v[168:171], v200 offset:4096
	ds_read_b128 v[172:175], v196 offset:4096
	ds_read_b128 v[176:179], v197
	ds_read_b128 v[180:183], v201
	ds_read_b128 v[184:187], v201 offset:4096
	ds_read_b128 v[188:191], v197 offset:4096
	s_add_u32 m0, s76, 0x8380
	s_nop 0
	global_load_lds_dwordx4 v[138:139], off offset:1152
	s_add_u32 m0, s76, 0x9380
	s_nop 0
	global_load_lds_dwordx4 v[142:143], off offset:1152
	s_add_u32 m0, s76, 0xa380
	s_nop 0
	global_load_lds_dwordx4 v[144:145], off offset:1152
	s_add_u32 m0, s76, 0xb380
	s_nop 0
	global_load_lds_dwordx4 v[152:153], off offset:1152
	s_add_u32 m0, s76, 0xc380
	s_nop 0
	global_load_lds_dwordx4 v[140:141], off offset:1152
	s_add_u32 m0, s76, 0xd380
	s_nop 0
	global_load_lds_dwordx4 v[146:147], off offset:1152
	s_add_u32 m0, s76, 0xe380
	s_nop 0
	global_load_lds_dwordx4 v[148:149], off offset:1152
	s_add_u32 m0, s76, 0xf380
	s_nop 0
	global_load_lds_dwordx4 v[150:151], off offset:1152
	s_waitcnt lgkmcnt(6)
	v_mfma_f32_32x32x16_bf16 v[48:63], v[156:159], v[164:167], v[48:63]
	s_waitcnt lgkmcnt(5)
	v_mfma_f32_32x32x16_bf16 v[32:47], v[156:159], v[168:171], v[32:47]
	s_waitcnt lgkmcnt(4)
	v_mfma_f32_32x32x16_bf16 v[16:31], v[172:175], v[164:167], v[16:31]
	v_mfma_f32_32x32x16_bf16 v[0:15], v[172:175], v[168:171], v[0:15]
	ds_read_b128 v[156:159], v198
	ds_read_b128 v[164:167], v202
	ds_read_b128 v[168:171], v202 offset:4096
	ds_read_b128 v[172:175], v198 offset:4096
	s_waitcnt lgkmcnt(6)
	v_mfma_f32_32x32x16_bf16 v[48:63], v[176:179], v[180:183], v[48:63]
	s_waitcnt lgkmcnt(5)
	v_mfma_f32_32x32x16_bf16 v[32:47], v[176:179], v[184:187], v[32:47]
	s_waitcnt lgkmcnt(4)
	v_mfma_f32_32x32x16_bf16 v[16:31], v[188:191], v[180:183], v[16:31]
	v_mfma_f32_32x32x16_bf16 v[0:15], v[188:191], v[184:187], v[0:15]
	ds_read_b128 v[176:179], v199
	ds_read_b128 v[180:183], v203
	ds_read_b128 v[184:187], v203 offset:4096
	ds_read_b128 v[188:191], v199 offset:4096
	s_waitcnt lgkmcnt(6)
	v_mfma_f32_32x32x16_bf16 v[48:63], v[156:159], v[164:167], v[48:63]
	s_waitcnt lgkmcnt(5)
	v_mfma_f32_32x32x16_bf16 v[32:47], v[156:159], v[168:171], v[32:47]
	s_waitcnt lgkmcnt(4)
	v_mfma_f32_32x32x16_bf16 v[16:31], v[172:175], v[164:167], v[16:31]
	v_mfma_f32_32x32x16_bf16 v[0:15], v[172:175], v[168:171], v[0:15]
	s_waitcnt lgkmcnt(2)
	v_mfma_f32_32x32x16_bf16 v[48:63], v[176:179], v[180:183], v[48:63]
	s_waitcnt lgkmcnt(1)
	v_mfma_f32_32x32x16_bf16 v[32:47], v[176:179], v[184:187], v[32:47]
	s_waitcnt lgkmcnt(0)
	v_mfma_f32_32x32x16_bf16 v[16:31], v[188:191], v[180:183], v[16:31]
	v_mfma_f32_32x32x16_bf16 v[0:15], v[188:191], v[184:187], v[0:15]
	s_setprio 0
	s_waitcnt vmcnt(0)
	s_barrier
;     ...
;     G_LOAD(x, 0);
;     G_STORE(x, 0);
;     __syncthreads();
;     if (KT > 1) G_LOAD(x, 1);
;     for (int kt = 0; kt < KT; kt += 2) {
;       if (kt + 2 < KT && dummy != 2) G_LOAD(y, kt + 2);
;       G_COMPUTE(0);
;       if (kt + 1 < KT && dummy != 2) G_STORE(x, 1);
;       __syncthreads();
;       if (kt + 1 >= KT) break;
;       if (kt + 3 < KT && dummy != 2) G_LOAD(x, kt + 3);
;       G_COMPUTE(1);
;       if (kt + 2 < KT && dummy != 2) G_STORE(y, 0);
;       __syncthreads();
	s_setprio 1
	ds_read_b128 v[156:159], v196 offset:32768
	ds_read_b128 v[164:167], v200 offset:32768
	ds_read_b128 v[168:171], v200 offset:36864
	ds_read_b128 v[172:175], v196 offset:36864
	ds_read_b128 v[176:179], v197 offset:32768
	ds_read_b128 v[180:183], v201 offset:32768
	ds_read_b128 v[184:187], v201 offset:36864
	ds_read_b128 v[188:191], v197 offset:36864
	s_add_u32 m0, s76, 0x300
	s_nop 0
	global_load_lds_dwordx4 v[138:139], off offset:1280
	s_add_u32 m0, s76, 0x1300
	s_nop 0
	global_load_lds_dwordx4 v[142:143], off offset:1280
	s_add_u32 m0, s76, 0x2300
	s_nop 0
	global_load_lds_dwordx4 v[144:145], off offset:1280
	s_add_u32 m0, s76, 0x3300
	s_nop 0
	global_load_lds_dwordx4 v[152:153], off offset:1280
	s_add_u32 m0, s76, 0x4300
	s_nop 0
	global_load_lds_dwordx4 v[140:141], off offset:1280
	s_add_u32 m0, s76, 0x5300
	s_nop 0
	global_load_lds_dwordx4 v[146:147], off offset:1280
	s_add_u32 m0, s76, 0x6300
	s_nop 0
	global_load_lds_dwordx4 v[148:149], off offset:1280
	s_add_u32 m0, s76, 0x7300
	s_nop 0
	global_load_lds_dwordx4 v[150:151], off offset:1280
	s_waitcnt lgkmcnt(6)
	v_mfma_f32_32x32x16_bf16 v[48:63], v[156:159], v[164:167], v[48:63]
	s_waitcnt lgkmcnt(5)
	v_mfma_f32_32x32x16_bf16 v[32:47], v[156:159], v[168:171], v[32:47]
	s_waitcnt lgkmcnt(4)
	v_mfma_f32_32x32x16_bf16 v[16:31], v[172:175], v[164:167], v[16:31]
	v_mfma_f32_32x32x16_bf16 v[0:15], v[172:175], v[168:171], v[0:15]
	ds_read_b128 v[156:159], v198 offset:32768
	ds_read_b128 v[164:167], v202 offset:32768
	ds_read_b128 v[168:171], v202 offset:36864
	ds_read_b128 v[172:175], v198 offset:36864
	s_waitcnt lgkmcnt(6)
	v_mfma_f32_32x32x16_bf16 v[48:63], v[176:179], v[180:183], v[48:63]
	s_waitcnt lgkmcnt(5)
	v_mfma_f32_32x32x16_bf16 v[32:47], v[176:179], v[184:187], v[32:47]
	s_waitcnt lgkmcnt(4)
	v_mfma_f32_32x32x16_bf16 v[16:31], v[188:191], v[180:183], v[16:31]
	v_mfma_f32_32x32x16_bf16 v[0:15], v[188:191], v[184:187], v[0:15]
	ds_read_b128 v[176:179], v199 offset:32768
	ds_read_b128 v[180:183], v203 offset:32768
	ds_read_b128 v[184:187], v203 offset:36864
	ds_read_b128 v[188:191], v199 offset:36864
	s_waitcnt lgkmcnt(6)
	v_mfma_f32_32x32x16_bf16 v[48:63], v[156:159], v[164:167], v[48:63]
	s_waitcnt lgkmcnt(5)
	v_mfma_f32_32x32x16_bf16 v[32:47], v[156:159], v[168:171], v[32:47]
	s_waitcnt lgkmcnt(4)
	v_mfma_f32_32x32x16_bf16 v[16:31], v[172:175], v[164:167], v[16:31]
	v_mfma_f32_32x32x16_bf16 v[0:15], v[172:175], v[168:171], v[0:15]
	s_waitcnt lgkmcnt(2)
	v_mfma_f32_32x32x16_bf16 v[48:63], v[176:179], v[180:183], v[48:63]
	s_waitcnt lgkmcnt(1)
	v_mfma_f32_32x32x16_bf16 v[32:47], v[176:179], v[184:187], v[32:47]
	s_waitcnt lgkmcnt(0)
	v_mfma_f32_32x32x16_bf16 v[16:31], v[188:191], v[180:183], v[16:31]
	v_mfma_f32_32x32x16_bf16 v[0:15], v[188:191], v[184:187], v[0:15]
	s_setprio 0
	s_waitcnt vmcnt(0)
	s_barrier
	s_setprio 1
	ds_read_b128 v[156:159], v196
	ds_read_b128 v[164:167], v200
	ds_read_b128 v[168:171], v200 offset:4096
	ds_read_b128 v[172:175], v196 offset:4096
	ds_read_b128 v[176:179], v197
	ds_read_b128 v[180:183], v201
	ds_read_b128 v[184:187], v201 offset:4096
	ds_read_b128 v[188:191], v197 offset:4096
	s_add_u32 m0, s76, 0x8280
	s_nop 0
	global_load_lds_dwordx4 v[138:139], off offset:1408
	s_add_u32 m0, s76, 0x9280
	s_nop 0
	global_load_lds_dwordx4 v[142:143], off offset:1408
	s_add_u32 m0, s76, 0xa280
	s_nop 0
	global_load_lds_dwordx4 v[144:145], off offset:1408
	s_add_u32 m0, s76, 0xb280
	s_nop 0
	global_load_lds_dwordx4 v[152:153], off offset:1408
	s_add_u32 m0, s76, 0xc280
	s_nop 0
	global_load_lds_dwordx4 v[140:141], off offset:1408
	s_add_u32 m0, s76, 0xd280
	s_nop 0
	global_load_lds_dwordx4 v[146:147], off offset:1408
	s_add_u32 m0, s76, 0xe280
	s_nop 0
	global_load_lds_dwordx4 v[148:149], off offset:1408
	s_add_u32 m0, s76, 0xf280
	s_nop 0
	global_load_lds_dwordx4 v[150:151], off offset:1408
	s_waitcnt lgkmcnt(6)
	v_mfma_f32_32x32x16_bf16 v[48:63], v[156:159], v[164:167], v[48:63]
	s_waitcnt lgkmcnt(5)
	v_mfma_f32_32x32x16_bf16 v[32:47], v[156:159], v[168:171], v[32:47]
	s_waitcnt lgkmcnt(4)
	v_mfma_f32_32x32x16_bf16 v[16:31], v[172:175], v[164:167], v[16:31]
	v_mfma_f32_32x32x16_bf16 v[0:15], v[172:175], v[168:171], v[0:15]
	ds_read_b128 v[156:159], v198
	ds_read_b128 v[164:167], v202
	ds_read_b128 v[168:171], v202 offset:4096
	ds_read_b128 v[172:175], v198 offset:4096
	s_waitcnt lgkmcnt(6)
	v_mfma_f32_32x32x16_bf16 v[48:63], v[176:179], v[180:183], v[48:63]
	s_waitcnt lgkmcnt(5)
	v_mfma_f32_32x32x16_bf16 v[32:47], v[176:179], v[184:187], v[32:47]
	s_waitcnt lgkmcnt(4)
	v_mfma_f32_32x32x16_bf16 v[16:31], v[188:191], v[180:183], v[16:31]
	v_mfma_f32_32x32x16_bf16 v[0:15], v[188:191], v[184:187], v[0:15]
	ds_read_b128 v[176:179], v199
	ds_read_b128 v[180:183], v203
	ds_read_b128 v[184:187], v203 offset:4096
	ds_read_b128 v[188:191], v199 offset:4096
	s_waitcnt lgkmcnt(6)
	v_mfma_f32_32x32x16_bf16 v[48:63], v[156:159], v[164:167], v[48:63]
	s_waitcnt lgkmcnt(5)
	v_mfma_f32_32x32x16_bf16 v[32:47], v[156:159], v[168:171], v[32:47]
	s_waitcnt lgkmcnt(4)
	v_mfma_f32_32x32x16_bf16 v[16:31], v[172:175], v[164:167], v[16:31]
	v_mfma_f32_32x32x16_bf16 v[0:15], v[172:175], v[168:171], v[0:15]
	s_waitcnt lgkmcnt(2)
	v_mfma_f32_32x32x16_bf16 v[48:63], v[176:179], v[180:183], v[48:63]
	s_waitcnt lgkmcnt(1)
	v_mfma_f32_32x32x16_bf16 v[32:47], v[176:179], v[184:187], v[32:47]
	s_waitcnt lgkmcnt(0)
	v_mfma_f32_32x32x16_bf16 v[16:31], v[188:191], v[180:183], v[16:31]
	v_mfma_f32_32x32x16_bf16 v[0:15], v[188:191], v[184:187], v[0:15]
	s_setprio 0
	s_waitcnt vmcnt(0)
	s_barrier
;     ...
;     G_LOAD(x, 0);
;     G_STORE(x, 0);
;     __syncthreads();
;     if (KT > 1) G_LOAD(x, 1);
;     for (int kt = 0; kt < KT; kt += 2) {
;       if (kt + 2 < KT && dummy != 2) G_LOAD(y, kt + 2);
;       G_COMPUTE(0);
;       if (kt + 1 < KT && dummy != 2) G_STORE(x, 1);
;       __syncthreads();
;       if (kt + 1 >= KT) break;
;       if (kt + 3 < KT && dummy != 2) G_LOAD(x, kt + 3);
;       G_COMPUTE(1);
;       if (kt + 2 < KT && dummy != 2) G_STORE(y, 0);
;       __syncthreads();
	s_setprio 1
	ds_read_b128 v[156:159], v196 offset:32768
	ds_read_b128 v[164:167], v200 offset:32768
	ds_read_b128 v[168:171], v200 offset:36864
	ds_read_b128 v[172:175], v196 offset:36864
	ds_read_b128 v[176:179], v197 offset:32768
	ds_read_b128 v[180:183], v201 offset:32768
	ds_read_b128 v[184:187], v201 offset:36864
	ds_read_b128 v[188:191], v197 offset:36864
	s_add_u32 m0, s76, 0x200
	s_nop 0
	global_load_lds_dwordx4 v[138:139], off offset:1536
	s_add_u32 m0, s76, 0x1200
	s_nop 0
	global_load_lds_dwordx4 v[142:143], off offset:1536
	s_add_u32 m0, s76, 0x2200
	s_nop 0
	global_load_lds_dwordx4 v[144:145], off offset:1536
	s_add_u32 m0, s76, 0x3200
	s_nop 0
	global_load_lds_dwordx4 v[152:153], off offset:1536
	s_add_u32 m0, s76, 0x4200
	s_nop 0
	global_load_lds_dwordx4 v[140:141], off offset:1536
	s_add_u32 m0, s76, 0x5200
	s_nop 0
	global_load_lds_dwordx4 v[146:147], off offset:1536
	s_add_u32 m0, s76, 0x6200
	s_nop 0
	global_load_lds_dwordx4 v[148:149], off offset:1536
	s_add_u32 m0, s76, 0x7200
	s_nop 0
	global_load_lds_dwordx4 v[150:151], off offset:1536
	s_waitcnt lgkmcnt(6)
	v_mfma_f32_32x32x16_bf16 v[48:63], v[156:159], v[164:167], v[48:63]
	s_waitcnt lgkmcnt(5)
	v_mfma_f32_32x32x16_bf16 v[32:47], v[156:159], v[168:171], v[32:47]
	s_waitcnt lgkmcnt(4)
	v_mfma_f32_32x32x16_bf16 v[16:31], v[172:175], v[164:167], v[16:31]
	v_mfma_f32_32x32x16_bf16 v[0:15], v[172:175], v[168:171], v[0:15]
	ds_read_b128 v[156:159], v198 offset:32768
	ds_read_b128 v[164:167], v202 offset:32768
	ds_read_b128 v[168:171], v202 offset:36864
	ds_read_b128 v[172:175], v198 offset:36864
	s_waitcnt lgkmcnt(6)
	v_mfma_f32_32x32x16_bf16 v[48:63], v[176:179], v[180:183], v[48:63]
	s_waitcnt lgkmcnt(5)
	v_mfma_f32_32x32x16_bf16 v[32:47], v[176:179], v[184:187], v[32:47]
	s_waitcnt lgkmcnt(4)
	v_mfma_f32_32x32x16_bf16 v[16:31], v[188:191], v[180:183], v[16:31]
	v_mfma_f32_32x32x16_bf16 v[0:15], v[188:191], v[184:187], v[0:15]
	ds_read_b128 v[176:179], v199 offset:32768
	ds_read_b128 v[180:183], v203 offset:32768
	ds_read_b128 v[184:187], v203 offset:36864
	ds_read_b128 v[188:191], v199 offset:36864
	s_waitcnt lgkmcnt(6)
	v_mfma_f32_32x32x16_bf16 v[48:63], v[156:159], v[164:167], v[48:63]
	s_waitcnt lgkmcnt(5)
	v_mfma_f32_32x32x16_bf16 v[32:47], v[156:159], v[168:171], v[32:47]
	s_waitcnt lgkmcnt(4)
	v_mfma_f32_32x32x16_bf16 v[16:31], v[172:175], v[164:167], v[16:31]
	v_mfma_f32_32x32x16_bf16 v[0:15], v[172:175], v[168:171], v[0:15]
	s_waitcnt lgkmcnt(2)
	v_mfma_f32_32x32x16_bf16 v[48:63], v[176:179], v[180:183], v[48:63]
	s_waitcnt lgkmcnt(1)
	v_mfma_f32_32x32x16_bf16 v[32:47], v[176:179], v[184:187], v[32:47]
	s_waitcnt lgkmcnt(0)
	v_mfma_f32_32x32x16_bf16 v[16:31], v[188:191], v[180:183], v[16:31]
	v_mfma_f32_32x32x16_bf16 v[0:15], v[188:191], v[184:187], v[0:15]
	s_setprio 0
	s_waitcnt vmcnt(0)
	s_barrier
	s_setprio 1
	ds_read_b128 v[156:159], v196
	ds_read_b128 v[164:167], v200
	ds_read_b128 v[168:171], v200 offset:4096
	ds_read_b128 v[172:175], v196 offset:4096
	ds_read_b128 v[176:179], v197
	ds_read_b128 v[180:183], v201
	ds_read_b128 v[184:187], v201 offset:4096
	ds_read_b128 v[188:191], v197 offset:4096
	s_add_u32 m0, s76, 0x8180
	s_nop 0
	global_load_lds_dwordx4 v[138:139], off offset:1664
	s_add_u32 m0, s76, 0x9180
	s_nop 0
	global_load_lds_dwordx4 v[142:143], off offset:1664
	s_add_u32 m0, s76, 0xa180
	s_nop 0
	global_load_lds_dwordx4 v[144:145], off offset:1664
	s_add_u32 m0, s76, 0xb180
	s_nop 0
	global_load_lds_dwordx4 v[152:153], off offset:1664
	s_add_u32 m0, s76, 0xc180
	s_nop 0
	global_load_lds_dwordx4 v[140:141], off offset:1664
	s_add_u32 m0, s76, 0xd180
	s_nop 0
	global_load_lds_dwordx4 v[146:147], off offset:1664
	s_add_u32 m0, s76, 0xe180
	s_nop 0
	global_load_lds_dwordx4 v[148:149], off offset:1664
	s_add_u32 m0, s76, 0xf180
	s_nop 0
	global_load_lds_dwordx4 v[150:151], off offset:1664
	s_waitcnt lgkmcnt(6)
	v_mfma_f32_32x32x16_bf16 v[48:63], v[156:159], v[164:167], v[48:63]
	s_waitcnt lgkmcnt(5)
	v_mfma_f32_32x32x16_bf16 v[32:47], v[156:159], v[168:171], v[32:47]
	s_waitcnt lgkmcnt(4)
	v_mfma_f32_32x32x16_bf16 v[16:31], v[172:175], v[164:167], v[16:31]
	v_mfma_f32_32x32x16_bf16 v[0:15], v[172:175], v[168:171], v[0:15]
	ds_read_b128 v[156:159], v198
	ds_read_b128 v[164:167], v202
	ds_read_b128 v[168:171], v202 offset:4096
	ds_read_b128 v[172:175], v198 offset:4096
	s_waitcnt lgkmcnt(6)
	v_mfma_f32_32x32x16_bf16 v[48:63], v[176:179], v[180:183], v[48:63]
	s_waitcnt lgkmcnt(5)
	v_mfma_f32_32x32x16_bf16 v[32:47], v[176:179], v[184:187], v[32:47]
	s_waitcnt lgkmcnt(4)
	v_mfma_f32_32x32x16_bf16 v[16:31], v[188:191], v[180:183], v[16:31]
	v_mfma_f32_32x32x16_bf16 v[0:15], v[188:191], v[184:187], v[0:15]
	ds_read_b128 v[176:179], v199
	ds_read_b128 v[180:183], v203
	ds_read_b128 v[184:187], v203 offset:4096
	ds_read_b128 v[188:191], v199 offset:4096
	s_waitcnt lgkmcnt(6)
	v_mfma_f32_32x32x16_bf16 v[48:63], v[156:159], v[164:167], v[48:63]
	s_waitcnt lgkmcnt(5)
	v_mfma_f32_32x32x16_bf16 v[32:47], v[156:159], v[168:171], v[32:47]
	s_waitcnt lgkmcnt(4)
	v_mfma_f32_32x32x16_bf16 v[16:31], v[172:175], v[164:167], v[16:31]
	v_mfma_f32_32x32x16_bf16 v[0:15], v[172:175], v[168:171], v[0:15]
	s_waitcnt lgkmcnt(2)
	v_mfma_f32_32x32x16_bf16 v[48:63], v[176:179], v[180:183], v[48:63]
	s_waitcnt lgkmcnt(1)
	v_mfma_f32_32x32x16_bf16 v[32:47], v[176:179], v[184:187], v[32:47]
	s_waitcnt lgkmcnt(0)
	v_mfma_f32_32x32x16_bf16 v[16:31], v[188:191], v[180:183], v[16:31]
	v_mfma_f32_32x32x16_bf16 v[0:15], v[188:191], v[184:187], v[0:15]
	s_setprio 0
	s_waitcnt vmcnt(0)
	s_barrier
;     ...
;     G_LOAD(x, 0);
;     G_STORE(x, 0);
;     __syncthreads();
;     if (KT > 1) G_LOAD(x, 1);
;     for (int kt = 0; kt < KT; kt += 2) {
;       if (kt + 2 < KT && dummy != 2) G_LOAD(y, kt + 2);
;       G_COMPUTE(0);
;       if (kt + 1 < KT && dummy != 2) G_STORE(x, 1);
;       __syncthreads();
;       if (kt + 1 >= KT) break;
;       if (kt + 3 < KT && dummy != 2) G_LOAD(x, kt + 3);
;       G_COMPUTE(1);
;       if (kt + 2 < KT && dummy != 2) G_STORE(y, 0);
;       __syncthreads();
	s_setprio 1
	ds_read_b128 v[156:159], v196 offset:32768
	ds_read_b128 v[164:167], v200 offset:32768
	ds_read_b128 v[168:171], v200 offset:36864
	ds_read_b128 v[172:175], v196 offset:36864
	ds_read_b128 v[176:179], v197 offset:32768
	ds_read_b128 v[180:183], v201 offset:32768
	ds_read_b128 v[184:187], v201 offset:36864
	ds_read_b128 v[188:191], v197 offset:36864
	s_add_u32 m0, s76, 0x100
	s_nop 0
	global_load_lds_dwordx4 v[138:139], off offset:1792
	s_add_u32 m0, s76, 0x1100
	s_nop 0
	global_load_lds_dwordx4 v[142:143], off offset:1792
	s_add_u32 m0, s76, 0x2100
	s_nop 0
	global_load_lds_dwordx4 v[144:145], off offset:1792
	s_add_u32 m0, s76, 0x3100
	s_nop 0
	global_load_lds_dwordx4 v[152:153], off offset:1792
	s_add_u32 m0, s76, 0x4100
	s_nop 0
	global_load_lds_dwordx4 v[140:141], off offset:1792
	s_add_u32 m0, s76, 0x5100
	s_nop 0
	global_load_lds_dwordx4 v[146:147], off offset:1792
	s_add_u32 m0, s76, 0x6100
	s_nop 0
	global_load_lds_dwordx4 v[148:149], off offset:1792
	s_add_u32 m0, s76, 0x7100
	s_nop 0
	global_load_lds_dwordx4 v[150:151], off offset:1792
	s_waitcnt lgkmcnt(6)
	v_mfma_f32_32x32x16_bf16 v[48:63], v[156:159], v[164:167], v[48:63]
	s_waitcnt lgkmcnt(5)
	v_mfma_f32_32x32x16_bf16 v[32:47], v[156:159], v[168:171], v[32:47]
	s_waitcnt lgkmcnt(4)
	v_mfma_f32_32x32x16_bf16 v[16:31], v[172:175], v[164:167], v[16:31]
	v_mfma_f32_32x32x16_bf16 v[0:15], v[172:175], v[168:171], v[0:15]
	ds_read_b128 v[156:159], v198 offset:32768
	ds_read_b128 v[164:167], v202 offset:32768
	ds_read_b128 v[168:171], v202 offset:36864
	ds_read_b128 v[172:175], v198 offset:36864
	s_waitcnt lgkmcnt(6)
	v_mfma_f32_32x32x16_bf16 v[48:63], v[176:179], v[180:183], v[48:63]
	s_waitcnt lgkmcnt(5)
	v_mfma_f32_32x32x16_bf16 v[32:47], v[176:179], v[184:187], v[32:47]
	s_waitcnt lgkmcnt(4)
	v_mfma_f32_32x32x16_bf16 v[16:31], v[188:191], v[180:183], v[16:31]
	v_mfma_f32_32x32x16_bf16 v[0:15], v[188:191], v[184:187], v[0:15]
	ds_read_b128 v[176:179], v199 offset:32768
	ds_read_b128 v[180:183], v203 offset:32768
	ds_read_b128 v[184:187], v203 offset:36864
	ds_read_b128 v[188:191], v199 offset:36864
	s_waitcnt lgkmcnt(6)
	v_mfma_f32_32x32x16_bf16 v[48:63], v[156:159], v[164:167], v[48:63]
	s_waitcnt lgkmcnt(5)
	v_mfma_f32_32x32x16_bf16 v[32:47], v[156:159], v[168:171], v[32:47]
	s_waitcnt lgkmcnt(4)
	v_mfma_f32_32x32x16_bf16 v[16:31], v[172:175], v[164:167], v[16:31]
	v_mfma_f32_32x32x16_bf16 v[0:15], v[172:175], v[168:171], v[0:15]
	s_waitcnt lgkmcnt(2)
	v_mfma_f32_32x32x16_bf16 v[48:63], v[176:179], v[180:183], v[48:63]
	s_waitcnt lgkmcnt(1)
	v_mfma_f32_32x32x16_bf16 v[32:47], v[176:179], v[184:187], v[32:47]
	s_waitcnt lgkmcnt(0)
	v_mfma_f32_32x32x16_bf16 v[16:31], v[188:191], v[180:183], v[16:31]
	v_mfma_f32_32x32x16_bf16 v[0:15], v[188:191], v[184:187], v[0:15]
	s_setprio 0
	s_waitcnt vmcnt(0)
	s_barrier
;     ...
;     if (EPI == EPI_P) {
;       const int wc0 = n0e + (cb & 64);
;       int vh = -1;
;       if (wc0 >= 1344 && wc0 < 1472) vh = (wc0 - 1344) >> 6;
;       else if (wc0 >= 1984 && wc0 < 2240) vh = 2 + ((wc0 - 1984) >> 6);
;       else if (wc0 >= 2752 && wc0 < 3008) vh = 6 + ((wc0 - 2752) >> 6);
	s_setprio 1
	ds_read_b128 v[156:159], v196
	ds_read_b128 v[164:167], v200
	ds_read_b128 v[168:171], v200 offset:4096
	ds_read_b128 v[172:175], v196 offset:4096
	ds_read_b128 v[176:179], v197
	ds_read_b128 v[180:183], v201
	ds_read_b128 v[184:187], v201 offset:4096
	ds_read_b128 v[188:191], v197 offset:4096
	s_add_u32 m0, s76, 0x8080
	s_nop 0
	global_load_lds_dwordx4 v[138:139], off offset:1920
	s_add_u32 m0, s76, 0x9080
	s_nop 0
	global_load_lds_dwordx4 v[142:143], off offset:1920
	s_add_u32 m0, s76, 0xa080
	s_nop 0
	global_load_lds_dwordx4 v[144:145], off offset:1920
	s_add_u32 m0, s76, 0xb080
	s_nop 0
	global_load_lds_dwordx4 v[152:153], off offset:1920
	s_add_u32 m0, s76, 0xc080
	s_nop 0
	global_load_lds_dwordx4 v[140:141], off offset:1920
	s_add_u32 m0, s76, 0xd080
	s_nop 0
	global_load_lds_dwordx4 v[146:147], off offset:1920
	s_add_u32 m0, s76, 0xe080
	s_nop 0
	global_load_lds_dwordx4 v[148:149], off offset:1920
	s_add_u32 m0, s76, 0xf080
	s_nop 0
	global_load_lds_dwordx4 v[150:151], off offset:1920
	s_waitcnt lgkmcnt(6)
	v_mfma_f32_32x32x16_bf16 v[48:63], v[156:159], v[164:167], v[48:63]
	s_waitcnt lgkmcnt(5)
	v_mfma_f32_32x32x16_bf16 v[32:47], v[156:159], v[168:171], v[32:47]
	s_waitcnt lgkmcnt(4)
	v_mfma_f32_32x32x16_bf16 v[16:31], v[172:175], v[164:167], v[16:31]
	v_mfma_f32_32x32x16_bf16 v[0:15], v[172:175], v[168:171], v[0:15]
	ds_read_b128 v[156:159], v198
	ds_read_b128 v[164:167], v202
	ds_read_b128 v[168:171], v202 offset:4096
	ds_read_b128 v[172:175], v198 offset:4096
	s_waitcnt lgkmcnt(6)
	v_mfma_f32_32x32x16_bf16 v[48:63], v[176:179], v[180:183], v[48:63]
	s_waitcnt lgkmcnt(5)
	v_mfma_f32_32x32x16_bf16 v[32:47], v[176:179], v[184:187], v[32:47]
	s_waitcnt lgkmcnt(4)
	v_mfma_f32_32x32x16_bf16 v[16:31], v[188:191], v[180:183], v[16:31]
	v_mfma_f32_32x32x16_bf16 v[0:15], v[188:191], v[184:187], v[0:15]
	ds_read_b128 v[176:179], v199
	ds_read_b128 v[180:183], v203
	ds_read_b128 v[184:187], v203 offset:4096
	ds_read_b128 v[188:191], v199 offset:4096
	s_waitcnt lgkmcnt(6)
	v_mfma_f32_32x32x16_bf16 v[48:63], v[156:159], v[164:167], v[48:63]
	s_waitcnt lgkmcnt(5)
	v_mfma_f32_32x32x16_bf16 v[32:47], v[156:159], v[168:171], v[32:47]
	s_waitcnt lgkmcnt(4)
	v_mfma_f32_32x32x16_bf16 v[16:31], v[172:175], v[164:167], v[16:31]
	v_mfma_f32_32x32x16_bf16 v[0:15], v[172:175], v[168:171], v[0:15]
	s_waitcnt lgkmcnt(2)
	v_mfma_f32_32x32x16_bf16 v[48:63], v[176:179], v[180:183], v[48:63]
	s_waitcnt lgkmcnt(1)
	v_mfma_f32_32x32x16_bf16 v[32:47], v[176:179], v[184:187], v[32:47]
	s_waitcnt lgkmcnt(0)
	v_mfma_f32_32x32x16_bf16 v[16:31], v[188:191], v[180:183], v[16:31]
	v_mfma_f32_32x32x16_bf16 v[0:15], v[188:191], v[184:187], v[0:15]
	s_setprio 0
	s_waitcnt vmcnt(0)
	s_barrier
	s_setprio 1
	ds_read_b128 v[156:159], v196 offset:32768
	ds_read_b128 v[164:167], v200 offset:32768
	ds_read_b128 v[168:171], v200 offset:36864
	ds_read_b128 v[172:175], v196 offset:36864
	ds_read_b128 v[176:179], v197 offset:32768
	ds_read_b128 v[180:183], v201 offset:32768
	ds_read_b128 v[184:187], v201 offset:36864
	ds_read_b128 v[188:191], v197 offset:36864
	s_waitcnt lgkmcnt(6)
	v_mfma_f32_32x32x16_bf16 v[48:63], v[156:159], v[164:167], v[48:63]
	s_waitcnt lgkmcnt(5)
	v_mfma_f32_32x32x16_bf16 v[32:47], v[156:159], v[168:171], v[32:47]
	s_waitcnt lgkmcnt(4)
	v_mfma_f32_32x32x16_bf16 v[16:31], v[172:175], v[164:167], v[16:31]
	v_mfma_f32_32x32x16_bf16 v[0:15], v[172:175], v[168:171], v[0:15]
	ds_read_b128 v[156:159], v198 offset:32768
	ds_read_b128 v[164:167], v202 offset:32768
	ds_read_b128 v[168:171], v202 offset:36864
	ds_read_b128 v[172:175], v198 offset:36864
	s_waitcnt lgkmcnt(6)
	v_mfma_f32_32x32x16_bf16 v[48:63], v[176:179], v[180:183], v[48:63]
	s_waitcnt lgkmcnt(5)
	v_mfma_f32_32x32x16_bf16 v[32:47], v[176:179], v[184:187], v[32:47]
	s_waitcnt lgkmcnt(4)
	v_mfma_f32_32x32x16_bf16 v[16:31], v[188:191], v[180:183], v[16:31]
	v_mfma_f32_32x32x16_bf16 v[0:15], v[188:191], v[184:187], v[0:15]
	ds_read_b128 v[176:179], v199 offset:32768
	ds_read_b128 v[180:183], v203 offset:32768
	ds_read_b128 v[184:187], v203 offset:36864
	ds_read_b128 v[188:191], v199 offset:36864
	s_waitcnt lgkmcnt(6)
	v_mfma_f32_32x32x16_bf16 v[48:63], v[156:159], v[164:167], v[48:63]
	s_waitcnt lgkmcnt(5)
	v_mfma_f32_32x32x16_bf16 v[32:47], v[156:159], v[168:171], v[32:47]
	s_waitcnt lgkmcnt(4)
	v_mfma_f32_32x32x16_bf16 v[16:31], v[172:175], v[164:167], v[16:31]
	v_mfma_f32_32x32x16_bf16 v[0:15], v[172:175], v[168:171], v[0:15]
	s_waitcnt lgkmcnt(2)
	v_mfma_f32_32x32x16_bf16 v[48:63], v[176:179], v[180:183], v[48:63]
	s_waitcnt lgkmcnt(1)
	v_mfma_f32_32x32x16_bf16 v[32:47], v[176:179], v[184:187], v[32:47]
	s_waitcnt lgkmcnt(0)
	v_mfma_f32_32x32x16_bf16 v[16:31], v[188:191], v[180:183], v[16:31]
	v_mfma_f32_32x32x16_bf16 v[0:15], v[188:191], v[184:187], v[0:15]
	s_setprio 0
	v_mov_b32_e32 v65, v155
	v_mov_b32_e32 v66, v96
	s_barrier
	s_movk_i32 s0, 0x7f
	v_and_b32_e32 v64, 64, v66
	v_add_u32_e32 v67, s4, v64
	v_add_u32_e32 v68, 0xfffffac0, v67
	v_cmp_lt_u32_e32 vcc, s0, v68
	s_and_saveexec_b64 s[0:1], vcc
	s_xor_b64 s[0:1], exec, s[0:1]
	s_cbranch_execz .LBB0_580
	v_add_u32_e32 v68, 0xfffff840, v67
	v_cmp_lt_u32_e32 vcc, s94, v68
	s_and_saveexec_b64 s[2:3], vcc
	s_xor_b64 s[2:3], exec, s[2:3]
	v_add_u32_e32 v64, 0xfffff540, v67
	s_movk_i32 s5, 0x100
	v_cmp_gt_u32_e32 vcc, s5, v64
	v_lshrrev_b32_e32 v64, 6, v64
	v_add_u32_e32 v64, 6, v64
	v_cndmask_b32_e32 v64, -1, v64, vcc
	s_andn2_saveexec_b64 s[2:3], s[2:3]
	v_lshrrev_b32_e32 v64, 6, v68
	v_add_u32_e32 v64, 2, v64
	s_or_b64 exec, exec, s[2:3]
